# v3 + LRU loop-top counted vmcnt (skip store acks) + removed mid-segment setprio 0/1 pairs in GEMM K-loops
# speedup vs baseline: 1.0014x; 1.0014x over previous
; #define PG8_STAGE(bufoff, gbase, voff) do { _Pragma("unroll") for (int _i = 0; _i < 2; ++_i) \
;         __builtin_amdgcn_global_load_lds((const unsigned*)((const char*)(gbase) + (voff)[_i]), (PG8_LAS unsigned*)(lds + (bufoff) + ldsw + _i * 8192), 16, 0, 0); } while (0)
; #define PG8_LDA(dst, b, h) do { _Pragma("unroll") for (int m = 0; m < 4; ++m) _Pragma("unroll") for (int k = 0; k < 2; ++k) dst[m][k] = *(const PG8_LAS bf16x8*)(lds + PG8_SA(b, h) + aoff + m * 2048 + k * 1024); } while (0)
; #define PG8_LDB(dst, b, h) do { _Pragma("unroll") for (int n = 0; n < 2; ++n) _Pragma("unroll") for (int k = 0; k < 2; ++k) dst[n][k] = *(const PG8_LAS bf16x8*)(lds + PG8_SB(b, h) + boff + n * 2048 + k * 1024); } while (0)
; #define PG8_MMA(ai, bj, At, Bt) do { __builtin_amdgcn_s_setprio(1); _Pragma("unroll") for (int m = 0; m < 4; ++m) _Pragma("unroll") for (int n = 0; n < 2; ++n) _Pragma("unroll") for (int k = 0; k < 2; ++k) \
;         acc[ai][bj][m][n] = __builtin_amdgcn_mfma_f32_16x16x32_bf16(Bt[n][k], At[m][k], acc[ai][bj][m][n], 0, 0, 0); __builtin_amdgcn_s_setprio(0); } while (0)
; #define PG8_WAIT_V(n) asm volatile("s_waitcnt vmcnt(" #n ")" ::: "memory")
; #define PG8_WAIT_L(n) asm volatile("s_waitcnt lgkmcnt(" #n ")" ::: "memory")
; #define PG8_BAR __builtin_amdgcn_s_barrier()
; #define PG8_SCHED __builtin_amdgcn_sched_barrier(0)
; template <class Epi, class Sched, bool ALIGN_EPI = false, bool SP2 = false>
; __device__ __forceinline__ void gemm_phase(PG8_LAS unsigned char* lds, const Gemm g, const Sched& S, const Epi& E) {
;     ...
;         for (int t = 0; t < nt; t += 2) {
;             const bool last = (t == nt - 2);
;             const char* a1 = cA + (size_t)(t + 1) * kstep;
;             const char* a2 = last ? nA : cA + (size_t)(t + 2) * kstep; const char* b2 = last ? nB : cB + (size_t)(t + 2) * kstep;
;             const char* a3 = a2 + kstep; const char* b3 = b2 + kstep;
;             if (last && has_next) S.a_ready(nxt);
;             if constexpr (SP2) {
;             PG8_LDB(B0, 0, 0); PG8_LDB(B1, 0, 1); PG8_SCHED; PG8_LDA(At, 0, 0); PG8_STAGE(PG8_SA(1, 1), a1 + hstepA, voffA);
;             PG8_WAIT_V(8); PG8_WAIT_L(0); PG8_BAR; PG8_MMA(0, 0, At, B0); PG8_MMA(0, 1, At, B1); PG8_BAR; PG8_SCHED;
;             PG8_LDA(At, 0, 1); PG8_STAGE(PG8_SB(0, 0), b2, voffB); PG8_STAGE(PG8_SB(0, 1), b2 + hstep, voffB); PG8_STAGE(PG8_SA(0, 0), a2, voffA);
.LBB0_108:
	s_add_u32 s54, s52, 0x100
	s_addc_u32 s55, s53, 0
	s_add_i32 s79, 0, 0x10000
	s_cmp_eq_u32 s78, 40
	s_cselect_b32 s59, s49, s55
	s_cselect_b32 s58, s48, s54
	v_add_u32_e32 v168, s79, v157
	s_cselect_b32 s57, s51, s77
	s_cselect_b32 s56, s50, s37
	s_add_i32 s80, 0, 0x14000
	ds_read_b128 v[102:105], v168
	ds_read_b128 v[110:113], v168 offset:1024
	ds_read_b128 v[150:153], v168 offset:2048
	ds_read_b128 v[170:173], v168 offset:3072
	v_add_u32_e32 v168, s80, v157
	ds_read_b128 v[174:177], v168
	ds_read_b128 v[178:181], v168 offset:1024
	ds_read_b128 v[182:185], v168 offset:2048
	ds_read_b128 v[198:201], v168 offset:3072
	v_lshl_add_u64 v[186:187], s[52:53], 0, v[166:167]
	s_add_i32 m0, s65, 0xc000
	ds_read_b128 v[202:205], v169
	ds_read_b128 v[206:209], v169 offset:1024
	ds_read_b128 v[210:213], v169 offset:2048
	ds_read_b128 v[214:217], v169 offset:3072
	ds_read_b128 v[218:221], v169 offset:4096
	ds_read_b128 v[222:225], v169 offset:5120
	ds_read_b128 v[226:229], v169 offset:6144
	ds_read_b128 v[236:239], v169 offset:7168
	global_load_lds_dwordx4 v[186:187], off
	v_lshl_add_u64 v[186:187], s[52:53], 0, v[146:147]
	s_add_i32 m0, s65, 0xe000
	s_nop 0
	global_load_lds_dwordx4 v[186:187], off
	s_waitcnt vmcnt(8)
	s_waitcnt lgkmcnt(0)
	s_barrier
	s_setprio 1
	s_waitcnt lgkmcnt(0)
	v_mfma_f32_16x16x32_bf16 v[134:137], v[102:105], v[202:205], v[134:137]
	v_mfma_f32_16x16x32_bf16 v[130:133], v[150:153], v[202:205], v[130:133]
	v_mfma_f32_16x16x32_bf16 v[126:129], v[102:105], v[210:213], v[126:129]
	v_mfma_f32_16x16x32_bf16 v[122:125], v[150:153], v[210:213], v[122:125]
	v_mfma_f32_16x16x32_bf16 v[118:121], v[102:105], v[218:221], v[118:121]
	v_mfma_f32_16x16x32_bf16 v[114:117], v[150:153], v[218:221], v[114:117]
	v_mfma_f32_16x16x32_bf16 v[106:109], v[102:105], v[226:229], v[106:109]
	v_mfma_f32_16x16x32_bf16 v[98:101], v[150:153], v[226:229], v[98:101]
	v_mfma_f32_16x16x32_bf16 v[134:137], v[110:113], v[206:209], v[134:137]
	v_mfma_f32_16x16x32_bf16 v[130:133], v[170:173], v[206:209], v[130:133]
	v_mfma_f32_16x16x32_bf16 v[126:129], v[110:113], v[214:217], v[126:129]
	v_mfma_f32_16x16x32_bf16 v[122:125], v[170:173], v[214:217], v[122:125]
	v_mfma_f32_16x16x32_bf16 v[118:121], v[110:113], v[222:225], v[118:121]
	v_mfma_f32_16x16x32_bf16 v[114:117], v[170:173], v[222:225], v[114:117]
	v_mfma_f32_16x16x32_bf16 v[106:109], v[110:113], v[236:239], v[106:109]
	v_mfma_f32_16x16x32_bf16 v[98:101], v[170:173], v[236:239], v[98:101]
	v_mfma_f32_16x16x32_bf16 v[62:65], v[174:177], v[202:205], v[62:65]
	v_mfma_f32_16x16x32_bf16 v[58:61], v[182:185], v[202:205], v[58:61]
	v_mfma_f32_16x16x32_bf16 v[54:57], v[174:177], v[210:213], v[54:57]
	v_mfma_f32_16x16x32_bf16 v[50:53], v[182:185], v[210:213], v[50:53]
	v_mfma_f32_16x16x32_bf16 v[46:49], v[174:177], v[218:221], v[46:49]
	v_mfma_f32_16x16x32_bf16 v[42:45], v[182:185], v[218:221], v[42:45]
	v_mfma_f32_16x16x32_bf16 v[38:41], v[174:177], v[226:229], v[38:41]
	v_mfma_f32_16x16x32_bf16 v[34:37], v[182:185], v[226:229], v[34:37]
	v_mfma_f32_16x16x32_bf16 v[62:65], v[178:181], v[206:209], v[62:65]
	v_mfma_f32_16x16x32_bf16 v[58:61], v[198:201], v[206:209], v[58:61]
	v_mfma_f32_16x16x32_bf16 v[54:57], v[178:181], v[214:217], v[54:57]
	v_mfma_f32_16x16x32_bf16 v[50:53], v[198:201], v[214:217], v[50:53]
	v_mfma_f32_16x16x32_bf16 v[46:49], v[178:181], v[222:225], v[46:49]
	v_mfma_f32_16x16x32_bf16 v[42:45], v[198:201], v[222:225], v[42:45]
	v_mfma_f32_16x16x32_bf16 v[38:41], v[178:181], v[236:239], v[38:41]
	v_mfma_f32_16x16x32_bf16 v[34:37], v[198:201], v[236:239], v[34:37]
	s_setprio 0
	s_barrier
	s_add_i32 s52, s79, s64
	v_lshl_add_u64 v[186:187], s[56:57], 0, v[140:141]
	s_mov_b32 m0, s52
	ds_read_b128 v[202:205], v169 offset:16384
	ds_read_b128 v[206:209], v169 offset:17408
	ds_read_b128 v[210:213], v169 offset:18432
	ds_read_b128 v[214:217], v169 offset:19456
	ds_read_b128 v[218:221], v169 offset:20480
	ds_read_b128 v[222:225], v169 offset:21504
	ds_read_b128 v[226:229], v169 offset:22528
	ds_read_b128 v[236:239], v169 offset:23552
	global_load_lds_dwordx4 v[186:187], off
	s_add_i32 m0, s52, 0x2000
	s_add_u32 s52, s56, 0xb0000
	v_lshl_add_u64 v[190:191], s[56:57], 0, v[144:145]
	s_addc_u32 s53, s57, 0
	s_add_i32 s79, s80, s64
	global_load_lds_dwordx4 v[190:191], off
	v_lshl_add_u64 v[194:195], s[52:53], 0, v[140:141]
	s_mov_b32 m0, s79
	v_lshl_add_u64 v[234:235], s[58:59], 0, v[142:143]
	global_load_lds_dwordx4 v[194:195], off
	v_lshl_add_u64 v[194:195], s[52:53], 0, v[144:145]
	s_add_i32 m0, s79, 0x2000
	s_nop 0
	global_load_lds_dwordx4 v[194:195], off
	v_lshl_add_u64 v[194:195], s[58:59], 0, v[138:139]
	s_mov_b32 m0, s65
	s_nop 0
	global_load_lds_dwordx4 v[194:195], off
	s_mov_b32 m0, s67
	s_nop 0
	global_load_lds_dwordx4 v[234:235], off
	s_waitcnt vmcnt(8)
	s_waitcnt lgkmcnt(0)
	s_barrier
; #define PG8_STAGE(bufoff, gbase, voff) do { _Pragma("unroll") for (int _i = 0; _i < 2; ++_i) \
;         __builtin_amdgcn_global_load_lds((const unsigned*)((const char*)(gbase) + (voff)[_i]), (PG8_LAS unsigned*)(lds + (bufoff) + ldsw + _i * 8192), 16, 0, 0); } while (0)
; #define PG8_LDA(dst, b, h) do { _Pragma("unroll") for (int m = 0; m < 4; ++m) _Pragma("unroll") for (int k = 0; k < 2; ++k) dst[m][k] = *(const PG8_LAS bf16x8*)(lds + PG8_SA(b, h) + aoff + m * 2048 + k * 1024); } while (0)
; #define PG8_LDB(dst, b, h) do { _Pragma("unroll") for (int n = 0; n < 2; ++n) _Pragma("unroll") for (int k = 0; k < 2; ++k) dst[n][k] = *(const PG8_LAS bf16x8*)(lds + PG8_SB(b, h) + boff + n * 2048 + k * 1024); } while (0)
; #define PG8_MMA(ai, bj, At, Bt) do { __builtin_amdgcn_s_setprio(1); _Pragma("unroll") for (int m = 0; m < 4; ++m) _Pragma("unroll") for (int n = 0; n < 2; ++n) _Pragma("unroll") for (int k = 0; k < 2; ++k) \
;         acc[ai][bj][m][n] = __builtin_amdgcn_mfma_f32_16x16x32_bf16(Bt[n][k], At[m][k], acc[ai][bj][m][n], 0, 0, 0); __builtin_amdgcn_s_setprio(0); } while (0)
; #define PG8_WAIT_V(n) asm volatile("s_waitcnt vmcnt(" #n ")" ::: "memory")
; #define PG8_WAIT_L(n) asm volatile("s_waitcnt lgkmcnt(" #n ")" ::: "memory")
; #define PG8_BAR __builtin_amdgcn_s_barrier()
; #define PG8_SCHED __builtin_amdgcn_sched_barrier(0)
; template <class Epi, class Sched, bool ALIGN_EPI = false, bool SP2 = false>
; __device__ __forceinline__ void gemm_phase(PG8_LAS unsigned char* lds, const Gemm g, const Sched& S, const Epi& E) {
;     ...
;             PG8_WAIT_V(8); PG8_WAIT_L(0); PG8_BAR; PG8_MMA(1, 0, At, B0); PG8_MMA(1, 1, At, B1); PG8_BAR; PG8_SCHED;
;             PG8_LDB(B0, 1, 0); PG8_LDB(B1, 1, 1); PG8_SCHED; PG8_LDA(At, 1, 0); PG8_STAGE(PG8_SA(0, 1), a2 + hstepA, voffA);
;             PG8_WAIT_V(8); PG8_WAIT_L(0); PG8_BAR; PG8_MMA(0, 0, At, B0); PG8_MMA(0, 1, At, B1); PG8_BAR; PG8_SCHED;
;             PG8_LDA(At, 1, 1); PG8_STAGE(PG8_SB(1, 0), b3, voffB); PG8_STAGE(PG8_SB(1, 1), b3 + hstep, voffB); PG8_STAGE(PG8_SA(1, 0), a3, voffA);
	s_setprio 1
	s_waitcnt lgkmcnt(0)
	v_mfma_f32_16x16x32_bf16 v[94:97], v[102:105], v[202:205], v[94:97]
	v_mfma_f32_16x16x32_bf16 v[90:93], v[150:153], v[202:205], v[90:93]
	v_mfma_f32_16x16x32_bf16 v[86:89], v[102:105], v[210:213], v[86:89]
	v_mfma_f32_16x16x32_bf16 v[82:85], v[150:153], v[210:213], v[82:85]
	v_mfma_f32_16x16x32_bf16 v[78:81], v[102:105], v[218:221], v[78:81]
	v_mfma_f32_16x16x32_bf16 v[74:77], v[150:153], v[218:221], v[74:77]
	v_mfma_f32_16x16x32_bf16 v[70:73], v[102:105], v[226:229], v[70:73]
	v_mfma_f32_16x16x32_bf16 v[66:69], v[150:153], v[226:229], v[66:69]
	v_mfma_f32_16x16x32_bf16 v[94:97], v[110:113], v[206:209], v[94:97]
	v_mfma_f32_16x16x32_bf16 v[90:93], v[170:173], v[206:209], v[90:93]
	v_mfma_f32_16x16x32_bf16 v[86:89], v[110:113], v[214:217], v[86:89]
	v_mfma_f32_16x16x32_bf16 v[82:85], v[170:173], v[214:217], v[82:85]
	v_mfma_f32_16x16x32_bf16 v[78:81], v[110:113], v[222:225], v[78:81]
	v_mfma_f32_16x16x32_bf16 v[74:77], v[170:173], v[222:225], v[74:77]
	v_mfma_f32_16x16x32_bf16 v[70:73], v[110:113], v[236:239], v[70:73]
	v_mfma_f32_16x16x32_bf16 v[66:69], v[170:173], v[236:239], v[66:69]
	v_mfma_f32_16x16x32_bf16 v[30:33], v[174:177], v[202:205], v[30:33]
	v_mfma_f32_16x16x32_bf16 v[26:29], v[182:185], v[202:205], v[26:29]
	v_mfma_f32_16x16x32_bf16 v[22:25], v[174:177], v[210:213], v[22:25]
	v_mfma_f32_16x16x32_bf16 v[18:21], v[182:185], v[210:213], v[18:21]
	v_mfma_f32_16x16x32_bf16 v[14:17], v[174:177], v[218:221], v[14:17]
	v_mfma_f32_16x16x32_bf16 v[10:13], v[182:185], v[218:221], v[10:13]
	v_mfma_f32_16x16x32_bf16 v[6:9], v[174:177], v[226:229], v[6:9]
	v_mfma_f32_16x16x32_bf16 v[2:5], v[182:185], v[226:229], v[2:5]
	v_mfma_f32_16x16x32_bf16 v[30:33], v[178:181], v[206:209], v[30:33]
	v_mfma_f32_16x16x32_bf16 v[26:29], v[198:201], v[206:209], v[26:29]
	v_mfma_f32_16x16x32_bf16 v[22:25], v[178:181], v[214:217], v[22:25]
	v_mfma_f32_16x16x32_bf16 v[18:21], v[198:201], v[214:217], v[18:21]
	v_mfma_f32_16x16x32_bf16 v[14:17], v[178:181], v[222:225], v[14:17]
	v_mfma_f32_16x16x32_bf16 v[10:13], v[198:201], v[222:225], v[10:13]
	v_mfma_f32_16x16x32_bf16 v[6:9], v[178:181], v[236:239], v[6:9]
	v_mfma_f32_16x16x32_bf16 v[2:5], v[198:201], v[236:239], v[2:5]
	s_setprio 0
	s_barrier
	s_add_i32 s79, 0, 0x18000
	v_add_u32_e32 v168, s79, v157
	s_add_i32 s80, 0, 0x1c000
	ds_read_b128 v[102:105], v168
	ds_read_b128 v[110:113], v168 offset:1024
	ds_read_b128 v[150:153], v168 offset:2048
	ds_read_b128 v[170:173], v168 offset:3072
	v_add_u32_e32 v168, s80, v157
	ds_read_b128 v[174:177], v168
	ds_read_b128 v[178:181], v168 offset:1024
	ds_read_b128 v[182:185], v168 offset:2048
	ds_read_b128 v[198:201], v168 offset:3072
	s_add_u32 s52, s58, 0xb0000
	s_addc_u32 s53, s59, 0
	s_mov_b32 m0, s68
	v_lshl_add_u64 v[246:247], s[52:53], 0, v[138:139]
	ds_read_b128 v[202:205], v169 offset:32768
	ds_read_b128 v[206:209], v169 offset:33792
	ds_read_b128 v[210:213], v169 offset:34816
	ds_read_b128 v[214:217], v169 offset:35840
	ds_read_b128 v[218:221], v169 offset:36864
	ds_read_b128 v[222:225], v169 offset:37888
	ds_read_b128 v[226:229], v169 offset:38912
	ds_read_b128 v[236:239], v169 offset:39936
	global_load_lds_dwordx4 v[246:247], off
	v_lshl_add_u64 v[246:247], s[52:53], 0, v[142:143]
	s_mov_b32 m0, s69
	s_nop 0
	global_load_lds_dwordx4 v[246:247], off
	s_waitcnt vmcnt(8)
	s_waitcnt lgkmcnt(0)
	s_barrier
	s_setprio 1
	s_waitcnt lgkmcnt(0)
	v_mfma_f32_16x16x32_bf16 v[134:137], v[102:105], v[202:205], v[134:137]
	v_mfma_f32_16x16x32_bf16 v[130:133], v[150:153], v[202:205], v[130:133]
	v_mfma_f32_16x16x32_bf16 v[126:129], v[102:105], v[210:213], v[126:129]
	v_mfma_f32_16x16x32_bf16 v[122:125], v[150:153], v[210:213], v[122:125]
	v_mfma_f32_16x16x32_bf16 v[118:121], v[102:105], v[218:221], v[118:121]
	v_mfma_f32_16x16x32_bf16 v[114:117], v[150:153], v[218:221], v[114:117]
	v_mfma_f32_16x16x32_bf16 v[106:109], v[102:105], v[226:229], v[106:109]
	v_mfma_f32_16x16x32_bf16 v[98:101], v[150:153], v[226:229], v[98:101]
	v_mfma_f32_16x16x32_bf16 v[134:137], v[110:113], v[206:209], v[134:137]
	v_mfma_f32_16x16x32_bf16 v[130:133], v[170:173], v[206:209], v[130:133]
	v_mfma_f32_16x16x32_bf16 v[126:129], v[110:113], v[214:217], v[126:129]
	v_mfma_f32_16x16x32_bf16 v[122:125], v[170:173], v[214:217], v[122:125]
	v_mfma_f32_16x16x32_bf16 v[118:121], v[110:113], v[222:225], v[118:121]
	v_mfma_f32_16x16x32_bf16 v[114:117], v[170:173], v[222:225], v[114:117]
	v_mfma_f32_16x16x32_bf16 v[106:109], v[110:113], v[236:239], v[106:109]
	v_mfma_f32_16x16x32_bf16 v[98:101], v[170:173], v[236:239], v[98:101]
	v_mfma_f32_16x16x32_bf16 v[62:65], v[174:177], v[202:205], v[62:65]
	v_mfma_f32_16x16x32_bf16 v[58:61], v[182:185], v[202:205], v[58:61]
	v_mfma_f32_16x16x32_bf16 v[54:57], v[174:177], v[210:213], v[54:57]
	v_mfma_f32_16x16x32_bf16 v[50:53], v[182:185], v[210:213], v[50:53]
	v_mfma_f32_16x16x32_bf16 v[46:49], v[174:177], v[218:221], v[46:49]
	v_mfma_f32_16x16x32_bf16 v[42:45], v[182:185], v[218:221], v[42:45]
	v_mfma_f32_16x16x32_bf16 v[38:41], v[174:177], v[226:229], v[38:41]
	v_mfma_f32_16x16x32_bf16 v[34:37], v[182:185], v[226:229], v[34:37]
	v_mfma_f32_16x16x32_bf16 v[62:65], v[178:181], v[206:209], v[62:65]
	v_mfma_f32_16x16x32_bf16 v[58:61], v[198:201], v[206:209], v[58:61]
	v_mfma_f32_16x16x32_bf16 v[54:57], v[178:181], v[214:217], v[54:57]
	v_mfma_f32_16x16x32_bf16 v[50:53], v[198:201], v[214:217], v[50:53]
	v_mfma_f32_16x16x32_bf16 v[46:49], v[178:181], v[222:225], v[46:49]
	v_mfma_f32_16x16x32_bf16 v[42:45], v[198:201], v[222:225], v[42:45]
	v_mfma_f32_16x16x32_bf16 v[38:41], v[178:181], v[236:239], v[38:41]
	v_mfma_f32_16x16x32_bf16 v[34:37], v[198:201], v[236:239], v[34:37]
	s_setprio 0
	s_barrier
; #define PG8_STAGE(bufoff, gbase, voff) do { _Pragma("unroll") for (int _i = 0; _i < 2; ++_i) \
;         __builtin_amdgcn_global_load_lds((const unsigned*)((const char*)(gbase) + (voff)[_i]), (PG8_LAS unsigned*)(lds + (bufoff) + ldsw + _i * 8192), 16, 0, 0); } while (0)
; #define PG8_LDA(dst, b, h) do { _Pragma("unroll") for (int m = 0; m < 4; ++m) _Pragma("unroll") for (int k = 0; k < 2; ++k) dst[m][k] = *(const PG8_LAS bf16x8*)(lds + PG8_SA(b, h) + aoff + m * 2048 + k * 1024); } while (0)
; #define PG8_MMA(ai, bj, At, Bt) do { __builtin_amdgcn_s_setprio(1); _Pragma("unroll") for (int m = 0; m < 4; ++m) _Pragma("unroll") for (int n = 0; n < 2; ++n) _Pragma("unroll") for (int k = 0; k < 2; ++k) \
;         acc[ai][bj][m][n] = __builtin_amdgcn_mfma_f32_16x16x32_bf16(Bt[n][k], At[m][k], acc[ai][bj][m][n], 0, 0, 0); __builtin_amdgcn_s_setprio(0); } while (0)
; #define PG8_WAIT_V(n) asm volatile("s_waitcnt vmcnt(" #n ")" ::: "memory")
; #define PG8_WAIT_L(n) asm volatile("s_waitcnt lgkmcnt(" #n ")" ::: "memory")
; #define PG8_BAR __builtin_amdgcn_s_barrier()
; #define PG8_SCHED __builtin_amdgcn_sched_barrier(0)
; template <class Epi, class Sched, bool ALIGN_EPI = false, bool SP2 = false>
; __device__ __forceinline__ void gemm_phase(PG8_LAS unsigned char* lds, const Gemm g, const Sched& S, const Epi& E) {
;     ...
;             PG8_LDA(At, 1, 1); PG8_STAGE(PG8_SB(1, 0), b3, voffB); PG8_STAGE(PG8_SB(1, 1), b3 + hstep, voffB); PG8_STAGE(PG8_SA(1, 0), a3, voffA);
;             PG8_WAIT_V(8); PG8_WAIT_L(0); PG8_BAR; PG8_MMA(1, 0, At, B0); PG8_MMA(1, 1, At, B1); PG8_BAR; PG8_SCHED;
;     ...
;         }
;         if constexpr (ALIGN_EPI) { if (wr == 0) PG8_BAR; }
	s_add_i32 s52, s79, s64
	v_lshl_add_u64 v[186:187], v[186:187], 0, s[88:89]
	s_mov_b32 m0, s52
	ds_read_b128 v[202:205], v169 offset:49152
	ds_read_b128 v[206:209], v169 offset:50176
	ds_read_b128 v[210:213], v169 offset:51200
	ds_read_b128 v[214:217], v169 offset:52224
	ds_read_b128 v[218:221], v169 offset:53248
	ds_read_b128 v[222:225], v169 offset:54272
	ds_read_b128 v[226:229], v169 offset:55296
	ds_read_b128 v[236:239], v169 offset:56320
	global_load_lds_dwordx4 v[186:187], off
	s_add_i32 m0, s52, 0x2000
	s_add_u32 s52, s56, 0xb0080
	v_lshl_add_u64 v[186:187], v[190:191], 0, s[88:89]
	s_addc_u32 s53, s57, 0
	s_add_i32 s56, s80, s64
	global_load_lds_dwordx4 v[186:187], off
	v_lshl_add_u64 v[186:187], s[52:53], 0, v[140:141]
	s_mov_b32 m0, s56
	s_nop 0
	global_load_lds_dwordx4 v[186:187], off
	v_lshl_add_u64 v[186:187], s[52:53], 0, v[144:145]
	s_add_i32 m0, s56, 0x2000
	s_nop 0
	global_load_lds_dwordx4 v[186:187], off
	v_lshl_add_u64 v[186:187], v[194:195], 0, s[88:89]
	s_mov_b32 m0, s70
	s_nop 0
	global_load_lds_dwordx4 v[186:187], off
	v_lshl_add_u64 v[186:187], v[234:235], 0, s[88:89]
	s_mov_b32 m0, s71
	s_nop 0
	global_load_lds_dwordx4 v[186:187], off
	s_waitcnt vmcnt(8)
	s_waitcnt lgkmcnt(0)
	s_barrier
	s_setprio 1
	s_waitcnt lgkmcnt(0)
	v_mfma_f32_16x16x32_bf16 v[94:97], v[102:105], v[202:205], v[94:97]
	v_mfma_f32_16x16x32_bf16 v[90:93], v[150:153], v[202:205], v[90:93]
	v_mfma_f32_16x16x32_bf16 v[86:89], v[102:105], v[210:213], v[86:89]
	v_mfma_f32_16x16x32_bf16 v[82:85], v[150:153], v[210:213], v[82:85]
	v_mfma_f32_16x16x32_bf16 v[78:81], v[102:105], v[218:221], v[78:81]
	v_mfma_f32_16x16x32_bf16 v[74:77], v[150:153], v[218:221], v[74:77]
	v_mfma_f32_16x16x32_bf16 v[70:73], v[102:105], v[226:229], v[70:73]
	v_mfma_f32_16x16x32_bf16 v[66:69], v[150:153], v[226:229], v[66:69]
	v_mfma_f32_16x16x32_bf16 v[94:97], v[110:113], v[206:209], v[94:97]
	v_mfma_f32_16x16x32_bf16 v[90:93], v[170:173], v[206:209], v[90:93]
	v_mfma_f32_16x16x32_bf16 v[86:89], v[110:113], v[214:217], v[86:89]
	v_mfma_f32_16x16x32_bf16 v[82:85], v[170:173], v[214:217], v[82:85]
	v_mfma_f32_16x16x32_bf16 v[78:81], v[110:113], v[222:225], v[78:81]
	v_mfma_f32_16x16x32_bf16 v[74:77], v[170:173], v[222:225], v[74:77]
	v_mfma_f32_16x16x32_bf16 v[70:73], v[110:113], v[236:239], v[70:73]
	v_mfma_f32_16x16x32_bf16 v[66:69], v[170:173], v[236:239], v[66:69]
	v_mfma_f32_16x16x32_bf16 v[30:33], v[174:177], v[202:205], v[30:33]
	v_mfma_f32_16x16x32_bf16 v[26:29], v[182:185], v[202:205], v[26:29]
	v_mfma_f32_16x16x32_bf16 v[22:25], v[174:177], v[210:213], v[22:25]
	v_mfma_f32_16x16x32_bf16 v[18:21], v[182:185], v[210:213], v[18:21]
	v_mfma_f32_16x16x32_bf16 v[14:17], v[174:177], v[218:221], v[14:17]
	v_mfma_f32_16x16x32_bf16 v[10:13], v[182:185], v[218:221], v[10:13]
	v_mfma_f32_16x16x32_bf16 v[6:9], v[174:177], v[226:229], v[6:9]
	v_mfma_f32_16x16x32_bf16 v[2:5], v[182:185], v[226:229], v[2:5]
	v_mfma_f32_16x16x32_bf16 v[30:33], v[178:181], v[206:209], v[30:33]
	v_mfma_f32_16x16x32_bf16 v[26:29], v[198:201], v[206:209], v[26:29]
	v_mfma_f32_16x16x32_bf16 v[22:25], v[178:181], v[214:217], v[22:25]
	v_mfma_f32_16x16x32_bf16 v[18:21], v[198:201], v[214:217], v[18:21]
	v_mfma_f32_16x16x32_bf16 v[14:17], v[178:181], v[222:225], v[14:17]
	v_mfma_f32_16x16x32_bf16 v[10:13], v[198:201], v[222:225], v[10:13]
	v_mfma_f32_16x16x32_bf16 v[6:9], v[178:181], v[236:239], v[6:9]
	v_mfma_f32_16x16x32_bf16 v[2:5], v[198:201], v[236:239], v[2:5]
	s_setprio 0
	s_barrier
	s_add_i32 s78, s78, 2
	s_add_u32 s37, s37, 0x100
	s_addc_u32 s77, s77, 0
	s_cmp_gt_u32 s78, 41
	s_mov_b64 s[52:53], s[54:55]
	s_cbranch_scc0 .LBB0_108
	s_and_b64 vcc, exec, s[40:41]
	s_cbranch_vccz .LBB0_111
	s_barrier

; #define PG8_STAGE(bufoff, gbase, voff) do { _Pragma("unroll") for (int _i = 0; _i < 2; ++_i) \
;         __builtin_amdgcn_global_load_lds((const unsigned*)((const char*)(gbase) + (voff)[_i]), (PG8_LAS unsigned*)(lds + (bufoff) + ldsw + _i * 8192), 16, 0, 0); } while (0)
; #define PG8_LDA(dst, b, h) do { _Pragma("unroll") for (int m = 0; m < 4; ++m) _Pragma("unroll") for (int k = 0; k < 2; ++k) dst[m][k] = *(const PG8_LAS bf16x8*)(lds + PG8_SA(b, h) + aoff + m * 2048 + k * 1024); } while (0)
; #define PG8_LDB(dst, b, h) do { _Pragma("unroll") for (int n = 0; n < 2; ++n) _Pragma("unroll") for (int k = 0; k < 2; ++k) dst[n][k] = *(const PG8_LAS bf16x8*)(lds + PG8_SB(b, h) + boff + n * 2048 + k * 1024); } while (0)
; #define PG8_MMA(ai, bj, At, Bt) do { __builtin_amdgcn_s_setprio(1); _Pragma("unroll") for (int m = 0; m < 4; ++m) _Pragma("unroll") for (int n = 0; n < 2; ++n) _Pragma("unroll") for (int k = 0; k < 2; ++k) \
;         acc[ai][bj][m][n] = __builtin_amdgcn_mfma_f32_16x16x32_bf16(Bt[n][k], At[m][k], acc[ai][bj][m][n], 0, 0, 0); __builtin_amdgcn_s_setprio(0); } while (0)
; #define PG8_WAIT_V(n) asm volatile("s_waitcnt vmcnt(" #n ")" ::: "memory")
; #define PG8_WAIT_L(n) asm volatile("s_waitcnt lgkmcnt(" #n ")" ::: "memory")
; #define PG8_BAR __builtin_amdgcn_s_barrier()
; #define PG8_SCHED __builtin_amdgcn_sched_barrier(0)
; template <class Epi, class Sched, bool ALIGN_EPI = false, bool SP2 = false>
; __device__ __forceinline__ void gemm_phase(PG8_LAS unsigned char* lds, const Gemm g, const Sched& S, const Epi& E) {
;     ...
;         for (int t = 0; t < nt; t += 2) {
;             const bool last = (t == nt - 2);
;             const char* a1 = cA + (size_t)(t + 1) * kstep;
;             const char* a2 = last ? nA : cA + (size_t)(t + 2) * kstep; const char* b2 = last ? nB : cB + (size_t)(t + 2) * kstep;
;             const char* a3 = a2 + kstep; const char* b3 = b2 + kstep;
;             if (last && has_next) S.a_ready(nxt);
;             if constexpr (SP2) {
;             PG8_LDB(B0, 0, 0); PG8_LDB(B1, 0, 1); PG8_SCHED; PG8_LDA(At, 0, 0); PG8_STAGE(PG8_SA(1, 1), a1 + hstepA, voffA);
;             PG8_WAIT_V(8); PG8_WAIT_L(0); PG8_BAR; PG8_MMA(0, 0, At, B0); PG8_MMA(0, 1, At, B1); PG8_BAR; PG8_SCHED;
;             PG8_LDA(At, 0, 1); PG8_STAGE(PG8_SB(0, 0), b2, voffB); PG8_STAGE(PG8_SB(0, 1), b2 + hstep, voffB); PG8_STAGE(PG8_SA(0, 0), a2, voffA);
.LBB0_157:
	s_add_u32 s0, s50, 0x100
	s_addc_u32 s1, s51, 0
	s_add_i32 s74, 0, 0x10000
	s_cmp_eq_u32 s73, 12
	s_cselect_b32 s55, s47, s1
	s_cselect_b32 s54, s46, s0
	v_add_u32_e32 v168, s74, v157
	s_cselect_b32 s53, s37, s72
	s_cselect_b32 s52, s45, s71
	s_add_i32 s75, 0, 0x14000
	ds_read_b128 v[130:133], v168
	ds_read_b128 v[134:137], v168 offset:1024
	ds_read_b128 v[150:153], v168 offset:2048
	ds_read_b128 v[170:173], v168 offset:3072
	v_add_u32_e32 v168, s75, v157
	ds_read_b128 v[174:177], v168
	ds_read_b128 v[178:181], v168 offset:1024
	ds_read_b128 v[182:185], v168 offset:2048
	ds_read_b128 v[198:201], v168 offset:3072
	v_lshl_add_u64 v[186:187], s[50:51], 0, v[146:147]
	s_add_i32 m0, s60, 0xc000
	ds_read_b128 v[202:205], v169
	ds_read_b128 v[206:209], v169 offset:1024
	ds_read_b128 v[210:213], v169 offset:2048
	ds_read_b128 v[214:217], v169 offset:3072
	ds_read_b128 v[218:221], v169 offset:4096
	ds_read_b128 v[222:225], v169 offset:5120
	ds_read_b128 v[226:229], v169 offset:6144
	ds_read_b128 v[236:239], v169 offset:7168
	global_load_lds_dwordx4 v[186:187], off
	v_lshl_add_u64 v[186:187], s[50:51], 0, v[166:167]
	s_add_i32 m0, s60, 0xe000
	s_nop 0
	global_load_lds_dwordx4 v[186:187], off
	s_waitcnt vmcnt(8)
	s_waitcnt lgkmcnt(0)
	s_barrier
	s_setprio 1
	s_waitcnt lgkmcnt(0)
	v_mfma_f32_16x16x32_bf16 v[126:129], v[130:133], v[202:205], v[126:129]
	v_mfma_f32_16x16x32_bf16 v[122:125], v[150:153], v[202:205], v[122:125]
	v_mfma_f32_16x16x32_bf16 v[118:121], v[130:133], v[210:213], v[118:121]
	v_mfma_f32_16x16x32_bf16 v[114:117], v[150:153], v[210:213], v[114:117]
	v_mfma_f32_16x16x32_bf16 v[110:113], v[130:133], v[218:221], v[110:113]
	v_mfma_f32_16x16x32_bf16 v[106:109], v[150:153], v[218:221], v[106:109]
	v_mfma_f32_16x16x32_bf16 v[102:105], v[130:133], v[226:229], v[102:105]
	v_mfma_f32_16x16x32_bf16 v[98:101], v[150:153], v[226:229], v[98:101]
	v_mfma_f32_16x16x32_bf16 v[126:129], v[134:137], v[206:209], v[126:129]
	v_mfma_f32_16x16x32_bf16 v[122:125], v[170:173], v[206:209], v[122:125]
	v_mfma_f32_16x16x32_bf16 v[118:121], v[134:137], v[214:217], v[118:121]
	v_mfma_f32_16x16x32_bf16 v[114:117], v[170:173], v[214:217], v[114:117]
	v_mfma_f32_16x16x32_bf16 v[110:113], v[134:137], v[222:225], v[110:113]
	v_mfma_f32_16x16x32_bf16 v[106:109], v[170:173], v[222:225], v[106:109]
	v_mfma_f32_16x16x32_bf16 v[102:105], v[134:137], v[236:239], v[102:105]
	v_mfma_f32_16x16x32_bf16 v[98:101], v[170:173], v[236:239], v[98:101]
	v_mfma_f32_16x16x32_bf16 v[62:65], v[174:177], v[202:205], v[62:65]
	v_mfma_f32_16x16x32_bf16 v[58:61], v[182:185], v[202:205], v[58:61]
	v_mfma_f32_16x16x32_bf16 v[54:57], v[174:177], v[210:213], v[54:57]
	v_mfma_f32_16x16x32_bf16 v[50:53], v[182:185], v[210:213], v[50:53]
	v_mfma_f32_16x16x32_bf16 v[46:49], v[174:177], v[218:221], v[46:49]
	v_mfma_f32_16x16x32_bf16 v[42:45], v[182:185], v[218:221], v[42:45]
	v_mfma_f32_16x16x32_bf16 v[38:41], v[174:177], v[226:229], v[38:41]
	v_mfma_f32_16x16x32_bf16 v[34:37], v[182:185], v[226:229], v[34:37]
	v_mfma_f32_16x16x32_bf16 v[62:65], v[178:181], v[206:209], v[62:65]
	v_mfma_f32_16x16x32_bf16 v[58:61], v[198:201], v[206:209], v[58:61]
	v_mfma_f32_16x16x32_bf16 v[54:57], v[178:181], v[214:217], v[54:57]
	v_mfma_f32_16x16x32_bf16 v[50:53], v[198:201], v[214:217], v[50:53]
	v_mfma_f32_16x16x32_bf16 v[46:49], v[178:181], v[222:225], v[46:49]
	v_mfma_f32_16x16x32_bf16 v[42:45], v[198:201], v[222:225], v[42:45]
	v_mfma_f32_16x16x32_bf16 v[38:41], v[178:181], v[236:239], v[38:41]
	v_mfma_f32_16x16x32_bf16 v[34:37], v[198:201], v[236:239], v[34:37]
	s_setprio 0
	s_barrier
	s_add_i32 s50, s74, s59
	v_lshl_add_u64 v[186:187], s[52:53], 0, v[140:141]
	s_mov_b32 m0, s50
	ds_read_b128 v[202:205], v169 offset:16384
	ds_read_b128 v[206:209], v169 offset:17408
	ds_read_b128 v[210:213], v169 offset:18432
	ds_read_b128 v[214:217], v169 offset:19456
	ds_read_b128 v[218:221], v169 offset:20480
	ds_read_b128 v[222:225], v169 offset:21504
	ds_read_b128 v[226:229], v169 offset:22528
	ds_read_b128 v[236:239], v169 offset:23552
	global_load_lds_dwordx4 v[186:187], off
	s_add_i32 m0, s50, 0x2000
	s_add_u32 s50, s52, 0x40000
	v_lshl_add_u64 v[190:191], s[52:53], 0, v[144:145]
	s_addc_u32 s51, s53, 0
	s_add_i32 s74, s75, s59
	global_load_lds_dwordx4 v[190:191], off
	v_lshl_add_u64 v[194:195], s[50:51], 0, v[140:141]
	s_mov_b32 m0, s74
	v_lshl_add_u64 v[234:235], s[54:55], 0, v[142:143]
	global_load_lds_dwordx4 v[194:195], off
	v_lshl_add_u64 v[194:195], s[50:51], 0, v[144:145]
	s_add_i32 m0, s74, 0x2000
	s_nop 0
	global_load_lds_dwordx4 v[194:195], off
	v_lshl_add_u64 v[194:195], s[54:55], 0, v[138:139]
	s_mov_b32 m0, s60
	s_nop 0
	global_load_lds_dwordx4 v[194:195], off
	s_mov_b32 m0, s61
	s_nop 0
	global_load_lds_dwordx4 v[234:235], off
	s_waitcnt vmcnt(8)
	s_waitcnt lgkmcnt(0)
	s_barrier
; #define PG8_STAGE(bufoff, gbase, voff) do { _Pragma("unroll") for (int _i = 0; _i < 2; ++_i) \
;         __builtin_amdgcn_global_load_lds((const unsigned*)((const char*)(gbase) + (voff)[_i]), (PG8_LAS unsigned*)(lds + (bufoff) + ldsw + _i * 8192), 16, 0, 0); } while (0)
; #define PG8_LDA(dst, b, h) do { _Pragma("unroll") for (int m = 0; m < 4; ++m) _Pragma("unroll") for (int k = 0; k < 2; ++k) dst[m][k] = *(const PG8_LAS bf16x8*)(lds + PG8_SA(b, h) + aoff + m * 2048 + k * 1024); } while (0)
; #define PG8_LDB(dst, b, h) do { _Pragma("unroll") for (int n = 0; n < 2; ++n) _Pragma("unroll") for (int k = 0; k < 2; ++k) dst[n][k] = *(const PG8_LAS bf16x8*)(lds + PG8_SB(b, h) + boff + n * 2048 + k * 1024); } while (0)
; #define PG8_MMA(ai, bj, At, Bt) do { __builtin_amdgcn_s_setprio(1); _Pragma("unroll") for (int m = 0; m < 4; ++m) _Pragma("unroll") for (int n = 0; n < 2; ++n) _Pragma("unroll") for (int k = 0; k < 2; ++k) \
;         acc[ai][bj][m][n] = __builtin_amdgcn_mfma_f32_16x16x32_bf16(Bt[n][k], At[m][k], acc[ai][bj][m][n], 0, 0, 0); __builtin_amdgcn_s_setprio(0); } while (0)
; #define PG8_WAIT_V(n) asm volatile("s_waitcnt vmcnt(" #n ")" ::: "memory")
; #define PG8_WAIT_L(n) asm volatile("s_waitcnt lgkmcnt(" #n ")" ::: "memory")
; #define PG8_BAR __builtin_amdgcn_s_barrier()
; #define PG8_SCHED __builtin_amdgcn_sched_barrier(0)
; template <class Epi, class Sched, bool ALIGN_EPI = false, bool SP2 = false>
; __device__ __forceinline__ void gemm_phase(PG8_LAS unsigned char* lds, const Gemm g, const Sched& S, const Epi& E) {
;     ...
;             PG8_WAIT_V(8); PG8_WAIT_L(0); PG8_BAR; PG8_MMA(1, 0, At, B0); PG8_MMA(1, 1, At, B1); PG8_BAR; PG8_SCHED;
;             PG8_LDB(B0, 1, 0); PG8_LDB(B1, 1, 1); PG8_SCHED; PG8_LDA(At, 1, 0); PG8_STAGE(PG8_SA(0, 1), a2 + hstepA, voffA);
;             PG8_WAIT_V(8); PG8_WAIT_L(0); PG8_BAR; PG8_MMA(0, 0, At, B0); PG8_MMA(0, 1, At, B1); PG8_BAR; PG8_SCHED;
;             PG8_LDA(At, 1, 1); PG8_STAGE(PG8_SB(1, 0), b3, voffB); PG8_STAGE(PG8_SB(1, 1), b3 + hstep, voffB); PG8_STAGE(PG8_SA(1, 0), a3, voffA);
	s_setprio 1
	s_waitcnt lgkmcnt(0)
	v_mfma_f32_16x16x32_bf16 v[94:97], v[130:133], v[202:205], v[94:97]
	v_mfma_f32_16x16x32_bf16 v[90:93], v[150:153], v[202:205], v[90:93]
	v_mfma_f32_16x16x32_bf16 v[86:89], v[130:133], v[210:213], v[86:89]
	v_mfma_f32_16x16x32_bf16 v[82:85], v[150:153], v[210:213], v[82:85]
	v_mfma_f32_16x16x32_bf16 v[78:81], v[130:133], v[218:221], v[78:81]
	v_mfma_f32_16x16x32_bf16 v[74:77], v[150:153], v[218:221], v[74:77]
	v_mfma_f32_16x16x32_bf16 v[70:73], v[130:133], v[226:229], v[70:73]
	v_mfma_f32_16x16x32_bf16 v[66:69], v[150:153], v[226:229], v[66:69]
	v_mfma_f32_16x16x32_bf16 v[94:97], v[134:137], v[206:209], v[94:97]
	v_mfma_f32_16x16x32_bf16 v[90:93], v[170:173], v[206:209], v[90:93]
	v_mfma_f32_16x16x32_bf16 v[86:89], v[134:137], v[214:217], v[86:89]
	v_mfma_f32_16x16x32_bf16 v[82:85], v[170:173], v[214:217], v[82:85]
	v_mfma_f32_16x16x32_bf16 v[78:81], v[134:137], v[222:225], v[78:81]
	v_mfma_f32_16x16x32_bf16 v[74:77], v[170:173], v[222:225], v[74:77]
	v_mfma_f32_16x16x32_bf16 v[70:73], v[134:137], v[236:239], v[70:73]
	v_mfma_f32_16x16x32_bf16 v[66:69], v[170:173], v[236:239], v[66:69]
	v_mfma_f32_16x16x32_bf16 v[30:33], v[174:177], v[202:205], v[30:33]
	v_mfma_f32_16x16x32_bf16 v[26:29], v[182:185], v[202:205], v[26:29]
	v_mfma_f32_16x16x32_bf16 v[22:25], v[174:177], v[210:213], v[22:25]
	v_mfma_f32_16x16x32_bf16 v[18:21], v[182:185], v[210:213], v[18:21]
	v_mfma_f32_16x16x32_bf16 v[14:17], v[174:177], v[218:221], v[14:17]
	v_mfma_f32_16x16x32_bf16 v[10:13], v[182:185], v[218:221], v[10:13]
	v_mfma_f32_16x16x32_bf16 v[6:9], v[174:177], v[226:229], v[6:9]
	v_mfma_f32_16x16x32_bf16 v[2:5], v[182:185], v[226:229], v[2:5]
	v_mfma_f32_16x16x32_bf16 v[30:33], v[178:181], v[206:209], v[30:33]
	v_mfma_f32_16x16x32_bf16 v[26:29], v[198:201], v[206:209], v[26:29]
	v_mfma_f32_16x16x32_bf16 v[22:25], v[178:181], v[214:217], v[22:25]
	v_mfma_f32_16x16x32_bf16 v[18:21], v[198:201], v[214:217], v[18:21]
	v_mfma_f32_16x16x32_bf16 v[14:17], v[178:181], v[222:225], v[14:17]
	v_mfma_f32_16x16x32_bf16 v[10:13], v[198:201], v[222:225], v[10:13]
	v_mfma_f32_16x16x32_bf16 v[6:9], v[178:181], v[236:239], v[6:9]
	v_mfma_f32_16x16x32_bf16 v[2:5], v[198:201], v[236:239], v[2:5]
	s_setprio 0
	s_barrier
	s_add_i32 s74, 0, 0x18000
	v_add_u32_e32 v168, s74, v157
	s_add_i32 s75, 0, 0x1c000
	ds_read_b128 v[130:133], v168
	ds_read_b128 v[134:137], v168 offset:1024
	ds_read_b128 v[150:153], v168 offset:2048
	ds_read_b128 v[170:173], v168 offset:3072
	v_add_u32_e32 v168, s75, v157
	ds_read_b128 v[174:177], v168
	ds_read_b128 v[178:181], v168 offset:1024
	ds_read_b128 v[182:185], v168 offset:2048
	ds_read_b128 v[198:201], v168 offset:3072
	s_add_u32 s50, s54, 0xc0000
	s_addc_u32 s51, s55, 0
	s_mov_b32 m0, s62
	v_lshl_add_u64 v[246:247], s[50:51], 0, v[138:139]
	ds_read_b128 v[202:205], v169 offset:32768
	ds_read_b128 v[206:209], v169 offset:33792
	ds_read_b128 v[210:213], v169 offset:34816
	ds_read_b128 v[214:217], v169 offset:35840
	ds_read_b128 v[218:221], v169 offset:36864
	ds_read_b128 v[222:225], v169 offset:37888
	ds_read_b128 v[226:229], v169 offset:38912
	ds_read_b128 v[236:239], v169 offset:39936
	global_load_lds_dwordx4 v[246:247], off
	v_lshl_add_u64 v[246:247], s[50:51], 0, v[142:143]
	s_mov_b32 m0, s63
	s_nop 0
	global_load_lds_dwordx4 v[246:247], off
	s_waitcnt vmcnt(8)
	s_waitcnt lgkmcnt(0)
	s_barrier
	s_setprio 1
	s_waitcnt lgkmcnt(0)
	v_mfma_f32_16x16x32_bf16 v[126:129], v[130:133], v[202:205], v[126:129]
	v_mfma_f32_16x16x32_bf16 v[122:125], v[150:153], v[202:205], v[122:125]
	v_mfma_f32_16x16x32_bf16 v[118:121], v[130:133], v[210:213], v[118:121]
	v_mfma_f32_16x16x32_bf16 v[114:117], v[150:153], v[210:213], v[114:117]
	v_mfma_f32_16x16x32_bf16 v[110:113], v[130:133], v[218:221], v[110:113]
	v_mfma_f32_16x16x32_bf16 v[106:109], v[150:153], v[218:221], v[106:109]
	v_mfma_f32_16x16x32_bf16 v[102:105], v[130:133], v[226:229], v[102:105]
	v_mfma_f32_16x16x32_bf16 v[98:101], v[150:153], v[226:229], v[98:101]
	v_mfma_f32_16x16x32_bf16 v[126:129], v[134:137], v[206:209], v[126:129]
	v_mfma_f32_16x16x32_bf16 v[122:125], v[170:173], v[206:209], v[122:125]
	v_mfma_f32_16x16x32_bf16 v[118:121], v[134:137], v[214:217], v[118:121]
	v_mfma_f32_16x16x32_bf16 v[114:117], v[170:173], v[214:217], v[114:117]
	v_mfma_f32_16x16x32_bf16 v[110:113], v[134:137], v[222:225], v[110:113]
	v_mfma_f32_16x16x32_bf16 v[106:109], v[170:173], v[222:225], v[106:109]
	v_mfma_f32_16x16x32_bf16 v[102:105], v[134:137], v[236:239], v[102:105]
	v_mfma_f32_16x16x32_bf16 v[98:101], v[170:173], v[236:239], v[98:101]
	v_mfma_f32_16x16x32_bf16 v[62:65], v[174:177], v[202:205], v[62:65]
	v_mfma_f32_16x16x32_bf16 v[58:61], v[182:185], v[202:205], v[58:61]
	v_mfma_f32_16x16x32_bf16 v[54:57], v[174:177], v[210:213], v[54:57]
	v_mfma_f32_16x16x32_bf16 v[50:53], v[182:185], v[210:213], v[50:53]
	v_mfma_f32_16x16x32_bf16 v[46:49], v[174:177], v[218:221], v[46:49]
	v_mfma_f32_16x16x32_bf16 v[42:45], v[182:185], v[218:221], v[42:45]
	v_mfma_f32_16x16x32_bf16 v[38:41], v[174:177], v[226:229], v[38:41]
	v_mfma_f32_16x16x32_bf16 v[34:37], v[182:185], v[226:229], v[34:37]
	v_mfma_f32_16x16x32_bf16 v[62:65], v[178:181], v[206:209], v[62:65]
	v_mfma_f32_16x16x32_bf16 v[58:61], v[198:201], v[206:209], v[58:61]
	v_mfma_f32_16x16x32_bf16 v[54:57], v[178:181], v[214:217], v[54:57]
	v_mfma_f32_16x16x32_bf16 v[50:53], v[198:201], v[214:217], v[50:53]
	v_mfma_f32_16x16x32_bf16 v[46:49], v[178:181], v[222:225], v[46:49]
	v_mfma_f32_16x16x32_bf16 v[42:45], v[198:201], v[222:225], v[42:45]
	v_mfma_f32_16x16x32_bf16 v[38:41], v[178:181], v[236:239], v[38:41]
	v_mfma_f32_16x16x32_bf16 v[34:37], v[198:201], v[236:239], v[34:37]
	s_setprio 0
	s_barrier
; #define PG8_STAGE(bufoff, gbase, voff) do { _Pragma("unroll") for (int _i = 0; _i < 2; ++_i) \
;         __builtin_amdgcn_global_load_lds((const unsigned*)((const char*)(gbase) + (voff)[_i]), (PG8_LAS unsigned*)(lds + (bufoff) + ldsw + _i * 8192), 16, 0, 0); } while (0)
; #define PG8_LDA(dst, b, h) do { _Pragma("unroll") for (int m = 0; m < 4; ++m) _Pragma("unroll") for (int k = 0; k < 2; ++k) dst[m][k] = *(const PG8_LAS bf16x8*)(lds + PG8_SA(b, h) + aoff + m * 2048 + k * 1024); } while (0)
; #define PG8_MMA(ai, bj, At, Bt) do { __builtin_amdgcn_s_setprio(1); _Pragma("unroll") for (int m = 0; m < 4; ++m) _Pragma("unroll") for (int n = 0; n < 2; ++n) _Pragma("unroll") for (int k = 0; k < 2; ++k) \
;         acc[ai][bj][m][n] = __builtin_amdgcn_mfma_f32_16x16x32_bf16(Bt[n][k], At[m][k], acc[ai][bj][m][n], 0, 0, 0); __builtin_amdgcn_s_setprio(0); } while (0)
; #define PG8_WAIT_V(n) asm volatile("s_waitcnt vmcnt(" #n ")" ::: "memory")
; #define PG8_WAIT_L(n) asm volatile("s_waitcnt lgkmcnt(" #n ")" ::: "memory")
; #define PG8_BAR __builtin_amdgcn_s_barrier()
; #define PG8_SCHED __builtin_amdgcn_sched_barrier(0)
; template <class Epi, class Sched, bool ALIGN_EPI = false, bool SP2 = false>
; __device__ __forceinline__ void gemm_phase(PG8_LAS unsigned char* lds, const Gemm g, const Sched& S, const Epi& E) {
;     ...
;             PG8_LDA(At, 1, 1); PG8_STAGE(PG8_SB(1, 0), b3, voffB); PG8_STAGE(PG8_SB(1, 1), b3 + hstep, voffB); PG8_STAGE(PG8_SA(1, 0), a3, voffA);
;             PG8_WAIT_V(8); PG8_WAIT_L(0); PG8_BAR; PG8_MMA(1, 0, At, B0); PG8_MMA(1, 1, At, B1); PG8_BAR; PG8_SCHED;
;     ...
;         }
;         if constexpr (ALIGN_EPI) { if (wr == 0) PG8_BAR; }
	s_add_i32 s50, s74, s59
	v_lshl_add_u64 v[186:187], v[186:187], 0, s[88:89]
	s_mov_b32 m0, s50
	ds_read_b128 v[202:205], v169 offset:49152
	ds_read_b128 v[206:209], v169 offset:50176
	ds_read_b128 v[210:213], v169 offset:51200
	ds_read_b128 v[214:217], v169 offset:52224
	ds_read_b128 v[218:221], v169 offset:53248
	ds_read_b128 v[222:225], v169 offset:54272
	ds_read_b128 v[226:229], v169 offset:55296
	ds_read_b128 v[236:239], v169 offset:56320
	global_load_lds_dwordx4 v[186:187], off
	s_add_i32 m0, s50, 0x2000
	s_add_u32 s50, s52, 0x40080
	v_lshl_add_u64 v[186:187], v[190:191], 0, s[88:89]
	s_addc_u32 s51, s53, 0
	s_add_i32 s52, s75, s59
	global_load_lds_dwordx4 v[186:187], off
	v_lshl_add_u64 v[186:187], s[50:51], 0, v[140:141]
	s_mov_b32 m0, s52
	s_nop 0
	global_load_lds_dwordx4 v[186:187], off
	v_lshl_add_u64 v[186:187], s[50:51], 0, v[144:145]
	s_add_i32 m0, s52, 0x2000
	s_nop 0
	global_load_lds_dwordx4 v[186:187], off
	v_lshl_add_u64 v[186:187], v[194:195], 0, s[88:89]
	s_mov_b32 m0, s65
	s_nop 0
	global_load_lds_dwordx4 v[186:187], off
	v_lshl_add_u64 v[186:187], v[234:235], 0, s[88:89]
	s_mov_b32 m0, s67
	s_nop 0
	global_load_lds_dwordx4 v[186:187], off
	s_waitcnt vmcnt(8)
	s_waitcnt lgkmcnt(0)
	s_barrier
	s_setprio 1
	s_waitcnt lgkmcnt(0)
	v_mfma_f32_16x16x32_bf16 v[94:97], v[130:133], v[202:205], v[94:97]
	v_mfma_f32_16x16x32_bf16 v[90:93], v[150:153], v[202:205], v[90:93]
	v_mfma_f32_16x16x32_bf16 v[86:89], v[130:133], v[210:213], v[86:89]
	v_mfma_f32_16x16x32_bf16 v[82:85], v[150:153], v[210:213], v[82:85]
	v_mfma_f32_16x16x32_bf16 v[78:81], v[130:133], v[218:221], v[78:81]
	v_mfma_f32_16x16x32_bf16 v[74:77], v[150:153], v[218:221], v[74:77]
	v_mfma_f32_16x16x32_bf16 v[70:73], v[130:133], v[226:229], v[70:73]
	v_mfma_f32_16x16x32_bf16 v[66:69], v[150:153], v[226:229], v[66:69]
	v_mfma_f32_16x16x32_bf16 v[94:97], v[134:137], v[206:209], v[94:97]
	v_mfma_f32_16x16x32_bf16 v[90:93], v[170:173], v[206:209], v[90:93]
	v_mfma_f32_16x16x32_bf16 v[86:89], v[134:137], v[214:217], v[86:89]
	v_mfma_f32_16x16x32_bf16 v[82:85], v[170:173], v[214:217], v[82:85]
	v_mfma_f32_16x16x32_bf16 v[78:81], v[134:137], v[222:225], v[78:81]
	v_mfma_f32_16x16x32_bf16 v[74:77], v[170:173], v[222:225], v[74:77]
	v_mfma_f32_16x16x32_bf16 v[70:73], v[134:137], v[236:239], v[70:73]
	v_mfma_f32_16x16x32_bf16 v[66:69], v[170:173], v[236:239], v[66:69]
	v_mfma_f32_16x16x32_bf16 v[30:33], v[174:177], v[202:205], v[30:33]
	v_mfma_f32_16x16x32_bf16 v[26:29], v[182:185], v[202:205], v[26:29]
	v_mfma_f32_16x16x32_bf16 v[22:25], v[174:177], v[210:213], v[22:25]
	v_mfma_f32_16x16x32_bf16 v[18:21], v[182:185], v[210:213], v[18:21]
	v_mfma_f32_16x16x32_bf16 v[14:17], v[174:177], v[218:221], v[14:17]
	v_mfma_f32_16x16x32_bf16 v[10:13], v[182:185], v[218:221], v[10:13]
	v_mfma_f32_16x16x32_bf16 v[6:9], v[174:177], v[226:229], v[6:9]
	v_mfma_f32_16x16x32_bf16 v[2:5], v[182:185], v[226:229], v[2:5]
	v_mfma_f32_16x16x32_bf16 v[30:33], v[178:181], v[206:209], v[30:33]
	v_mfma_f32_16x16x32_bf16 v[26:29], v[198:201], v[206:209], v[26:29]
	v_mfma_f32_16x16x32_bf16 v[22:25], v[178:181], v[214:217], v[22:25]
	v_mfma_f32_16x16x32_bf16 v[18:21], v[198:201], v[214:217], v[18:21]
	v_mfma_f32_16x16x32_bf16 v[14:17], v[178:181], v[222:225], v[14:17]
	v_mfma_f32_16x16x32_bf16 v[10:13], v[198:201], v[222:225], v[10:13]
	v_mfma_f32_16x16x32_bf16 v[6:9], v[178:181], v[236:239], v[6:9]
	v_mfma_f32_16x16x32_bf16 v[2:5], v[198:201], v[236:239], v[2:5]
	s_setprio 0
	s_barrier
	s_add_i32 s73, s73, 2
	s_add_u32 s71, s71, 0x100
	s_addc_u32 s72, s72, 0
	s_cmp_gt_u32 s73, 13
	s_mov_b64 s[50:51], s[0:1]
	s_cbranch_scc0 .LBB0_157
	s_and_b64 vcc, exec, s[8:9]
	s_cbranch_vccz .LBB0_160
	s_barrier

; #define PG8_STAGE(bufoff, gbase, voff) do { _Pragma("unroll") for (int _i = 0; _i < 2; ++_i) \
;         __builtin_amdgcn_global_load_lds((const unsigned*)((const char*)(gbase) + (voff)[_i]), (PG8_LAS unsigned*)(lds + (bufoff) + ldsw + _i * 8192), 16, 0, 0); } while (0)
; #define PG8_LDA(dst, b, h) do { _Pragma("unroll") for (int m = 0; m < 4; ++m) _Pragma("unroll") for (int k = 0; k < 2; ++k) dst[m][k] = *(const PG8_LAS bf16x8*)(lds + PG8_SA(b, h) + aoff + m * 2048 + k * 1024); } while (0)
; #define PG8_LDB(dst, b, h) do { _Pragma("unroll") for (int n = 0; n < 2; ++n) _Pragma("unroll") for (int k = 0; k < 2; ++k) dst[n][k] = *(const PG8_LAS bf16x8*)(lds + PG8_SB(b, h) + boff + n * 2048 + k * 1024); } while (0)
; #define PG8_MMA(ai, bj, At, Bt) do { __builtin_amdgcn_s_setprio(1); _Pragma("unroll") for (int m = 0; m < 4; ++m) _Pragma("unroll") for (int n = 0; n < 2; ++n) _Pragma("unroll") for (int k = 0; k < 2; ++k) \
;         acc[ai][bj][m][n] = __builtin_amdgcn_mfma_f32_16x16x32_bf16(Bt[n][k], At[m][k], acc[ai][bj][m][n], 0, 0, 0); __builtin_amdgcn_s_setprio(0); } while (0)
; #define PG8_WAIT_V(n) asm volatile("s_waitcnt vmcnt(" #n ")" ::: "memory")
; template <class Epi, class Sched, bool ALIGN_EPI = false, bool SP2 = false>
; __device__ __forceinline__ void gemm_phase(PG8_LAS unsigned char* lds, const Gemm g, const Sched& S, const Epi& E) {
;     ...
;         const char* nA = has_next ? (const char*)g.A + (size_t)nxt.pm * tstepA : cA; const char* nB = has_next ? (const char*)g.Bt + (size_t)nxt.pn * tstep : cB;
;         for (int t = 0; t < nt; t += 2) {
;             const bool last = (t == nt - 2);
;             const char* a1 = cA + (size_t)(t + 1) * kstep;
;             const char* a2 = last ? nA : cA + (size_t)(t + 2) * kstep; const char* b2 = last ? nB : cB + (size_t)(t + 2) * kstep;
;             const char* a3 = a2 + kstep; const char* b3 = b2 + kstep;
;             if (last && has_next) S.a_ready(nxt);
;             if constexpr (SP2) {
;             PG8_LDB(B0, 0, 0); PG8_LDB(B1, 0, 1); PG8_SCHED; PG8_LDA(At, 0, 0); PG8_STAGE(PG8_SA(1, 1), a1 + hstepA, voffA);
;             PG8_WAIT_V(8); PG8_WAIT_L(0); PG8_BAR; PG8_MMA(0, 0, At, B0); PG8_MMA(0, 1, At, B1); PG8_BAR; PG8_SCHED;
;             PG8_LDA(At, 0, 1); PG8_STAGE(PG8_SB(0, 0), b2, voffB); PG8_STAGE(PG8_SB(0, 1), b2 + hstep, voffB); PG8_STAGE(PG8_SA(0, 0), a2, voffA);
.LBB0_190:
	s_add_u32 s57, s50, s56
	s_addc_u32 s62, s51, 0
	s_add_u32 s60, s57, 0x100
	s_addc_u32 s61, s62, 0
	s_and_b64 s[58:59], s[54:55], exec
	s_cselect_b32 s59, s9, s61
	s_cselect_b32 s58, s39, s60
	s_add_u32 s56, s48, s56
	s_addc_u32 s60, s49, 0
	s_add_u32 s56, s56, 0x100
	s_addc_u32 s60, s60, 0
	s_add_i32 s85, 0, 0x10000
	s_and_b64 s[54:55], s[54:55], exec
	s_cselect_b32 s61, s41, s60
	s_cselect_b32 s60, s37, s56
	s_add_i32 s55, 0, 0x14000
	s_add_u32 s64, s57, 0x10080
	s_addc_u32 s65, s62, 0
	s_add_i32 s84, s85, s68
	s_add_i32 m0, s13, 0xc000
	s_add_i32 s97, s13, 0xe000
	s_add_i32 s81, s84, 0x2000
	v_add_u32_e32 v145, s85, v142
	s_add_u32 s62, s60, 0x10000
	ds_read_b128 v[138:141], v145
	ds_read_b128 v[150:153], v145 offset:1024
	ds_read_b128 v[166:169], v145 offset:2048
	ds_read_b128 v[170:173], v145 offset:3072
	v_add_u32_e32 v145, s55, v142
	s_addc_u32 s63, s61, 0
	s_add_i32 s83, s55, s68
	ds_read_b128 v[174:177], v145
	ds_read_b128 v[178:181], v145 offset:1024
	ds_read_b128 v[182:185], v145 offset:2048
	ds_read_b128 v[198:201], v145 offset:3072
	s_add_i32 s82, s83, 0x2000
	s_add_i32 s80, 0, 0x18000
	s_add_i32 s79, 0, 0x1c000
	s_add_u32 s56, s58, 0x10000
	s_addc_u32 s57, s59, 0
	s_add_i32 s78, s80, s68
	s_add_i32 s77, s78, 0x2000
	s_add_u32 s54, s60, 0x10080
	s_addc_u32 s55, s61, 0
	s_add_i32 s86, s79, s68
	s_add_i32 s85, s86, 0x2000
	v_lshl_add_u64 v[146:147], s[64:65], 0, v[130:131]
	ds_read_b128 v[202:205], v144
	ds_read_b128 v[206:209], v144 offset:1024
	ds_read_b128 v[210:213], v144 offset:2048
	ds_read_b128 v[214:217], v144 offset:3072
	ds_read_b128 v[218:221], v144 offset:4096
	ds_read_b128 v[222:225], v144 offset:5120
	ds_read_b128 v[226:229], v144 offset:6144
	ds_read_b128 v[236:239], v144 offset:7168
	global_load_lds_dwordx4 v[146:147], off
	v_lshl_add_u64 v[146:147], s[64:65], 0, v[134:135]
	s_mov_b32 m0, s97
	s_nop 0
	global_load_lds_dwordx4 v[146:147], off
	s_waitcnt vmcnt(8)
	s_waitcnt lgkmcnt(0)
	s_barrier
	s_setprio 1
	s_waitcnt lgkmcnt(0)
	v_mfma_f32_16x16x32_bf16 v[126:129], v[138:141], v[202:205], v[126:129]
	v_mfma_f32_16x16x32_bf16 v[122:125], v[166:169], v[202:205], v[122:125]
	v_mfma_f32_16x16x32_bf16 v[118:121], v[138:141], v[210:213], v[118:121]
	v_mfma_f32_16x16x32_bf16 v[110:113], v[166:169], v[210:213], v[110:113]
	v_mfma_f32_16x16x32_bf16 v[102:105], v[138:141], v[218:221], v[102:105]
	v_mfma_f32_16x16x32_bf16 v[94:97], v[166:169], v[218:221], v[94:97]
	v_mfma_f32_16x16x32_bf16 v[86:89], v[138:141], v[226:229], v[86:89]
	v_mfma_f32_16x16x32_bf16 v[78:81], v[166:169], v[226:229], v[78:81]
	v_mfma_f32_16x16x32_bf16 v[126:129], v[150:153], v[206:209], v[126:129]
	v_mfma_f32_16x16x32_bf16 v[122:125], v[170:173], v[206:209], v[122:125]
	v_mfma_f32_16x16x32_bf16 v[118:121], v[150:153], v[214:217], v[118:121]
	v_mfma_f32_16x16x32_bf16 v[110:113], v[170:173], v[214:217], v[110:113]
	v_mfma_f32_16x16x32_bf16 v[102:105], v[150:153], v[222:225], v[102:105]
	v_mfma_f32_16x16x32_bf16 v[94:97], v[170:173], v[222:225], v[94:97]
	v_mfma_f32_16x16x32_bf16 v[86:89], v[150:153], v[236:239], v[86:89]
	v_mfma_f32_16x16x32_bf16 v[78:81], v[170:173], v[236:239], v[78:81]
	v_mfma_f32_16x16x32_bf16 v[114:117], v[174:177], v[202:205], v[114:117]
	v_mfma_f32_16x16x32_bf16 v[106:109], v[182:185], v[202:205], v[106:109]
	v_mfma_f32_16x16x32_bf16 v[98:101], v[174:177], v[210:213], v[98:101]
	v_mfma_f32_16x16x32_bf16 v[90:93], v[182:185], v[210:213], v[90:93]
	v_mfma_f32_16x16x32_bf16 v[82:85], v[174:177], v[218:221], v[82:85]
	v_mfma_f32_16x16x32_bf16 v[74:77], v[182:185], v[218:221], v[74:77]
	v_mfma_f32_16x16x32_bf16 v[70:73], v[174:177], v[226:229], v[70:73]
	v_mfma_f32_16x16x32_bf16 v[66:69], v[182:185], v[226:229], v[66:69]
	v_mfma_f32_16x16x32_bf16 v[114:117], v[178:181], v[206:209], v[114:117]
	v_mfma_f32_16x16x32_bf16 v[106:109], v[198:201], v[206:209], v[106:109]
	v_mfma_f32_16x16x32_bf16 v[98:101], v[178:181], v[214:217], v[98:101]
	v_mfma_f32_16x16x32_bf16 v[90:93], v[198:201], v[214:217], v[90:93]
	v_mfma_f32_16x16x32_bf16 v[82:85], v[178:181], v[222:225], v[82:85]
	v_mfma_f32_16x16x32_bf16 v[74:77], v[198:201], v[222:225], v[74:77]
	v_mfma_f32_16x16x32_bf16 v[70:73], v[178:181], v[236:239], v[70:73]
	v_mfma_f32_16x16x32_bf16 v[66:69], v[198:201], v[236:239], v[66:69]
	s_setprio 0
	s_barrier
	s_mov_b32 m0, s84
	v_lshl_add_u64 v[146:147], s[60:61], 0, v[132:133]
	ds_read_b128 v[202:205], v144 offset:16384
	ds_read_b128 v[206:209], v144 offset:17408
	ds_read_b128 v[210:213], v144 offset:18432
	ds_read_b128 v[214:217], v144 offset:19456
	ds_read_b128 v[218:221], v144 offset:20480
	ds_read_b128 v[222:225], v144 offset:21504
	ds_read_b128 v[226:229], v144 offset:22528
	ds_read_b128 v[236:239], v144 offset:23552
	global_load_lds_dwordx4 v[146:147], off
	v_lshl_add_u64 v[186:187], s[60:61], 0, v[136:137]
	s_mov_b32 m0, s81
	v_lshl_add_u64 v[190:191], s[62:63], 0, v[132:133]
	global_load_lds_dwordx4 v[186:187], off
	s_mov_b32 m0, s83
	v_lshl_add_u64 v[194:195], s[58:59], 0, v[134:135]
	global_load_lds_dwordx4 v[190:191], off
	v_lshl_add_u64 v[190:191], s[62:63], 0, v[136:137]
	s_mov_b32 m0, s82
	s_nop 0
	global_load_lds_dwordx4 v[190:191], off
	v_lshl_add_u64 v[190:191], s[58:59], 0, v[130:131]
	s_mov_b32 m0, s13
	s_nop 0
	global_load_lds_dwordx4 v[190:191], off
	s_mov_b32 m0, s69
	s_nop 0
	global_load_lds_dwordx4 v[194:195], off
	s_waitcnt vmcnt(8)
	s_waitcnt lgkmcnt(0)
	s_barrier
; #define PG8_STAGE(bufoff, gbase, voff) do { _Pragma("unroll") for (int _i = 0; _i < 2; ++_i) \
;         __builtin_amdgcn_global_load_lds((const unsigned*)((const char*)(gbase) + (voff)[_i]), (PG8_LAS unsigned*)(lds + (bufoff) + ldsw + _i * 8192), 16, 0, 0); } while (0)
; #define PG8_LDA(dst, b, h) do { _Pragma("unroll") for (int m = 0; m < 4; ++m) _Pragma("unroll") for (int k = 0; k < 2; ++k) dst[m][k] = *(const PG8_LAS bf16x8*)(lds + PG8_SA(b, h) + aoff + m * 2048 + k * 1024); } while (0)
; #define PG8_LDB(dst, b, h) do { _Pragma("unroll") for (int n = 0; n < 2; ++n) _Pragma("unroll") for (int k = 0; k < 2; ++k) dst[n][k] = *(const PG8_LAS bf16x8*)(lds + PG8_SB(b, h) + boff + n * 2048 + k * 1024); } while (0)
; #define PG8_MMA(ai, bj, At, Bt) do { __builtin_amdgcn_s_setprio(1); _Pragma("unroll") for (int m = 0; m < 4; ++m) _Pragma("unroll") for (int n = 0; n < 2; ++n) _Pragma("unroll") for (int k = 0; k < 2; ++k) \
;         acc[ai][bj][m][n] = __builtin_amdgcn_mfma_f32_16x16x32_bf16(Bt[n][k], At[m][k], acc[ai][bj][m][n], 0, 0, 0); __builtin_amdgcn_s_setprio(0); } while (0)
; #define PG8_WAIT_V(n) asm volatile("s_waitcnt vmcnt(" #n ")" ::: "memory")
; #define PG8_WAIT_L(n) asm volatile("s_waitcnt lgkmcnt(" #n ")" ::: "memory")
; #define PG8_BAR __builtin_amdgcn_s_barrier()
; #define PG8_SCHED __builtin_amdgcn_sched_barrier(0)
; template <class Epi, class Sched, bool ALIGN_EPI = false, bool SP2 = false>
; __device__ __forceinline__ void gemm_phase(PG8_LAS unsigned char* lds, const Gemm g, const Sched& S, const Epi& E) {
;     ...
;             PG8_WAIT_V(8); PG8_WAIT_L(0); PG8_BAR; PG8_MMA(1, 0, At, B0); PG8_MMA(1, 1, At, B1); PG8_BAR; PG8_SCHED;
;             PG8_LDB(B0, 1, 0); PG8_LDB(B1, 1, 1); PG8_SCHED; PG8_LDA(At, 1, 0); PG8_STAGE(PG8_SA(0, 1), a2 + hstepA, voffA);
;             PG8_WAIT_V(8); PG8_WAIT_L(0); PG8_BAR; PG8_MMA(0, 0, At, B0); PG8_MMA(0, 1, At, B1); PG8_BAR; PG8_SCHED;
;             PG8_LDA(At, 1, 1); PG8_STAGE(PG8_SB(1, 0), b3, voffB); PG8_STAGE(PG8_SB(1, 1), b3 + hstep, voffB); PG8_STAGE(PG8_SA(1, 0), a3, voffA);
	s_setprio 1
	s_waitcnt lgkmcnt(0)
	v_mfma_f32_16x16x32_bf16 v[62:65], v[138:141], v[202:205], v[62:65]
	v_mfma_f32_16x16x32_bf16 v[58:61], v[166:169], v[202:205], v[58:61]
	v_mfma_f32_16x16x32_bf16 v[54:57], v[138:141], v[210:213], v[54:57]
	v_mfma_f32_16x16x32_bf16 v[46:49], v[166:169], v[210:213], v[46:49]
	v_mfma_f32_16x16x32_bf16 v[38:41], v[138:141], v[218:221], v[38:41]
	v_mfma_f32_16x16x32_bf16 v[30:33], v[166:169], v[218:221], v[30:33]
	v_mfma_f32_16x16x32_bf16 v[22:25], v[138:141], v[226:229], v[22:25]
	v_mfma_f32_16x16x32_bf16 v[14:17], v[166:169], v[226:229], v[14:17]
	v_mfma_f32_16x16x32_bf16 v[62:65], v[150:153], v[206:209], v[62:65]
	v_mfma_f32_16x16x32_bf16 v[58:61], v[170:173], v[206:209], v[58:61]
	v_mfma_f32_16x16x32_bf16 v[54:57], v[150:153], v[214:217], v[54:57]
	v_mfma_f32_16x16x32_bf16 v[46:49], v[170:173], v[214:217], v[46:49]
	v_mfma_f32_16x16x32_bf16 v[38:41], v[150:153], v[222:225], v[38:41]
	v_mfma_f32_16x16x32_bf16 v[30:33], v[170:173], v[222:225], v[30:33]
	v_mfma_f32_16x16x32_bf16 v[22:25], v[150:153], v[236:239], v[22:25]
	v_mfma_f32_16x16x32_bf16 v[14:17], v[170:173], v[236:239], v[14:17]
	v_mfma_f32_16x16x32_bf16 v[50:53], v[174:177], v[202:205], v[50:53]
	v_mfma_f32_16x16x32_bf16 v[42:45], v[182:185], v[202:205], v[42:45]
	v_mfma_f32_16x16x32_bf16 v[34:37], v[174:177], v[210:213], v[34:37]
	v_mfma_f32_16x16x32_bf16 v[26:29], v[182:185], v[210:213], v[26:29]
	v_mfma_f32_16x16x32_bf16 v[18:21], v[174:177], v[218:221], v[18:21]
	v_mfma_f32_16x16x32_bf16 v[10:13], v[182:185], v[218:221], v[10:13]
	v_mfma_f32_16x16x32_bf16 v[6:9], v[174:177], v[226:229], v[6:9]
	v_mfma_f32_16x16x32_bf16 v[2:5], v[182:185], v[226:229], v[2:5]
	v_mfma_f32_16x16x32_bf16 v[50:53], v[178:181], v[206:209], v[50:53]
	v_mfma_f32_16x16x32_bf16 v[42:45], v[198:201], v[206:209], v[42:45]
	v_mfma_f32_16x16x32_bf16 v[34:37], v[178:181], v[214:217], v[34:37]
	v_mfma_f32_16x16x32_bf16 v[26:29], v[198:201], v[214:217], v[26:29]
	v_mfma_f32_16x16x32_bf16 v[18:21], v[178:181], v[222:225], v[18:21]
	v_mfma_f32_16x16x32_bf16 v[10:13], v[198:201], v[222:225], v[10:13]
	v_mfma_f32_16x16x32_bf16 v[6:9], v[178:181], v[236:239], v[6:9]
	v_mfma_f32_16x16x32_bf16 v[2:5], v[198:201], v[236:239], v[2:5]
	s_setprio 0
	s_barrier
	v_add_u32_e32 v145, s80, v142
	ds_read_b128 v[138:141], v145
	ds_read_b128 v[150:153], v145 offset:1024
	ds_read_b128 v[166:169], v145 offset:2048
	ds_read_b128 v[170:173], v145 offset:3072
	v_add_u32_e32 v145, s79, v142
	ds_read_b128 v[174:177], v145
	ds_read_b128 v[178:181], v145 offset:1024
	ds_read_b128 v[182:185], v145 offset:2048
	ds_read_b128 v[198:201], v145 offset:3072
	s_mov_b32 m0, s70
	v_lshl_add_u64 v[234:235], s[56:57], 0, v[130:131]
	ds_read_b128 v[202:205], v144 offset:32768
	ds_read_b128 v[206:209], v144 offset:33792
	ds_read_b128 v[210:213], v144 offset:34816
	ds_read_b128 v[214:217], v144 offset:35840
	ds_read_b128 v[218:221], v144 offset:36864
	ds_read_b128 v[222:225], v144 offset:37888
	ds_read_b128 v[226:229], v144 offset:38912
	ds_read_b128 v[236:239], v144 offset:39936
	global_load_lds_dwordx4 v[234:235], off
	v_lshl_add_u64 v[234:235], s[56:57], 0, v[134:135]
	s_mov_b32 m0, s71
	s_nop 0
	global_load_lds_dwordx4 v[234:235], off
	s_waitcnt vmcnt(8)
	s_waitcnt lgkmcnt(0)
	s_barrier
	s_setprio 1
	s_waitcnt lgkmcnt(0)
	v_mfma_f32_16x16x32_bf16 v[126:129], v[138:141], v[202:205], v[126:129]
	v_mfma_f32_16x16x32_bf16 v[122:125], v[166:169], v[202:205], v[122:125]
	v_mfma_f32_16x16x32_bf16 v[118:121], v[138:141], v[210:213], v[118:121]
	v_mfma_f32_16x16x32_bf16 v[110:113], v[166:169], v[210:213], v[110:113]
	v_mfma_f32_16x16x32_bf16 v[102:105], v[138:141], v[218:221], v[102:105]
	v_mfma_f32_16x16x32_bf16 v[94:97], v[166:169], v[218:221], v[94:97]
	v_mfma_f32_16x16x32_bf16 v[86:89], v[138:141], v[226:229], v[86:89]
	v_mfma_f32_16x16x32_bf16 v[78:81], v[166:169], v[226:229], v[78:81]
	v_mfma_f32_16x16x32_bf16 v[126:129], v[150:153], v[206:209], v[126:129]
	v_mfma_f32_16x16x32_bf16 v[122:125], v[170:173], v[206:209], v[122:125]
	v_mfma_f32_16x16x32_bf16 v[118:121], v[150:153], v[214:217], v[118:121]
	v_mfma_f32_16x16x32_bf16 v[110:113], v[170:173], v[214:217], v[110:113]
	v_mfma_f32_16x16x32_bf16 v[102:105], v[150:153], v[222:225], v[102:105]
	v_mfma_f32_16x16x32_bf16 v[94:97], v[170:173], v[222:225], v[94:97]
	v_mfma_f32_16x16x32_bf16 v[86:89], v[150:153], v[236:239], v[86:89]
	v_mfma_f32_16x16x32_bf16 v[78:81], v[170:173], v[236:239], v[78:81]
	v_mfma_f32_16x16x32_bf16 v[114:117], v[174:177], v[202:205], v[114:117]
	v_mfma_f32_16x16x32_bf16 v[106:109], v[182:185], v[202:205], v[106:109]
	v_mfma_f32_16x16x32_bf16 v[98:101], v[174:177], v[210:213], v[98:101]
	v_mfma_f32_16x16x32_bf16 v[90:93], v[182:185], v[210:213], v[90:93]
	v_mfma_f32_16x16x32_bf16 v[82:85], v[174:177], v[218:221], v[82:85]
	v_mfma_f32_16x16x32_bf16 v[74:77], v[182:185], v[218:221], v[74:77]
	v_mfma_f32_16x16x32_bf16 v[70:73], v[174:177], v[226:229], v[70:73]
	v_mfma_f32_16x16x32_bf16 v[66:69], v[182:185], v[226:229], v[66:69]
	v_mfma_f32_16x16x32_bf16 v[114:117], v[178:181], v[206:209], v[114:117]
	v_mfma_f32_16x16x32_bf16 v[106:109], v[198:201], v[206:209], v[106:109]
	v_mfma_f32_16x16x32_bf16 v[98:101], v[178:181], v[214:217], v[98:101]
	v_mfma_f32_16x16x32_bf16 v[90:93], v[198:201], v[214:217], v[90:93]
	v_mfma_f32_16x16x32_bf16 v[82:85], v[178:181], v[222:225], v[82:85]
	v_mfma_f32_16x16x32_bf16 v[74:77], v[198:201], v[222:225], v[74:77]
	v_mfma_f32_16x16x32_bf16 v[70:73], v[178:181], v[236:239], v[70:73]
	v_mfma_f32_16x16x32_bf16 v[66:69], v[198:201], v[236:239], v[66:69]
	s_setprio 0
	s_barrier
; #define PG8_STAGE(bufoff, gbase, voff) do { _Pragma("unroll") for (int _i = 0; _i < 2; ++_i) \
;         __builtin_amdgcn_global_load_lds((const unsigned*)((const char*)(gbase) + (voff)[_i]), (PG8_LAS unsigned*)(lds + (bufoff) + ldsw + _i * 8192), 16, 0, 0); } while (0)
; #define PG8_LDA(dst, b, h) do { _Pragma("unroll") for (int m = 0; m < 4; ++m) _Pragma("unroll") for (int k = 0; k < 2; ++k) dst[m][k] = *(const PG8_LAS bf16x8*)(lds + PG8_SA(b, h) + aoff + m * 2048 + k * 1024); } while (0)
; #define PG8_MMA(ai, bj, At, Bt) do { __builtin_amdgcn_s_setprio(1); _Pragma("unroll") for (int m = 0; m < 4; ++m) _Pragma("unroll") for (int n = 0; n < 2; ++n) _Pragma("unroll") for (int k = 0; k < 2; ++k) \
;         acc[ai][bj][m][n] = __builtin_amdgcn_mfma_f32_16x16x32_bf16(Bt[n][k], At[m][k], acc[ai][bj][m][n], 0, 0, 0); __builtin_amdgcn_s_setprio(0); } while (0)
; #define PG8_WAIT_V(n) asm volatile("s_waitcnt vmcnt(" #n ")" ::: "memory")
; #define PG8_WAIT_L(n) asm volatile("s_waitcnt lgkmcnt(" #n ")" ::: "memory")
; #define PG8_BAR __builtin_amdgcn_s_barrier()
; #define PG8_SCHED __builtin_amdgcn_sched_barrier(0)
; template <class Epi, class Sched, bool ALIGN_EPI = false, bool SP2 = false>
; __device__ __forceinline__ void gemm_phase(PG8_LAS unsigned char* lds, const Gemm g, const Sched& S, const Epi& E) {
;     ...
;             PG8_LDA(At, 1, 1); PG8_STAGE(PG8_SB(1, 0), b3, voffB); PG8_STAGE(PG8_SB(1, 1), b3 + hstep, voffB); PG8_STAGE(PG8_SA(1, 0), a3, voffA);
;             PG8_WAIT_V(8); PG8_WAIT_L(0); PG8_BAR; PG8_MMA(1, 0, At, B0); PG8_MMA(1, 1, At, B1); PG8_BAR; PG8_SCHED;
;     ...
;         if constexpr (ALIGN_EPI) { if (wr == 0) PG8_BAR; }
	s_mov_b32 m0, s78
	v_lshl_add_u64 v[146:147], v[146:147], 0, s[88:89]
	ds_read_b128 v[202:205], v144 offset:49152
	ds_read_b128 v[206:209], v144 offset:50176
	ds_read_b128 v[210:213], v144 offset:51200
	ds_read_b128 v[214:217], v144 offset:52224
	ds_read_b128 v[218:221], v144 offset:53248
	ds_read_b128 v[222:225], v144 offset:54272
	ds_read_b128 v[226:229], v144 offset:55296
	ds_read_b128 v[236:239], v144 offset:56320
	global_load_lds_dwordx4 v[146:147], off
	v_lshl_add_u64 v[146:147], v[186:187], 0, s[88:89]
	s_mov_b32 m0, s77
	s_nop 0
	global_load_lds_dwordx4 v[146:147], off
	v_lshl_add_u64 v[146:147], s[54:55], 0, v[132:133]
	s_mov_b32 m0, s86
	s_nop 0
	global_load_lds_dwordx4 v[146:147], off
	v_lshl_add_u64 v[146:147], s[54:55], 0, v[136:137]
	s_mov_b32 m0, s85
	s_nop 0
	global_load_lds_dwordx4 v[146:147], off
	v_lshl_add_u64 v[146:147], v[190:191], 0, s[88:89]
	s_mov_b32 m0, s72
	s_nop 0
	global_load_lds_dwordx4 v[146:147], off
	v_lshl_add_u64 v[146:147], v[194:195], 0, s[88:89]
	s_mov_b32 m0, s73
	s_nop 0
	global_load_lds_dwordx4 v[146:147], off
	s_waitcnt vmcnt(8)
	s_waitcnt lgkmcnt(0)
	s_barrier
	s_setprio 1
	s_waitcnt lgkmcnt(0)
	v_mfma_f32_16x16x32_bf16 v[62:65], v[138:141], v[202:205], v[62:65]
	v_mfma_f32_16x16x32_bf16 v[58:61], v[166:169], v[202:205], v[58:61]
	v_mfma_f32_16x16x32_bf16 v[54:57], v[138:141], v[210:213], v[54:57]
	v_mfma_f32_16x16x32_bf16 v[46:49], v[166:169], v[210:213], v[46:49]
	v_mfma_f32_16x16x32_bf16 v[38:41], v[138:141], v[218:221], v[38:41]
	v_mfma_f32_16x16x32_bf16 v[30:33], v[166:169], v[218:221], v[30:33]
	v_mfma_f32_16x16x32_bf16 v[22:25], v[138:141], v[226:229], v[22:25]
	v_mfma_f32_16x16x32_bf16 v[14:17], v[166:169], v[226:229], v[14:17]
	v_mfma_f32_16x16x32_bf16 v[62:65], v[150:153], v[206:209], v[62:65]
	v_mfma_f32_16x16x32_bf16 v[58:61], v[170:173], v[206:209], v[58:61]
	v_mfma_f32_16x16x32_bf16 v[54:57], v[150:153], v[214:217], v[54:57]
	v_mfma_f32_16x16x32_bf16 v[46:49], v[170:173], v[214:217], v[46:49]
	v_mfma_f32_16x16x32_bf16 v[38:41], v[150:153], v[222:225], v[38:41]
	v_mfma_f32_16x16x32_bf16 v[30:33], v[170:173], v[222:225], v[30:33]
	v_mfma_f32_16x16x32_bf16 v[22:25], v[150:153], v[236:239], v[22:25]
	v_mfma_f32_16x16x32_bf16 v[14:17], v[170:173], v[236:239], v[14:17]
	v_mfma_f32_16x16x32_bf16 v[50:53], v[174:177], v[202:205], v[50:53]
	v_mfma_f32_16x16x32_bf16 v[42:45], v[182:185], v[202:205], v[42:45]
	v_mfma_f32_16x16x32_bf16 v[34:37], v[174:177], v[210:213], v[34:37]
	v_mfma_f32_16x16x32_bf16 v[26:29], v[182:185], v[210:213], v[26:29]
	v_mfma_f32_16x16x32_bf16 v[18:21], v[174:177], v[218:221], v[18:21]
	v_mfma_f32_16x16x32_bf16 v[10:13], v[182:185], v[218:221], v[10:13]
	v_mfma_f32_16x16x32_bf16 v[6:9], v[174:177], v[226:229], v[6:9]
	v_mfma_f32_16x16x32_bf16 v[2:5], v[182:185], v[226:229], v[2:5]
	v_mfma_f32_16x16x32_bf16 v[50:53], v[178:181], v[206:209], v[50:53]
	v_mfma_f32_16x16x32_bf16 v[42:45], v[198:201], v[206:209], v[42:45]
	v_mfma_f32_16x16x32_bf16 v[34:37], v[178:181], v[214:217], v[34:37]
	v_mfma_f32_16x16x32_bf16 v[26:29], v[198:201], v[214:217], v[26:29]
	v_mfma_f32_16x16x32_bf16 v[18:21], v[178:181], v[222:225], v[18:21]
	v_mfma_f32_16x16x32_bf16 v[10:13], v[198:201], v[222:225], v[10:13]
	v_mfma_f32_16x16x32_bf16 v[6:9], v[178:181], v[236:239], v[6:9]
	v_mfma_f32_16x16x32_bf16 v[2:5], v[198:201], v[236:239], v[2:5]
	s_setprio 0
	s_barrier
	s_movk_i32 s56, 0x100
	s_andn2_b64 vcc, exec, s[52:53]
	s_mov_b64 s[54:55], -1
	s_mov_b64 s[52:53], 0
	s_cbranch_vccz .LBB0_190
	s_and_b64 vcc, exec, s[6:7]
	s_cbranch_vccz .LBB0_193
	s_barrier

; #define PG8_STAGE(bufoff, gbase, voff) do { _Pragma("unroll") for (int _i = 0; _i < 2; ++_i) \
;         __builtin_amdgcn_global_load_lds((const unsigned*)((const char*)(gbase) + (voff)[_i]), (PG8_LAS unsigned*)(lds + (bufoff) + ldsw + _i * 8192), 16, 0, 0); } while (0)
; #define PG8_LDA(dst, b, h) do { _Pragma("unroll") for (int m = 0; m < 4; ++m) _Pragma("unroll") for (int k = 0; k < 2; ++k) dst[m][k] = *(const PG8_LAS bf16x8*)(lds + PG8_SA(b, h) + aoff + m * 2048 + k * 1024); } while (0)
; #define PG8_LDB(dst, b, h) do { _Pragma("unroll") for (int n = 0; n < 2; ++n) _Pragma("unroll") for (int k = 0; k < 2; ++k) dst[n][k] = *(const PG8_LAS bf16x8*)(lds + PG8_SB(b, h) + boff + n * 2048 + k * 1024); } while (0)
; #define PG8_MMA(ai, bj, At, Bt) do { __builtin_amdgcn_s_setprio(1); _Pragma("unroll") for (int m = 0; m < 4; ++m) _Pragma("unroll") for (int n = 0; n < 2; ++n) _Pragma("unroll") for (int k = 0; k < 2; ++k) \
;         acc[ai][bj][m][n] = __builtin_amdgcn_mfma_f32_16x16x32_bf16(Bt[n][k], At[m][k], acc[ai][bj][m][n], 0, 0, 0); __builtin_amdgcn_s_setprio(0); } while (0)
; #define PG8_WAIT_V(n) asm volatile("s_waitcnt vmcnt(" #n ")" ::: "memory")
; #define PG8_BAR __builtin_amdgcn_s_barrier()
; template <class Epi, class Sched, bool ALIGN_EPI = false, bool SP2 = false>
; __device__ __forceinline__ void gemm_phase(PG8_LAS unsigned char* lds, const Gemm g, const Sched& S, const Epi& E) {
;     ...
;         for (int t = 0; t < nt; t += 2) {
;             const bool last = (t == nt - 2);
;             const char* a1 = cA + (size_t)(t + 1) * kstep;
;             const char* a2 = last ? nA : cA + (size_t)(t + 2) * kstep; const char* b2 = last ? nB : cB + (size_t)(t + 2) * kstep;
;             const char* a3 = a2 + kstep; const char* b3 = b2 + kstep;
;             if (last && has_next) S.a_ready(nxt);
;             if constexpr (SP2) {
;             PG8_LDB(B0, 0, 0); PG8_LDB(B1, 0, 1); PG8_SCHED; PG8_LDA(At, 0, 0); PG8_STAGE(PG8_SA(1, 1), a1 + hstepA, voffA);
;             PG8_WAIT_V(8); PG8_WAIT_L(0); PG8_BAR; PG8_MMA(0, 0, At, B0); PG8_MMA(0, 1, At, B1); PG8_BAR; PG8_SCHED;
;             PG8_LDA(At, 0, 1); PG8_STAGE(PG8_SB(0, 0), b2, voffB); PG8_STAGE(PG8_SB(0, 1), b2 + hstep, voffB); PG8_STAGE(PG8_SA(0, 0), a2, voffA);
;             PG8_WAIT_V(8); PG8_WAIT_L(0); PG8_BAR; PG8_MMA(1, 0, At, B0); PG8_MMA(1, 1, At, B1); PG8_BAR; PG8_SCHED;
.LBB0_221:
	s_add_u32 s42, s40, 0x100
	s_addc_u32 s43, s41, 0
	s_add_i32 s65, 0, 0x10000
	s_cmp_eq_u32 s64, 8
	s_cselect_b32 s47, s13, s43
	s_cselect_b32 s46, s12, s42
	v_add_u32_e32 v165, s65, v146
	s_cselect_b32 s45, s39, s63
	s_cselect_b32 s44, s38, s37
	s_add_i32 s67, 0, 0x14000
	ds_read_b128 v[142:145], v165
	ds_read_b128 v[150:153], v165 offset:1024
	ds_read_b128 v[166:169], v165 offset:2048
	ds_read_b128 v[170:173], v165 offset:3072
	v_add_u32_e32 v165, s67, v146
	ds_read_b128 v[174:177], v165
	ds_read_b128 v[178:181], v165 offset:1024
	ds_read_b128 v[182:185], v165 offset:2048
	ds_read_b128 v[198:201], v165 offset:3072
	v_lshl_add_u64 v[186:187], s[40:41], 0, v[138:139]
	s_add_i32 m0, s50, 0xc000
	ds_read_b128 v[202:205], v157
	ds_read_b128 v[206:209], v157 offset:1024
	ds_read_b128 v[210:213], v157 offset:2048
	ds_read_b128 v[214:217], v157 offset:3072
	ds_read_b128 v[218:221], v157 offset:4096
	ds_read_b128 v[222:225], v157 offset:5120
	ds_read_b128 v[226:229], v157 offset:6144
	ds_read_b128 v[236:239], v157 offset:7168
	global_load_lds_dwordx4 v[186:187], off
	v_lshl_add_u64 v[186:187], s[40:41], 0, v[140:141]
	s_add_i32 m0, s50, 0xe000
	s_nop 0
	global_load_lds_dwordx4 v[186:187], off
	s_waitcnt vmcnt(8)
	s_waitcnt lgkmcnt(0)
	s_barrier
	s_setprio 1
	s_waitcnt lgkmcnt(0)
	v_mfma_f32_16x16x32_bf16 v[126:129], v[142:145], v[202:205], v[126:129]
	v_mfma_f32_16x16x32_bf16 v[122:125], v[166:169], v[202:205], v[122:125]
	v_mfma_f32_16x16x32_bf16 v[118:121], v[142:145], v[210:213], v[118:121]
	v_mfma_f32_16x16x32_bf16 v[110:113], v[166:169], v[210:213], v[110:113]
	v_mfma_f32_16x16x32_bf16 v[102:105], v[142:145], v[218:221], v[102:105]
	v_mfma_f32_16x16x32_bf16 v[94:97], v[166:169], v[218:221], v[94:97]
	v_mfma_f32_16x16x32_bf16 v[86:89], v[142:145], v[226:229], v[86:89]
	v_mfma_f32_16x16x32_bf16 v[78:81], v[166:169], v[226:229], v[78:81]
	v_mfma_f32_16x16x32_bf16 v[126:129], v[150:153], v[206:209], v[126:129]
	v_mfma_f32_16x16x32_bf16 v[122:125], v[170:173], v[206:209], v[122:125]
	v_mfma_f32_16x16x32_bf16 v[118:121], v[150:153], v[214:217], v[118:121]
	v_mfma_f32_16x16x32_bf16 v[110:113], v[170:173], v[214:217], v[110:113]
	v_mfma_f32_16x16x32_bf16 v[102:105], v[150:153], v[222:225], v[102:105]
	v_mfma_f32_16x16x32_bf16 v[94:97], v[170:173], v[222:225], v[94:97]
	v_mfma_f32_16x16x32_bf16 v[86:89], v[150:153], v[236:239], v[86:89]
	v_mfma_f32_16x16x32_bf16 v[78:81], v[170:173], v[236:239], v[78:81]
	v_mfma_f32_16x16x32_bf16 v[114:117], v[174:177], v[202:205], v[114:117]
	v_mfma_f32_16x16x32_bf16 v[106:109], v[182:185], v[202:205], v[106:109]
	v_mfma_f32_16x16x32_bf16 v[98:101], v[174:177], v[210:213], v[98:101]
	v_mfma_f32_16x16x32_bf16 v[90:93], v[182:185], v[210:213], v[90:93]
	v_mfma_f32_16x16x32_bf16 v[82:85], v[174:177], v[218:221], v[82:85]
	v_mfma_f32_16x16x32_bf16 v[74:77], v[182:185], v[218:221], v[74:77]
	v_mfma_f32_16x16x32_bf16 v[70:73], v[174:177], v[226:229], v[70:73]
	v_mfma_f32_16x16x32_bf16 v[66:69], v[182:185], v[226:229], v[66:69]
	v_mfma_f32_16x16x32_bf16 v[114:117], v[178:181], v[206:209], v[114:117]
	v_mfma_f32_16x16x32_bf16 v[106:109], v[198:201], v[206:209], v[106:109]
	v_mfma_f32_16x16x32_bf16 v[98:101], v[178:181], v[214:217], v[98:101]
	v_mfma_f32_16x16x32_bf16 v[90:93], v[198:201], v[214:217], v[90:93]
	v_mfma_f32_16x16x32_bf16 v[82:85], v[178:181], v[222:225], v[82:85]
	v_mfma_f32_16x16x32_bf16 v[74:77], v[198:201], v[222:225], v[74:77]
	v_mfma_f32_16x16x32_bf16 v[70:73], v[178:181], v[236:239], v[70:73]
	v_mfma_f32_16x16x32_bf16 v[66:69], v[198:201], v[236:239], v[66:69]
	s_setprio 0
	s_barrier
	s_add_i32 s40, s65, s49
	v_lshl_add_u64 v[186:187], s[44:45], 0, v[132:133]
	s_mov_b32 m0, s40
	ds_read_b128 v[202:205], v157 offset:16384
	ds_read_b128 v[206:209], v157 offset:17408
	ds_read_b128 v[210:213], v157 offset:18432
	ds_read_b128 v[214:217], v157 offset:19456
	ds_read_b128 v[218:221], v157 offset:20480
	ds_read_b128 v[222:225], v157 offset:21504
	ds_read_b128 v[226:229], v157 offset:22528
	ds_read_b128 v[236:239], v157 offset:23552
	global_load_lds_dwordx4 v[186:187], off
	s_add_i32 m0, s40, 0x2000
	s_add_u32 s40, s44, 0x30000
	v_lshl_add_u64 v[190:191], s[44:45], 0, v[136:137]
	s_addc_u32 s41, s45, 0
	s_add_i32 s65, s67, s49
	global_load_lds_dwordx4 v[190:191], off
	v_lshl_add_u64 v[194:195], s[40:41], 0, v[132:133]
	s_mov_b32 m0, s65
	v_lshl_add_u64 v[234:235], s[46:47], 0, v[134:135]
	global_load_lds_dwordx4 v[194:195], off
	v_lshl_add_u64 v[194:195], s[40:41], 0, v[136:137]
	s_add_i32 m0, s65, 0x2000
	s_nop 0
	global_load_lds_dwordx4 v[194:195], off
	v_lshl_add_u64 v[194:195], s[46:47], 0, v[130:131]
	s_mov_b32 m0, s50
	s_nop 0
	global_load_lds_dwordx4 v[194:195], off
	s_mov_b32 m0, s51
	s_nop 0
	global_load_lds_dwordx4 v[234:235], off
	s_waitcnt vmcnt(8)
	s_waitcnt lgkmcnt(0)
	s_barrier
; #define PG8_STAGE(bufoff, gbase, voff) do { _Pragma("unroll") for (int _i = 0; _i < 2; ++_i) \
;         __builtin_amdgcn_global_load_lds((const unsigned*)((const char*)(gbase) + (voff)[_i]), (PG8_LAS unsigned*)(lds + (bufoff) + ldsw + _i * 8192), 16, 0, 0); } while (0)
; #define PG8_LDA(dst, b, h) do { _Pragma("unroll") for (int m = 0; m < 4; ++m) _Pragma("unroll") for (int k = 0; k < 2; ++k) dst[m][k] = *(const PG8_LAS bf16x8*)(lds + PG8_SA(b, h) + aoff + m * 2048 + k * 1024); } while (0)
; #define PG8_LDB(dst, b, h) do { _Pragma("unroll") for (int n = 0; n < 2; ++n) _Pragma("unroll") for (int k = 0; k < 2; ++k) dst[n][k] = *(const PG8_LAS bf16x8*)(lds + PG8_SB(b, h) + boff + n * 2048 + k * 1024); } while (0)
; #define PG8_MMA(ai, bj, At, Bt) do { __builtin_amdgcn_s_setprio(1); _Pragma("unroll") for (int m = 0; m < 4; ++m) _Pragma("unroll") for (int n = 0; n < 2; ++n) _Pragma("unroll") for (int k = 0; k < 2; ++k) \
;         acc[ai][bj][m][n] = __builtin_amdgcn_mfma_f32_16x16x32_bf16(Bt[n][k], At[m][k], acc[ai][bj][m][n], 0, 0, 0); __builtin_amdgcn_s_setprio(0); } while (0)
; #define PG8_WAIT_V(n) asm volatile("s_waitcnt vmcnt(" #n ")" ::: "memory")
; #define PG8_WAIT_L(n) asm volatile("s_waitcnt lgkmcnt(" #n ")" ::: "memory")
; #define PG8_BAR __builtin_amdgcn_s_barrier()
; #define PG8_SCHED __builtin_amdgcn_sched_barrier(0)
; template <class Epi, class Sched, bool ALIGN_EPI = false, bool SP2 = false>
; __device__ __forceinline__ void gemm_phase(PG8_LAS unsigned char* lds, const Gemm g, const Sched& S, const Epi& E) {
;     ...
;             PG8_WAIT_V(8); PG8_WAIT_L(0); PG8_BAR; PG8_MMA(1, 0, At, B0); PG8_MMA(1, 1, At, B1); PG8_BAR; PG8_SCHED;
;             PG8_LDB(B0, 1, 0); PG8_LDB(B1, 1, 1); PG8_SCHED; PG8_LDA(At, 1, 0); PG8_STAGE(PG8_SA(0, 1), a2 + hstepA, voffA);
;             PG8_WAIT_V(8); PG8_WAIT_L(0); PG8_BAR; PG8_MMA(0, 0, At, B0); PG8_MMA(0, 1, At, B1); PG8_BAR; PG8_SCHED;
	s_setprio 1
	s_waitcnt lgkmcnt(0)
	v_mfma_f32_16x16x32_bf16 v[62:65], v[142:145], v[202:205], v[62:65]
	v_mfma_f32_16x16x32_bf16 v[58:61], v[166:169], v[202:205], v[58:61]
	v_mfma_f32_16x16x32_bf16 v[54:57], v[142:145], v[210:213], v[54:57]
	v_mfma_f32_16x16x32_bf16 v[46:49], v[166:169], v[210:213], v[46:49]
	v_mfma_f32_16x16x32_bf16 v[38:41], v[142:145], v[218:221], v[38:41]
	v_mfma_f32_16x16x32_bf16 v[30:33], v[166:169], v[218:221], v[30:33]
	v_mfma_f32_16x16x32_bf16 v[22:25], v[142:145], v[226:229], v[22:25]
	v_mfma_f32_16x16x32_bf16 v[14:17], v[166:169], v[226:229], v[14:17]
	v_mfma_f32_16x16x32_bf16 v[62:65], v[150:153], v[206:209], v[62:65]
	v_mfma_f32_16x16x32_bf16 v[58:61], v[170:173], v[206:209], v[58:61]
	v_mfma_f32_16x16x32_bf16 v[54:57], v[150:153], v[214:217], v[54:57]
	v_mfma_f32_16x16x32_bf16 v[46:49], v[170:173], v[214:217], v[46:49]
	v_mfma_f32_16x16x32_bf16 v[38:41], v[150:153], v[222:225], v[38:41]
	v_mfma_f32_16x16x32_bf16 v[30:33], v[170:173], v[222:225], v[30:33]
	v_mfma_f32_16x16x32_bf16 v[22:25], v[150:153], v[236:239], v[22:25]
	v_mfma_f32_16x16x32_bf16 v[14:17], v[170:173], v[236:239], v[14:17]
	v_mfma_f32_16x16x32_bf16 v[50:53], v[174:177], v[202:205], v[50:53]
	v_mfma_f32_16x16x32_bf16 v[42:45], v[182:185], v[202:205], v[42:45]
	v_mfma_f32_16x16x32_bf16 v[34:37], v[174:177], v[210:213], v[34:37]
	v_mfma_f32_16x16x32_bf16 v[26:29], v[182:185], v[210:213], v[26:29]
	v_mfma_f32_16x16x32_bf16 v[18:21], v[174:177], v[218:221], v[18:21]
	v_mfma_f32_16x16x32_bf16 v[10:13], v[182:185], v[218:221], v[10:13]
	v_mfma_f32_16x16x32_bf16 v[6:9], v[174:177], v[226:229], v[6:9]
	v_mfma_f32_16x16x32_bf16 v[2:5], v[182:185], v[226:229], v[2:5]
	v_mfma_f32_16x16x32_bf16 v[50:53], v[178:181], v[206:209], v[50:53]
	v_mfma_f32_16x16x32_bf16 v[42:45], v[198:201], v[206:209], v[42:45]
	v_mfma_f32_16x16x32_bf16 v[34:37], v[178:181], v[214:217], v[34:37]
	v_mfma_f32_16x16x32_bf16 v[26:29], v[198:201], v[214:217], v[26:29]
	v_mfma_f32_16x16x32_bf16 v[18:21], v[178:181], v[222:225], v[18:21]
	v_mfma_f32_16x16x32_bf16 v[10:13], v[198:201], v[222:225], v[10:13]
	v_mfma_f32_16x16x32_bf16 v[6:9], v[178:181], v[236:239], v[6:9]
	v_mfma_f32_16x16x32_bf16 v[2:5], v[198:201], v[236:239], v[2:5]
	s_setprio 0
	s_barrier
	s_add_i32 s65, 0, 0x18000
	v_add_u32_e32 v165, s65, v146
	s_add_i32 s67, 0, 0x1c000
	ds_read_b128 v[142:145], v165
	ds_read_b128 v[150:153], v165 offset:1024
	ds_read_b128 v[166:169], v165 offset:2048
	ds_read_b128 v[170:173], v165 offset:3072
	v_add_u32_e32 v165, s67, v146
	ds_read_b128 v[174:177], v165
	ds_read_b128 v[178:181], v165 offset:1024
	ds_read_b128 v[182:185], v165 offset:2048
	ds_read_b128 v[198:201], v165 offset:3072
	s_add_u32 s40, s46, 0x30000
	s_addc_u32 s41, s47, 0
	s_mov_b32 m0, s52
	v_lshl_add_u64 v[246:247], s[40:41], 0, v[130:131]
	ds_read_b128 v[202:205], v157 offset:32768
	ds_read_b128 v[206:209], v157 offset:33792
	ds_read_b128 v[210:213], v157 offset:34816
	ds_read_b128 v[214:217], v157 offset:35840
	ds_read_b128 v[218:221], v157 offset:36864
	ds_read_b128 v[222:225], v157 offset:37888
	ds_read_b128 v[226:229], v157 offset:38912
	ds_read_b128 v[236:239], v157 offset:39936
	global_load_lds_dwordx4 v[246:247], off
	v_lshl_add_u64 v[246:247], s[40:41], 0, v[134:135]
	s_mov_b32 m0, s53
	s_nop 0
	global_load_lds_dwordx4 v[246:247], off
	s_waitcnt vmcnt(8)
	s_waitcnt lgkmcnt(0)
	s_barrier
	s_setprio 1
	s_waitcnt lgkmcnt(0)
	v_mfma_f32_16x16x32_bf16 v[126:129], v[142:145], v[202:205], v[126:129]
	v_mfma_f32_16x16x32_bf16 v[122:125], v[166:169], v[202:205], v[122:125]
	v_mfma_f32_16x16x32_bf16 v[118:121], v[142:145], v[210:213], v[118:121]
	v_mfma_f32_16x16x32_bf16 v[110:113], v[166:169], v[210:213], v[110:113]
	v_mfma_f32_16x16x32_bf16 v[102:105], v[142:145], v[218:221], v[102:105]
	v_mfma_f32_16x16x32_bf16 v[94:97], v[166:169], v[218:221], v[94:97]
	v_mfma_f32_16x16x32_bf16 v[86:89], v[142:145], v[226:229], v[86:89]
	v_mfma_f32_16x16x32_bf16 v[78:81], v[166:169], v[226:229], v[78:81]
	v_mfma_f32_16x16x32_bf16 v[126:129], v[150:153], v[206:209], v[126:129]
	v_mfma_f32_16x16x32_bf16 v[122:125], v[170:173], v[206:209], v[122:125]
	v_mfma_f32_16x16x32_bf16 v[118:121], v[150:153], v[214:217], v[118:121]
	v_mfma_f32_16x16x32_bf16 v[110:113], v[170:173], v[214:217], v[110:113]
	v_mfma_f32_16x16x32_bf16 v[102:105], v[150:153], v[222:225], v[102:105]
	v_mfma_f32_16x16x32_bf16 v[94:97], v[170:173], v[222:225], v[94:97]
	v_mfma_f32_16x16x32_bf16 v[86:89], v[150:153], v[236:239], v[86:89]
	v_mfma_f32_16x16x32_bf16 v[78:81], v[170:173], v[236:239], v[78:81]
	v_mfma_f32_16x16x32_bf16 v[114:117], v[174:177], v[202:205], v[114:117]
	v_mfma_f32_16x16x32_bf16 v[106:109], v[182:185], v[202:205], v[106:109]
	v_mfma_f32_16x16x32_bf16 v[98:101], v[174:177], v[210:213], v[98:101]
	v_mfma_f32_16x16x32_bf16 v[90:93], v[182:185], v[210:213], v[90:93]
	v_mfma_f32_16x16x32_bf16 v[82:85], v[174:177], v[218:221], v[82:85]
	v_mfma_f32_16x16x32_bf16 v[74:77], v[182:185], v[218:221], v[74:77]
	v_mfma_f32_16x16x32_bf16 v[70:73], v[174:177], v[226:229], v[70:73]
	v_mfma_f32_16x16x32_bf16 v[66:69], v[182:185], v[226:229], v[66:69]
	v_mfma_f32_16x16x32_bf16 v[114:117], v[178:181], v[206:209], v[114:117]
	v_mfma_f32_16x16x32_bf16 v[106:109], v[198:201], v[206:209], v[106:109]
	v_mfma_f32_16x16x32_bf16 v[98:101], v[178:181], v[214:217], v[98:101]
	v_mfma_f32_16x16x32_bf16 v[90:93], v[198:201], v[214:217], v[90:93]
	v_mfma_f32_16x16x32_bf16 v[82:85], v[178:181], v[222:225], v[82:85]
	v_mfma_f32_16x16x32_bf16 v[74:77], v[198:201], v[222:225], v[74:77]
	v_mfma_f32_16x16x32_bf16 v[70:73], v[178:181], v[236:239], v[70:73]
	v_mfma_f32_16x16x32_bf16 v[66:69], v[198:201], v[236:239], v[66:69]
	s_setprio 0
	s_barrier
; #define PG8_STAGE(bufoff, gbase, voff) do { _Pragma("unroll") for (int _i = 0; _i < 2; ++_i) \
;         __builtin_amdgcn_global_load_lds((const unsigned*)((const char*)(gbase) + (voff)[_i]), (PG8_LAS unsigned*)(lds + (bufoff) + ldsw + _i * 8192), 16, 0, 0); } while (0)
; #define PG8_LDA(dst, b, h) do { _Pragma("unroll") for (int m = 0; m < 4; ++m) _Pragma("unroll") for (int k = 0; k < 2; ++k) dst[m][k] = *(const PG8_LAS bf16x8*)(lds + PG8_SA(b, h) + aoff + m * 2048 + k * 1024); } while (0)
; #define PG8_MMA(ai, bj, At, Bt) do { __builtin_amdgcn_s_setprio(1); _Pragma("unroll") for (int m = 0; m < 4; ++m) _Pragma("unroll") for (int n = 0; n < 2; ++n) _Pragma("unroll") for (int k = 0; k < 2; ++k) \
;         acc[ai][bj][m][n] = __builtin_amdgcn_mfma_f32_16x16x32_bf16(Bt[n][k], At[m][k], acc[ai][bj][m][n], 0, 0, 0); __builtin_amdgcn_s_setprio(0); } while (0)
; #define PG8_WAIT_V(n) asm volatile("s_waitcnt vmcnt(" #n ")" ::: "memory")
; #define PG8_WAIT_L(n) asm volatile("s_waitcnt lgkmcnt(" #n ")" ::: "memory")
; #define PG8_BAR __builtin_amdgcn_s_barrier()
; #define PG8_SCHED __builtin_amdgcn_sched_barrier(0)
; template <class Epi, class Sched, bool ALIGN_EPI = false, bool SP2 = false>
; __device__ __forceinline__ void gemm_phase(PG8_LAS unsigned char* lds, const Gemm g, const Sched& S, const Epi& E) {
;     ...
;             PG8_LDA(At, 1, 1); PG8_STAGE(PG8_SB(1, 0), b3, voffB); PG8_STAGE(PG8_SB(1, 1), b3 + hstep, voffB); PG8_STAGE(PG8_SA(1, 0), a3, voffA);
;             PG8_WAIT_V(8); PG8_WAIT_L(0); PG8_BAR; PG8_MMA(1, 0, At, B0); PG8_MMA(1, 1, At, B1); PG8_BAR; PG8_SCHED;
;     ...
;         if constexpr (ALIGN_EPI) { if (wr == 0) PG8_BAR; }
	s_add_i32 s40, s65, s49
	v_lshl_add_u64 v[186:187], v[186:187], 0, s[88:89]
	s_mov_b32 m0, s40
	ds_read_b128 v[202:205], v157 offset:49152
	ds_read_b128 v[206:209], v157 offset:50176
	ds_read_b128 v[210:213], v157 offset:51200
	ds_read_b128 v[214:217], v157 offset:52224
	ds_read_b128 v[218:221], v157 offset:53248
	ds_read_b128 v[222:225], v157 offset:54272
	ds_read_b128 v[226:229], v157 offset:55296
	ds_read_b128 v[236:239], v157 offset:56320
	global_load_lds_dwordx4 v[186:187], off
	s_add_i32 m0, s40, 0x2000
	s_add_u32 s40, s44, 0x30080
	v_lshl_add_u64 v[186:187], v[190:191], 0, s[88:89]
	s_addc_u32 s41, s45, 0
	s_add_i32 s44, s67, s49
	global_load_lds_dwordx4 v[186:187], off
	v_lshl_add_u64 v[186:187], s[40:41], 0, v[132:133]
	s_mov_b32 m0, s44
	s_nop 0
	global_load_lds_dwordx4 v[186:187], off
	v_lshl_add_u64 v[186:187], s[40:41], 0, v[136:137]
	s_add_i32 m0, s44, 0x2000
	s_nop 0
	global_load_lds_dwordx4 v[186:187], off
	v_lshl_add_u64 v[186:187], v[194:195], 0, s[88:89]
	s_mov_b32 m0, s54
	s_nop 0
	global_load_lds_dwordx4 v[186:187], off
	v_lshl_add_u64 v[186:187], v[234:235], 0, s[88:89]
	s_mov_b32 m0, s55
	s_nop 0
	global_load_lds_dwordx4 v[186:187], off
	s_waitcnt vmcnt(8)
	s_waitcnt lgkmcnt(0)
	s_barrier
	s_setprio 1
	s_waitcnt lgkmcnt(0)
	v_mfma_f32_16x16x32_bf16 v[62:65], v[142:145], v[202:205], v[62:65]
	v_mfma_f32_16x16x32_bf16 v[58:61], v[166:169], v[202:205], v[58:61]
	v_mfma_f32_16x16x32_bf16 v[54:57], v[142:145], v[210:213], v[54:57]
	v_mfma_f32_16x16x32_bf16 v[46:49], v[166:169], v[210:213], v[46:49]
	v_mfma_f32_16x16x32_bf16 v[38:41], v[142:145], v[218:221], v[38:41]
	v_mfma_f32_16x16x32_bf16 v[30:33], v[166:169], v[218:221], v[30:33]
	v_mfma_f32_16x16x32_bf16 v[22:25], v[142:145], v[226:229], v[22:25]
	v_mfma_f32_16x16x32_bf16 v[14:17], v[166:169], v[226:229], v[14:17]
	v_mfma_f32_16x16x32_bf16 v[62:65], v[150:153], v[206:209], v[62:65]
	v_mfma_f32_16x16x32_bf16 v[58:61], v[170:173], v[206:209], v[58:61]
	v_mfma_f32_16x16x32_bf16 v[54:57], v[150:153], v[214:217], v[54:57]
	v_mfma_f32_16x16x32_bf16 v[46:49], v[170:173], v[214:217], v[46:49]
	v_mfma_f32_16x16x32_bf16 v[38:41], v[150:153], v[222:225], v[38:41]
	v_mfma_f32_16x16x32_bf16 v[30:33], v[170:173], v[222:225], v[30:33]
	v_mfma_f32_16x16x32_bf16 v[22:25], v[150:153], v[236:239], v[22:25]
	v_mfma_f32_16x16x32_bf16 v[14:17], v[170:173], v[236:239], v[14:17]
	v_mfma_f32_16x16x32_bf16 v[50:53], v[174:177], v[202:205], v[50:53]
	v_mfma_f32_16x16x32_bf16 v[42:45], v[182:185], v[202:205], v[42:45]
	v_mfma_f32_16x16x32_bf16 v[34:37], v[174:177], v[210:213], v[34:37]
	v_mfma_f32_16x16x32_bf16 v[26:29], v[182:185], v[210:213], v[26:29]
	v_mfma_f32_16x16x32_bf16 v[18:21], v[174:177], v[218:221], v[18:21]
	v_mfma_f32_16x16x32_bf16 v[10:13], v[182:185], v[218:221], v[10:13]
	v_mfma_f32_16x16x32_bf16 v[6:9], v[174:177], v[226:229], v[6:9]
	v_mfma_f32_16x16x32_bf16 v[2:5], v[182:185], v[226:229], v[2:5]
	v_mfma_f32_16x16x32_bf16 v[50:53], v[178:181], v[206:209], v[50:53]
	v_mfma_f32_16x16x32_bf16 v[42:45], v[198:201], v[206:209], v[42:45]
	v_mfma_f32_16x16x32_bf16 v[34:37], v[178:181], v[214:217], v[34:37]
	v_mfma_f32_16x16x32_bf16 v[26:29], v[198:201], v[214:217], v[26:29]
	v_mfma_f32_16x16x32_bf16 v[18:21], v[178:181], v[222:225], v[18:21]
	v_mfma_f32_16x16x32_bf16 v[10:13], v[198:201], v[222:225], v[10:13]
	v_mfma_f32_16x16x32_bf16 v[6:9], v[178:181], v[236:239], v[6:9]
	v_mfma_f32_16x16x32_bf16 v[2:5], v[198:201], v[236:239], v[2:5]
	s_setprio 0
	s_barrier
	s_add_i32 s64, s64, 2
	s_add_u32 s37, s37, 0x100
	s_addc_u32 s63, s63, 0
	s_cmp_gt_u32 s64, 9
	s_mov_b64 s[40:41], s[42:43]
	s_cbranch_scc0 .LBB0_221
	s_and_b64 vcc, exec, s[8:9]
	s_cbranch_vccz .LBB0_224
	s_barrier

; #define PG8_STAGE(bufoff, gbase, voff) do { _Pragma("unroll") for (int _i = 0; _i < 2; ++_i) \
;         __builtin_amdgcn_global_load_lds((const unsigned*)((const char*)(gbase) + (voff)[_i]), (PG8_LAS unsigned*)(lds + (bufoff) + ldsw + _i * 8192), 16, 0, 0); } while (0)
; #define PG8_LDA(dst, b, h) do { _Pragma("unroll") for (int m = 0; m < 4; ++m) _Pragma("unroll") for (int k = 0; k < 2; ++k) dst[m][k] = *(const PG8_LAS bf16x8*)(lds + PG8_SA(b, h) + aoff + m * 2048 + k * 1024); } while (0)
; #define PG8_LDB(dst, b, h) do { _Pragma("unroll") for (int n = 0; n < 2; ++n) _Pragma("unroll") for (int k = 0; k < 2; ++k) dst[n][k] = *(const PG8_LAS bf16x8*)(lds + PG8_SB(b, h) + boff + n * 2048 + k * 1024); } while (0)
; #define PG8_MMA(ai, bj, At, Bt) do { __builtin_amdgcn_s_setprio(1); _Pragma("unroll") for (int m = 0; m < 4; ++m) _Pragma("unroll") for (int n = 0; n < 2; ++n) _Pragma("unroll") for (int k = 0; k < 2; ++k) \
;         acc[ai][bj][m][n] = __builtin_amdgcn_mfma_f32_16x16x32_bf16(Bt[n][k], At[m][k], acc[ai][bj][m][n], 0, 0, 0); __builtin_amdgcn_s_setprio(0); } while (0)
; #define PG8_WAIT_V(n) asm volatile("s_waitcnt vmcnt(" #n ")" ::: "memory")
; #define PG8_BAR __builtin_amdgcn_s_barrier()
; template <class Epi, class Sched, bool ALIGN_EPI = false, bool SP2 = false>
; __device__ __forceinline__ void gemm_phase(PG8_LAS unsigned char* lds, const Gemm g, const Sched& S, const Epi& E) {
;     ...
;         for (int t = 0; t < nt; t += 2) {
;             const bool last = (t == nt - 2);
;             const char* a1 = cA + (size_t)(t + 1) * kstep;
;             const char* a2 = last ? nA : cA + (size_t)(t + 2) * kstep; const char* b2 = last ? nB : cB + (size_t)(t + 2) * kstep;
;             const char* a3 = a2 + kstep; const char* b3 = b2 + kstep;
;             if (last && has_next) S.a_ready(nxt);
;             if constexpr (SP2) {
;             PG8_LDB(B0, 0, 0); PG8_LDB(B1, 0, 1); PG8_SCHED; PG8_LDA(At, 0, 0); PG8_STAGE(PG8_SA(1, 1), a1 + hstepA, voffA);
;             PG8_WAIT_V(8); PG8_WAIT_L(0); PG8_BAR; PG8_MMA(0, 0, At, B0); PG8_MMA(0, 1, At, B1); PG8_BAR; PG8_SCHED;
;             PG8_LDA(At, 0, 1); PG8_STAGE(PG8_SB(0, 0), b2, voffB); PG8_STAGE(PG8_SB(0, 1), b2 + hstep, voffB); PG8_STAGE(PG8_SA(0, 0), a2, voffA);
;             PG8_WAIT_V(8); PG8_WAIT_L(0); PG8_BAR; PG8_MMA(1, 0, At, B0); PG8_MMA(1, 1, At, B1); PG8_BAR; PG8_SCHED;
.LBB0_248:
	s_add_u32 s50, s48, 0xfffe0080
	s_addc_u32 s51, s49, -1
	s_add_i32 s68, 0, 0x10000
	s_cmp_eq_u32 s67, 4
	s_cselect_b32 s53, s9, s51
	s_cselect_b32 s52, s39, s50
	v_add_u32_e32 v165, s68, v146
	s_cselect_b32 s51, s37, s65
	s_cselect_b32 s50, s41, s64
	s_add_i32 s70, 0, 0x14000
	ds_read_b128 v[142:145], v165
	ds_read_b128 v[150:153], v165 offset:1024
	ds_read_b128 v[166:169], v165 offset:2048
	ds_read_b128 v[170:173], v165 offset:3072
	v_add_u32_e32 v165, s70, v146
	ds_read_b128 v[174:177], v165
	ds_read_b128 v[178:181], v165 offset:1024
	ds_read_b128 v[182:185], v165 offset:2048
	ds_read_b128 v[198:201], v165 offset:3072
	v_lshl_add_u64 v[186:187], s[48:49], 0, v[138:139]
	s_add_i32 m0, s13, 0xc000
	ds_read_b128 v[202:205], v157
	ds_read_b128 v[206:209], v157 offset:1024
	ds_read_b128 v[210:213], v157 offset:2048
	ds_read_b128 v[214:217], v157 offset:3072
	ds_read_b128 v[218:221], v157 offset:4096
	ds_read_b128 v[222:225], v157 offset:5120
	ds_read_b128 v[226:229], v157 offset:6144
	ds_read_b128 v[236:239], v157 offset:7168
	global_load_lds_dwordx4 v[186:187], off
	v_lshl_add_u64 v[186:187], s[48:49], 0, v[140:141]
	s_add_i32 m0, s13, 0xe000
	s_nop 0
	global_load_lds_dwordx4 v[186:187], off
	s_waitcnt vmcnt(8)
	s_waitcnt lgkmcnt(0)
	s_barrier
	s_setprio 1
	s_waitcnt lgkmcnt(0)
	v_mfma_f32_16x16x32_bf16 v[126:129], v[142:145], v[202:205], v[126:129]
	v_mfma_f32_16x16x32_bf16 v[122:125], v[166:169], v[202:205], v[122:125]
	v_mfma_f32_16x16x32_bf16 v[118:121], v[142:145], v[210:213], v[118:121]
	v_mfma_f32_16x16x32_bf16 v[110:113], v[166:169], v[210:213], v[110:113]
	v_mfma_f32_16x16x32_bf16 v[102:105], v[142:145], v[218:221], v[102:105]
	v_mfma_f32_16x16x32_bf16 v[94:97], v[166:169], v[218:221], v[94:97]
	v_mfma_f32_16x16x32_bf16 v[86:89], v[142:145], v[226:229], v[86:89]
	v_mfma_f32_16x16x32_bf16 v[78:81], v[166:169], v[226:229], v[78:81]
	v_mfma_f32_16x16x32_bf16 v[126:129], v[150:153], v[206:209], v[126:129]
	v_mfma_f32_16x16x32_bf16 v[122:125], v[170:173], v[206:209], v[122:125]
	v_mfma_f32_16x16x32_bf16 v[118:121], v[150:153], v[214:217], v[118:121]
	v_mfma_f32_16x16x32_bf16 v[110:113], v[170:173], v[214:217], v[110:113]
	v_mfma_f32_16x16x32_bf16 v[102:105], v[150:153], v[222:225], v[102:105]
	v_mfma_f32_16x16x32_bf16 v[94:97], v[170:173], v[222:225], v[94:97]
	v_mfma_f32_16x16x32_bf16 v[86:89], v[150:153], v[236:239], v[86:89]
	v_mfma_f32_16x16x32_bf16 v[78:81], v[170:173], v[236:239], v[78:81]
	v_mfma_f32_16x16x32_bf16 v[114:117], v[174:177], v[202:205], v[114:117]
	v_mfma_f32_16x16x32_bf16 v[106:109], v[182:185], v[202:205], v[106:109]
	v_mfma_f32_16x16x32_bf16 v[98:101], v[174:177], v[210:213], v[98:101]
	v_mfma_f32_16x16x32_bf16 v[90:93], v[182:185], v[210:213], v[90:93]
	v_mfma_f32_16x16x32_bf16 v[82:85], v[174:177], v[218:221], v[82:85]
	v_mfma_f32_16x16x32_bf16 v[74:77], v[182:185], v[218:221], v[74:77]
	v_mfma_f32_16x16x32_bf16 v[70:73], v[174:177], v[226:229], v[70:73]
	v_mfma_f32_16x16x32_bf16 v[66:69], v[182:185], v[226:229], v[66:69]
	v_mfma_f32_16x16x32_bf16 v[114:117], v[178:181], v[206:209], v[114:117]
	v_mfma_f32_16x16x32_bf16 v[106:109], v[198:201], v[206:209], v[106:109]
	v_mfma_f32_16x16x32_bf16 v[98:101], v[178:181], v[214:217], v[98:101]
	v_mfma_f32_16x16x32_bf16 v[90:93], v[198:201], v[214:217], v[90:93]
	v_mfma_f32_16x16x32_bf16 v[82:85], v[178:181], v[222:225], v[82:85]
	v_mfma_f32_16x16x32_bf16 v[74:77], v[198:201], v[222:225], v[74:77]
	v_mfma_f32_16x16x32_bf16 v[70:73], v[178:181], v[236:239], v[70:73]
	v_mfma_f32_16x16x32_bf16 v[66:69], v[198:201], v[236:239], v[66:69]
	s_setprio 0
	s_barrier
	s_add_i32 s68, s68, s55
	v_lshl_add_u64 v[186:187], s[50:51], 0, v[132:133]
	s_mov_b32 m0, s68
	ds_read_b128 v[202:205], v157 offset:16384
	ds_read_b128 v[206:209], v157 offset:17408
	ds_read_b128 v[210:213], v157 offset:18432
	ds_read_b128 v[214:217], v157 offset:19456
	ds_read_b128 v[218:221], v157 offset:20480
	ds_read_b128 v[222:225], v157 offset:21504
	ds_read_b128 v[226:229], v157 offset:22528
	ds_read_b128 v[236:239], v157 offset:23552
	global_load_lds_dwordx4 v[186:187], off
	s_add_i32 m0, s68, 0x2000
	s_add_u32 s68, s50, 0x20000
	v_lshl_add_u64 v[190:191], s[50:51], 0, v[136:137]
	s_addc_u32 s69, s51, 0
	s_add_i32 s70, s70, s55
	global_load_lds_dwordx4 v[190:191], off
	v_lshl_add_u64 v[194:195], s[68:69], 0, v[132:133]
	s_mov_b32 m0, s70
	v_lshl_add_u64 v[234:235], s[52:53], 0, v[134:135]
	global_load_lds_dwordx4 v[194:195], off
	v_lshl_add_u64 v[194:195], s[68:69], 0, v[136:137]
	s_add_i32 m0, s70, 0x2000
	s_nop 0
	global_load_lds_dwordx4 v[194:195], off
	v_lshl_add_u64 v[194:195], s[52:53], 0, v[130:131]
	s_mov_b32 m0, s13
	s_nop 0
	global_load_lds_dwordx4 v[194:195], off
	s_mov_b32 m0, s56
	s_nop 0
	global_load_lds_dwordx4 v[234:235], off
	s_waitcnt vmcnt(8)
	s_waitcnt lgkmcnt(0)
	s_barrier
; #define PG8_STAGE(bufoff, gbase, voff) do { _Pragma("unroll") for (int _i = 0; _i < 2; ++_i) \
;         __builtin_amdgcn_global_load_lds((const unsigned*)((const char*)(gbase) + (voff)[_i]), (PG8_LAS unsigned*)(lds + (bufoff) + ldsw + _i * 8192), 16, 0, 0); } while (0)
; #define PG8_LDA(dst, b, h) do { _Pragma("unroll") for (int m = 0; m < 4; ++m) _Pragma("unroll") for (int k = 0; k < 2; ++k) dst[m][k] = *(const PG8_LAS bf16x8*)(lds + PG8_SA(b, h) + aoff + m * 2048 + k * 1024); } while (0)
; #define PG8_LDB(dst, b, h) do { _Pragma("unroll") for (int n = 0; n < 2; ++n) _Pragma("unroll") for (int k = 0; k < 2; ++k) dst[n][k] = *(const PG8_LAS bf16x8*)(lds + PG8_SB(b, h) + boff + n * 2048 + k * 1024); } while (0)
; #define PG8_MMA(ai, bj, At, Bt) do { __builtin_amdgcn_s_setprio(1); _Pragma("unroll") for (int m = 0; m < 4; ++m) _Pragma("unroll") for (int n = 0; n < 2; ++n) _Pragma("unroll") for (int k = 0; k < 2; ++k) \
;         acc[ai][bj][m][n] = __builtin_amdgcn_mfma_f32_16x16x32_bf16(Bt[n][k], At[m][k], acc[ai][bj][m][n], 0, 0, 0); __builtin_amdgcn_s_setprio(0); } while (0)
; #define PG8_WAIT_V(n) asm volatile("s_waitcnt vmcnt(" #n ")" ::: "memory")
; #define PG8_WAIT_L(n) asm volatile("s_waitcnt lgkmcnt(" #n ")" ::: "memory")
; #define PG8_BAR __builtin_amdgcn_s_barrier()
; #define PG8_SCHED __builtin_amdgcn_sched_barrier(0)
; template <class Epi, class Sched, bool ALIGN_EPI = false, bool SP2 = false>
; __device__ __forceinline__ void gemm_phase(PG8_LAS unsigned char* lds, const Gemm g, const Sched& S, const Epi& E) {
;     ...
;             PG8_WAIT_V(8); PG8_WAIT_L(0); PG8_BAR; PG8_MMA(1, 0, At, B0); PG8_MMA(1, 1, At, B1); PG8_BAR; PG8_SCHED;
;             PG8_LDB(B0, 1, 0); PG8_LDB(B1, 1, 1); PG8_SCHED; PG8_LDA(At, 1, 0); PG8_STAGE(PG8_SA(0, 1), a2 + hstepA, voffA);
;             PG8_WAIT_V(8); PG8_WAIT_L(0); PG8_BAR; PG8_MMA(0, 0, At, B0); PG8_MMA(0, 1, At, B1); PG8_BAR; PG8_SCHED;
	s_setprio 1
	s_waitcnt lgkmcnt(0)
	v_mfma_f32_16x16x32_bf16 v[62:65], v[142:145], v[202:205], v[62:65]
	v_mfma_f32_16x16x32_bf16 v[58:61], v[166:169], v[202:205], v[58:61]
	v_mfma_f32_16x16x32_bf16 v[54:57], v[142:145], v[210:213], v[54:57]
	v_mfma_f32_16x16x32_bf16 v[46:49], v[166:169], v[210:213], v[46:49]
	v_mfma_f32_16x16x32_bf16 v[38:41], v[142:145], v[218:221], v[38:41]
	v_mfma_f32_16x16x32_bf16 v[30:33], v[166:169], v[218:221], v[30:33]
	v_mfma_f32_16x16x32_bf16 v[22:25], v[142:145], v[226:229], v[22:25]
	v_mfma_f32_16x16x32_bf16 v[14:17], v[166:169], v[226:229], v[14:17]
	v_mfma_f32_16x16x32_bf16 v[62:65], v[150:153], v[206:209], v[62:65]
	v_mfma_f32_16x16x32_bf16 v[58:61], v[170:173], v[206:209], v[58:61]
	v_mfma_f32_16x16x32_bf16 v[54:57], v[150:153], v[214:217], v[54:57]
	v_mfma_f32_16x16x32_bf16 v[46:49], v[170:173], v[214:217], v[46:49]
	v_mfma_f32_16x16x32_bf16 v[38:41], v[150:153], v[222:225], v[38:41]
	v_mfma_f32_16x16x32_bf16 v[30:33], v[170:173], v[222:225], v[30:33]
	v_mfma_f32_16x16x32_bf16 v[22:25], v[150:153], v[236:239], v[22:25]
	v_mfma_f32_16x16x32_bf16 v[14:17], v[170:173], v[236:239], v[14:17]
	v_mfma_f32_16x16x32_bf16 v[50:53], v[174:177], v[202:205], v[50:53]
	v_mfma_f32_16x16x32_bf16 v[42:45], v[182:185], v[202:205], v[42:45]
	v_mfma_f32_16x16x32_bf16 v[34:37], v[174:177], v[210:213], v[34:37]
	v_mfma_f32_16x16x32_bf16 v[26:29], v[182:185], v[210:213], v[26:29]
	v_mfma_f32_16x16x32_bf16 v[18:21], v[174:177], v[218:221], v[18:21]
	v_mfma_f32_16x16x32_bf16 v[10:13], v[182:185], v[218:221], v[10:13]
	v_mfma_f32_16x16x32_bf16 v[6:9], v[174:177], v[226:229], v[6:9]
	v_mfma_f32_16x16x32_bf16 v[2:5], v[182:185], v[226:229], v[2:5]
	v_mfma_f32_16x16x32_bf16 v[50:53], v[178:181], v[206:209], v[50:53]
	v_mfma_f32_16x16x32_bf16 v[42:45], v[198:201], v[206:209], v[42:45]
	v_mfma_f32_16x16x32_bf16 v[34:37], v[178:181], v[214:217], v[34:37]
	v_mfma_f32_16x16x32_bf16 v[26:29], v[198:201], v[214:217], v[26:29]
	v_mfma_f32_16x16x32_bf16 v[18:21], v[178:181], v[222:225], v[18:21]
	v_mfma_f32_16x16x32_bf16 v[10:13], v[198:201], v[222:225], v[10:13]
	v_mfma_f32_16x16x32_bf16 v[6:9], v[178:181], v[236:239], v[6:9]
	v_mfma_f32_16x16x32_bf16 v[2:5], v[198:201], v[236:239], v[2:5]
	s_setprio 0
	s_barrier
	s_add_i32 s68, 0, 0x18000
	v_add_u32_e32 v165, s68, v146
	s_add_i32 s69, 0, 0x1c000
	ds_read_b128 v[142:145], v165
	ds_read_b128 v[150:153], v165 offset:1024
	ds_read_b128 v[166:169], v165 offset:2048
	ds_read_b128 v[170:173], v165 offset:3072
	v_add_u32_e32 v165, s69, v146
	ds_read_b128 v[174:177], v165
	ds_read_b128 v[178:181], v165 offset:1024
	ds_read_b128 v[182:185], v165 offset:2048
	ds_read_b128 v[198:201], v165 offset:3072
	s_add_u32 s52, s52, 0x20000
	s_addc_u32 s53, s53, 0
	s_mov_b32 m0, s57
	v_lshl_add_u64 v[246:247], s[52:53], 0, v[130:131]
	ds_read_b128 v[202:205], v157 offset:32768
	ds_read_b128 v[206:209], v157 offset:33792
	ds_read_b128 v[210:213], v157 offset:34816
	ds_read_b128 v[214:217], v157 offset:35840
	ds_read_b128 v[218:221], v157 offset:36864
	ds_read_b128 v[222:225], v157 offset:37888
	ds_read_b128 v[226:229], v157 offset:38912
	ds_read_b128 v[236:239], v157 offset:39936
	global_load_lds_dwordx4 v[246:247], off
	v_lshl_add_u64 v[246:247], s[52:53], 0, v[134:135]
	s_mov_b32 m0, s58
	s_nop 0
	global_load_lds_dwordx4 v[246:247], off
	s_waitcnt vmcnt(8)
	s_waitcnt lgkmcnt(0)
	s_barrier
	s_setprio 1
	s_waitcnt lgkmcnt(0)
	v_mfma_f32_16x16x32_bf16 v[126:129], v[142:145], v[202:205], v[126:129]
	v_mfma_f32_16x16x32_bf16 v[122:125], v[166:169], v[202:205], v[122:125]
	v_mfma_f32_16x16x32_bf16 v[118:121], v[142:145], v[210:213], v[118:121]
	v_mfma_f32_16x16x32_bf16 v[110:113], v[166:169], v[210:213], v[110:113]
	v_mfma_f32_16x16x32_bf16 v[102:105], v[142:145], v[218:221], v[102:105]
	v_mfma_f32_16x16x32_bf16 v[94:97], v[166:169], v[218:221], v[94:97]
	v_mfma_f32_16x16x32_bf16 v[86:89], v[142:145], v[226:229], v[86:89]
	v_mfma_f32_16x16x32_bf16 v[78:81], v[166:169], v[226:229], v[78:81]
	v_mfma_f32_16x16x32_bf16 v[126:129], v[150:153], v[206:209], v[126:129]
	v_mfma_f32_16x16x32_bf16 v[122:125], v[170:173], v[206:209], v[122:125]
	v_mfma_f32_16x16x32_bf16 v[118:121], v[150:153], v[214:217], v[118:121]
	v_mfma_f32_16x16x32_bf16 v[110:113], v[170:173], v[214:217], v[110:113]
	v_mfma_f32_16x16x32_bf16 v[102:105], v[150:153], v[222:225], v[102:105]
	v_mfma_f32_16x16x32_bf16 v[94:97], v[170:173], v[222:225], v[94:97]
	v_mfma_f32_16x16x32_bf16 v[86:89], v[150:153], v[236:239], v[86:89]
	v_mfma_f32_16x16x32_bf16 v[78:81], v[170:173], v[236:239], v[78:81]
	v_mfma_f32_16x16x32_bf16 v[114:117], v[174:177], v[202:205], v[114:117]
	v_mfma_f32_16x16x32_bf16 v[106:109], v[182:185], v[202:205], v[106:109]
	v_mfma_f32_16x16x32_bf16 v[98:101], v[174:177], v[210:213], v[98:101]
	v_mfma_f32_16x16x32_bf16 v[90:93], v[182:185], v[210:213], v[90:93]
	v_mfma_f32_16x16x32_bf16 v[82:85], v[174:177], v[218:221], v[82:85]
	v_mfma_f32_16x16x32_bf16 v[74:77], v[182:185], v[218:221], v[74:77]
	v_mfma_f32_16x16x32_bf16 v[70:73], v[174:177], v[226:229], v[70:73]
	v_mfma_f32_16x16x32_bf16 v[66:69], v[182:185], v[226:229], v[66:69]
	v_mfma_f32_16x16x32_bf16 v[114:117], v[178:181], v[206:209], v[114:117]
	v_mfma_f32_16x16x32_bf16 v[106:109], v[198:201], v[206:209], v[106:109]
	v_mfma_f32_16x16x32_bf16 v[98:101], v[178:181], v[214:217], v[98:101]
	v_mfma_f32_16x16x32_bf16 v[90:93], v[198:201], v[214:217], v[90:93]
	v_mfma_f32_16x16x32_bf16 v[82:85], v[178:181], v[222:225], v[82:85]
	v_mfma_f32_16x16x32_bf16 v[74:77], v[198:201], v[222:225], v[74:77]
	v_mfma_f32_16x16x32_bf16 v[70:73], v[178:181], v[236:239], v[70:73]
	v_mfma_f32_16x16x32_bf16 v[66:69], v[198:201], v[236:239], v[66:69]
	s_setprio 0
	s_barrier
; #define PG8_STAGE(bufoff, gbase, voff) do { _Pragma("unroll") for (int _i = 0; _i < 2; ++_i) \
;         __builtin_amdgcn_global_load_lds((const unsigned*)((const char*)(gbase) + (voff)[_i]), (PG8_LAS unsigned*)(lds + (bufoff) + ldsw + _i * 8192), 16, 0, 0); } while (0)
; #define PG8_LDA(dst, b, h) do { _Pragma("unroll") for (int m = 0; m < 4; ++m) _Pragma("unroll") for (int k = 0; k < 2; ++k) dst[m][k] = *(const PG8_LAS bf16x8*)(lds + PG8_SA(b, h) + aoff + m * 2048 + k * 1024); } while (0)
; #define PG8_MMA(ai, bj, At, Bt) do { __builtin_amdgcn_s_setprio(1); _Pragma("unroll") for (int m = 0; m < 4; ++m) _Pragma("unroll") for (int n = 0; n < 2; ++n) _Pragma("unroll") for (int k = 0; k < 2; ++k) \
;         acc[ai][bj][m][n] = __builtin_amdgcn_mfma_f32_16x16x32_bf16(Bt[n][k], At[m][k], acc[ai][bj][m][n], 0, 0, 0); __builtin_amdgcn_s_setprio(0); } while (0)
; #define PG8_WAIT_V(n) asm volatile("s_waitcnt vmcnt(" #n ")" ::: "memory")
; #define PG8_WAIT_L(n) asm volatile("s_waitcnt lgkmcnt(" #n ")" ::: "memory")
; #define PG8_BAR __builtin_amdgcn_s_barrier()
; #define PG8_SCHED __builtin_amdgcn_sched_barrier(0)
; template <class Epi, class Sched, bool ALIGN_EPI = false, bool SP2 = false>
; __device__ __forceinline__ void gemm_phase(PG8_LAS unsigned char* lds, const Gemm g, const Sched& S, const Epi& E) {
;     ...
;             PG8_LDA(At, 1, 1); PG8_STAGE(PG8_SB(1, 0), b3, voffB); PG8_STAGE(PG8_SB(1, 1), b3 + hstep, voffB); PG8_STAGE(PG8_SA(1, 0), a3, voffA);
;             PG8_WAIT_V(8); PG8_WAIT_L(0); PG8_BAR; PG8_MMA(1, 0, At, B0); PG8_MMA(1, 1, At, B1); PG8_BAR; PG8_SCHED;
;     ...
;         if constexpr (ALIGN_EPI) { if (wr == 0) PG8_BAR; }
	s_add_i32 s52, s68, s55
	v_lshl_add_u64 v[186:187], v[186:187], 0, s[88:89]
	s_mov_b32 m0, s52
	ds_read_b128 v[202:205], v157 offset:49152
	ds_read_b128 v[206:209], v157 offset:50176
	ds_read_b128 v[210:213], v157 offset:51200
	ds_read_b128 v[214:217], v157 offset:52224
	ds_read_b128 v[218:221], v157 offset:53248
	ds_read_b128 v[222:225], v157 offset:54272
	ds_read_b128 v[226:229], v157 offset:55296
	ds_read_b128 v[236:239], v157 offset:56320
	global_load_lds_dwordx4 v[186:187], off
	s_add_i32 m0, s52, 0x2000
	s_add_u32 s50, s50, 0x20080
	v_lshl_add_u64 v[186:187], v[190:191], 0, s[88:89]
	s_addc_u32 s51, s51, 0
	s_add_i32 s52, s69, s55
	global_load_lds_dwordx4 v[186:187], off
	v_lshl_add_u64 v[186:187], s[50:51], 0, v[132:133]
	s_mov_b32 m0, s52
	s_nop 0
	global_load_lds_dwordx4 v[186:187], off
	v_lshl_add_u64 v[186:187], s[50:51], 0, v[136:137]
	s_add_i32 m0, s52, 0x2000
	s_nop 0
	global_load_lds_dwordx4 v[186:187], off
	v_lshl_add_u64 v[186:187], v[194:195], 0, s[88:89]
	s_mov_b32 m0, s59
	s_nop 0
	global_load_lds_dwordx4 v[186:187], off
	v_lshl_add_u64 v[186:187], v[234:235], 0, s[88:89]
	s_mov_b32 m0, s60
	s_nop 0
	global_load_lds_dwordx4 v[186:187], off
	s_waitcnt vmcnt(8)
	s_waitcnt lgkmcnt(0)
	s_barrier
	s_setprio 1
	s_waitcnt lgkmcnt(0)
	v_mfma_f32_16x16x32_bf16 v[62:65], v[142:145], v[202:205], v[62:65]
	v_mfma_f32_16x16x32_bf16 v[58:61], v[166:169], v[202:205], v[58:61]
	v_mfma_f32_16x16x32_bf16 v[54:57], v[142:145], v[210:213], v[54:57]
	v_mfma_f32_16x16x32_bf16 v[46:49], v[166:169], v[210:213], v[46:49]
	v_mfma_f32_16x16x32_bf16 v[38:41], v[142:145], v[218:221], v[38:41]
	v_mfma_f32_16x16x32_bf16 v[30:33], v[166:169], v[218:221], v[30:33]
	v_mfma_f32_16x16x32_bf16 v[22:25], v[142:145], v[226:229], v[22:25]
	v_mfma_f32_16x16x32_bf16 v[14:17], v[166:169], v[226:229], v[14:17]
	v_mfma_f32_16x16x32_bf16 v[62:65], v[150:153], v[206:209], v[62:65]
	v_mfma_f32_16x16x32_bf16 v[58:61], v[170:173], v[206:209], v[58:61]
	v_mfma_f32_16x16x32_bf16 v[54:57], v[150:153], v[214:217], v[54:57]
	v_mfma_f32_16x16x32_bf16 v[46:49], v[170:173], v[214:217], v[46:49]
	v_mfma_f32_16x16x32_bf16 v[38:41], v[150:153], v[222:225], v[38:41]
	v_mfma_f32_16x16x32_bf16 v[30:33], v[170:173], v[222:225], v[30:33]
	v_mfma_f32_16x16x32_bf16 v[22:25], v[150:153], v[236:239], v[22:25]
	v_mfma_f32_16x16x32_bf16 v[14:17], v[170:173], v[236:239], v[14:17]
	v_mfma_f32_16x16x32_bf16 v[50:53], v[174:177], v[202:205], v[50:53]
	v_mfma_f32_16x16x32_bf16 v[42:45], v[182:185], v[202:205], v[42:45]
	v_mfma_f32_16x16x32_bf16 v[34:37], v[174:177], v[210:213], v[34:37]
	v_mfma_f32_16x16x32_bf16 v[26:29], v[182:185], v[210:213], v[26:29]
	v_mfma_f32_16x16x32_bf16 v[18:21], v[174:177], v[218:221], v[18:21]
	v_mfma_f32_16x16x32_bf16 v[10:13], v[182:185], v[218:221], v[10:13]
	v_mfma_f32_16x16x32_bf16 v[6:9], v[174:177], v[226:229], v[6:9]
	v_mfma_f32_16x16x32_bf16 v[2:5], v[182:185], v[226:229], v[2:5]
	v_mfma_f32_16x16x32_bf16 v[50:53], v[178:181], v[206:209], v[50:53]
	v_mfma_f32_16x16x32_bf16 v[42:45], v[198:201], v[206:209], v[42:45]
	v_mfma_f32_16x16x32_bf16 v[34:37], v[178:181], v[214:217], v[34:37]
	v_mfma_f32_16x16x32_bf16 v[26:29], v[198:201], v[214:217], v[26:29]
	v_mfma_f32_16x16x32_bf16 v[18:21], v[178:181], v[222:225], v[18:21]
	v_mfma_f32_16x16x32_bf16 v[10:13], v[198:201], v[222:225], v[10:13]
	v_mfma_f32_16x16x32_bf16 v[6:9], v[178:181], v[236:239], v[6:9]
	v_mfma_f32_16x16x32_bf16 v[2:5], v[198:201], v[236:239], v[2:5]
	s_setprio 0
	s_barrier
	s_add_i32 s67, s67, 2
	s_add_u32 s48, s48, 0x100
	s_addc_u32 s49, s49, 0
	s_add_u32 s64, s64, 0x100
	s_addc_u32 s65, s65, 0
	s_cmp_gt_u32 s67, 5
	s_cbranch_scc0 .LBB0_248
	s_and_b64 vcc, exec, s[6:7]
	s_cbranch_vccz .LBB0_251
	s_barrier

; #define PG8_STAGE(bufoff, gbase, voff) do { _Pragma("unroll") for (int _i = 0; _i < 2; ++_i) \
;         __builtin_amdgcn_global_load_lds((const unsigned*)((const char*)(gbase) + (voff)[_i]), (PG8_LAS unsigned*)(lds + (bufoff) + ldsw + _i * 8192), 16, 0, 0); } while (0)
; #define PG8_LDA(dst, b, h) do { _Pragma("unroll") for (int m = 0; m < 4; ++m) _Pragma("unroll") for (int k = 0; k < 2; ++k) dst[m][k] = *(const PG8_LAS bf16x8*)(lds + PG8_SA(b, h) + aoff + m * 2048 + k * 1024); } while (0)
; #define PG8_LDB(dst, b, h) do { _Pragma("unroll") for (int n = 0; n < 2; ++n) _Pragma("unroll") for (int k = 0; k < 2; ++k) dst[n][k] = *(const PG8_LAS bf16x8*)(lds + PG8_SB(b, h) + boff + n * 2048 + k * 1024); } while (0)
; #define PG8_MMA(ai, bj, At, Bt) do { __builtin_amdgcn_s_setprio(1); _Pragma("unroll") for (int m = 0; m < 4; ++m) _Pragma("unroll") for (int n = 0; n < 2; ++n) _Pragma("unroll") for (int k = 0; k < 2; ++k) \
;         acc[ai][bj][m][n] = __builtin_amdgcn_mfma_f32_16x16x32_bf16(Bt[n][k], At[m][k], acc[ai][bj][m][n], 0, 0, 0); __builtin_amdgcn_s_setprio(0); } while (0)
; #define PG8_WAIT_V(n) asm volatile("s_waitcnt vmcnt(" #n ")" ::: "memory")
; #define PG8_BAR __builtin_amdgcn_s_barrier()
; template <class Epi, class Sched, bool ALIGN_EPI = false, bool SP2 = false>
; __device__ __forceinline__ void gemm_phase(PG8_LAS unsigned char* lds, const Gemm g, const Sched& S, const Epi& E) {
;     ...
;         for (int t = 0; t < nt; t += 2) {
;             const bool last = (t == nt - 2);
;             const char* a1 = cA + (size_t)(t + 1) * kstep;
;             const char* a2 = last ? nA : cA + (size_t)(t + 2) * kstep; const char* b2 = last ? nB : cB + (size_t)(t + 2) * kstep;
;             const char* a3 = a2 + kstep; const char* b3 = b2 + kstep;
;             if (last && has_next) S.a_ready(nxt);
;             if constexpr (SP2) {
;             PG8_LDB(B0, 0, 0); PG8_LDB(B1, 0, 1); PG8_SCHED; PG8_LDA(At, 0, 0); PG8_STAGE(PG8_SA(1, 1), a1 + hstepA, voffA);
;             PG8_WAIT_V(8); PG8_WAIT_L(0); PG8_BAR; PG8_MMA(0, 0, At, B0); PG8_MMA(0, 1, At, B1); PG8_BAR; PG8_SCHED;
;             PG8_LDA(At, 0, 1); PG8_STAGE(PG8_SB(0, 0), b2, voffB); PG8_STAGE(PG8_SB(0, 1), b2 + hstep, voffB); PG8_STAGE(PG8_SA(0, 0), a2, voffA);
;             PG8_WAIT_V(8); PG8_WAIT_L(0); PG8_BAR; PG8_MMA(1, 0, At, B0); PG8_MMA(1, 1, At, B1); PG8_BAR; PG8_SCHED;
.LBB0_275:
	s_add_u32 s50, s48, 0xfffc0080
	s_addc_u32 s51, s49, -1
	s_add_i32 s69, 0, 0x10000
	s_cmp_eq_u32 s68, 12
	s_cselect_b32 s53, s13, s51
	s_cselect_b32 s52, s15, s50
	s_cselect_b32 s51, s9, s47
	s_cselect_b32 s50, s37, s39
	s_add_i32 s72, 0, 0x14000
	v_add_u32_e32 v142, s69, v157
	v_add_u32_e32 v146, s72, v157
	ds_read_b128 v[90:93], v142
	ds_read_b128 v[94:97], v142 offset:1024
	ds_read_b128 v[138:141], v142 offset:2048
	ds_read_b128 v[142:145], v142 offset:3072
	ds_read_b128 v[150:153], v146
	ds_read_b128 v[178:181], v146 offset:1024
	ds_read_b128 v[182:185], v146 offset:2048
	ds_read_b128 v[198:201], v146 offset:3072
	v_lshl_add_u64 v[146:147], s[48:49], 0, v[176:177]
	s_add_i32 m0, s57, 0xc000
	ds_read_b128 v[202:205], v186
	ds_read_b128 v[206:209], v186 offset:1024
	ds_read_b128 v[210:213], v186 offset:2048
	ds_read_b128 v[214:217], v186 offset:3072
	ds_read_b128 v[218:221], v186 offset:4096
	ds_read_b128 v[222:225], v186 offset:5120
	ds_read_b128 v[226:229], v186 offset:6144
	ds_read_b128 v[236:239], v186 offset:7168
	global_load_lds_dwordx4 v[146:147], off
	v_lshl_add_u64 v[146:147], s[48:49], 0, v[174:175]
	s_add_i32 m0, s57, 0xe000
	s_nop 0
	global_load_lds_dwordx4 v[146:147], off
	s_waitcnt vmcnt(8)
	s_waitcnt lgkmcnt(0)
	s_barrier
	s_setprio 1
	s_waitcnt lgkmcnt(0)
	v_mfma_f32_16x16x32_bf16 v[134:137], v[90:93], v[202:205], v[134:137]
	v_mfma_f32_16x16x32_bf16 v[130:133], v[138:141], v[202:205], v[130:133]
	v_mfma_f32_16x16x32_bf16 v[126:129], v[90:93], v[210:213], v[126:129]
	v_mfma_f32_16x16x32_bf16 v[122:125], v[138:141], v[210:213], v[122:125]
	v_mfma_f32_16x16x32_bf16 v[118:121], v[90:93], v[218:221], v[118:121]
	v_mfma_f32_16x16x32_bf16 v[114:117], v[138:141], v[218:221], v[114:117]
	v_mfma_f32_16x16x32_bf16 v[110:113], v[90:93], v[226:229], v[110:113]
	v_mfma_f32_16x16x32_bf16 v[106:109], v[138:141], v[226:229], v[106:109]
	v_mfma_f32_16x16x32_bf16 v[134:137], v[94:97], v[206:209], v[134:137]
	v_mfma_f32_16x16x32_bf16 v[130:133], v[142:145], v[206:209], v[130:133]
	v_mfma_f32_16x16x32_bf16 v[126:129], v[94:97], v[214:217], v[126:129]
	v_mfma_f32_16x16x32_bf16 v[122:125], v[142:145], v[214:217], v[122:125]
	v_mfma_f32_16x16x32_bf16 v[118:121], v[94:97], v[222:225], v[118:121]
	v_mfma_f32_16x16x32_bf16 v[114:117], v[142:145], v[222:225], v[114:117]
	v_mfma_f32_16x16x32_bf16 v[110:113], v[94:97], v[236:239], v[110:113]
	v_mfma_f32_16x16x32_bf16 v[106:109], v[142:145], v[236:239], v[106:109]
	v_mfma_f32_16x16x32_bf16 v[62:65], v[150:153], v[202:205], v[62:65]
	v_mfma_f32_16x16x32_bf16 v[58:61], v[182:185], v[202:205], v[58:61]
	v_mfma_f32_16x16x32_bf16 v[54:57], v[150:153], v[210:213], v[54:57]
	v_mfma_f32_16x16x32_bf16 v[50:53], v[182:185], v[210:213], v[50:53]
	v_mfma_f32_16x16x32_bf16 v[46:49], v[150:153], v[218:221], v[46:49]
	v_mfma_f32_16x16x32_bf16 v[42:45], v[182:185], v[218:221], v[42:45]
	v_mfma_f32_16x16x32_bf16 v[38:41], v[150:153], v[226:229], v[38:41]
	v_mfma_f32_16x16x32_bf16 v[34:37], v[182:185], v[226:229], v[34:37]
	v_mfma_f32_16x16x32_bf16 v[62:65], v[178:181], v[206:209], v[62:65]
	v_mfma_f32_16x16x32_bf16 v[58:61], v[198:201], v[206:209], v[58:61]
	v_mfma_f32_16x16x32_bf16 v[54:57], v[178:181], v[214:217], v[54:57]
	v_mfma_f32_16x16x32_bf16 v[50:53], v[198:201], v[214:217], v[50:53]
	v_mfma_f32_16x16x32_bf16 v[46:49], v[178:181], v[222:225], v[46:49]
	v_mfma_f32_16x16x32_bf16 v[42:45], v[198:201], v[222:225], v[42:45]
	v_mfma_f32_16x16x32_bf16 v[38:41], v[178:181], v[236:239], v[38:41]
	v_mfma_f32_16x16x32_bf16 v[34:37], v[198:201], v[236:239], v[34:37]
	s_setprio 0
	s_barrier
	s_add_i32 s69, s69, s56
	v_lshl_add_u64 v[146:147], s[50:51], 0, v[168:169]
	s_mov_b32 m0, s69
	ds_read_b128 v[202:205], v186 offset:16384
	ds_read_b128 v[206:209], v186 offset:17408
	ds_read_b128 v[210:213], v186 offset:18432
	ds_read_b128 v[214:217], v186 offset:19456
	ds_read_b128 v[218:221], v186 offset:20480
	ds_read_b128 v[222:225], v186 offset:21504
	ds_read_b128 v[226:229], v186 offset:22528
	ds_read_b128 v[236:239], v186 offset:23552
	global_load_lds_dwordx4 v[146:147], off
	s_add_i32 m0, s69, 0x2000
	s_add_u32 s70, s50, 0x40000
	v_lshl_add_u64 v[190:191], s[50:51], 0, v[172:173]
	s_addc_u32 s71, s51, 0
	s_add_i32 s69, s72, s56
	global_load_lds_dwordx4 v[190:191], off
	v_lshl_add_u64 v[194:195], s[70:71], 0, v[168:169]
	s_mov_b32 m0, s69
	v_lshl_add_u64 v[234:235], s[52:53], 0, v[170:171]
	global_load_lds_dwordx4 v[194:195], off
	v_lshl_add_u64 v[194:195], s[70:71], 0, v[172:173]
	s_add_i32 m0, s69, 0x2000
	s_nop 0
	global_load_lds_dwordx4 v[194:195], off
	v_lshl_add_u64 v[194:195], s[52:53], 0, v[166:167]
	s_mov_b32 m0, s57
	s_nop 0
	global_load_lds_dwordx4 v[194:195], off
	s_mov_b32 m0, s58
	s_nop 0
	global_load_lds_dwordx4 v[234:235], off
	s_waitcnt vmcnt(8)
	s_waitcnt lgkmcnt(0)
	s_barrier
; #define PG8_STAGE(bufoff, gbase, voff) do { _Pragma("unroll") for (int _i = 0; _i < 2; ++_i) \
;         __builtin_amdgcn_global_load_lds((const unsigned*)((const char*)(gbase) + (voff)[_i]), (PG8_LAS unsigned*)(lds + (bufoff) + ldsw + _i * 8192), 16, 0, 0); } while (0)
; #define PG8_LDA(dst, b, h) do { _Pragma("unroll") for (int m = 0; m < 4; ++m) _Pragma("unroll") for (int k = 0; k < 2; ++k) dst[m][k] = *(const PG8_LAS bf16x8*)(lds + PG8_SA(b, h) + aoff + m * 2048 + k * 1024); } while (0)
; #define PG8_LDB(dst, b, h) do { _Pragma("unroll") for (int n = 0; n < 2; ++n) _Pragma("unroll") for (int k = 0; k < 2; ++k) dst[n][k] = *(const PG8_LAS bf16x8*)(lds + PG8_SB(b, h) + boff + n * 2048 + k * 1024); } while (0)
; #define PG8_MMA(ai, bj, At, Bt) do { __builtin_amdgcn_s_setprio(1); _Pragma("unroll") for (int m = 0; m < 4; ++m) _Pragma("unroll") for (int n = 0; n < 2; ++n) _Pragma("unroll") for (int k = 0; k < 2; ++k) \
;         acc[ai][bj][m][n] = __builtin_amdgcn_mfma_f32_16x16x32_bf16(Bt[n][k], At[m][k], acc[ai][bj][m][n], 0, 0, 0); __builtin_amdgcn_s_setprio(0); } while (0)
; #define PG8_WAIT_V(n) asm volatile("s_waitcnt vmcnt(" #n ")" ::: "memory")
; #define PG8_WAIT_L(n) asm volatile("s_waitcnt lgkmcnt(" #n ")" ::: "memory")
; #define PG8_BAR __builtin_amdgcn_s_barrier()
; #define PG8_SCHED __builtin_amdgcn_sched_barrier(0)
; template <class Epi, class Sched, bool ALIGN_EPI = false, bool SP2 = false>
; __device__ __forceinline__ void gemm_phase(PG8_LAS unsigned char* lds, const Gemm g, const Sched& S, const Epi& E) {
;     ...
;             PG8_WAIT_V(8); PG8_WAIT_L(0); PG8_BAR; PG8_MMA(1, 0, At, B0); PG8_MMA(1, 1, At, B1); PG8_BAR; PG8_SCHED;
;             PG8_LDB(B0, 1, 0); PG8_LDB(B1, 1, 1); PG8_SCHED; PG8_LDA(At, 1, 0); PG8_STAGE(PG8_SA(0, 1), a2 + hstepA, voffA);
;             PG8_WAIT_V(8); PG8_WAIT_L(0); PG8_BAR; PG8_MMA(0, 0, At, B0); PG8_MMA(0, 1, At, B1); PG8_BAR; PG8_SCHED;
	s_setprio 1
	s_waitcnt lgkmcnt(0)
	v_mfma_f32_16x16x32_bf16 v[102:105], v[90:93], v[202:205], v[102:105]
	v_mfma_f32_16x16x32_bf16 v[98:101], v[138:141], v[202:205], v[98:101]
	v_mfma_f32_16x16x32_bf16 v[86:89], v[90:93], v[210:213], v[86:89]
	v_mfma_f32_16x16x32_bf16 v[82:85], v[138:141], v[210:213], v[82:85]
	v_mfma_f32_16x16x32_bf16 v[78:81], v[90:93], v[218:221], v[78:81]
	v_mfma_f32_16x16x32_bf16 v[74:77], v[138:141], v[218:221], v[74:77]
	v_mfma_f32_16x16x32_bf16 v[70:73], v[90:93], v[226:229], v[70:73]
	v_mfma_f32_16x16x32_bf16 v[66:69], v[138:141], v[226:229], v[66:69]
	v_mfma_f32_16x16x32_bf16 v[102:105], v[94:97], v[206:209], v[102:105]
	v_mfma_f32_16x16x32_bf16 v[98:101], v[142:145], v[206:209], v[98:101]
	v_mfma_f32_16x16x32_bf16 v[86:89], v[94:97], v[214:217], v[86:89]
	v_mfma_f32_16x16x32_bf16 v[82:85], v[142:145], v[214:217], v[82:85]
	v_mfma_f32_16x16x32_bf16 v[78:81], v[94:97], v[222:225], v[78:81]
	v_mfma_f32_16x16x32_bf16 v[74:77], v[142:145], v[222:225], v[74:77]
	v_mfma_f32_16x16x32_bf16 v[70:73], v[94:97], v[236:239], v[70:73]
	v_mfma_f32_16x16x32_bf16 v[66:69], v[142:145], v[236:239], v[66:69]
	v_mfma_f32_16x16x32_bf16 v[30:33], v[150:153], v[202:205], v[30:33]
	v_mfma_f32_16x16x32_bf16 v[26:29], v[182:185], v[202:205], v[26:29]
	v_mfma_f32_16x16x32_bf16 v[22:25], v[150:153], v[210:213], v[22:25]
	v_mfma_f32_16x16x32_bf16 v[18:21], v[182:185], v[210:213], v[18:21]
	v_mfma_f32_16x16x32_bf16 v[14:17], v[150:153], v[218:221], v[14:17]
	v_mfma_f32_16x16x32_bf16 v[10:13], v[182:185], v[218:221], v[10:13]
	v_mfma_f32_16x16x32_bf16 v[6:9], v[150:153], v[226:229], v[6:9]
	v_mfma_f32_16x16x32_bf16 v[2:5], v[182:185], v[226:229], v[2:5]
	v_mfma_f32_16x16x32_bf16 v[30:33], v[178:181], v[206:209], v[30:33]
	v_mfma_f32_16x16x32_bf16 v[26:29], v[198:201], v[206:209], v[26:29]
	v_mfma_f32_16x16x32_bf16 v[22:25], v[178:181], v[214:217], v[22:25]
	v_mfma_f32_16x16x32_bf16 v[18:21], v[198:201], v[214:217], v[18:21]
	v_mfma_f32_16x16x32_bf16 v[14:17], v[178:181], v[222:225], v[14:17]
	v_mfma_f32_16x16x32_bf16 v[10:13], v[198:201], v[222:225], v[10:13]
	v_mfma_f32_16x16x32_bf16 v[6:9], v[178:181], v[236:239], v[6:9]
	v_mfma_f32_16x16x32_bf16 v[2:5], v[198:201], v[236:239], v[2:5]
	s_setprio 0
	s_barrier
	s_add_i32 s69, 0, 0x18000
	s_add_i32 s70, 0, 0x1c000
	v_add_u32_e32 v142, s69, v157
	v_add_u32_e32 v187, s70, v157
	ds_read_b128 v[90:93], v142
	ds_read_b128 v[94:97], v142 offset:1024
	ds_read_b128 v[138:141], v142 offset:2048
	ds_read_b128 v[142:145], v142 offset:3072
	ds_read_b128 v[150:153], v187
	ds_read_b128 v[178:181], v187 offset:1024
	ds_read_b128 v[182:185], v187 offset:2048
	ds_read_b128 v[198:201], v187 offset:3072
	s_add_u32 s52, s52, 0x40000
	s_addc_u32 s53, s53, 0
	s_mov_b32 m0, s59
	v_lshl_add_u64 v[246:247], s[52:53], 0, v[166:167]
	ds_read_b128 v[202:205], v186 offset:32768
	ds_read_b128 v[206:209], v186 offset:33792
	ds_read_b128 v[210:213], v186 offset:34816
	ds_read_b128 v[214:217], v186 offset:35840
	ds_read_b128 v[218:221], v186 offset:36864
	ds_read_b128 v[222:225], v186 offset:37888
	ds_read_b128 v[226:229], v186 offset:38912
	ds_read_b128 v[236:239], v186 offset:39936
	global_load_lds_dwordx4 v[246:247], off
	v_lshl_add_u64 v[246:247], s[52:53], 0, v[170:171]
	s_mov_b32 m0, s60
	s_nop 0
	global_load_lds_dwordx4 v[246:247], off
	s_waitcnt vmcnt(8)
	s_waitcnt lgkmcnt(0)
	s_barrier
	s_setprio 1
	s_waitcnt lgkmcnt(0)
	v_mfma_f32_16x16x32_bf16 v[134:137], v[90:93], v[202:205], v[134:137]
	v_mfma_f32_16x16x32_bf16 v[130:133], v[138:141], v[202:205], v[130:133]
	v_mfma_f32_16x16x32_bf16 v[126:129], v[90:93], v[210:213], v[126:129]
	v_mfma_f32_16x16x32_bf16 v[122:125], v[138:141], v[210:213], v[122:125]
	v_mfma_f32_16x16x32_bf16 v[118:121], v[90:93], v[218:221], v[118:121]
	v_mfma_f32_16x16x32_bf16 v[114:117], v[138:141], v[218:221], v[114:117]
	v_mfma_f32_16x16x32_bf16 v[110:113], v[90:93], v[226:229], v[110:113]
	v_mfma_f32_16x16x32_bf16 v[106:109], v[138:141], v[226:229], v[106:109]
	v_mfma_f32_16x16x32_bf16 v[134:137], v[94:97], v[206:209], v[134:137]
	v_mfma_f32_16x16x32_bf16 v[130:133], v[142:145], v[206:209], v[130:133]
	v_mfma_f32_16x16x32_bf16 v[126:129], v[94:97], v[214:217], v[126:129]
	v_mfma_f32_16x16x32_bf16 v[122:125], v[142:145], v[214:217], v[122:125]
	v_mfma_f32_16x16x32_bf16 v[118:121], v[94:97], v[222:225], v[118:121]
	v_mfma_f32_16x16x32_bf16 v[114:117], v[142:145], v[222:225], v[114:117]
	v_mfma_f32_16x16x32_bf16 v[110:113], v[94:97], v[236:239], v[110:113]
	v_mfma_f32_16x16x32_bf16 v[106:109], v[142:145], v[236:239], v[106:109]
	v_mfma_f32_16x16x32_bf16 v[62:65], v[150:153], v[202:205], v[62:65]
	v_mfma_f32_16x16x32_bf16 v[58:61], v[182:185], v[202:205], v[58:61]
	v_mfma_f32_16x16x32_bf16 v[54:57], v[150:153], v[210:213], v[54:57]
	v_mfma_f32_16x16x32_bf16 v[50:53], v[182:185], v[210:213], v[50:53]
	v_mfma_f32_16x16x32_bf16 v[46:49], v[150:153], v[218:221], v[46:49]
	v_mfma_f32_16x16x32_bf16 v[42:45], v[182:185], v[218:221], v[42:45]
	v_mfma_f32_16x16x32_bf16 v[38:41], v[150:153], v[226:229], v[38:41]
	v_mfma_f32_16x16x32_bf16 v[34:37], v[182:185], v[226:229], v[34:37]
	v_mfma_f32_16x16x32_bf16 v[62:65], v[178:181], v[206:209], v[62:65]
	v_mfma_f32_16x16x32_bf16 v[58:61], v[198:201], v[206:209], v[58:61]
	v_mfma_f32_16x16x32_bf16 v[54:57], v[178:181], v[214:217], v[54:57]
	v_mfma_f32_16x16x32_bf16 v[50:53], v[198:201], v[214:217], v[50:53]
	v_mfma_f32_16x16x32_bf16 v[46:49], v[178:181], v[222:225], v[46:49]
	v_mfma_f32_16x16x32_bf16 v[42:45], v[198:201], v[222:225], v[42:45]
	v_mfma_f32_16x16x32_bf16 v[38:41], v[178:181], v[236:239], v[38:41]
	v_mfma_f32_16x16x32_bf16 v[34:37], v[198:201], v[236:239], v[34:37]
	s_setprio 0
	s_barrier
; #define PG8_STAGE(bufoff, gbase, voff) do { _Pragma("unroll") for (int _i = 0; _i < 2; ++_i) \
;         __builtin_amdgcn_global_load_lds((const unsigned*)((const char*)(gbase) + (voff)[_i]), (PG8_LAS unsigned*)(lds + (bufoff) + ldsw + _i * 8192), 16, 0, 0); } while (0)
; #define PG8_LDA(dst, b, h) do { _Pragma("unroll") for (int m = 0; m < 4; ++m) _Pragma("unroll") for (int k = 0; k < 2; ++k) dst[m][k] = *(const PG8_LAS bf16x8*)(lds + PG8_SA(b, h) + aoff + m * 2048 + k * 1024); } while (0)
; #define PG8_MMA(ai, bj, At, Bt) do { __builtin_amdgcn_s_setprio(1); _Pragma("unroll") for (int m = 0; m < 4; ++m) _Pragma("unroll") for (int n = 0; n < 2; ++n) _Pragma("unroll") for (int k = 0; k < 2; ++k) \
;         acc[ai][bj][m][n] = __builtin_amdgcn_mfma_f32_16x16x32_bf16(Bt[n][k], At[m][k], acc[ai][bj][m][n], 0, 0, 0); __builtin_amdgcn_s_setprio(0); } while (0)
; #define PG8_WAIT_V(n) asm volatile("s_waitcnt vmcnt(" #n ")" ::: "memory")
; #define PG8_WAIT_L(n) asm volatile("s_waitcnt lgkmcnt(" #n ")" ::: "memory")
; #define PG8_BAR __builtin_amdgcn_s_barrier()
; #define PG8_SCHED __builtin_amdgcn_sched_barrier(0)
; template <class Epi, class Sched, bool ALIGN_EPI = false, bool SP2 = false>
; __device__ __forceinline__ void gemm_phase(PG8_LAS unsigned char* lds, const Gemm g, const Sched& S, const Epi& E) {
;     ...
;             PG8_LDA(At, 1, 1); PG8_STAGE(PG8_SB(1, 0), b3, voffB); PG8_STAGE(PG8_SB(1, 1), b3 + hstep, voffB); PG8_STAGE(PG8_SA(1, 0), a3, voffA);
;             PG8_WAIT_V(8); PG8_WAIT_L(0); PG8_BAR; PG8_MMA(1, 0, At, B0); PG8_MMA(1, 1, At, B1); PG8_BAR; PG8_SCHED;
;     ...
;         if constexpr (ALIGN_EPI) { if (wr == 0) PG8_BAR; }
	s_add_i32 s52, s69, s56
	v_lshl_add_u64 v[146:147], v[146:147], 0, s[88:89]
	s_mov_b32 m0, s52
	ds_read_b128 v[202:205], v186 offset:49152
	ds_read_b128 v[206:209], v186 offset:50176
	ds_read_b128 v[210:213], v186 offset:51200
	ds_read_b128 v[214:217], v186 offset:52224
	ds_read_b128 v[218:221], v186 offset:53248
	ds_read_b128 v[222:225], v186 offset:54272
	ds_read_b128 v[226:229], v186 offset:55296
	ds_read_b128 v[236:239], v186 offset:56320
	global_load_lds_dwordx4 v[146:147], off
	s_add_i32 m0, s52, 0x2000
	s_add_u32 s50, s50, 0x40080
	v_lshl_add_u64 v[146:147], v[190:191], 0, s[88:89]
	s_addc_u32 s51, s51, 0
	s_add_i32 s52, s70, s56
	global_load_lds_dwordx4 v[146:147], off
	v_lshl_add_u64 v[146:147], s[50:51], 0, v[168:169]
	s_mov_b32 m0, s52
	s_nop 0
	global_load_lds_dwordx4 v[146:147], off
	v_lshl_add_u64 v[146:147], s[50:51], 0, v[172:173]
	s_add_i32 m0, s52, 0x2000
	s_nop 0
	global_load_lds_dwordx4 v[146:147], off
	v_lshl_add_u64 v[146:147], v[194:195], 0, s[88:89]
	s_mov_b32 m0, s63
	s_nop 0
	global_load_lds_dwordx4 v[146:147], off
	v_lshl_add_u64 v[146:147], v[234:235], 0, s[88:89]
	s_mov_b32 m0, s64
	s_nop 0
	global_load_lds_dwordx4 v[146:147], off
	s_waitcnt vmcnt(8)
	s_waitcnt lgkmcnt(0)
	s_barrier
	s_setprio 1
	s_waitcnt lgkmcnt(0)
	v_mfma_f32_16x16x32_bf16 v[102:105], v[90:93], v[202:205], v[102:105]
	v_mfma_f32_16x16x32_bf16 v[98:101], v[138:141], v[202:205], v[98:101]
	v_mfma_f32_16x16x32_bf16 v[86:89], v[90:93], v[210:213], v[86:89]
	v_mfma_f32_16x16x32_bf16 v[82:85], v[138:141], v[210:213], v[82:85]
	v_mfma_f32_16x16x32_bf16 v[78:81], v[90:93], v[218:221], v[78:81]
	v_mfma_f32_16x16x32_bf16 v[74:77], v[138:141], v[218:221], v[74:77]
	v_mfma_f32_16x16x32_bf16 v[70:73], v[90:93], v[226:229], v[70:73]
	v_mfma_f32_16x16x32_bf16 v[66:69], v[138:141], v[226:229], v[66:69]
	v_mfma_f32_16x16x32_bf16 v[102:105], v[94:97], v[206:209], v[102:105]
	v_mfma_f32_16x16x32_bf16 v[98:101], v[142:145], v[206:209], v[98:101]
	v_mfma_f32_16x16x32_bf16 v[86:89], v[94:97], v[214:217], v[86:89]
	v_mfma_f32_16x16x32_bf16 v[82:85], v[142:145], v[214:217], v[82:85]
	v_mfma_f32_16x16x32_bf16 v[78:81], v[94:97], v[222:225], v[78:81]
	v_mfma_f32_16x16x32_bf16 v[74:77], v[142:145], v[222:225], v[74:77]
	v_mfma_f32_16x16x32_bf16 v[70:73], v[94:97], v[236:239], v[70:73]
	v_mfma_f32_16x16x32_bf16 v[66:69], v[142:145], v[236:239], v[66:69]
	v_mfma_f32_16x16x32_bf16 v[30:33], v[150:153], v[202:205], v[30:33]
	v_mfma_f32_16x16x32_bf16 v[26:29], v[182:185], v[202:205], v[26:29]
	v_mfma_f32_16x16x32_bf16 v[22:25], v[150:153], v[210:213], v[22:25]
	v_mfma_f32_16x16x32_bf16 v[18:21], v[182:185], v[210:213], v[18:21]
	v_mfma_f32_16x16x32_bf16 v[14:17], v[150:153], v[218:221], v[14:17]
	v_mfma_f32_16x16x32_bf16 v[10:13], v[182:185], v[218:221], v[10:13]
	v_mfma_f32_16x16x32_bf16 v[6:9], v[150:153], v[226:229], v[6:9]
	v_mfma_f32_16x16x32_bf16 v[2:5], v[182:185], v[226:229], v[2:5]
	v_mfma_f32_16x16x32_bf16 v[30:33], v[178:181], v[206:209], v[30:33]
	v_mfma_f32_16x16x32_bf16 v[26:29], v[198:201], v[206:209], v[26:29]
	v_mfma_f32_16x16x32_bf16 v[22:25], v[178:181], v[214:217], v[22:25]
	v_mfma_f32_16x16x32_bf16 v[18:21], v[198:201], v[214:217], v[18:21]
	v_mfma_f32_16x16x32_bf16 v[14:17], v[178:181], v[222:225], v[14:17]
	v_mfma_f32_16x16x32_bf16 v[10:13], v[198:201], v[222:225], v[10:13]
	v_mfma_f32_16x16x32_bf16 v[6:9], v[178:181], v[236:239], v[6:9]
	v_mfma_f32_16x16x32_bf16 v[2:5], v[198:201], v[236:239], v[2:5]
	s_setprio 0
	s_barrier
	s_add_i32 s68, s68, 2
	s_add_u32 s39, s39, 0x100
	s_addc_u32 s47, s47, 0
	s_add_u32 s48, s48, 0x100
	s_addc_u32 s49, s49, 0
	s_cmp_gt_u32 s68, 13
	s_cbranch_scc0 .LBB0_275
	s_and_b64 vcc, exec, s[6:7]
	s_cbranch_vccz .LBB0_278
	s_barrier

; #define LAS __attribute__((address_space(3)))
; template <bool PHASE_B>
; __device__ __forceinline__ void lru_item(const Params& p, LAS unsigned char* lds, int ci, int ci_next, int jb, const int tid, v4u (&xvn)[3]) {
;     const int lane = tid & 63, rt = tid >> 6, fr = lane & 15, fq = lane >> 4;
;     const int t0 = ci * LCH;
; #pragma unroll
;     for (int k = 0; k < 3; ++k) { const int c = k * NTHR + tid, rr = c >> 3, d8 = c & 7; if (c < 131 * 8) *(LAS v4u*)(lds + LR_XR + rr * 144 + d8 * 16) = xvn[k]; }
;     float cin[2][4]; v4u gv[2];
;     __syncthreads();
;     if (ci_next >= 0) lru_load(p, ci_next, jb, tid, xvn);
;     const LAS float* CW = (const LAS float*)(lds + LR_CW); const LAS float* CB = (const LAS float*)(lds + LR_CB); const LAS float* GC = (const LAS float*)(lds + LR_GC);
;     bf16x8 af[2];
; #pragma unroll
;     for (int ks = 0; ks < 2; ++ks) { const int cb0 = 32 * ks + 8 * fq;
;         f32x4 s0 = *(const LAS f32x4*)(CB + cb0), s1 = *(const LAS f32x4*)(CB + cb0 + 4);
; #pragma unroll
;         for (int tap = 0; tap < 4; ++tap) { const v4u v = *(const LAS v4u*)(lds + LR_XR + (16 * rt + fr + tap) * 144 + cb0 * 2);
;             const f32x4 w0 = *(const LAS f32x4*)(CW + tap * 64 + cb0), w1 = *(const LAS f32x4*)(CW + tap * 64 + cb0 + 4);
;             s0 += (f32x4){bflo(v.x), bfhi(v.x), bflo(v.y), bfhi(v.y)} * w0; s1 += (f32x4){bflo(v.z), bfhi(v.z), bflo(v.w), bfhi(v.w)} * w1; }
;         v4u o; o.x = pk2(s0[0], s0[1]); o.y = pk2(s0[2], s0[3]); o.z = pk2(s1[0], s1[1]); o.w = pk2(s1[2], s1[3]);
;         af[ks] = __builtin_bit_cast(bf16x8, o); }
;     float xc[4][4];
; #pragma unroll
;     for (int ct = 0; ct < 4; ++ct) { const int ch = 16 * ct + fr; float xr7[7];
; #pragma unroll
;         for (int j = 0; j < 7; ++j) xr7[j] = __builtin_bit_cast(float, (unsigned)(*(const LAS bf16*)(lds + LR_XR + (16 * rt + 4 * fq + j) * 144 + ch * 2)) << 16);
; __global__ void __launch_bounds__(NTHR, 2) fwd_kernel(Params p) {
;     ...
;             { const int jb = bx % 12, gi = bx / 12, gs = (G - jb + 11) / 12; lru_setup(p, L, lds, jb, tid);
;               v4u xvn[3] = {(v4u){0u, 0u, 0u, 0u}, (v4u){0u, 0u, 0u, 0u}, (v4u){0u, 0u, 0u, 0u}};
;               if (gi < NCH) lru_load(p, gi, jb, tid, xvn);
;               for (int ci = gi; ci < NCH; ci += gs) lru_item<true>(p, lds, ci, (ci + gs < NCH) ? ci + gs : -1, jb, tid, xvn); }
.LBB0_337:
	s_or_b64 exec, exec, s[0:1]
	s_sub_i32 s0, s94, s9
	v_and_b32_e32 v28, 64, v231
	s_add_i32 s0, s0, 11
	v_xor_b32_e32 v27, 16, v231
	v_add_u32_e32 v28, 64, v28
	s_mul_hi_i32 s0, s0, 0x2aaaaaab
	v_cmp_lt_i32_e32 vcc, v27, v28
	s_lshr_b32 s1, s0, 31
	s_ashr_i32 s9, s0, 1
	s_movk_i32 s0, 0x418
	v_and_b32_e32 v14, 15, v164
	v_ashrrev_i32_e32 v17, 6, v164
	v_cndmask_b32_e32 v27, v231, v27, vcc
	v_cmp_gt_i32_e64 s[44:45], s0, v164
	s_movk_i32 s0, 0x218
	v_bfe_u32 v16, v164, 4, 2
	v_lshlrev_b32_e32 v18, 4, v17
	v_lshlrev_b32_e32 v20, 1, v14
	v_lshlrev_b32_e32 v171, 2, v27
	v_xor_b32_e32 v27, 32, v231
	v_cmp_gt_i32_e64 s[46:47], s0, v164
	v_or_b32_e32 v19, v18, v14
	s_movk_i32 s0, 0x90
	v_lshl_or_b32 v18, v16, 2, v18
	v_add_u32_e32 v168, 0, v20
	v_cmp_lt_i32_e32 vcc, v27, v28
	v_mul_lo_u32 v157, v19, s0
	v_mul_lo_u32 v169, v18, s0
	v_add_u32_e32 v170, v168, v20
	v_cndmask_b32_e32 v27, v231, v27, vcc
	s_movk_i32 s0, 0x8c
	s_add_i32 s9, s9, s1
	v_lshlrev_b32_e32 v172, 2, v27
	v_and_b32_e32 v27, 0x1fffffc0, v164
	v_mad_u32_u24 v173, v14, s0, v170
	s_movk_i32 s0, 0xff74
	s_movk_i32 s1, 0x110
	v_lshrrev_b32_e32 v15, 4, v164
	v_lshl_add_u32 v165, v16, 5, 0
	v_lshlrev_b32_e32 v166, 4, v16
	v_lshlrev_b32_e32 v27, 3, v27
	v_cmp_gt_u32_e64 s[52:53], 2, v16
	v_mad_i32_i24 v174, v14, s0, v173
	v_lshlrev_b32_e32 v16, 3, v14
	v_readlane_b32 s0, v254, 11
	v_mul_lo_u32 v18, v18, s1
	v_or_b32_e32 v20, 16, v14
	v_bitop3_b32 v26, v15, 3, v15 bitop3:0xc
	v_and_b32_e32 v28, 16, v164
	v_add3_u32 v175, 0, v27, v16
	v_bitop3_b32 v15, v15, 1, 3 bitop3:8
	v_add_u32_e32 v27, s0, v18
	v_or_b32_e32 v22, 32, v14
	v_cmp_eq_u32_e64 s[50:51], 0, v28
	v_cmp_eq_u32_e64 s[54:55], 0, v15
	v_lshlrev_b32_e32 v15, 2, v20
	v_add_u32_e32 v28, 0x110, v27
	v_add_u32_e32 v29, 0x220, v27
	v_add_u32_e32 v31, 0x330, v27
	v_lshl_add_u32 v21, v20, 1, 0
	v_or_b32_e32 v24, 48, v14
	v_add_u32_e32 v20, s0, v15
	v_add_u32_e32 v177, v27, v15
	v_add_u32_e32 v178, v28, v15
	v_add_u32_e32 v179, v29, v15
	v_add_u32_e32 v180, v31, v15
	v_lshlrev_b32_e32 v15, 2, v22
	v_lshl_add_u32 v23, v22, 1, 0
	v_ashrrev_i32_e32 v16, 2, v164
	v_and_b32_e32 v1, 48, v1
	v_add_u32_e32 v22, s0, v15
	v_add_u32_e32 v181, v27, v15
	v_add_u32_e32 v182, v28, v15
	v_add_u32_e32 v183, v29, v15
	v_add_u32_e32 v184, v31, v15
	v_lshlrev_b32_e32 v15, 2, v24
	v_lshl_add_u32 v25, v24, 1, 0
	v_lshlrev_b32_e32 v14, 2, v14
	v_cmp_lt_i32_e64 s[58:59], 0, v17
	v_cmp_lt_i32_e64 s[60:61], 1, v17
	v_cmp_lt_i32_e64 s[62:63], 2, v17
	v_cmp_lt_i32_e64 s[64:65], 3, v17
	v_cmp_lt_i32_e64 s[66:67], 4, v17
	v_cmp_lt_i32_e64 s[68:69], 5, v17
	v_cmp_lt_i32_e64 s[70:71], 6, v17
	v_add_u32_e32 v24, s0, v15
	v_add_u32_e32 v185, v27, v15
	v_add_u32_e32 v186, v28, v15
	v_add_u32_e32 v187, v29, v15
	v_add_u32_e32 v188, v31, v15
	v_cmp_gt_i32_e64 s[72:73], 7, v17
	v_cmp_gt_i32_e64 s[74:75], 6, v17
	v_cmp_gt_i32_e64 s[76:77], 5, v17
	v_cmp_gt_i32_e64 s[78:79], 4, v17
	v_cmp_gt_i32_e64 s[80:81], 3, v17
	v_cmp_gt_i32_e64 s[82:83], 2, v17
	v_cmp_gt_i32_e64 s[84:85], 1, v17
	v_mul_lo_u32 v15, v16, s1
	v_lshlrev_b32_e32 v17, 2, v1
	v_cmp_gt_u32_e64 s[56:57], 2, v26
	v_add_u32_e32 v26, s0, v14
	v_add3_u32 v195, s0, v15, v17
	s_lshl_b64 s[0:1], s[4:5], 2
	v_readlane_b32 s12, v253, 3
	v_readlane_b32 s13, v253, 4
	s_add_u32 s0, s12, s0
	s_addc_u32 s1, s13, s1
	v_mov_b32_e32 v15, v0
	v_lshl_add_u64 v[32:33], s[0:1], 0, v[14:15]
	s_lshl_b64 s[0:1], s[4:5], 1
	v_readlane_b32 s12, v252, 59
	v_readlane_b32 s13, v252, 60
	s_add_u32 s0, s12, s0
	v_add3_u32 v19, 0, v166, 64
	v_add_u32_e32 v176, v174, v14
	s_addc_u32 s1, s13, s1
	v_lshlrev_b32_e32 v14, 1, v1
	v_cmp_gt_i32_e64 s[48:49], 24, v164
	v_sub_u32_e32 v167, v165, v166
	v_add_u32_e32 v190, 0xf500, v176
	v_add_u32_e32 v191, 0xf580, v176
	v_add_u32_e32 v192, 0xf600, v176
	v_add_u32_e32 v194, 0xf680, v176
	v_lshl_add_u64 v[34:35], s[0:1], 0, v[14:15]
	v_add_u32_e32 v196, s6, v16
	s_lshl_b32 s12, s9, 7
	s_lshl_b32 s13, s8, 1
	s_lshl_b32 s86, s9, 1
	v_add_u32_e32 v198, v19, v157
	v_add_u32_e32 v199, v21, v169
	v_add_u32_e32 v200, v23, v169
	v_add_u32_e32 v201, v25, v169
	v_add_u32_e32 v202, v26, v18
	v_add_u32_e32 v203, v20, v18
	v_add_u32_e32 v204, v22, v18
	v_add_u32_e32 v205, v24, v18
	s_waitcnt vmcnt(0)
	s_branch .LBB0_340

; #define LAS __attribute__((address_space(3)))
; template <bool PHASE_B>
; __device__ __forceinline__ void lru_item(const Params& p, LAS unsigned char* lds, int ci, int ci_next, int jb, const int tid, v4u (&xvn)[3]) {
;     ...
;     for (int k = 0; k < 3; ++k) { const int c = k * NTHR + tid, rr = c >> 3, d8 = c & 7; if (c < 131 * 8) *(LAS v4u*)(lds + LR_XR + rr * 144 + d8 * 16) = xvn[k]; }
.LBB0_340:
	s_and_saveexec_b64 s[0:1], s[44:45]
	s_cbranch_execz .LBB0_351
	s_waitcnt vmcnt(2)
	ds_write_b128 v143, v[6:9]
	s_or_b64 exec, exec, s[0:1]
	s_and_saveexec_b64 s[0:1], s[46:47]
	s_cbranch_execnz .LBB0_352

; #define LAS __attribute__((address_space(3)))
; __device__ __forceinline__ void lru_load(const Params& p, int ci, int jb, const int tid, v4u (&xv)[3]) {
;     const int t0 = ci * LCH;
;     int cs, S;
;     if (ci < 128) { cs = ci & 63; S = 8192; } else { cs = (ci - 128) & 15; S = 2048; }
;     const bf16* QKVX = (const bf16*)(p.ws + WS_QKVX);
; #pragma unroll
;     for (int k = 0; k < 3; ++k) { const int c = k * NTHR + tid, rr = c >> 3, d8 = c & 7, sq = cs * LCH + rr - 1; xv[k] = (v4u){0u, 0u, 0u, 0u};
;         if (c < 131 * 8 && sq >= 0 && sq < S) xv[k] = *(const v4u*)(QKVX + (size_t)(t0 + rr - 1) * 3072 + 2304 + jb * 64 + d8 * 8); }
; template <bool PHASE_B>
; __device__ __forceinline__ void lru_item(const Params& p, LAS unsigned char* lds, int ci, int ci_next, int jb, const int tid, v4u (&xvn)[3]) {
;     ...
;     for (int k = 0; k < 3; ++k) { const int c = k * NTHR + tid, rr = c >> 3, d8 = c & 7; if (c < 131 * 8) *(LAS v4u*)(lds + LR_XR + rr * 144 + d8 * 16) = xvn[k]; }
;     float cin[2][4]; v4u gv[2];
;     __syncthreads();
;     if (ci_next >= 0) lru_load(p, ci_next, jb, tid, xvn);
.LBB0_343:
	s_waitcnt vmcnt(2)
	ds_write_b128 v147, v[10:13]
.LBB0_344:
	s_or_b64 exec, exec, s[0:1]
	s_add_i32 s8, s8, s9
	s_cmpk_gt_i32 s8, 0xff
	s_cselect_b64 s[6:7], -1, 0
	s_cmpk_lt_i32 s8, 0x100
	s_cselect_b32 s0, s8, -1
	s_cmp_lt_i32 s0, 0
	s_waitcnt lgkmcnt(0)
	s_barrier
	s_cbranch_scc1 .LBB0_339
	s_lshl_b32 s15, s0, 7
	s_cmpk_lt_u32 s0, 0x80
	s_movk_i32 s1, 0x800
	s_cselect_b32 s37, 0x2000, s1
	s_cselect_b32 s1, 63, 15
	s_and_b32 s0, s1, s0
	s_lshl_b32 s97, s0, 7
	v_add_u32_e32 v1, s97, v142
	v_cmp_gt_i32_e32 vcc, 1, v1
	v_cmp_lt_i32_e64 s[0:1], s37, v1
	v_readlane_b32 s40, v254, 55
	s_or_b64 s[0:1], vcc, s[0:1]
	v_readlane_b32 s41, v254, 56
	s_add_i32 s15, s15, -1
	s_nor_b64 vcc, s[40:41], s[0:1]
	s_waitcnt vmcnt(2)
	v_mov_b32_e32 v2, 0
	v_mov_b32_e32 v6, 0
	v_mov_b32_e32 v7, 0
	v_mov_b32_e32 v8, 0
	v_mov_b32_e32 v9, 0
	s_and_saveexec_b64 s[0:1], vcc
	s_cbranch_execz .LBB0_347
	v_readlane_b32 s40, v252, 0
	v_readlane_b32 s41, v252, 1
	v_add_u32_e32 v1, s15, v142
	v_mov_b32_e32 v31, v0
	v_mov_b64_e32 v[4:5], s[40:41]
	v_mad_i64_i32 v[4:5], vcc, v1, s96, v[4:5]
	v_lshl_add_u64 v[4:5], s[4:5], 1, v[4:5]
	v_lshl_add_u64 v[4:5], v[4:5], 0, v[30:31]
	v_add_co_u32_e32 v4, vcc, 0x9201000, v4
	v_readlane_b32 s42, v252, 2
	s_nop 0
	v_addc_co_u32_e32 v5, vcc, 0, v5, vcc
	global_load_dwordx4 v[6:9], v[4:5], off offset:512
	v_readlane_b32 s43, v252, 3

; #define LAS __attribute__((address_space(3)))
; template <bool PHASE_B>
; __device__ __forceinline__ void lru_item(const Params& p, LAS unsigned char* lds, int ci, int ci_next, int jb, const int tid, v4u (&xvn)[3]) {
;     ...
;     for (int k = 0; k < 3; ++k) { const int c = k * NTHR + tid, rr = c >> 3, d8 = c & 7; if (c < 131 * 8) *(LAS v4u*)(lds + LR_XR + rr * 144 + d8 * 16) = xvn[k]; }
.LBB0_352:
	s_waitcnt vmcnt(2)
	ds_write_b128 v145, v[2:5]
	s_or_b64 exec, exec, s[0:1]
	s_and_saveexec_b64 s[0:1], s[48:49]
	s_cbranch_execnz .LBB0_343
	s_branch .LBB0_344

; #define LAS __attribute__((address_space(3)))
; template <bool PHASE_B>
; __device__ __forceinline__ void lru_item(const Params& p, LAS unsigned char* lds, int ci, int ci_next, int jb, const int tid, v4u (&xvn)[3]) {
;     const int lane = tid & 63, rt = tid >> 6, fr = lane & 15, fq = lane >> 4;
;     const int t0 = ci * LCH;
; #pragma unroll
;     for (int k = 0; k < 3; ++k) { const int c = k * NTHR + tid, rr = c >> 3, d8 = c & 7; if (c < 131 * 8) *(LAS v4u*)(lds + LR_XR + rr * 144 + d8 * 16) = xvn[k]; }
;     float cin[2][4]; v4u gv[2];
;     __syncthreads();
;     if (ci_next >= 0) lru_load(p, ci_next, jb, tid, xvn);
;     const LAS float* CW = (const LAS float*)(lds + LR_CW); const LAS float* CB = (const LAS float*)(lds + LR_CB); const LAS float* GC = (const LAS float*)(lds + LR_GC);
;     bf16x8 af[2];
; #pragma unroll
;     for (int ks = 0; ks < 2; ++ks) { const int cb0 = 32 * ks + 8 * fq;
;         f32x4 s0 = *(const LAS f32x4*)(CB + cb0), s1 = *(const LAS f32x4*)(CB + cb0 + 4);
; #pragma unroll
;         for (int tap = 0; tap < 4; ++tap) { const v4u v = *(const LAS v4u*)(lds + LR_XR + (16 * rt + fr + tap) * 144 + cb0 * 2);
;             const f32x4 w0 = *(const LAS f32x4*)(CW + tap * 64 + cb0), w1 = *(const LAS f32x4*)(CW + tap * 64 + cb0 + 4);
;             s0 += (f32x4){bflo(v.x), bfhi(v.x), bflo(v.y), bfhi(v.y)} * w0; s1 += (f32x4){bflo(v.z), bfhi(v.z), bflo(v.w), bfhi(v.w)} * w1; }
;         v4u o; o.x = pk2(s0[0], s0[1]); o.y = pk2(s0[2], s0[3]); o.z = pk2(s1[0], s1[1]); o.w = pk2(s1[2], s1[3]);
;         af[ks] = __builtin_bit_cast(bf16x8, o); }
;     float xc[4][4];
; #pragma unroll
;     for (int ct = 0; ct < 4; ++ct) { const int ch = 16 * ct + fr; float xr7[7];
; #pragma unroll
;         for (int j = 0; j < 7; ++j) xr7[j] = __builtin_bit_cast(float, (unsigned)(*(const LAS bf16*)(lds + LR_XR + (16 * rt + 4 * fq + j) * 144 + ch * 2)) << 16);
; __global__ void __launch_bounds__(NTHR, 2) fwd_kernel(Params p) {
;     ...
;             { const int jb = bx % 12, gi = bx / 12, gs = (G - jb + 11) / 12; lru_setup(p, L, lds, jb, tid);
;               v4u xvn[3] = {(v4u){0u, 0u, 0u, 0u}, (v4u){0u, 0u, 0u, 0u}, (v4u){0u, 0u, 0u, 0u}};
;               if (gi < NCH) lru_load(p, gi, jb, tid, xvn);
;               for (int ci = gi; ci < NCH; ci += gs) lru_item<false>(p, lds, ci, (ci + gs < NCH) ? ci + gs : -1, jb, tid, xvn); }
.LBB0_527:
	s_or_b64 exec, exec, s[8:9]
	v_and_b32_e32 v25, 64, v231
	s_sub_i32 s8, s94, s12
	v_xor_b32_e32 v24, 16, v231
	v_add_u32_e32 v25, 64, v25
	s_add_i32 s8, s8, 11
	v_cmp_lt_i32_e32 vcc, v24, v25
	s_mul_hi_i32 s8, s8, 0x2aaaaaab
	s_lshr_b32 s9, s8, 31
	v_cndmask_b32_e32 v24, v231, v24, vcc
	s_ashr_i32 s57, s8, 1
	s_movk_i32 s2, 0x418
	v_ashrrev_i32_e32 v1, 6, v164
	v_lshlrev_b32_e32 v83, 2, v24
	v_xor_b32_e32 v24, 32, v231
	s_add_i32 s57, s57, s9
	v_cmp_gt_i32_e64 s[8:9], s2, v164
	s_movk_i32 s2, 0x218
	v_lshrrev_b32_e32 v15, 4, v162
	v_lshlrev_b32_e32 v16, 4, v1
	v_lshlrev_b32_e32 v20, 1, v124
	v_cmp_lt_i32_e32 vcc, v24, v25
	v_cmp_gt_i32_e64 s[38:39], s2, v164
	v_or_b32_e32 v17, v16, v124
	s_movk_i32 s2, 0x90
	v_lshl_or_b32 v16, v15, 2, v16
	v_add_u32_e32 v80, 0, v20
	v_cndmask_b32_e32 v24, v231, v24, vcc
	v_mul_lo_u32 v17, v17, s2
	v_lshl_add_u32 v78, v15, 5, 0
	v_mul_lo_u32 v81, v16, s2
	v_add_u32_e32 v82, v80, v20
	v_xor_b32_e32 v23, 3, v15
	v_lshlrev_b32_e32 v84, 2, v24
	v_and_b32_e32 v24, 0x1fffffc0, v164
	v_and_b32_e32 v25, 16, v164
	s_movk_i32 s2, 0x8c
	v_bitop3_b32 v15, v15, 1, 3 bitop3:0x48
	s_movk_i32 s12, 0x80
	v_lshlrev_b32_e32 v14, 3, v162
	v_lshlrev_b32_e32 v24, 3, v24
	v_cmp_eq_u32_e64 s[42:43], 0, v25
	v_mad_u32_u24 v85, v124, s2, v82
	v_lshlrev_b32_e32 v25, 3, v124
	v_cmp_eq_u32_e64 s[46:47], 0, v15
	v_cmp_gt_i32_e64 s[50:51], s12, v164
	v_lshlrev_b32_e32 v15, 12, v1
	s_lshl_b64 s[12:13], s[52:53], 3
	v_readlane_b32 s2, v253, 5
	v_and_b32_e32 v79, 48, v164
	v_and_b32_e32 v19, 48, v162
	v_add3_u32 v86, 0, v24, v25
	v_cmp_gt_u32_e64 s[48:49], 2, v23
	v_add3_u32 v23, 0, v14, v15
	v_cmp_gt_u32_e32 vcc, 64, v164
	v_mov_b32_e32 v15, 0xe00
	v_mov_b32_e32 v24, 0x200
	v_mov_b32_e32 v25, 0xa00
	v_mov_b32_e32 v32, 0x400
	v_mov_b32_e32 v31, 0x800
	v_mov_b32_e32 v33, 0x600
	v_readlane_b32 s3, v253, 6
	s_add_u32 s12, s2, s12
	v_add_u32_e32 v18, 0, v79
	v_add3_u32 v19, 0, v19, 64
	v_add_u32_e32 v16, 32, v80
	v_add_u32_e32 v20, 64, v80
	v_add_u32_e32 v21, 0x60, v80
	v_mul_i32_i24_e32 v26, 0xffffff74, v124
	v_cndmask_b32_e64 v27, v15, 0, vcc
	v_cndmask_b32_e32 v28, v232, v24, vcc
	v_cndmask_b32_e32 v29, v25, v32, vcc
	v_cndmask_b32_e32 v30, v31, v33, vcc
	v_cndmask_b32_e32 v31, v33, v31, vcc
	v_cndmask_b32_e32 v32, v32, v25, vcc
	v_cndmask_b32_e32 v33, v24, v232, vcc
	v_cndmask_b32_e32 v34, 0, v15, vcc
	s_addc_u32 s13, s3, s13
	v_mov_b32_e32 v15, v0
	v_cmp_gt_i32_e64 s[40:41], 24, v164
	v_cmp_gt_u32_e64 s[44:45], 32, v162
	v_lshl_add_u64 v[24:25], s[12:13], 0, v[14:15]
	v_lshl_add_u32 v87, s56, 1, v1
	s_lshl_b32 s58, s57, 1
	v_add_u32_e32 v88, v18, v17
	v_add_u32_e32 v89, v19, v17
	v_add_u32_e32 v90, v16, v81
	v_add_u32_e32 v91, v20, v81
	v_add_u32_e32 v92, v21, v81
	v_add_u32_e32 v93, v85, v26
	v_add_u32_e32 v94, v23, v27
	v_add_u32_e32 v95, v23, v28
	v_add_u32_e32 v96, v23, v29
	v_add_u32_e32 v97, v23, v30
	v_add_u32_e32 v98, v23, v31
	v_add_u32_e32 v99, v23, v32
	v_add_u32_e32 v100, v23, v33
	v_add_u32_e32 v101, v23, v34
	s_waitcnt vmcnt(0)
	s_branch .LBB0_529

; #define LAS __attribute__((address_space(3)))
; template <bool PHASE_B>
; __device__ __forceinline__ void lru_item(const Params& p, LAS unsigned char* lds, int ci, int ci_next, int jb, const int tid, v4u (&xvn)[3]) {
;     ...
;     for (int k = 0; k < 3; ++k) { const int c = k * NTHR + tid, rr = c >> 3, d8 = c & 7; if (c < 131 * 8) *(LAS v4u*)(lds + LR_XR + rr * 144 + d8 * 16) = xvn[k]; }
.LBB0_529:
	s_and_saveexec_b64 s[12:13], s[8:9]
	s_cbranch_execz .LBB0_543
	s_waitcnt vmcnt(1)
	ds_write_b128 v73, v[6:9]
	s_or_b64 exec, exec, s[12:13]
	s_and_saveexec_b64 s[12:13], s[38:39]
	s_cbranch_execnz .LBB0_544

; #define LAS __attribute__((address_space(3)))
; __device__ __forceinline__ void lru_load(const Params& p, int ci, int jb, const int tid, v4u (&xv)[3]) {
;     const int t0 = ci * LCH;
;     int cs, S;
;     if (ci < 128) { cs = ci & 63; S = 8192; } else { cs = (ci - 128) & 15; S = 2048; }
;     const bf16* QKVX = (const bf16*)(p.ws + WS_QKVX);
; #pragma unroll
;     for (int k = 0; k < 3; ++k) { const int c = k * NTHR + tid, rr = c >> 3, d8 = c & 7, sq = cs * LCH + rr - 1; xv[k] = (v4u){0u, 0u, 0u, 0u};
;         if (c < 131 * 8 && sq >= 0 && sq < S) xv[k] = *(const v4u*)(QKVX + (size_t)(t0 + rr - 1) * 3072 + 2304 + jb * 64 + d8 * 8); }
; template <bool PHASE_B>
; __device__ __forceinline__ void lru_item(const Params& p, LAS unsigned char* lds, int ci, int ci_next, int jb, const int tid, v4u (&xvn)[3]) {
;     ...
;     for (int k = 0; k < 3; ++k) { const int c = k * NTHR + tid, rr = c >> 3, d8 = c & 7; if (c < 131 * 8) *(LAS v4u*)(lds + LR_XR + rr * 144 + d8 * 16) = xvn[k]; }
;     float cin[2][4]; v4u gv[2];
;     __syncthreads();
;     if (ci_next >= 0) lru_load(p, ci_next, jb, tid, xvn);
.LBB0_532:
	s_waitcnt vmcnt(1)
	ds_write_b128 v77, v[10:13]
.LBB0_533:
	s_or_b64 exec, exec, s[12:13]
	s_add_i32 s56, s56, s57
	s_cmpk_gt_i32 s56, 0xff
	s_cselect_b64 s[54:55], -1, 0
	s_cmpk_lt_i32 s56, 0x100
	s_cselect_b32 s12, s56, -1
	s_cmp_lt_i32 s12, 0
	s_waitcnt lgkmcnt(0)
	s_barrier
	s_cbranch_scc1 .LBB0_541
	s_lshl_b32 s15, s12, 7
	s_cmpk_lt_u32 s12, 0x80
	s_movk_i32 s2, 0x800
	s_cselect_b32 s13, 63, 15
	s_cselect_b32 s37, 0x2000, s2
	s_and_b32 s12, s13, s12
	s_lshl_b32 s59, s12, 7
	v_add_u32_e32 v1, s59, v72
	v_cmp_gt_i32_e32 vcc, 1, v1
	v_cmp_lt_i32_e64 s[12:13], s37, v1
	s_or_b64 s[12:13], vcc, s[12:13]
	s_add_i32 s15, s15, -1
	s_nor_b64 s[60:61], s[0:1], s[12:13]
	s_waitcnt vmcnt(1)
	v_mov_b32_e32 v2, 0
	v_mov_b32_e32 v6, 0
	v_mov_b32_e32 v7, 0
	v_mov_b32_e32 v8, 0
	v_mov_b32_e32 v9, 0
	s_and_saveexec_b64 s[12:13], s[60:61]
	s_cbranch_execz .LBB0_536
	v_readlane_b32 s60, v252, 0
	v_readlane_b32 s61, v252, 1
	v_add_u32_e32 v1, s15, v72
	v_mov_b32_e32 v23, v0
	v_mov_b64_e32 v[4:5], s[60:61]
	v_mad_i64_i32 v[4:5], s[60:61], v1, s64, v[4:5]
	v_lshl_add_u64 v[4:5], s[52:53], 1, v[4:5]
	v_lshl_add_u64 v[4:5], v[4:5], 0, v[22:23]
	v_add_co_u32_e32 v4, vcc, 0x9201000, v4
	v_readlane_b32 s62, v252, 2
	s_nop 0
	v_addc_co_u32_e32 v5, vcc, 0, v5, vcc
	global_load_dwordx4 v[6:9], v[4:5], off offset:512
	v_readlane_b32 s63, v252, 3

; #define LAS __attribute__((address_space(3)))
; __device__ __forceinline__ unsigned pk2(float lo, float hi) { return f2bf(lo) | (f2bf(hi) << 16); }
; template <bool PHASE_B>
; __device__ __forceinline__ void lru_item(const Params& p, LAS unsigned char* lds, int ci, int ci_next, int jb, const int tid, v4u (&xvn)[3]) {
;     ...
;     for (int ks = 0; ks < 2; ++ks) { const int cb0 = 32 * ks + 8 * fq;
;         f32x4 s0 = *(const LAS f32x4*)(CB + cb0), s1 = *(const LAS f32x4*)(CB + cb0 + 4);
; #pragma unroll
;         for (int tap = 0; tap < 4; ++tap) { const v4u v = *(const LAS v4u*)(lds + LR_XR + (16 * rt + fr + tap) * 144 + cb0 * 2);
;             const f32x4 w0 = *(const LAS f32x4*)(CW + tap * 64 + cb0), w1 = *(const LAS f32x4*)(CW + tap * 64 + cb0 + 4);
;             s0 += (f32x4){bflo(v.x), bfhi(v.x), bflo(v.y), bfhi(v.y)} * w0; s1 += (f32x4){bflo(v.z), bfhi(v.z), bflo(v.w), bfhi(v.w)} * w1; }
;         v4u o; o.x = pk2(s0[0], s0[1]); o.y = pk2(s0[2], s0[3]); o.z = pk2(s1[0], s1[1]); o.w = pk2(s1[2], s1[3]);
;         af[ks] = __builtin_bit_cast(bf16x8, o); }
.LBB0_541:
	ds_read_b128 v[14:17], v88
	ds_read_b128 v[18:21], v78 offset:56832
	ds_read_b128 v[26:29], v78 offset:56848
	ds_read_b128 v[30:33], v78 offset:55808
	ds_read_b128 v[34:37], v78 offset:55824
	ds_read_b128 v[38:41], v88 offset:144
	s_waitcnt lgkmcnt(5)
	v_lshlrev_b32_e32 v42, 16, v14
	v_and_b32_e32 v43, 0xffff0000, v14
	v_lshlrev_b32_e32 v14, 16, v15
	v_and_b32_e32 v15, 0xffff0000, v15
	s_waitcnt lgkmcnt(2)
	v_pk_fma_f32 v[32:33], v[32:33], v[14:15], v[20:21]
	v_lshlrev_b32_e32 v14, 16, v16
	v_and_b32_e32 v15, 0xffff0000, v16
	v_lshlrev_b32_e32 v16, 16, v17
	v_and_b32_e32 v17, 0xffff0000, v17
	v_pk_fma_f32 v[30:31], v[30:31], v[42:43], v[18:19]
	s_waitcnt lgkmcnt(1)
	v_pk_fma_f32 v[26:27], v[34:35], v[14:15], v[26:27]
	v_pk_fma_f32 v[28:29], v[36:37], v[16:17], v[28:29]
	ds_read_b128 v[14:17], v78 offset:56064
	ds_read_b128 v[18:21], v78 offset:56080
	s_waitcnt lgkmcnt(2)
	v_lshlrev_b32_e32 v34, 16, v38
	v_and_b32_e32 v35, 0xffff0000, v38
	v_lshlrev_b32_e32 v36, 16, v39
	v_and_b32_e32 v37, 0xffff0000, v39
	s_waitcnt lgkmcnt(1)
	v_pk_fma_f32 v[34:35], v[14:15], v[34:35], v[30:31]
	v_lshlrev_b32_e32 v14, 16, v41
	v_and_b32_e32 v15, 0xffff0000, v41
	v_pk_fma_f32 v[36:37], v[16:17], v[36:37], v[32:33]
	s_waitcnt lgkmcnt(0)
	v_pk_fma_f32 v[38:39], v[20:21], v[14:15], v[28:29]
	ds_read_b128 v[14:17], v88 offset:288
	v_lshlrev_b32_e32 v30, 16, v40
	v_and_b32_e32 v31, 0xffff0000, v40
	v_pk_fma_f32 v[40:41], v[18:19], v[30:31], v[26:27]
	ds_read_b128 v[18:21], v78 offset:56320
	ds_read_b128 v[26:29], v78 offset:56336
	ds_read_b128 v[30:33], v88 offset:432
	s_waitcnt lgkmcnt(3)
	v_lshlrev_b32_e32 v42, 16, v14
	v_and_b32_e32 v43, 0xffff0000, v14
	v_lshlrev_b32_e32 v14, 16, v15
	v_and_b32_e32 v15, 0xffff0000, v15
	s_waitcnt lgkmcnt(2)
	v_pk_fma_f32 v[36:37], v[20:21], v[14:15], v[36:37]
	v_lshlrev_b32_e32 v14, 16, v16
	v_and_b32_e32 v15, 0xffff0000, v16
	v_lshlrev_b32_e32 v16, 16, v17
	v_and_b32_e32 v17, 0xffff0000, v17
	v_pk_fma_f32 v[34:35], v[18:19], v[42:43], v[34:35]
	s_waitcnt lgkmcnt(1)
	v_pk_fma_f32 v[26:27], v[26:27], v[14:15], v[40:41]
	v_pk_fma_f32 v[28:29], v[28:29], v[16:17], v[38:39]
	ds_read_b128 v[14:17], v78 offset:56576
	ds_read_b128 v[18:21], v78 offset:56592
	s_waitcnt lgkmcnt(2)
	v_lshlrev_b32_e32 v38, 16, v30
	v_and_b32_e32 v39, 0xffff0000, v30
	v_lshlrev_b32_e32 v30, 16, v31
	s_waitcnt lgkmcnt(1)
	v_pk_fma_f32 v[14:15], v[14:15], v[38:39], v[34:35]
	v_and_b32_e32 v31, 0xffff0000, v31
	v_bfe_u32 v1, v14, 16, 1
	v_add3_u32 v1, v14, v1, s33
	v_bfe_u32 v14, v15, 16, 1
	v_pk_fma_f32 v[16:17], v[16:17], v[30:31], v[36:37]
	v_lshrrev_b32_e32 v1, 16, v1
	v_add3_u32 v14, v15, v14, s33
	v_and_or_b32 v14, v14, s11, v1
	v_bfe_u32 v1, v16, 16, 1
	v_lshlrev_b32_e32 v30, 16, v32
	v_and_b32_e32 v31, 0xffff0000, v32
	v_add3_u32 v1, v16, v1, s33
	v_bfe_u32 v15, v17, 16, 1
	s_waitcnt lgkmcnt(0)
	v_pk_fma_f32 v[18:19], v[18:19], v[30:31], v[26:27]
	v_lshrrev_b32_e32 v1, 16, v1
	v_add3_u32 v15, v17, v15, s33
	v_and_or_b32 v15, v15, s11, v1
	v_bfe_u32 v1, v18, 16, 1
	v_lshlrev_b32_e32 v32, 16, v33
	v_and_b32_e32 v33, 0xffff0000, v33
	v_add3_u32 v1, v18, v1, s33
	v_bfe_u32 v16, v19, 16, 1
	v_pk_fma_f32 v[20:21], v[20:21], v[32:33], v[28:29]
	v_lshrrev_b32_e32 v1, 16, v1
	v_add3_u32 v16, v19, v16, s33
	v_and_or_b32 v16, v16, s11, v1
	v_bfe_u32 v1, v20, 16, 1
	v_bfe_u32 v17, v21, 16, 1
	v_add3_u32 v1, v20, v1, s33
	v_add3_u32 v17, v21, v17, s33
	ds_read_b128 v[18:21], v89
	ds_read_b128 v[26:29], v78 offset:56960
	ds_read_b128 v[30:33], v78 offset:56976
	ds_read_b128 v[34:37], v78 offset:55936
	ds_read_b128 v[38:41], v78 offset:55952
	ds_read_b128 v[42:45], v89 offset:144
	s_waitcnt lgkmcnt(5)
	v_lshlrev_b32_e32 v46, 16, v18
	v_and_b32_e32 v47, 0xffff0000, v18
	v_lshlrev_b32_e32 v18, 16, v19
	v_and_b32_e32 v19, 0xffff0000, v19
	s_waitcnt lgkmcnt(2)
	v_pk_fma_f32 v[36:37], v[36:37], v[18:19], v[28:29]
	v_lshlrev_b32_e32 v18, 16, v20
	v_and_b32_e32 v19, 0xffff0000, v20
	v_lshlrev_b32_e32 v20, 16, v21
	v_and_b32_e32 v21, 0xffff0000, v21
	v_pk_fma_f32 v[34:35], v[34:35], v[46:47], v[26:27]
	s_waitcnt lgkmcnt(1)
	v_pk_fma_f32 v[30:31], v[38:39], v[18:19], v[30:31]
	v_pk_fma_f32 v[32:33], v[40:41], v[20:21], v[32:33]
	ds_read_b128 v[18:21], v78 offset:56192
	ds_read_b128 v[26:29], v78 offset:56208
	s_waitcnt lgkmcnt(2)
	v_lshlrev_b32_e32 v38, 16, v42
	v_and_b32_e32 v39, 0xffff0000, v42
	v_lshlrev_b32_e32 v40, 16, v43
	v_and_b32_e32 v41, 0xffff0000, v43
	s_waitcnt lgkmcnt(1)
	v_pk_fma_f32 v[38:39], v[18:19], v[38:39], v[34:35]
	v_lshlrev_b32_e32 v18, 16, v45
	v_and_b32_e32 v19, 0xffff0000, v45
	v_pk_fma_f32 v[40:41], v[20:21], v[40:41], v[36:37]
	s_waitcnt lgkmcnt(0)
	v_pk_fma_f32 v[42:43], v[28:29], v[18:19], v[32:33]
	ds_read_b128 v[18:21], v89 offset:288
	v_lshlrev_b32_e32 v34, 16, v44
	v_and_b32_e32 v35, 0xffff0000, v44
	v_pk_fma_f32 v[44:45], v[26:27], v[34:35], v[30:31]
	ds_read_b128 v[26:29], v78 offset:56448
	ds_read_b128 v[30:33], v78 offset:56464
	ds_read_b128 v[34:37], v89 offset:432
	s_waitcnt lgkmcnt(3)
	v_lshlrev_b32_e32 v46, 16, v18
	v_and_b32_e32 v47, 0xffff0000, v18
	v_lshlrev_b32_e32 v18, 16, v19
	v_and_b32_e32 v19, 0xffff0000, v19
	s_waitcnt lgkmcnt(2)
	v_pk_fma_f32 v[40:41], v[28:29], v[18:19], v[40:41]
	v_lshlrev_b32_e32 v18, 16, v20
	v_and_b32_e32 v19, 0xffff0000, v20
	v_lshlrev_b32_e32 v20, 16, v21
	v_and_b32_e32 v21, 0xffff0000, v21
	v_pk_fma_f32 v[38:39], v[26:27], v[46:47], v[38:39]
	s_waitcnt lgkmcnt(1)
	v_pk_fma_f32 v[30:31], v[30:31], v[18:19], v[44:45]
	v_pk_fma_f32 v[32:33], v[32:33], v[20:21], v[42:43]
	ds_read_b128 v[18:21], v78 offset:56704
	ds_read_b128 v[26:29], v78 offset:56720
	s_waitcnt lgkmcnt(2)
; #define LAS __attribute__((address_space(3)))
; #define MFMA16(a, b, c) __builtin_amdgcn_mfma_f32_16x16x32_bf16(a, b, c, 0, 0, 0)
; template <bool PHASE_B>
; __device__ __forceinline__ void lru_item(const Params& p, LAS unsigned char* lds, int ci, int ci_next, int jb, const int tid, v4u (&xvn)[3]) {
;     ...
;         v4u o; o.x = pk2(s0[0], s0[1]); o.y = pk2(s0[2], s0[3]); o.z = pk2(s1[0], s1[1]); o.w = pk2(s1[2], s1[3]);
;         af[ks] = __builtin_bit_cast(bf16x8, o); }
;     float xc[4][4];
; #pragma unroll
;     for (int ct = 0; ct < 4; ++ct) { const int ch = 16 * ct + fr; float xr7[7];
; #pragma unroll
;         for (int j = 0; j < 7; ++j) xr7[j] = __builtin_bit_cast(float, (unsigned)(*(const LAS bf16*)(lds + LR_XR + (16 * rt + 4 * fq + j) * 144 + ch * 2)) << 16);
;         const float w0 = CW[ch], w1 = CW[64 + ch], w2 = CW[128 + ch], w3 = CW[192 + ch], b = CB[ch];
; #pragma unroll
;         for (int e = 0; e < 4; ++e) xc[ct][e] = b + xr7[e] * w0 + xr7[e + 1] * w1 + xr7[e + 2] * w2 + xr7[e + 3] * w3; }
;     float av[2][4][4], uv[2][4][4], pA[2][4], pH[2][4];
; #pragma unroll
;     for (int dir = 0; dir < 2; ++dir) {
; #pragma unroll
;         for (int ct = 0; ct < 4; ++ct) {
;             f32x4 ga = (f32x4){0.f, 0.f, 0.f, 0.f}, gx = (f32x4){0.f, 0.f, 0.f, 0.f};
; #pragma unroll
;             for (int ks = 0; ks < 2; ++ks) {
;                 const bf16x8 wa = *(const LAS bf16x8*)(lds + LR_WG + ((dir * 2 + 0) * 64 + 16 * ct + fr) * 144 + (32 * ks + 8 * fq) * 2);
;                 const bf16x8 wx = *(const LAS bf16x8*)(lds + LR_WG + ((dir * 2 + 1) * 64 + 16 * ct + fr) * 144 + (32 * ks + 8 * fq) * 2);
;                 ga = MFMA16(af[ks], wa, ga); gx = MFMA16(af[ks], wx, gx); }
;             const int ch = 16 * ct + fr; const float bav = GC[(dir * 3 + 0) * 64 + ch], bxv = GC[(dir * 3 + 1) * 64 + ch], c8 = GC[(dir * 3 + 2) * 64 + ch];
;             float Al = 1.f, Hl = 0.f;
; #pragma unroll
;             for (int ee = 0; ee < 4; ++ee) { const int e = dir ? 3 - ee : ee;
;                 const float r = __builtin_amdgcn_rcpf(1.f + __expf(-(ga[e] + bav))), ig = __builtin_amdgcn_rcpf(1.f + __expf(-(gx[e] + bxv)));
;                 const float la = -c8 * r; const float a = __expf(la); const float u = __builtin_amdgcn_sqrtf((1.f - a) * (1.f + a)) * (ig * xc[ct][e]);
;                 av[dir][ct][e] = a; uv[dir][ct][e] = u; Hl = a * Hl + u; Al *= a; }
	v_lshlrev_b32_e32 v42, 16, v34
	v_and_b32_e32 v43, 0xffff0000, v34
	v_lshlrev_b32_e32 v34, 16, v35
	s_waitcnt lgkmcnt(1)
	v_pk_fma_f32 v[18:19], v[18:19], v[42:43], v[38:39]
	v_and_b32_e32 v35, 0xffff0000, v35
	v_bfe_u32 v23, v18, 16, 1
	v_add3_u32 v18, v18, v23, s33
	v_bfe_u32 v23, v19, 16, 1
	v_pk_fma_f32 v[20:21], v[20:21], v[34:35], v[40:41]
	v_lshrrev_b32_e32 v18, 16, v18
	v_add3_u32 v19, v19, v23, s33
	v_and_or_b32 v18, v19, s11, v18
	v_bfe_u32 v19, v20, 16, 1
	v_lshlrev_b32_e32 v34, 16, v36
	v_and_b32_e32 v35, 0xffff0000, v36
	v_lshlrev_b32_e32 v36, 16, v37
	v_and_b32_e32 v37, 0xffff0000, v37
	v_add3_u32 v19, v20, v19, s33
	v_bfe_u32 v20, v21, 16, 1
	s_waitcnt lgkmcnt(0)
	v_pk_fma_f32 v[28:29], v[28:29], v[36:37], v[32:33]
	v_pk_fma_f32 v[26:27], v[26:27], v[34:35], v[30:31]
	v_lshrrev_b32_e32 v19, 16, v19
	v_add3_u32 v20, v21, v20, s33
	v_and_or_b32 v19, v20, s11, v19
	v_bfe_u32 v20, v26, 16, 1
	v_bfe_u32 v23, v29, 16, 1
	v_add3_u32 v20, v26, v20, s33
	v_bfe_u32 v21, v27, 16, 1
	v_add3_u32 v32, v29, v23, s33
	v_add_u32_e32 v23, v80, v81
	v_add_u32_e32 v30, 0xd800, v82
	v_add_u32_e32 v58, 0xdc00, v82
	v_lshrrev_b32_e32 v20, 16, v20
	v_add3_u32 v21, v27, v21, s33
	ds_read_u16 v49, v23
	ds_read_u16 v51, v23 offset:144
	ds_read_u16 v60, v23 offset:288
	ds_read_u16 v26, v23 offset:864
	ds_read_u16 v70, v23 offset:432
	ds_read_u16 v109, v23 offset:576
	ds_read_u16 v116, v90
	ds_read_u16 v110, v23 offset:720
	ds_read2_b32 v[46:47], v30 offset0:128 offset1:144
	ds_read2_b32 v[40:41], v30 offset0:192 offset1:208
	ds_read2_b32 v[52:53], v58 offset1:16
	ds_read2_b32 v[44:45], v58 offset0:64 offset1:80
	ds_read2_b32 v[34:35], v58 offset0:128 offset1:144
	ds_read_u16 v117, v90 offset:144
	ds_read_u16 v118, v90 offset:288
	ds_read_u16 v119, v90 offset:432
	ds_read_u16 v23, v90 offset:864
	ds_read_u16 v120, v90 offset:576
	ds_read_u16 v123, v91
	ds_read_u16 v122, v91 offset:144
	ds_read_u16 v121, v90 offset:720
	v_and_or_b32 v20, v21, s11, v20
	v_bfe_u32 v21, v28, 16, 1
	s_waitcnt lgkmcnt(4)
	v_lshlrev_b32_e32 v50, 16, v23
	v_add_u32_e32 v23, v85, v79
	v_add3_u32 v21, v28, v21, s33
	v_lshlrev_b32_e32 v48, 16, v26
	ds_read_u16 v124, v91 offset:288
	ds_read_u16 v125, v91 offset:432
	ds_read_u16 v126, v91 offset:576
	ds_read_u16 v127, v91 offset:720
	ds_read_u16 v31, v91 offset:864
	ds_read_u16 v43, v92
	ds_read_u16 v61, v92 offset:144
	ds_read_u16 v103, v92 offset:288
	ds_read_b128 v[26:29], v23 offset:18944
	v_perm_b32 v17, v17, v1, s65
	ds_read2_b32 v[38:39], v30 offset0:160 offset1:176
	ds_read_b128 v[54:57], v23 offset:28160
	ds_read_b128 v[62:65], v23 offset:19008
	v_perm_b32 v21, v32, v21, s65
	s_waitcnt lgkmcnt(3)
	v_mfma_f32_16x16x32_bf16 v[66:69], v[14:17], v[26:29], 0
	v_lshlrev_b32_e32 v42, 16, v31
	ds_read2_b32 v[30:31], v30 offset0:224 offset1:240
	ds_read_b128 v[104:107], v23 offset:28224
	ds_read2_b32 v[36:37], v58 offset0:32 offset1:48
	ds_read2_b32 v[32:33], v58 offset0:96 offset1:112
	ds_read2_b32 v[26:27], v58 offset0:160 offset1:176
	s_waitcnt lgkmcnt(6)
	v_mfma_f32_16x16x32_bf16 v[54:57], v[14:17], v[54:57], 0
	v_lshlrev_b32_e32 v71, 16, v49
	v_lshlrev_b32_e32 v122, 16, v122
	v_lshlrev_b32_e32 v123, 16, v123
	s_waitcnt lgkmcnt(5)
	v_mfma_f32_16x16x32_bf16 v[62:65], v[18:21], v[62:65], v[66:69]
	s_nop 2
	ds_read_b32 v66, v93 offset:57088
	ds_read_u16 v128, v92 offset:432
	ds_read_u16 v102, v92 offset:576
	ds_read_u16 v29, v92 offset:720
	ds_read_u16 v1, v92 offset:864
	v_mov_b32_e32 v67, v46
	s_waitcnt lgkmcnt(4)
	v_add_f32_e32 v28, v62, v66
	v_mfma_f32_16x16x32_bf16 v[56:59], v[18:21], v[104:107], v[54:57]
	s_nop 2
	ds_read_b32 v54, v93 offset:57344
	ds_read_b32 v55, v93 offset:57600
	v_mul_f32_e32 v28, 0xbfb8aa3b, v28
	v_exp_f32_e32 v28, v28
	s_waitcnt lgkmcnt(1)
	v_add_f32_e32 v56, v56, v54
	v_mul_f32_e32 v56, 0xbfb8aa3b, v56
	v_exp_f32_e32 v56, v56
	v_add_f32_e32 v28, 1.0, v28
	v_rcp_f32_e32 v62, v28
	v_lshlrev_b32_e32 v28, 16, v1
	v_add_f32_e32 v1, 1.0, v56
	v_rcp_f32_e32 v129, v1
	s_waitcnt lgkmcnt(0)
	v_mul_f32_e32 v1, v62, v55
	v_mul_f32_e32 v1, 0xbfb8aa3b, v1
	v_exp_f32_e32 v56, v1
	v_add_f32_e32 v1, v63, v66
	v_mul_f32_e32 v1, 0xbfb8aa3b, v1
	v_exp_f32_e32 v1, v1
	v_add_f32_e32 v57, v57, v54
	v_sub_f32_e32 v62, 1.0, v56
	v_add_f32_e32 v63, 1.0, v56
	v_add_f32_e32 v1, 1.0, v1
	v_rcp_f32_e32 v1, v1
	v_mul_f32_e32 v57, 0xbfb8aa3b, v57
	v_mul_f32_e32 v62, v62, v63
	v_exp_f32_e32 v57, v57
	v_mul_f32_e32 v1, v1, v55
	v_mul_f32_e32 v1, 0xbfb8aa3b, v1
	v_exp_f32_e32 v130, v1
	v_sqrt_f32_e32 v1, v62
	v_add_f32_e32 v62, v64, v66
	v_mul_f32_e32 v62, 0xbfb8aa3b, v62
	v_exp_f32_e32 v62, v62
	v_add_f32_e32 v57, 1.0, v57
	v_rcp_f32_e32 v131, v57
	v_sub_f32_e32 v57, 1.0, v130
	v_add_f32_e32 v63, 1.0, v130
	v_mul_f32_e32 v57, v57, v63
	v_sqrt_f32_e32 v63, v57
	v_add_f32_e32 v57, 1.0, v62
	v_rcp_f32_e32 v57, v57
	v_add_f32_e32 v58, v58, v54
	v_mul_f32_e32 v58, 0xbfb8aa3b, v58
	v_exp_f32_e32 v58, v58
	v_mul_f32_e32 v57, v57, v55
	v_mul_f32_e32 v57, 0xbfb8aa3b, v57
	v_exp_f32_e32 v105, v57
	v_add_f32_e32 v62, v65, v66
	v_mul_f32_e32 v62, 0xbfb8aa3b, v62
	v_exp_f32_e32 v62, v62
	v_add_f32_e32 v58, 1.0, v58
	v_rcp_f32_e32 v132, v58
	v_sub_f32_e32 v58, 1.0, v105
	v_add_f32_e32 v64, 1.0, v105
	v_mul_f32_e32 v58, v58, v64
	v_sqrt_f32_e32 v65, v58
	v_add_f32_e32 v58, 1.0, v62
	v_rcp_f32_e32 v58, v58
	v_add_f32_e32 v54, v59, v54
	v_mul_f32_e32 v54, 0xbfb8aa3b, v54
	v_exp_f32_e32 v54, v54
	v_mul_f32_e32 v55, v58, v55
	v_mul_f32_e32 v55, 0xbfb8aa3b, v55
	v_exp_f32_e32 v59, v55
	v_add_f32_e32 v54, 1.0, v54
	v_rcp_f32_e32 v58, v54
	v_mov_b32_e32 v66, v40
	v_sub_f32_e32 v54, 1.0, v59
	v_add_f32_e32 v55, 1.0, v59
	v_mul_f32_e32 v54, v54, v55
; template <bool PHASE_B>
; __device__ __forceinline__ void lru_item(const Params& p, LAS unsigned char* lds, int ci, int ci_next, int jb, const int tid, v4u (&xvn)[3]) {
;     ...
;         for (int e = 0; e < 4; ++e) xc[ct][e] = b + xr7[e] * w0 + xr7[e + 1] * w1 + xr7[e + 2] * w2 + xr7[e + 3] * w3; }
;     float av[2][4][4], uv[2][4][4], pA[2][4], pH[2][4];
; #pragma unroll
;     for (int dir = 0; dir < 2; ++dir) {
; #pragma unroll
;         for (int ct = 0; ct < 4; ++ct) {
;             f32x4 ga = (f32x4){0.f, 0.f, 0.f, 0.f}, gx = (f32x4){0.f, 0.f, 0.f, 0.f};
; #pragma unroll
;             for (int ks = 0; ks < 2; ++ks) {
;                 const bf16x8 wa = *(const LAS bf16x8*)(lds + LR_WG + ((dir * 2 + 0) * 64 + 16 * ct + fr) * 144 + (32 * ks + 8 * fq) * 2);
;                 const bf16x8 wx = *(const LAS bf16x8*)(lds + LR_WG + ((dir * 2 + 1) * 64 + 16 * ct + fr) * 144 + (32 * ks + 8 * fq) * 2);
;                 ga = MFMA16(af[ks], wa, ga); gx = MFMA16(af[ks], wx, gx); }
;             const int ch = 16 * ct + fr; const float bav = GC[(dir * 3 + 0) * 64 + ch], bxv = GC[(dir * 3 + 1) * 64 + ch], c8 = GC[(dir * 3 + 2) * 64 + ch];
;             float Al = 1.f, Hl = 0.f;
; #pragma unroll
;             for (int ee = 0; ee < 4; ++ee) { const int e = dir ? 3 - ee : ee;
;                 const float r = __builtin_amdgcn_rcpf(1.f + __expf(-(ga[e] + bav))), ig = __builtin_amdgcn_rcpf(1.f + __expf(-(gx[e] + bxv)));
;                 const float la = -c8 * r; const float a = __expf(la); const float u = __builtin_amdgcn_sqrtf((1.f - a) * (1.f + a)) * (ig * xc[ct][e]);
;                 av[dir][ct][e] = a; uv[dir][ct][e] = u; Hl = a * Hl + u; Al *= a; }
;             const int o = dir ? 3 - fq : fq; const bool odd = (o & 1) != 0, hi2 = (o & 2) != 0;
;             const float A1 = __shfl_xor(Al, 16), H1 = __shfl_xor(Hl, 16);
;             const float pxA = odd ? A1 : 1.f, pxH = odd ? H1 : 0.f;
;             const float gA = Al * A1, gH = odd ? (Al * H1 + Hl) : (A1 * Hl + H1);
;             const float A2 = __shfl_xor(gA, 32), H2 = __shfl_xor(gH, 32);
;             const float PA = hi2 ? pxA * A2 : pxA, PH = hi2 ? (pxA * H2 + pxH) : pxH;
;             const float TA = gA * A2, TH = hi2 ? (gA * H2 + gH) : (A2 * gH + H2);
;             pA[dir][ct] = PA; pH[dir][ct] = PH;
;             ((LAS f32x2*)(lds + LR_SEG))[(dir * 8 + rt) * 64 + ch] = (f32x2){TA, TH};
	v_sqrt_f32_e32 v133, v54
	v_lshlrev_b32_e32 v55, 16, v60
	v_lshlrev_b32_e32 v54, 16, v70
	v_lshlrev_b32_e32 v70, 16, v51
	v_pk_mul_f32 v[106:107], v[66:67], v[70:71]
	v_pk_mov_b32 v[70:71], v[54:55], v[70:71] op_sel:[1,0]
	v_pk_mul_f32 v[68:69], v[66:67], v[54:55]
	v_pk_mul_f32 v[66:67], v[66:67], v[70:71]
	v_add_f32_e32 v49, v107, v34
	v_add_f32_e32 v51, v67, v34
	v_mov_b32_e32 v62, v40
	v_add_f32_e32 v40, v69, v34
	v_fma_f32 v108, v46, v54, v34
	v_add_f32_e32 v34, v106, v49
	v_add_f32_e32 v46, v66, v51
	v_lshlrev_b32_e32 v107, 16, v109
	v_lshlrev_b32_e32 v106, 16, v110
	v_mov_b32_e32 v66, v44
	v_mov_b32_e32 v67, v52
	v_pk_mul_f32 v[110:111], v[66:67], v[54:55]
	v_pk_mov_b32 v[54:55], v[106:107], v[54:55] op_sel:[1,0]
	v_add_f32_e32 v40, v68, v40
	v_pk_mul_f32 v[112:113], v[66:67], v[54:55]
	v_pk_mul_f32 v[114:115], v[66:67], v[106:107]
	v_add_f32_e32 v49, v113, v46
	v_lshlrev_b32_e32 v67, 16, v118
	v_lshlrev_b32_e32 v66, 16, v119
	v_mov_b32_e32 v46, v41
	v_lshlrev_b32_e32 v68, 16, v117
	v_lshlrev_b32_e32 v69, 16, v116
	v_pk_mul_f32 v[70:71], v[46:47], v[68:69]
	v_pk_mov_b32 v[68:69], v[66:67], v[68:69] op_sel:[1,0]
	v_mul_f32_e32 v57, v56, v130
	v_pk_mul_f32 v[68:69], v[46:47], v[68:69]
	v_mul_f32_e32 v57, v105, v57
	v_mul_f32_e32 v104, v52, v106
	v_pk_mul_f32 v[54:55], v[46:47], v[66:67]
	v_add_f32_e32 v52, v71, v35
	v_add_f32_e32 v46, v69, v35
	v_mov_b32_e32 v64, v44
	v_mul_f32_e32 v44, v59, v57
	v_add_f32_e32 v113, v115, v40
	v_add_f32_e32 v40, v55, v35
	v_fmac_f32_e32 v35, v47, v66
	v_add_f32_e32 v55, v70, v52
	v_add_f32_e32 v57, v68, v46
	v_lshlrev_b32_e32 v47, 16, v120
	v_lshlrev_b32_e32 v46, 16, v121
	v_mov_b32_e32 v52, v45
	v_add_f32_e32 v34, v111, v34
	v_pk_mul_f32 v[70:71], v[52:53], v[66:67]
	v_pk_mov_b32 v[66:67], v[46:47], v[66:67] op_sel:[1,0]
	v_add_f32_e32 v34, v110, v34
	v_pk_mul_f32 v[68:69], v[52:53], v[66:67]
	v_add_f32_e32 v40, v54, v40
	v_add_f32_e32 v69, v69, v57
	v_mul_f32_e32 v57, v34, v129
	v_mul_f32_e32 v54, v53, v46
	v_pk_mul_f32 v[66:67], v[52:53], v[46:47]
	v_pk_mul_f32 v[52:53], v[56:57], v[0:1]
	v_add_f32_e32 v67, v67, v40
	v_add_f32_e32 v1, v52, v53
	v_add_f32_e32 v40, v112, v49
	v_mul_f32_e32 v109, v130, v1
	v_mul_f32_e32 v53, v40, v131
	v_mov_b32_e32 v52, v107
	v_pk_fma_f32 v[52:53], v[62:63], v[52:53], v[108:109]
	v_add_f32_e32 v46, v114, v113
	v_pk_add_f32 v[56:57], v[104:105], v[52:53]
	v_pk_mul_f32 v[52:53], v[104:105], v[52:53]
	v_mul_f32_e32 v49, v46, v132
	v_mov_b32_e32 v57, v53
	v_pk_fma_f32 v[52:53], v[64:65], v[48:49], v[56:57]
	ds_bpermute_b32 v51, v83, v44
	v_pk_mul_f32 v[48:49], v[52:53], v[58:59]
	v_lshlrev_b32_e32 v121, 16, v124
	v_fmac_f32_e32 v49, v48, v133
	ds_bpermute_b32 v1, v83, v49
	s_waitcnt lgkmcnt(1)
	v_mul_f32_e32 v60, v44, v51
	ds_bpermute_b32 v111, v84, v60
	v_lshlrev_b32_e32 v120, 16, v125
	v_mov_b32_e32 v116, v30
	s_waitcnt lgkmcnt(1)
	v_fma_f32 v44, v44, v1, v49
	v_fmac_f32_e32 v1, v49, v51
	v_cndmask_b32_e64 v1, v44, v1, s[42:43]
	ds_bpermute_b32 v44, v84, v1
	v_mov_b32_e32 v117, v38
	v_pk_mul_f32 v[58:59], v[116:117], v[122:123]
	v_pk_mov_b32 v[56:57], v[120:121], v[122:123] op_sel:[1,0]
	v_pk_mul_f32 v[118:119], v[116:117], v[120:121]
	v_add_f32_e32 v48, v59, v26
	v_pk_mul_f32 v[62:63], v[116:117], v[56:57]
	v_add_f32_e32 v71, v71, v55
	v_add_f32_e32 v55, v119, v26
	v_add_f32_e32 v49, v63, v26
	v_fma_f32 v56, v38, v120, v26
	v_add_f32_e32 v26, v58, v48
	s_waitcnt lgkmcnt(0)
	v_fma_f32 v48, v60, v44, v1
	v_fmac_f32_e32 v44, v1, v111
	v_mul_f32_e32 v106, v60, v111
	v_cndmask_b32_e64 v107, v48, v44, s[44:45]
	ds_write_b64 v86, v[106:107] offset:58624
	v_add_f32_e32 v38, v62, v49
	ds_read_b128 v[62:65], v23 offset:21248
	ds_read_b128 v[104:107], v23 offset:30464
	ds_read_b128 v[108:111], v23 offset:21312
	s_waitcnt lgkmcnt(2)
	v_mfma_f32_16x16x32_bf16 v[112:115], v[14:17], v[62:65], 0
	v_mov_b32_e32 v122, v32
	v_mov_b32_e32 v123, v36
	v_lshlrev_b32_e32 v58, 16, v127
	v_pk_mul_f32 v[62:63], v[122:123], v[120:121]
	v_add_f32_e32 v53, v118, v55
	ds_read_b128 v[116:119], v23 offset:30528
	v_mul_f32_e32 v60, v36, v58
	v_add_f32_e32 v36, v63, v26
	ds_read_b32 v26, v93 offset:57152
	s_waitcnt lgkmcnt(2)
	v_mfma_f32_16x16x32_bf16 v[108:111], v[18:21], v[108:111], v[112:115]
	ds_read_b32 v51, v93 offset:57408
	ds_read_b32 v57, v93 offset:57664
	v_lshlrev_b32_e32 v59, 16, v126
	v_pk_mov_b32 v[48:49], v[58:59], v[120:121] op_sel:[1,0]
	v_mfma_f32_16x16x32_bf16 v[104:107], v[14:17], v[104:107], 0
	s_waitcnt lgkmcnt(2)
	s_nop 1
	v_add_f32_e32 v1, v108, v26
	v_mul_f32_e32 v1, 0xbfb8aa3b, v1
	v_exp_f32_e32 v1, v1
	v_mfma_f32_16x16x32_bf16 v[104:107], v[18:21], v[116:119], v[104:107]
	v_mul_f32_e64 v64, v122, v48
	v_mul_f32_e64 v65, v123, v49
	v_lshlrev_b32_e32 v117, 16, v103
	v_add_f32_e32 v1, 1.0, v1
	v_rcp_f32_e32 v1, v1
	v_lshlrev_b32_e32 v116, 16, v128
	s_waitcnt lgkmcnt(1)
	s_nop 0
	v_add_f32_e32 v44, v104, v51
	v_mul_f32_e32 v44, 0xbfb8aa3b, v44
	v_exp_f32_e32 v44, v44
	s_waitcnt lgkmcnt(0)
; #define LAS __attribute__((address_space(3)))
; #define MFMA16(a, b, c) __builtin_amdgcn_mfma_f32_16x16x32_bf16(a, b, c, 0, 0, 0)
; template <bool PHASE_B>
; __device__ __forceinline__ void lru_item(const Params& p, LAS unsigned char* lds, int ci, int ci_next, int jb, const int tid, v4u (&xvn)[3]) {
;     ...
;                 const bf16x8 wa = *(const LAS bf16x8*)(lds + LR_WG + ((dir * 2 + 0) * 64 + 16 * ct + fr) * 144 + (32 * ks + 8 * fq) * 2);
;                 const bf16x8 wx = *(const LAS bf16x8*)(lds + LR_WG + ((dir * 2 + 1) * 64 + 16 * ct + fr) * 144 + (32 * ks + 8 * fq) * 2);
;                 ga = MFMA16(af[ks], wa, ga); gx = MFMA16(af[ks], wx, gx); }
;             const int ch = 16 * ct + fr; const float bav = GC[(dir * 3 + 0) * 64 + ch], bxv = GC[(dir * 3 + 1) * 64 + ch], c8 = GC[(dir * 3 + 2) * 64 + ch];
;             float Al = 1.f, Hl = 0.f;
; #pragma unroll
;             for (int ee = 0; ee < 4; ++ee) { const int e = dir ? 3 - ee : ee;
;                 const float r = __builtin_amdgcn_rcpf(1.f + __expf(-(ga[e] + bav))), ig = __builtin_amdgcn_rcpf(1.f + __expf(-(gx[e] + bxv)));
;                 const float la = -c8 * r; const float a = __expf(la); const float u = __builtin_amdgcn_sqrtf((1.f - a) * (1.f + a)) * (ig * xc[ct][e]);
;                 av[dir][ct][e] = a; uv[dir][ct][e] = u; Hl = a * Hl + u; Al *= a; }
;             const int o = dir ? 3 - fq : fq; const bool odd = (o & 1) != 0, hi2 = (o & 2) != 0;
;             const float A1 = __shfl_xor(Al, 16), H1 = __shfl_xor(Hl, 16);
;             const float pxA = odd ? A1 : 1.f, pxH = odd ? H1 : 0.f;
;             const float gA = Al * A1, gH = odd ? (Al * H1 + Hl) : (A1 * Hl + H1);
;             const float A2 = __shfl_xor(gA, 32), H2 = __shfl_xor(gH, 32);
;             const float PA = hi2 ? pxA * A2 : pxA, PH = hi2 ? (pxA * H2 + pxH) : pxH;
;             const float TA = gA * A2, TH = hi2 ? (gA * H2 + gH) : (A2 * gH + H2);
;             pA[dir][ct] = PA; pH[dir][ct] = PH;
;             ((LAS f32x2*)(lds + LR_SEG))[(dir * 8 + rt) * 64 + ch] = (f32x2){TA, TH};
	v_mul_f32_e32 v1, v1, v57
	v_mul_f32_e32 v1, 0xbfb8aa3b, v1
	v_add_f32_e32 v44, 1.0, v44
	v_rcp_f32_e32 v63, v44
	v_exp_f32_e32 v44, v1
	v_add_f32_e32 v1, v109, v26
	v_mul_f32_e32 v1, 0xbfb8aa3b, v1
	v_exp_f32_e32 v1, v1
	v_sub_f32_e32 v48, 1.0, v44
	v_add_f32_e32 v49, 1.0, v44
	v_mul_f32_e32 v48, v48, v49
	v_add_f32_e32 v1, 1.0, v1
	v_rcp_f32_e32 v1, v1
	v_add_f32_e32 v49, v105, v51
	v_mul_f32_e32 v49, 0xbfb8aa3b, v49
	v_exp_f32_e32 v49, v49
	v_mul_f32_e32 v1, v1, v57
	v_mul_f32_e32 v1, 0xbfb8aa3b, v1
	v_exp_f32_e32 v108, v1
	v_sqrt_f32_e32 v1, v48
	v_add_f32_e32 v48, 1.0, v49
	v_add_f32_e32 v49, v110, v26
	v_mul_f32_e32 v49, 0xbfb8aa3b, v49
	v_add_f32_e32 v26, v111, v26
	v_exp_f32_e32 v55, v49
	v_mul_f32_e32 v26, 0xbfb8aa3b, v26
	v_exp_f32_e32 v26, v26
	v_rcp_f32_e32 v109, v48
	v_sub_f32_e32 v48, 1.0, v108
	v_add_f32_e32 v49, 1.0, v108
	v_mul_f32_e32 v48, v48, v49
	v_sqrt_f32_e32 v49, v48
	v_add_f32_e32 v48, 1.0, v55
	v_rcp_f32_e32 v48, v48
	v_add_f32_e32 v26, 1.0, v26
	v_rcp_f32_e32 v26, v26
	v_add_f32_e32 v55, v106, v51
	v_mul_f32_e32 v48, v48, v57
	v_add_f32_e32 v51, v107, v51
	v_mul_f32_e32 v55, 0xbfb8aa3b, v55
	v_mul_f32_e32 v48, 0xbfb8aa3b, v48
	v_mul_f32_e32 v51, 0xbfb8aa3b, v51
	v_mul_f32_e32 v26, v26, v57
	v_exp_f32_e32 v104, v55
	v_exp_f32_e32 v55, v48
	v_exp_f32_e32 v51, v51
	v_mul_f32_e32 v26, 0xbfb8aa3b, v26
	v_exp_f32_e32 v107, v26
	v_mul_f32_e32 v48, v44, v108
	v_mul_f32_e32 v26, v55, v48
	v_add_f32_e32 v48, 1.0, v51
	v_add_f32_e32 v104, 1.0, v104
	v_rcp_f32_e32 v106, v48
	v_sub_f32_e32 v48, 1.0, v107
	v_add_f32_e32 v51, 1.0, v107
	v_rcp_f32_e32 v110, v104
	v_sub_f32_e32 v104, 1.0, v55
	v_add_f32_e32 v105, 1.0, v55
	v_mul_f32_e32 v48, v48, v51
	v_mul_f32_e32 v104, v104, v105
	v_sqrt_f32_e32 v57, v48
	v_mov_b32_e32 v48, v41
	v_mul_f32_e32 v41, v107, v26
	v_add_f32_e32 v26, v70, v71
	v_sqrt_f32_e32 v105, v104
	v_mov_b32_e32 v104, v45
	v_mul_f32_e32 v45, v26, v63
	v_pk_mul_f32 v[44:45], v[44:45], v[0:1]
	v_mov_b32_e32 v70, v35
	v_add_f32_e32 v1, v44, v45
	v_add_f32_e32 v44, v68, v69
	v_mul_f32_e32 v71, v108, v1
	v_mul_f32_e32 v69, v44, v109
	v_mov_b32_e32 v68, v47
	v_pk_fma_f32 v[48:49], v[48:49], v[68:69], v[70:71]
	ds_bpermute_b32 v111, v83, v41
	v_pk_add_f32 v[68:69], v[54:55], v[48:49]
	v_pk_mul_f32 v[48:49], v[54:55], v[48:49]
	v_add_f32_e32 v35, v65, v38
	v_add_f32_e32 v48, v66, v67
	v_mov_b32_e32 v69, v49
	v_mul_f32_e32 v51, v48, v110
	v_pk_fma_f32 v[54:55], v[104:105], v[50:51], v[68:69]
	s_waitcnt lgkmcnt(0)
	v_mul_f32_e32 v38, v41, v111
	v_pk_mul_f32 v[50:51], v[54:55], v[106:107]
	ds_bpermute_b32 v45, v84, v38
	v_fmac_f32_e32 v51, v50, v57
	ds_bpermute_b32 v1, v83, v51
	v_pk_mul_f32 v[70:71], v[122:123], v[58:59]
	s_waitcnt lgkmcnt(1)
	v_mul_f32_e32 v50, v38, v45
	v_add_f32_e32 v47, v71, v53
	s_waitcnt lgkmcnt(0)
	v_fma_f32 v41, v41, v1, v51
	v_fmac_f32_e32 v1, v51, v111
	v_cndmask_b32_e64 v1, v41, v1, s[42:43]
	ds_bpermute_b32 v41, v84, v1
	s_waitcnt lgkmcnt(0)
	v_fma_f32 v38, v38, v41, v1
	v_fmac_f32_e32 v41, v1, v45
	v_cndmask_b32_e64 v51, v38, v41, s[44:45]
	ds_write_b64 v86, v[50:51] offset:58752
	ds_read_b128 v[66:69], v23 offset:23552
	ds_read_b128 v[104:107], v23 offset:32768
	ds_read_b128 v[108:111], v23 offset:23616
	s_waitcnt lgkmcnt(2)
	v_mfma_f32_16x16x32_bf16 v[66:69], v[14:17], v[66:69], 0
	ds_read_b128 v[112:115], v23 offset:32832
	v_lshlrev_b32_e32 v51, 16, v43
	ds_read_b32 v43, v93 offset:57216
	s_waitcnt lgkmcnt(2)
	v_mfma_f32_16x16x32_bf16 v[66:69], v[18:21], v[108:111], v[66:69]
	v_mov_b32_e32 v38, v31
	v_lshlrev_b32_e32 v50, 16, v61
	v_pk_mul_f32 v[120:121], v[38:39], v[50:51]
	v_mfma_f32_16x16x32_bf16 v[104:107], v[14:17], v[104:107], 0
	v_pk_mov_b32 v[50:51], v[116:117], v[50:51] op_sel:[1,0]
	s_waitcnt lgkmcnt(0)
	s_nop 1
	v_add_f32_e32 v1, v66, v43
	v_mul_f32_e32 v1, 0xbfb8aa3b, v1
	v_pk_mul_f32 v[118:119], v[38:39], v[116:117]
	v_pk_mul_f32 v[108:109], v[38:39], v[50:51]
	v_mfma_f32_16x16x32_bf16 v[104:107], v[18:21], v[112:115], v[104:107]
	ds_read_b32 v38, v93 offset:57472
	ds_read_b32 v49, v93 offset:57728
	v_exp_f32_e32 v1, v1
	v_add_f32_e32 v61, v68, v43
	v_mul_f32_e32 v61, 0xbfb8aa3b, v61
	s_waitcnt lgkmcnt(1)
	s_nop 1
	v_add_f32_e32 v50, v104, v38
	v_add_f32_e32 v1, 1.0, v1
	v_mul_f32_e32 v50, 0xbfb8aa3b, v50
	v_rcp_f32_e32 v1, v1
	v_exp_f32_e32 v50, v50
	v_exp_f32_e32 v61, v61
	v_mov_b32_e32 v68, v32
	s_waitcnt lgkmcnt(0)
	v_mul_f32_e32 v1, v1, v49
	v_add_f32_e32 v50, 1.0, v50
	v_mul_f32_e32 v1, 0xbfb8aa3b, v1
	v_rcp_f32_e32 v51, v50
	v_exp_f32_e32 v50, v1
	v_add_f32_e32 v1, v67, v43
	v_mul_f32_e32 v1, 0xbfb8aa3b, v1
	v_exp_f32_e32 v1, v1
	v_sub_f32_e32 v55, 1.0, v50
	v_add_f32_e32 v57, 1.0, v50
	v_mul_f32_e32 v55, v55, v57
	v_add_f32_e32 v1, 1.0, v1
	v_rcp_f32_e32 v1, v1
	v_add_f32_e32 v57, v105, v38
	v_mul_f32_e32 v57, 0xbfb8aa3b, v57
	v_exp_f32_e32 v57, v57
	v_mul_f32_e32 v1, v1, v49
	v_mul_f32_e32 v1, 0xbfb8aa3b, v1
	v_exp_f32_e32 v58, v1
	v_add_f32_e32 v43, v69, v43
	v_mul_f32_e32 v43, 0xbfb8aa3b, v43
	v_sqrt_f32_e32 v1, v55
	v_add_f32_e32 v55, 1.0, v57
	v_sub_f32_e32 v57, 1.0, v58
	v_add_f32_e32 v63, 1.0, v58
	v_exp_f32_e32 v43, v43
	v_mul_f32_e32 v57, v57, v63
	v_sqrt_f32_e32 v67, v57
	v_add_f32_e32 v57, 1.0, v61
	v_rcp_f32_e32 v57, v57
	v_add_f32_e32 v43, 1.0, v43
	v_rcp_f32_e32 v43, v43
	v_add_f32_e32 v61, v106, v38
	v_mul_f32_e32 v57, v57, v49
	v_mul_f32_e32 v61, 0xbfb8aa3b, v61
	v_mul_f32_e32 v57, 0xbfb8aa3b, v57
	v_add_f32_e32 v38, v107, v38
	v_exp_f32_e32 v63, v61
	v_exp_f32_e32 v61, v57
	v_mul_f32_e32 v38, 0xbfb8aa3b, v38
	v_mul_f32_e32 v43, v43, v49
	v_exp_f32_e32 v38, v38
	v_mul_f32_e32 v43, 0xbfb8aa3b, v43
	v_exp_f32_e32 v105, v43
	v_sub_f32_e32 v65, 1.0, v61
	v_add_f32_e32 v66, 1.0, v61
	v_rcp_f32_e32 v55, v55
	v_mul_f32_e32 v65, v65, v66
	v_add_f32_e32 v38, 1.0, v38
	v_mov_b32_e32 v66, v30
	v_add_f32_e32 v30, v62, v36
	v_rcp_f32_e32 v104, v38
	v_sub_f32_e32 v38, 1.0, v105
	v_add_f32_e32 v49, 1.0, v105
	v_mul_f32_e32 v51, v30, v51
	v_mul_f32_e32 v57, v50, v58
	v_mul_f32_e32 v38, v38, v49
	v_pk_mul_f32 v[50:51], v[50:51], v[0:1]
	v_add_f32_e32 v63, 1.0, v63
	v_sqrt_f32_e32 v49, v38
	v_add_f32_e32 v1, v50, v51
	v_add_f32_e32 v38, v64, v35
	v_rcp_f32_e32 v63, v63
	v_mul_f32_e32 v43, v61, v57
	v_mul_f32_e32 v57, v58, v1
	v_mul_f32_e32 v51, v38, v55
	v_mov_b32_e32 v50, v59
	v_sqrt_f32_e32 v69, v65
	v_pk_fma_f32 v[50:51], v[66:67], v[50:51], v[56:57]
	v_mul_f32_e32 v32, v105, v43
	v_pk_add_f32 v[56:57], v[60:61], v[50:51]
	v_pk_mul_f32 v[50:51], v[60:61], v[50:51]
	ds_bpermute_b32 v65, v83, v32
	v_add_f32_e32 v50, v70, v47
	v_mov_b32_e32 v57, v51
	v_mul_f32_e32 v43, v50, v63
	v_pk_fma_f32 v[56:57], v[68:69], v[42:43], v[56:57]
	s_waitcnt lgkmcnt(0)
; #define LAS __attribute__((address_space(3)))
; #define MFMA16(a, b, c) __builtin_amdgcn_mfma_f32_16x16x32_bf16(a, b, c, 0, 0, 0)
; template <bool PHASE_B>
; __device__ __forceinline__ void lru_item(const Params& p, LAS unsigned char* lds, int ci, int ci_next, int jb, const int tid, v4u (&xvn)[3]) {
;     ...
;                 const bf16x8 wa = *(const LAS bf16x8*)(lds + LR_WG + ((dir * 2 + 0) * 64 + 16 * ct + fr) * 144 + (32 * ks + 8 * fq) * 2);
;                 const bf16x8 wx = *(const LAS bf16x8*)(lds + LR_WG + ((dir * 2 + 1) * 64 + 16 * ct + fr) * 144 + (32 * ks + 8 * fq) * 2);
;                 ga = MFMA16(af[ks], wa, ga); gx = MFMA16(af[ks], wx, gx); }
;             const int ch = 16 * ct + fr; const float bav = GC[(dir * 3 + 0) * 64 + ch], bxv = GC[(dir * 3 + 1) * 64 + ch], c8 = GC[(dir * 3 + 2) * 64 + ch];
;             float Al = 1.f, Hl = 0.f;
; #pragma unroll
;             for (int ee = 0; ee < 4; ++ee) { const int e = dir ? 3 - ee : ee;
;                 const float r = __builtin_amdgcn_rcpf(1.f + __expf(-(ga[e] + bav))), ig = __builtin_amdgcn_rcpf(1.f + __expf(-(gx[e] + bxv)));
;                 const float la = -c8 * r; const float a = __expf(la); const float u = __builtin_amdgcn_sqrtf((1.f - a) * (1.f + a)) * (ig * xc[ct][e]);
;                 av[dir][ct][e] = a; uv[dir][ct][e] = u; Hl = a * Hl + u; Al *= a; }
;             const int o = dir ? 3 - fq : fq; const bool odd = (o & 1) != 0, hi2 = (o & 2) != 0;
;             const float A1 = __shfl_xor(Al, 16), H1 = __shfl_xor(Hl, 16);
;             const float pxA = odd ? A1 : 1.f, pxH = odd ? H1 : 0.f;
;             const float gA = Al * A1, gH = odd ? (Al * H1 + Hl) : (A1 * Hl + H1);
;             const float A2 = __shfl_xor(gA, 32), H2 = __shfl_xor(gH, 32);
;             const float PA = hi2 ? pxA * A2 : pxA, PH = hi2 ? (pxA * H2 + pxH) : pxH;
;             const float TA = gA * A2, TH = hi2 ? (gA * H2 + gH) : (A2 * gH + H2);
;             pA[dir][ct] = PA; pH[dir][ct] = PH;
;             ((LAS f32x2*)(lds + LR_SEG))[(dir * 8 + rt) * 64 + ch] = (f32x2){TA, TH};
	v_mul_f32_e32 v36, v32, v65
	v_pk_mul_f32 v[42:43], v[56:57], v[104:105]
	v_add_f32_e32 v41, v119, v27
	v_fmac_f32_e32 v43, v42, v49
	ds_bpermute_b32 v1, v83, v43
	v_add_f32_e32 v45, v121, v27
	v_add_f32_e32 v53, v109, v27
	v_fmac_f32_e32 v27, v39, v116
	ds_bpermute_b32 v39, v84, v36
	s_waitcnt lgkmcnt(1)
	v_fma_f32 v32, v32, v1, v43
	v_fmac_f32_e32 v1, v43, v65
	v_cndmask_b32_e64 v1, v32, v1, s[42:43]
	ds_bpermute_b32 v32, v84, v1
	s_waitcnt lgkmcnt(1)
	v_mul_f32_e32 v58, v36, v39
	v_lshlrev_b32_e32 v43, 16, v102
	v_lshlrev_b32_e32 v42, 16, v29
	v_add_f32_e32 v35, v120, v45
	s_waitcnt lgkmcnt(0)
	v_fma_f32 v36, v36, v32, v1
	v_fmac_f32_e32 v32, v1, v39
	v_cndmask_b32_e64 v59, v36, v32, s[44:45]
	ds_write_b64 v86, v[58:59] offset:58880
	ds_read_b128 v[58:61], v23 offset:25856
	ds_read_b128 v[62:65], v23 offset:35072
	ds_read_b128 v[66:69], v23 offset:25920
	s_waitcnt lgkmcnt(2)
	v_mfma_f32_16x16x32_bf16 v[58:61], v[14:17], v[58:61], 0
	ds_read_b128 v[102:105], v23 offset:35136
	ds_read_b32 v32, v93 offset:57280
	v_add_f32_e32 v45, v108, v53
	s_waitcnt lgkmcnt(2)
	v_mfma_f32_16x16x32_bf16 v[58:61], v[18:21], v[66:69], v[58:61]
	v_mov_b32_e32 v36, v33
	v_pk_mov_b32 v[108:109], v[42:43], v[116:117] op_sel:[1,0]
	v_mul_f32_e32 v70, v37, v42
	v_mfma_f32_16x16x32_bf16 v[62:65], v[14:17], v[62:65], 0
	v_mul_f32_e64 v106, v36, v116
	v_mul_f32_e64 v107, v37, v117
	s_waitcnt lgkmcnt(0)
	s_nop 0
	v_add_f32_e32 v1, v58, v32
	v_mul_f32_e32 v1, 0xbfb8aa3b, v1
	v_pk_mul_f32 v[108:109], v[36:37], v[108:109]
	v_pk_mul_f32 v[66:67], v[36:37], v[42:43]
	v_mfma_f32_16x16x32_bf16 v[62:65], v[18:21], v[102:105], v[62:65]
	ds_read_b32 v37, v93 offset:57536
	ds_read_b32 v39, v93 offset:57792
	v_exp_f32_e32 v1, v1
	v_add_f32_e32 v29, v107, v35
	v_add_f32_e32 v35, v109, v45
	s_waitcnt lgkmcnt(1)
	s_nop 1
	v_add_f32_e32 v36, v62, v37
	v_add_f32_e32 v1, 1.0, v1
	v_mul_f32_e32 v36, 0xbfb8aa3b, v36
	v_rcp_f32_e32 v1, v1
	v_exp_f32_e32 v36, v36
	v_add_f32_e32 v51, v60, v32
	v_mul_f32_e32 v51, 0xbfb8aa3b, v51
	s_waitcnt lgkmcnt(0)
	v_mul_f32_e32 v1, v1, v39
	v_add_f32_e32 v36, 1.0, v36
	v_mul_f32_e32 v1, 0xbfb8aa3b, v1
	v_rcp_f32_e32 v42, v36
	v_exp_f32_e32 v36, v1
	v_add_f32_e32 v1, v59, v32
	v_mul_f32_e32 v1, 0xbfb8aa3b, v1
	v_exp_f32_e32 v1, v1
	v_sub_f32_e32 v45, 1.0, v36
	v_add_f32_e32 v47, 1.0, v36
	v_mul_f32_e32 v45, v45, v47
	v_add_f32_e32 v1, 1.0, v1
	v_rcp_f32_e32 v1, v1
	v_add_f32_e32 v47, v63, v37
	v_mul_f32_e32 v47, 0xbfb8aa3b, v47
	v_exp_f32_e32 v47, v47
	v_mul_f32_e32 v1, v1, v39
	v_mul_f32_e32 v1, 0xbfb8aa3b, v1
	v_exp_f32_e32 v49, v1
	v_add_f32_e32 v32, v61, v32
	v_mul_f32_e32 v32, 0xbfb8aa3b, v32
	v_exp_f32_e32 v51, v51
	v_exp_f32_e32 v32, v32
	v_sqrt_f32_e32 v1, v45
	v_add_f32_e32 v45, 1.0, v47
	v_sub_f32_e32 v47, 1.0, v49
	v_add_f32_e32 v53, 1.0, v49
	v_mul_f32_e32 v47, v47, v53
	v_sqrt_f32_e32 v59, v47
	v_add_f32_e32 v47, 1.0, v51
	v_add_f32_e32 v32, 1.0, v32
	v_rcp_f32_e32 v47, v47
	v_rcp_f32_e32 v32, v32
	v_add_f32_e32 v51, v64, v37
	v_add_f32_e32 v37, v65, v37
	v_mul_f32_e32 v47, v47, v39
	v_mul_f32_e32 v37, 0xbfb8aa3b, v37
	v_mul_f32_e32 v32, v32, v39
	v_mul_f32_e32 v47, 0xbfb8aa3b, v47
	v_exp_f32_e32 v37, v37
	v_mul_f32_e32 v32, 0xbfb8aa3b, v32
	v_exp_f32_e32 v71, v47
	v_exp_f32_e32 v63, v32
	v_mul_f32_e32 v51, 0xbfb8aa3b, v51
	v_mul_f32_e32 v47, v36, v49
	v_add_f32_e32 v37, 1.0, v37
	v_exp_f32_e32 v51, v51
	v_mul_f32_e32 v32, v71, v47
	v_rcp_f32_e32 v62, v37
	v_sub_f32_e32 v37, 1.0, v63
	v_add_f32_e32 v39, 1.0, v63
	v_rcp_f32_e32 v45, v45
	v_mul_f32_e32 v37, v37, v39
	v_mov_b32_e32 v58, v31
	v_mul_f32_e32 v31, v63, v32
	v_add_f32_e32 v32, v106, v29
	v_sqrt_f32_e32 v39, v37
	v_mul_f32_e32 v37, v32, v42
	v_pk_mul_f32 v[36:37], v[36:37], v[0:1]
	v_add_f32_e32 v51, 1.0, v51
	v_sub_f32_e32 v53, 1.0, v71
	v_add_f32_e32 v55, 1.0, v71
	v_add_f32_e32 v1, v36, v37
	v_add_f32_e32 v36, v108, v35
	v_rcp_f32_e32 v51, v51
	v_mul_f32_e32 v53, v53, v55
	v_mul_f32_e32 v65, v49, v1
	v_mov_b32_e32 v64, v27
	v_mul_f32_e32 v69, v36, v45
	v_mov_b32_e32 v68, v43
	v_add_f32_e32 v41, v118, v41
	v_sqrt_f32_e32 v61, v53
	v_pk_fma_f32 v[42:43], v[58:59], v[68:69], v[64:65]
	v_add_f32_e32 v41, v67, v41
	v_pk_add_f32 v[58:59], v[70:71], v[42:43]
	v_pk_mul_f32 v[42:43], v[70:71], v[42:43]
	v_mov_b32_e32 v60, v33
	v_add_f32_e32 v42, v66, v41
	v_mov_b32_e32 v59, v43
	v_mul_f32_e32 v29, v42, v51
	v_pk_fma_f32 v[28:29], v[60:61], v[28:29], v[58:59]
	ds_bpermute_b32 v33, v83, v31
	v_pk_mul_f32 v[58:59], v[28:29], v[62:63]
	s_waitcnt lgkmcnt(0)
	v_mul_f32_e32 v27, v31, v33
	v_fmac_f32_e32 v59, v58, v39
	ds_bpermute_b32 v1, v83, v59
	ds_bpermute_b32 v29, v84, v27
	s_waitcnt lgkmcnt(1)
	v_fma_f32 v31, v31, v1, v59
	v_fmac_f32_e32 v1, v59, v33
	v_cndmask_b32_e64 v1, v31, v1, s[42:43]
	ds_bpermute_b32 v31, v84, v1
	s_waitcnt lgkmcnt(1)
	v_mul_f32_e32 v58, v27, v29
	s_waitcnt lgkmcnt(0)
	v_fma_f32 v27, v27, v31, v1
	v_fmac_f32_e32 v31, v1, v29
	v_cndmask_b32_e64 v59, v27, v31, s[44:45]
	ds_write_b64 v86, v[58:59] offset:59008
	ds_read_b128 v[58:61], v23 offset:37376
	ds_read_b128 v[62:65], v23 offset:37440
	s_waitcnt lgkmcnt(1)
	v_mfma_f32_16x16x32_bf16 v[58:61], v[14:17], v[58:61], 0
	ds_read_b128 v[66:69], v23 offset:46592
	ds_read_b128 v[102:105], v23 offset:46656
	ds_read_b32 v27, v93 offset:57856
	ds_read_b32 v29, v93 offset:58112
	ds_read_b32 v31, v93 offset:58368
	s_waitcnt lgkmcnt(5)
	v_mfma_f32_16x16x32_bf16 v[58:61], v[18:21], v[62:65], v[58:61]
	s_waitcnt lgkmcnt(4)
	v_mfma_f32_16x16x32_bf16 v[66:69], v[14:17], v[66:69], 0
	s_waitcnt lgkmcnt(3)
	v_mfma_f32_16x16x32_bf16 v[62:65], v[18:21], v[102:105], v[66:69]
	s_waitcnt lgkmcnt(2)
; #define LAS __attribute__((address_space(3)))
; #define MFMA16(a, b, c) __builtin_amdgcn_mfma_f32_16x16x32_bf16(a, b, c, 0, 0, 0)
; template <bool PHASE_B>
; __device__ __forceinline__ void lru_item(const Params& p, LAS unsigned char* lds, int ci, int ci_next, int jb, const int tid, v4u (&xvn)[3]) {
;     ...
;                 const bf16x8 wa = *(const LAS bf16x8*)(lds + LR_WG + ((dir * 2 + 0) * 64 + 16 * ct + fr) * 144 + (32 * ks + 8 * fq) * 2);
;                 const bf16x8 wx = *(const LAS bf16x8*)(lds + LR_WG + ((dir * 2 + 1) * 64 + 16 * ct + fr) * 144 + (32 * ks + 8 * fq) * 2);
;                 ga = MFMA16(af[ks], wa, ga); gx = MFMA16(af[ks], wx, gx); }
;             const int ch = 16 * ct + fr; const float bav = GC[(dir * 3 + 0) * 64 + ch], bxv = GC[(dir * 3 + 1) * 64 + ch], c8 = GC[(dir * 3 + 2) * 64 + ch];
;             float Al = 1.f, Hl = 0.f;
; #pragma unroll
;             for (int ee = 0; ee < 4; ++ee) { const int e = dir ? 3 - ee : ee;
;                 const float r = __builtin_amdgcn_rcpf(1.f + __expf(-(ga[e] + bav))), ig = __builtin_amdgcn_rcpf(1.f + __expf(-(gx[e] + bxv)));
;                 const float la = -c8 * r; const float a = __expf(la); const float u = __builtin_amdgcn_sqrtf((1.f - a) * (1.f + a)) * (ig * xc[ct][e]);
;                 av[dir][ct][e] = a; uv[dir][ct][e] = u; Hl = a * Hl + u; Al *= a; }
;             const int o = dir ? 3 - fq : fq; const bool odd = (o & 1) != 0, hi2 = (o & 2) != 0;
;             const float A1 = __shfl_xor(Al, 16), H1 = __shfl_xor(Hl, 16);
;             const float pxA = odd ? A1 : 1.f, pxH = odd ? H1 : 0.f;
;             const float gA = Al * A1, gH = odd ? (Al * H1 + Hl) : (A1 * Hl + H1);
;             const float A2 = __shfl_xor(gA, 32), H2 = __shfl_xor(gH, 32);
;             const float PA = hi2 ? pxA * A2 : pxA, PH = hi2 ? (pxA * H2 + pxH) : pxH;
;             const float TA = gA * A2, TH = hi2 ? (gA * H2 + gH) : (A2 * gH + H2);
;             pA[dir][ct] = PA; pH[dir][ct] = PH;
;             ((LAS f32x2*)(lds + LR_SEG))[(dir * 8 + rt) * 64 + ch] = (f32x2){TA, TH};
	s_nop 2
	v_add_f32_e32 v1, v61, v27
	v_mul_f32_e32 v1, 0xbfb8aa3b, v1
	v_exp_f32_e32 v1, v1
	s_nop 0
	v_add_f32_e32 v1, 1.0, v1
	v_rcp_f32_e32 v1, v1
	s_waitcnt lgkmcnt(1)
	v_add_f32_e32 v33, v65, v29
	v_mul_f32_e32 v33, 0xbfb8aa3b, v33
	v_exp_f32_e32 v33, v33
	s_waitcnt lgkmcnt(0)
	v_mul_f32_e32 v1, v1, v31
	v_mul_f32_e32 v1, 0xbfb8aa3b, v1
	v_exp_f32_e32 v66, v1
	v_add_f32_e32 v1, 1.0, v33
	v_rcp_f32_e32 v33, v1
	v_sub_f32_e32 v1, 1.0, v66
	v_add_f32_e32 v35, 1.0, v66
	v_mul_f32_e32 v1, v1, v35
	v_add_f32_e32 v35, v60, v27
	v_mul_f32_e32 v35, 0xbfb8aa3b, v35
	v_exp_f32_e32 v35, v35
	v_mul_f32_e32 v67, v52, v33
	v_sqrt_f32_e32 v1, v1
	v_mul_f32_e32 v52, 0, v66
	v_add_f32_e32 v33, 1.0, v35
	v_rcp_f32_e32 v33, v33
	v_add_f32_e32 v35, v64, v29
	v_mul_f32_e32 v35, 0xbfb8aa3b, v35
	v_exp_f32_e32 v35, v35
	v_mul_f32_e32 v33, v33, v31
	v_mul_f32_e32 v33, 0xbfb8aa3b, v33
	v_exp_f32_e32 v53, v33
	s_nop 0
	v_pk_fma_f32 v[60:61], v[66:67], v[0:1], v[52:53] op_sel_hi:[1,1,0]
	v_add_f32_e32 v1, 1.0, v35
	v_rcp_f32_e32 v52, v1
	v_sub_f32_e32 v1, 1.0, v53
	v_add_f32_e32 v33, 1.0, v53
	v_mul_f32_e32 v1, v1, v33
	v_add_f32_e32 v33, v59, v27
	v_mul_f32_e32 v33, 0xbfb8aa3b, v33
	v_sqrt_f32_e32 v1, v1
	v_exp_f32_e32 v33, v33
	v_add_f32_e32 v27, v58, v27
	v_mov_b32_e32 v47, v61
	v_mul_f32_e32 v27, 0xbfb8aa3b, v27
	v_pk_mul_f32 v[46:47], v[46:47], v[52:53]
	v_exp_f32_e32 v27, v27
	v_fmac_f32_e32 v47, v46, v1
	v_add_f32_e32 v1, 1.0, v33
	v_rcp_f32_e32 v1, v1
	v_add_f32_e32 v27, 1.0, v27
	v_add_f32_e32 v33, v63, v29
	v_rcp_f32_e32 v27, v27
	v_mul_f32_e32 v33, 0xbfb8aa3b, v33
	v_mul_f32_e32 v1, v1, v31
	v_exp_f32_e32 v33, v33
	v_mul_f32_e32 v1, 0xbfb8aa3b, v1
	v_exp_f32_e32 v61, v1
	v_add_f32_e32 v29, v62, v29
	v_mul_f32_e32 v29, 0xbfb8aa3b, v29
	v_mul_f32_e32 v27, v27, v31
	v_exp_f32_e32 v29, v29
	v_mul_f32_e32 v27, 0xbfb8aa3b, v27
	v_add_f32_e32 v33, 1.0, v33
	v_mov_b32_e32 v41, v47
	v_exp_f32_e32 v47, v27
	v_rcp_f32_e32 v60, v33
	v_sub_f32_e32 v33, 1.0, v61
	v_add_f32_e32 v35, 1.0, v61
	v_mul_f32_e32 v33, v33, v35
	v_sqrt_f32_e32 v33, v33
	v_add_f32_e32 v27, 1.0, v29
	v_rcp_f32_e32 v46, v27
	v_sub_f32_e32 v27, 1.0, v47
	v_add_f32_e32 v29, 1.0, v47
	v_mul_f32_e32 v27, v27, v29
	v_pk_mul_f32 v[40:41], v[40:41], v[60:61]
	v_sqrt_f32_e32 v27, v27
	v_fmac_f32_e32 v41, v40, v33
	v_mul_f32_e32 v1, v66, v53
	v_mov_b32_e32 v35, v41
	v_mul_f32_e32 v1, v61, v1
	v_pk_mul_f32 v[34:35], v[34:35], v[46:47]
	v_mul_f32_e32 v1, v47, v1
	v_fmac_f32_e32 v35, v34, v27
	ds_bpermute_b32 v27, v83, v1
	ds_bpermute_b32 v29, v83, v35
	s_waitcnt lgkmcnt(1)
	v_mul_f32_e32 v31, v1, v27
	s_waitcnt lgkmcnt(0)
	v_fma_f32 v1, v1, v29, v35
	v_fmac_f32_e32 v29, v35, v27
	v_cndmask_b32_e64 v1, v1, v29, s[46:47]
	ds_bpermute_b32 v27, v84, v31
	ds_bpermute_b32 v29, v84, v1
	s_waitcnt lgkmcnt(1)
	v_mul_f32_e32 v34, v31, v27
	s_waitcnt lgkmcnt(0)
	v_fma_f32 v31, v31, v29, v1
	v_fmac_f32_e32 v29, v1, v27
	v_cndmask_b32_e64 v35, v31, v29, s[48:49]
	ds_write_b64 v86, v[34:35] offset:62720
	ds_read_b128 v[58:61], v23 offset:39680
	ds_read_b128 v[62:65], v23 offset:39744
	s_waitcnt lgkmcnt(1)
	v_mfma_f32_16x16x32_bf16 v[58:61], v[14:17], v[58:61], 0
	ds_read_b128 v[66:69], v23 offset:48896
	ds_read_b128 v[102:105], v23 offset:48960
	ds_read_b32 v27, v93 offset:57920
	ds_read_b32 v29, v93 offset:58176
	ds_read_b32 v31, v93 offset:58432
	s_waitcnt lgkmcnt(5)
	v_mfma_f32_16x16x32_bf16 v[58:61], v[18:21], v[62:65], v[58:61]
	s_waitcnt lgkmcnt(4)
	v_mfma_f32_16x16x32_bf16 v[66:69], v[14:17], v[66:69], 0
	s_waitcnt lgkmcnt(3)
	v_mfma_f32_16x16x32_bf16 v[62:65], v[18:21], v[102:105], v[66:69]
	s_waitcnt lgkmcnt(2)
	s_nop 2
	v_add_f32_e32 v1, v61, v27
	v_mul_f32_e32 v1, 0xbfb8aa3b, v1
	v_exp_f32_e32 v1, v1
	s_nop 0
	v_add_f32_e32 v1, 1.0, v1
	v_rcp_f32_e32 v1, v1
	s_waitcnt lgkmcnt(1)
	v_add_f32_e32 v33, v65, v29
	v_mul_f32_e32 v33, 0xbfb8aa3b, v33
	v_exp_f32_e32 v33, v33
	s_waitcnt lgkmcnt(0)
	v_mul_f32_e32 v1, v1, v31
	v_mul_f32_e32 v1, 0xbfb8aa3b, v1
	v_exp_f32_e32 v34, v1
	v_add_f32_e32 v1, 1.0, v33
	v_rcp_f32_e32 v33, v1
	v_sub_f32_e32 v1, 1.0, v34
	v_add_f32_e32 v35, 1.0, v34
	v_mul_f32_e32 v1, v1, v35
	v_add_f32_e32 v35, v60, v27
	v_mul_f32_e32 v35, 0xbfb8aa3b, v35
	v_exp_f32_e32 v37, v35
	v_mul_f32_e32 v35, v54, v33
	v_sqrt_f32_e32 v1, v1
	v_mul_f32_e32 v40, 0, v34
	v_add_f32_e32 v33, 1.0, v37
	v_rcp_f32_e32 v33, v33
	v_add_f32_e32 v37, v64, v29
	v_mul_f32_e32 v37, 0xbfb8aa3b, v37
	v_exp_f32_e32 v37, v37
	v_mul_f32_e32 v33, v33, v31
	v_mul_f32_e32 v33, 0xbfb8aa3b, v33
	v_exp_f32_e32 v41, v33
	s_nop 0
	v_pk_fma_f32 v[46:47], v[34:35], v[0:1], v[40:41] op_sel_hi:[1,1,0]
	v_add_f32_e32 v1, 1.0, v37
	v_rcp_f32_e32 v40, v1
	v_sub_f32_e32 v1, 1.0, v41
	v_add_f32_e32 v33, 1.0, v41
	v_mul_f32_e32 v1, v1, v33
	v_add_f32_e32 v33, v59, v27
	v_mul_f32_e32 v33, 0xbfb8aa3b, v33
	v_sqrt_f32_e32 v1, v1
	v_exp_f32_e32 v33, v33
	v_mov_b32_e32 v49, v47
	v_add_f32_e32 v27, v58, v27
	v_pk_mul_f32 v[46:47], v[48:49], v[40:41]
	v_mul_f32_e32 v27, 0xbfb8aa3b, v27
	v_fmac_f32_e32 v47, v46, v1
	v_add_f32_e32 v1, 1.0, v33
	v_add_f32_e32 v33, v63, v29
	v_exp_f32_e32 v27, v27
	v_rcp_f32_e32 v1, v1
	v_mul_f32_e32 v33, 0xbfb8aa3b, v33
	v_exp_f32_e32 v33, v33
	v_add_f32_e32 v27, 1.0, v27
	v_mul_f32_e32 v1, v1, v31
	v_rcp_f32_e32 v27, v27
	v_mul_f32_e32 v1, 0xbfb8aa3b, v1
	v_add_f32_e32 v33, 1.0, v33
	v_exp_f32_e32 v35, v1
	v_mul_f32_e32 v1, v34, v41
	v_rcp_f32_e32 v34, v33
	v_add_f32_e32 v29, v62, v29
	v_mul_f32_e32 v29, 0xbfb8aa3b, v29
	v_mul_f32_e32 v27, v27, v31
	v_mov_b32_e32 v45, v47
	v_exp_f32_e32 v29, v29
	v_mul_f32_e32 v27, 0xbfb8aa3b, v27
	v_pk_mul_f32 v[40:41], v[44:45], v[34:35]
	v_exp_f32_e32 v45, v27
	v_sub_f32_e32 v33, 1.0, v35
	v_add_f32_e32 v37, 1.0, v35
	v_mul_f32_e32 v33, v33, v37
	v_sqrt_f32_e32 v33, v33
	v_add_f32_e32 v27, 1.0, v29
	v_rcp_f32_e32 v44, v27
	v_sub_f32_e32 v27, 1.0, v45
	v_add_f32_e32 v29, 1.0, v45
	v_mul_f32_e32 v27, v27, v29
	v_sqrt_f32_e32 v29, v27
	v_fmac_f32_e32 v41, v40, v33
	v_mov_b32_e32 v27, v41
	v_mul_f32_e32 v1, v35, v1
	v_pk_mul_f32 v[26:27], v[26:27], v[44:45]
	v_mul_f32_e32 v1, v45, v1
	v_fmac_f32_e32 v27, v26, v29
	ds_bpermute_b32 v26, v83, v1
	ds_bpermute_b32 v29, v83, v27
	s_waitcnt lgkmcnt(1)
; #define LAS __attribute__((address_space(3)))
; #define MFMA16(a, b, c) __builtin_amdgcn_mfma_f32_16x16x32_bf16(a, b, c, 0, 0, 0)
; template <bool PHASE_B>
; __device__ __forceinline__ void lru_item(const Params& p, LAS unsigned char* lds, int ci, int ci_next, int jb, const int tid, v4u (&xvn)[3]) {
;     ...
;                 const bf16x8 wa = *(const LAS bf16x8*)(lds + LR_WG + ((dir * 2 + 0) * 64 + 16 * ct + fr) * 144 + (32 * ks + 8 * fq) * 2);
;                 const bf16x8 wx = *(const LAS bf16x8*)(lds + LR_WG + ((dir * 2 + 1) * 64 + 16 * ct + fr) * 144 + (32 * ks + 8 * fq) * 2);
;                 ga = MFMA16(af[ks], wa, ga); gx = MFMA16(af[ks], wx, gx); }
;             const int ch = 16 * ct + fr; const float bav = GC[(dir * 3 + 0) * 64 + ch], bxv = GC[(dir * 3 + 1) * 64 + ch], c8 = GC[(dir * 3 + 2) * 64 + ch];
;             float Al = 1.f, Hl = 0.f;
; #pragma unroll
;             for (int ee = 0; ee < 4; ++ee) { const int e = dir ? 3 - ee : ee;
;                 const float r = __builtin_amdgcn_rcpf(1.f + __expf(-(ga[e] + bav))), ig = __builtin_amdgcn_rcpf(1.f + __expf(-(gx[e] + bxv)));
;                 const float la = -c8 * r; const float a = __expf(la); const float u = __builtin_amdgcn_sqrtf((1.f - a) * (1.f + a)) * (ig * xc[ct][e]);
;                 av[dir][ct][e] = a; uv[dir][ct][e] = u; Hl = a * Hl + u; Al *= a; }
;             const int o = dir ? 3 - fq : fq; const bool odd = (o & 1) != 0, hi2 = (o & 2) != 0;
;             const float A1 = __shfl_xor(Al, 16), H1 = __shfl_xor(Hl, 16);
;             const float pxA = odd ? A1 : 1.f, pxH = odd ? H1 : 0.f;
;             const float gA = Al * A1, gH = odd ? (Al * H1 + Hl) : (A1 * Hl + H1);
;             const float A2 = __shfl_xor(gA, 32), H2 = __shfl_xor(gH, 32);
;             const float PA = hi2 ? pxA * A2 : pxA, PH = hi2 ? (pxA * H2 + pxH) : pxH;
;             const float TA = gA * A2, TH = hi2 ? (gA * H2 + gH) : (A2 * gH + H2);
;             pA[dir][ct] = PA; pH[dir][ct] = PH;
;             ((LAS f32x2*)(lds + LR_SEG))[(dir * 8 + rt) * 64 + ch] = (f32x2){TA, TH};
	v_mul_f32_e32 v31, v1, v26
	s_waitcnt lgkmcnt(0)
	v_fma_f32 v1, v1, v29, v27
	v_fmac_f32_e32 v29, v27, v26
	v_cndmask_b32_e64 v1, v1, v29, s[46:47]
	ds_bpermute_b32 v27, v84, v31
	ds_bpermute_b32 v29, v84, v1
	s_waitcnt lgkmcnt(1)
	v_mul_f32_e32 v26, v31, v27
	s_waitcnt lgkmcnt(0)
	v_fma_f32 v31, v31, v29, v1
	v_fmac_f32_e32 v29, v1, v27
	v_cndmask_b32_e64 v27, v31, v29, s[48:49]
	ds_write_b64 v86, v[26:27] offset:62848
	ds_read_b128 v[44:47], v23 offset:41984
	ds_read_b128 v[52:55], v23 offset:42048
	s_waitcnt lgkmcnt(1)
	v_mfma_f32_16x16x32_bf16 v[44:47], v[14:17], v[44:47], 0
	ds_read_b128 v[58:61], v23 offset:51200
	ds_read_b128 v[62:65], v23 offset:51264
	ds_read_b32 v29, v93 offset:57984
	ds_read_b32 v31, v93 offset:58240
	ds_read_b32 v33, v93 offset:58496
	s_waitcnt lgkmcnt(5)
	v_mfma_f32_16x16x32_bf16 v[44:47], v[18:21], v[52:55], v[44:47]
	s_waitcnt lgkmcnt(4)
	v_mfma_f32_16x16x32_bf16 v[58:61], v[14:17], v[58:61], 0
	s_waitcnt lgkmcnt(3)
	v_mfma_f32_16x16x32_bf16 v[52:55], v[18:21], v[62:65], v[58:61]
	s_waitcnt lgkmcnt(2)
	s_nop 2
	v_add_f32_e32 v1, v47, v29
	v_mul_f32_e32 v1, 0xbfb8aa3b, v1
	v_exp_f32_e32 v1, v1
	s_nop 0
	v_add_f32_e32 v1, 1.0, v1
	v_rcp_f32_e32 v1, v1
	s_waitcnt lgkmcnt(1)
	v_add_f32_e32 v26, v55, v31
	v_mul_f32_e32 v26, 0xbfb8aa3b, v26
	v_exp_f32_e32 v27, v26
	s_waitcnt lgkmcnt(0)
	v_mul_f32_e32 v1, v1, v33
	v_mul_f32_e32 v1, 0xbfb8aa3b, v1
	v_exp_f32_e32 v26, v1
	v_add_f32_e32 v1, 1.0, v27
	v_rcp_f32_e32 v27, v1
	v_add_f32_e32 v37, v54, v31
	v_sub_f32_e32 v1, 1.0, v26
	v_add_f32_e32 v34, 1.0, v26
	v_mul_f32_e32 v1, v1, v34
	v_add_f32_e32 v34, v46, v29
	v_mul_f32_e32 v34, 0xbfb8aa3b, v34
	v_exp_f32_e32 v35, v34
	v_mul_f32_e32 v37, 0xbfb8aa3b, v37
	v_sqrt_f32_e32 v1, v1
	v_exp_f32_e32 v37, v37
	v_add_f32_e32 v35, 1.0, v35
	v_rcp_f32_e32 v35, v35
	v_mul_f32_e32 v27, v56, v27
	v_mul_f32_e32 v34, 0, v26
	v_mul_f32_e32 v35, v35, v33
	v_mul_f32_e32 v35, 0xbfb8aa3b, v35
	v_exp_f32_e32 v35, v35
	s_nop 0
	v_pk_fma_f32 v[40:41], v[26:27], v[0:1], v[34:35] op_sel_hi:[1,1,0]
	v_add_f32_e32 v1, 1.0, v37
	v_rcp_f32_e32 v34, v1
	v_sub_f32_e32 v1, 1.0, v35
	v_add_f32_e32 v27, 1.0, v35
	v_mul_f32_e32 v1, v1, v27
	v_add_f32_e32 v27, v45, v29
	v_mul_f32_e32 v27, 0xbfb8aa3b, v27
	v_sqrt_f32_e32 v1, v1
	v_exp_f32_e32 v27, v27
	v_mov_b32_e32 v51, v41
	v_pk_mul_f32 v[40:41], v[50:51], v[34:35]
	v_add_f32_e32 v29, v44, v29
	v_fmac_f32_e32 v41, v40, v1
	v_add_f32_e32 v1, 1.0, v27
	v_rcp_f32_e32 v1, v1
	v_add_f32_e32 v27, v53, v31
	v_mul_f32_e32 v27, 0xbfb8aa3b, v27
	v_exp_f32_e32 v34, v27
	v_mul_f32_e32 v1, v1, v33
	v_mul_f32_e32 v1, 0xbfb8aa3b, v1
	v_exp_f32_e32 v27, v1
	v_mul_f32_e32 v1, v26, v35
	v_add_f32_e32 v26, 1.0, v34
	v_mul_f32_e32 v29, 0xbfb8aa3b, v29
	v_rcp_f32_e32 v26, v26
	v_exp_f32_e32 v29, v29
	v_sub_f32_e32 v34, 1.0, v27
	v_add_f32_e32 v35, 1.0, v27
	v_mul_f32_e32 v34, v34, v35
	v_mov_b32_e32 v39, v41
	v_sqrt_f32_e32 v37, v34
	v_pk_mul_f32 v[34:35], v[38:39], v[26:27]
	v_add_f32_e32 v26, 1.0, v29
	v_rcp_f32_e32 v26, v26
	v_add_f32_e32 v29, v52, v31
	v_mul_f32_e32 v29, 0xbfb8aa3b, v29
	v_exp_f32_e32 v29, v29
	v_mul_f32_e32 v26, v26, v33
	v_mul_f32_e32 v26, 0xbfb8aa3b, v26
	v_exp_f32_e32 v39, v26
	v_add_f32_e32 v26, 1.0, v29
	v_rcp_f32_e32 v38, v26
	v_fmac_f32_e32 v35, v34, v37
	v_sub_f32_e32 v26, 1.0, v39
	v_add_f32_e32 v29, 1.0, v39
	v_mul_f32_e32 v26, v26, v29
	v_sqrt_f32_e32 v29, v26
	v_mov_b32_e32 v31, v35
	v_mul_f32_e32 v1, v27, v1
	v_pk_mul_f32 v[26:27], v[30:31], v[38:39]
	v_mul_f32_e32 v1, v39, v1
	v_fmac_f32_e32 v27, v26, v29
	ds_bpermute_b32 v26, v83, v1
	ds_bpermute_b32 v29, v83, v27
	s_waitcnt lgkmcnt(1)
	v_mul_f32_e32 v30, v1, v26
	s_waitcnt lgkmcnt(0)
	v_fma_f32 v1, v1, v29, v27
	v_fmac_f32_e32 v29, v27, v26
	v_cndmask_b32_e64 v1, v1, v29, s[46:47]
	ds_bpermute_b32 v27, v84, v30
	ds_bpermute_b32 v29, v84, v1
	s_waitcnt lgkmcnt(1)
	v_mul_f32_e32 v26, v30, v27
	s_waitcnt lgkmcnt(0)
	v_fma_f32 v30, v30, v29, v1
	v_fmac_f32_e32 v29, v1, v27
	v_cndmask_b32_e64 v27, v30, v29, s[48:49]
	ds_write_b64 v86, v[26:27] offset:62976
	ds_read_b128 v[38:41], v23 offset:44288
	ds_read_b128 v[44:47], v23 offset:44352
	s_waitcnt lgkmcnt(1)
	v_mfma_f32_16x16x32_bf16 v[38:41], v[14:17], v[38:41], 0
	ds_read_b128 v[48:51], v23 offset:53504
	ds_read_b128 v[52:55], v23 offset:53568
	ds_read_b32 v23, v93 offset:58048
	ds_read_b32 v26, v93 offset:58304
	ds_read_b32 v27, v93 offset:58560
	s_waitcnt lgkmcnt(5)
	v_mfma_f32_16x16x32_bf16 v[38:41], v[18:21], v[44:47], v[38:41]
	s_waitcnt lgkmcnt(4)
	v_mfma_f32_16x16x32_bf16 v[14:17], v[14:17], v[48:51], 0
	s_waitcnt lgkmcnt(3)
; template <bool PHASE_B>
; __device__ __forceinline__ void lru_item(const Params& p, LAS unsigned char* lds, int ci, int ci_next, int jb, const int tid, v4u (&xvn)[3]) {
;     ...
;                 const bf16x8 wa = *(const LAS bf16x8*)(lds + LR_WG + ((dir * 2 + 0) * 64 + 16 * ct + fr) * 144 + (32 * ks + 8 * fq) * 2);
;                 const bf16x8 wx = *(const LAS bf16x8*)(lds + LR_WG + ((dir * 2 + 1) * 64 + 16 * ct + fr) * 144 + (32 * ks + 8 * fq) * 2);
;                 ga = MFMA16(af[ks], wa, ga); gx = MFMA16(af[ks], wx, gx); }
;             const int ch = 16 * ct + fr; const float bav = GC[(dir * 3 + 0) * 64 + ch], bxv = GC[(dir * 3 + 1) * 64 + ch], c8 = GC[(dir * 3 + 2) * 64 + ch];
;             float Al = 1.f, Hl = 0.f;
; #pragma unroll
;             for (int ee = 0; ee < 4; ++ee) { const int e = dir ? 3 - ee : ee;
;                 const float r = __builtin_amdgcn_rcpf(1.f + __expf(-(ga[e] + bav))), ig = __builtin_amdgcn_rcpf(1.f + __expf(-(gx[e] + bxv)));
;                 const float la = -c8 * r; const float a = __expf(la); const float u = __builtin_amdgcn_sqrtf((1.f - a) * (1.f + a)) * (ig * xc[ct][e]);
;                 av[dir][ct][e] = a; uv[dir][ct][e] = u; Hl = a * Hl + u; Al *= a; }
;             const int o = dir ? 3 - fq : fq; const bool odd = (o & 1) != 0, hi2 = (o & 2) != 0;
;             const float A1 = __shfl_xor(Al, 16), H1 = __shfl_xor(Hl, 16);
;             const float pxA = odd ? A1 : 1.f, pxH = odd ? H1 : 0.f;
;             const float gA = Al * A1, gH = odd ? (Al * H1 + Hl) : (A1 * Hl + H1);
;             const float A2 = __shfl_xor(gA, 32), H2 = __shfl_xor(gH, 32);
;             const float PA = hi2 ? pxA * A2 : pxA, PH = hi2 ? (pxA * H2 + pxH) : pxH;
;             const float TA = gA * A2, TH = hi2 ? (gA * H2 + gH) : (A2 * gH + H2);
;             pA[dir][ct] = PA; pH[dir][ct] = PH;
;             ((LAS f32x2*)(lds + LR_SEG))[(dir * 8 + rt) * 64 + ch] = (f32x2){TA, TH};
;         }
;     }
;     if constexpr (PHASE_B) {
; #pragma unroll
;         for (int dir = 0; dir < 2; ++dir)
; #pragma unroll
;             for (int ct = 0; ct < 4; ++ct) cin[dir][ct] = ((const float*)(p.ws + WS_CIN))[(size_t)(ci * 2 + dir) * 768 + jb * 64 + 16 * ct + fr];
;         const bf16* gp = (const bf16*)(p.ws + WS_GR) + (size_t)(t0 + (tid >> 2)) * 768 + jb * 64 + (tid & 3) * 16;
;         gv[0] = *(const v4u*)gp; gv[1] = *(const v4u*)(gp + 8);
;     }
	v_mfma_f32_16x16x32_bf16 v[14:17], v[18:21], v[52:55], v[14:17]
	s_waitcnt lgkmcnt(2)
	s_nop 2
	v_add_f32_e32 v1, v41, v23
	v_mul_f32_e32 v1, 0xbfb8aa3b, v1
	v_exp_f32_e32 v1, v1
	s_nop 0
	v_add_f32_e32 v1, 1.0, v1
	v_rcp_f32_e32 v1, v1
	s_waitcnt lgkmcnt(1)
	v_add_f32_e32 v17, v17, v26
	v_mul_f32_e32 v17, 0xbfb8aa3b, v17
	v_exp_f32_e32 v17, v17
	s_waitcnt lgkmcnt(0)
	v_mul_f32_e32 v1, v1, v27
	v_mul_f32_e32 v1, 0xbfb8aa3b, v1
	v_exp_f32_e32 v18, v1
	v_add_f32_e32 v1, 1.0, v17
	v_rcp_f32_e32 v17, v1
	v_add_f32_e32 v16, v16, v26
	v_sub_f32_e32 v1, 1.0, v18
	v_add_f32_e32 v19, 1.0, v18
	v_mul_f32_e32 v1, v1, v19
	v_add_f32_e32 v19, v40, v23
	v_mul_f32_e32 v19, 0xbfb8aa3b, v19
	v_exp_f32_e32 v21, v19
	v_mul_f32_e32 v19, v28, v17
	v_mul_f32_e32 v16, 0xbfb8aa3b, v16
	v_sqrt_f32_e32 v1, v1
	v_add_f32_e32 v17, 1.0, v21
	v_rcp_f32_e32 v17, v17
	v_exp_f32_e32 v16, v16
	v_mul_f32_e32 v20, 0, v18
	v_pk_fma_f32 v[20:21], v[18:19], v[0:1], v[20:21] op_sel_hi:[1,1,0]
	v_mul_f32_e32 v17, v17, v27
	v_mul_f32_e32 v17, 0xbfb8aa3b, v17
	v_exp_f32_e32 v17, v17
	v_add_f32_e32 v1, 1.0, v16
	v_rcp_f32_e32 v16, v1
	v_mov_b32_e32 v43, v21
	v_sub_f32_e32 v1, 1.0, v17
	v_add_f32_e32 v19, 1.0, v17
	v_mul_f32_e32 v1, v1, v19
	v_add_f32_e32 v19, v39, v23
	v_mul_f32_e32 v19, 0xbfb8aa3b, v19
	v_sqrt_f32_e32 v1, v1
	v_exp_f32_e32 v19, v19
	v_pk_mul_f32 v[20:21], v[42:43], v[16:17]
	v_add_f32_e32 v15, v15, v26
	v_fmac_f32_e32 v21, v20, v1
	v_add_f32_e32 v1, 1.0, v19
	v_rcp_f32_e32 v1, v1
	v_mul_f32_e32 v15, 0xbfb8aa3b, v15
	v_exp_f32_e32 v15, v15
	v_add_f32_e32 v14, v14, v26
	v_mul_f32_e32 v1, v1, v27
	v_mul_f32_e32 v1, 0xbfb8aa3b, v1
	v_exp_f32_e32 v19, v1
	v_add_f32_e32 v15, 1.0, v15
	v_mul_f32_e32 v1, v18, v17
	v_rcp_f32_e32 v18, v15
	v_sub_f32_e32 v15, 1.0, v19
	v_add_f32_e32 v16, 1.0, v19
	v_mul_f32_e32 v15, v15, v16
	v_add_f32_e32 v16, v38, v23
	v_mul_f32_e32 v16, 0xbfb8aa3b, v16
	v_exp_f32_e32 v20, v16
	v_sqrt_f32_e32 v23, v15
	v_mul_f32_e32 v14, 0xbfb8aa3b, v14
	v_exp_f32_e32 v14, v14
	v_add_f32_e32 v15, 1.0, v20
	v_rcp_f32_e32 v15, v15
	v_mov_b32_e32 v37, v21
	v_pk_mul_f32 v[16:17], v[36:37], v[18:19]
	v_add_f32_e32 v14, 1.0, v14
	v_mul_f32_e32 v15, v15, v27
	v_mul_f32_e32 v15, 0xbfb8aa3b, v15
	v_exp_f32_e32 v15, v15
	v_fmac_f32_e32 v17, v16, v23
	v_rcp_f32_e32 v14, v14
	v_mov_b32_e32 v33, v17
	v_sub_f32_e32 v16, 1.0, v15
	v_add_f32_e32 v18, 1.0, v15
	v_mul_f32_e32 v16, v16, v18
	v_sqrt_f32_e32 v18, v16
	v_mul_f32_e32 v1, v19, v1
	v_pk_mul_f32 v[16:17], v[32:33], v[14:15]
	v_mul_f32_e32 v1, v15, v1
	v_fmac_f32_e32 v17, v16, v18
	ds_bpermute_b32 v14, v83, v1
	ds_bpermute_b32 v15, v83, v17
	s_waitcnt lgkmcnt(1)
	v_mul_f32_e32 v16, v1, v14
	s_waitcnt lgkmcnt(0)
	v_fma_f32 v1, v1, v15, v17
	v_fmac_f32_e32 v15, v17, v14
	v_cndmask_b32_e64 v1, v1, v15, s[46:47]
	ds_bpermute_b32 v15, v84, v16
	ds_bpermute_b32 v17, v84, v1
	s_waitcnt lgkmcnt(1)
	v_mul_f32_e32 v14, v16, v15
	s_waitcnt lgkmcnt(0)
	v_fma_f32 v16, v16, v17, v1
	v_fmac_f32_e32 v17, v1, v15
	v_cndmask_b32_e64 v15, v16, v17, s[48:49]
	ds_write_b64 v86, v[14:15] offset:63104
	s_waitcnt vmcnt(0) lgkmcnt(0)
	s_barrier
	s_and_saveexec_b64 s[12:13], s[50:51]
	s_cbranch_execz .LBB0_528
	ds_read_b64 v[14:15], v94 offset:58624
	ds_read_b64 v[16:17], v95 offset:58624
	ds_read_b64 v[18:19], v96 offset:58624
	ds_read_b64 v[20:21], v97 offset:58624
	s_waitcnt lgkmcnt(3)
	v_fma_f32 v1, 0, v14, v15
	s_waitcnt lgkmcnt(2)
	v_pk_mul_f32 v[14:15], v[14:15], v[16:17]
	v_fmac_f32_e32 v17, v16, v1
	s_waitcnt lgkmcnt(1)
	v_fma_f32 v1, v18, v17, v19
	ds_read_b64 v[16:17], v98 offset:58624
	ds_read_b64 v[26:27], v99 offset:58624
	ds_read_b64 v[28:29], v100 offset:58624
	ds_read_b64 v[30:31], v101 offset:58624
	s_waitcnt lgkmcnt(4)
	v_fma_f32 v1, v20, v1, v21
	v_mov_b32_e32 v32, v14
	v_mov_b32_e32 v34, v18
	s_waitcnt lgkmcnt(3)
	v_fma_f32 v33, v16, v1, v17
	s_waitcnt lgkmcnt(2)
	v_mov_b32_e32 v35, v26
	v_pk_mul_f32 v[14:15], v[14:15], v[18:19]
	v_pk_fma_f32 v[18:19], v[32:33], v[34:35], v[26:27]
	v_pk_mul_f32 v[14:15], v[14:15], v[20:21]
	s_waitcnt lgkmcnt(1)
	v_mov_b32_e32 v17, v28
	v_mov_b32_e32 v15, v19
	v_pk_mul_f32 v[18:19], v[14:15], v[16:17]
	v_pk_fma_f32 v[14:15], v[14:15], v[16:17], v[28:29]
	v_pk_mul_f32 v[18:19], v[18:19], v[26:27]
	v_mov_b32_e32 v16, v28
	v_mov_b32_e32 v14, v18
	s_waitcnt lgkmcnt(0)
	v_mov_b32_e32 v17, v30
	v_pk_mul_f32 v[18:19], v[18:19], v[28:29]
	v_pk_fma_f32 v[14:15], v[14:15], v[16:17], v[30:31]
	v_pk_mul_f32 v[18:19], v[18:19], v[30:31]
	s_nop 0
	v_mov_b32_e32 v19, v15
	v_mad_i64_i32 v[14:15], s[60:61], v87, s64, v[24:25]
	global_store_dwordx2 v[14:15], v[18:19], off
	s_branch .LBB0_528

; #define LAS __attribute__((address_space(3)))
; template <bool PHASE_B>
; __device__ __forceinline__ void lru_item(const Params& p, LAS unsigned char* lds, int ci, int ci_next, int jb, const int tid, v4u (&xvn)[3]) {
;     ...
;     for (int k = 0; k < 3; ++k) { const int c = k * NTHR + tid, rr = c >> 3, d8 = c & 7; if (c < 131 * 8) *(LAS v4u*)(lds + LR_XR + rr * 144 + d8 * 16) = xvn[k]; }
.LBB0_544:
	s_waitcnt vmcnt(1)
	ds_write_b128 v75, v[2:5]
	s_or_b64 exec, exec, s[12:13]
	s_and_saveexec_b64 s[12:13], s[40:41]
	s_cbranch_execnz .LBB0_532
	s_branch .LBB0_533

; #define PG8_STAGE(bufoff, gbase, voff) do { _Pragma("unroll") for (int _i = 0; _i < 2; ++_i) \
;         __builtin_amdgcn_global_load_lds((const unsigned*)((const char*)(gbase) + (voff)[_i]), (PG8_LAS unsigned*)(lds + (bufoff) + ldsw + _i * 8192), 16, 0, 0); } while (0)
; #define PG8_LDA(dst, b, h) do { _Pragma("unroll") for (int m = 0; m < 4; ++m) _Pragma("unroll") for (int k = 0; k < 2; ++k) dst[m][k] = *(const PG8_LAS bf16x8*)(lds + PG8_SA(b, h) + aoff + m * 2048 + k * 1024); } while (0)
; #define PG8_LDB(dst, b, h) do { _Pragma("unroll") for (int n = 0; n < 2; ++n) _Pragma("unroll") for (int k = 0; k < 2; ++k) dst[n][k] = *(const PG8_LAS bf16x8*)(lds + PG8_SB(b, h) + boff + n * 2048 + k * 1024); } while (0)
; #define PG8_MMA(ai, bj, At, Bt) do { __builtin_amdgcn_s_setprio(1); _Pragma("unroll") for (int m = 0; m < 4; ++m) _Pragma("unroll") for (int n = 0; n < 2; ++n) _Pragma("unroll") for (int k = 0; k < 2; ++k) \
;         acc[ai][bj][m][n] = __builtin_amdgcn_mfma_f32_16x16x32_bf16(Bt[n][k], At[m][k], acc[ai][bj][m][n], 0, 0, 0); __builtin_amdgcn_s_setprio(0); } while (0)
; #define PG8_WAIT_V(n) asm volatile("s_waitcnt vmcnt(" #n ")" ::: "memory")
; #define PG8_BAR __builtin_amdgcn_s_barrier()
; template <class Epi, class Sched, bool ALIGN_EPI = false, bool SP2 = false>
; __device__ __forceinline__ void gemm_phase(PG8_LAS unsigned char* lds, const Gemm g, const Sched& S, const Epi& E) {
;     ...
;         for (int t = 0; t < nt; t += 2) {
;             const bool last = (t == nt - 2);
;             const char* a1 = cA + (size_t)(t + 1) * kstep;
;             const char* a2 = last ? nA : cA + (size_t)(t + 2) * kstep; const char* b2 = last ? nB : cB + (size_t)(t + 2) * kstep;
;             const char* a3 = a2 + kstep; const char* b3 = b2 + kstep;
;             if (last && has_next) S.a_ready(nxt);
;             if constexpr (SP2) {
;             PG8_LDB(B0, 0, 0); PG8_LDB(B1, 0, 1); PG8_SCHED; PG8_LDA(At, 0, 0); PG8_STAGE(PG8_SA(1, 1), a1 + hstepA, voffA);
;             PG8_WAIT_V(8); PG8_WAIT_L(0); PG8_BAR; PG8_MMA(0, 0, At, B0); PG8_MMA(0, 1, At, B1); PG8_BAR; PG8_SCHED;
;             PG8_LDA(At, 0, 1); PG8_STAGE(PG8_SB(0, 0), b2, voffB); PG8_STAGE(PG8_SB(0, 1), b2 + hstep, voffB); PG8_STAGE(PG8_SA(0, 0), a2, voffA);
;             PG8_WAIT_V(8); PG8_WAIT_L(0); PG8_BAR; PG8_MMA(1, 0, At, B0); PG8_MMA(1, 1, At, B1); PG8_BAR; PG8_SCHED;
.LBB0_560:
	s_add_u32 s48, s44, 0xfffc0080
	s_addc_u32 s49, s45, -1
	s_add_i32 s65, 0, 0x10000
	s_cmp_eq_u32 s53, 12
	s_cselect_b32 s51, s9, s49
	s_cselect_b32 s50, s15, s48
	v_add_u32_e32 v146, s65, v157
	s_cselect_b32 s49, s7, s52
	s_cselect_b32 s48, s37, s41
	s_add_i32 s68, 0, 0x14000
	ds_read_b128 v[142:145], v146
	ds_read_b128 v[150:153], v146 offset:1024
	ds_read_b128 v[168:171], v146 offset:2048
	ds_read_b128 v[172:175], v146 offset:3072
	v_add_u32_e32 v146, s68, v157
	ds_read_b128 v[176:179], v146
	ds_read_b128 v[180:183], v146 offset:1024
	ds_read_b128 v[184:187], v146 offset:2048
	ds_read_b128 v[198:201], v146 offset:3072
	v_lshl_add_u64 v[146:147], s[44:45], 0, v[140:141]
	s_add_i32 m0, s47, 0xc000
	ds_read_b128 v[202:205], v166
	ds_read_b128 v[206:209], v166 offset:1024
	ds_read_b128 v[210:213], v166 offset:2048
	ds_read_b128 v[214:217], v166 offset:3072
	ds_read_b128 v[218:221], v166 offset:4096
	ds_read_b128 v[222:225], v166 offset:5120
	ds_read_b128 v[226:229], v166 offset:6144
	ds_read_b128 v[236:239], v166 offset:7168
	global_load_lds_dwordx4 v[146:147], off
	v_lshl_add_u64 v[146:147], s[44:45], 0, v[138:139]
	s_add_i32 m0, s47, 0xe000
	s_nop 0
	global_load_lds_dwordx4 v[146:147], off
	s_waitcnt vmcnt(8)
	s_waitcnt lgkmcnt(0)
	s_barrier
	s_setprio 1
	s_waitcnt lgkmcnt(0)
	v_mfma_f32_16x16x32_bf16 v[126:129], v[142:145], v[202:205], v[126:129]
	v_mfma_f32_16x16x32_bf16 v[122:125], v[168:171], v[202:205], v[122:125]
	v_mfma_f32_16x16x32_bf16 v[110:113], v[142:145], v[210:213], v[110:113]
	v_mfma_f32_16x16x32_bf16 v[106:109], v[168:171], v[210:213], v[106:109]
	v_mfma_f32_16x16x32_bf16 v[94:97], v[142:145], v[218:221], v[94:97]
	v_mfma_f32_16x16x32_bf16 v[90:93], v[168:171], v[218:221], v[90:93]
	v_mfma_f32_16x16x32_bf16 v[78:81], v[142:145], v[226:229], v[78:81]
	v_mfma_f32_16x16x32_bf16 v[74:77], v[168:171], v[226:229], v[74:77]
	v_mfma_f32_16x16x32_bf16 v[126:129], v[150:153], v[206:209], v[126:129]
	v_mfma_f32_16x16x32_bf16 v[122:125], v[172:175], v[206:209], v[122:125]
	v_mfma_f32_16x16x32_bf16 v[110:113], v[150:153], v[214:217], v[110:113]
	v_mfma_f32_16x16x32_bf16 v[106:109], v[172:175], v[214:217], v[106:109]
	v_mfma_f32_16x16x32_bf16 v[94:97], v[150:153], v[222:225], v[94:97]
	v_mfma_f32_16x16x32_bf16 v[90:93], v[172:175], v[222:225], v[90:93]
	v_mfma_f32_16x16x32_bf16 v[78:81], v[150:153], v[236:239], v[78:81]
	v_mfma_f32_16x16x32_bf16 v[74:77], v[172:175], v[236:239], v[74:77]
	v_mfma_f32_16x16x32_bf16 v[118:121], v[176:179], v[202:205], v[118:121]
	v_mfma_f32_16x16x32_bf16 v[114:117], v[184:187], v[202:205], v[114:117]
	v_mfma_f32_16x16x32_bf16 v[102:105], v[176:179], v[210:213], v[102:105]
	v_mfma_f32_16x16x32_bf16 v[98:101], v[184:187], v[210:213], v[98:101]
	v_mfma_f32_16x16x32_bf16 v[86:89], v[176:179], v[218:221], v[86:89]
	v_mfma_f32_16x16x32_bf16 v[82:85], v[184:187], v[218:221], v[82:85]
	v_mfma_f32_16x16x32_bf16 v[70:73], v[176:179], v[226:229], v[70:73]
	v_mfma_f32_16x16x32_bf16 v[66:69], v[184:187], v[226:229], v[66:69]
	v_mfma_f32_16x16x32_bf16 v[118:121], v[180:183], v[206:209], v[118:121]
	v_mfma_f32_16x16x32_bf16 v[114:117], v[198:201], v[206:209], v[114:117]
	v_mfma_f32_16x16x32_bf16 v[102:105], v[180:183], v[214:217], v[102:105]
	v_mfma_f32_16x16x32_bf16 v[98:101], v[198:201], v[214:217], v[98:101]
	v_mfma_f32_16x16x32_bf16 v[86:89], v[180:183], v[222:225], v[86:89]
	v_mfma_f32_16x16x32_bf16 v[82:85], v[198:201], v[222:225], v[82:85]
	v_mfma_f32_16x16x32_bf16 v[70:73], v[180:183], v[236:239], v[70:73]
	v_mfma_f32_16x16x32_bf16 v[66:69], v[198:201], v[236:239], v[66:69]
	s_setprio 0
	s_barrier
	s_add_i32 s65, s65, s56
	v_lshl_add_u64 v[146:147], s[48:49], 0, v[132:133]
	s_mov_b32 m0, s65
	ds_read_b128 v[202:205], v166 offset:16384
	ds_read_b128 v[206:209], v166 offset:17408
	ds_read_b128 v[210:213], v166 offset:18432
	ds_read_b128 v[214:217], v166 offset:19456
	ds_read_b128 v[218:221], v166 offset:20480
	ds_read_b128 v[222:225], v166 offset:21504
	ds_read_b128 v[226:229], v166 offset:22528
	ds_read_b128 v[236:239], v166 offset:23552
	global_load_lds_dwordx4 v[146:147], off
	s_add_i32 m0, s65, 0x2000
	s_add_u32 s66, s48, 0x40000
	v_lshl_add_u64 v[190:191], s[48:49], 0, v[136:137]
	s_addc_u32 s67, s49, 0
	s_add_i32 s65, s68, s56
	global_load_lds_dwordx4 v[190:191], off
	v_lshl_add_u64 v[194:195], s[66:67], 0, v[132:133]
	s_mov_b32 m0, s65
	v_lshl_add_u64 v[234:235], s[50:51], 0, v[134:135]
	global_load_lds_dwordx4 v[194:195], off
	v_lshl_add_u64 v[194:195], s[66:67], 0, v[136:137]
	s_add_i32 m0, s65, 0x2000
	s_nop 0
	global_load_lds_dwordx4 v[194:195], off
	v_lshl_add_u64 v[194:195], s[50:51], 0, v[130:131]
	s_mov_b32 m0, s47
	s_nop 0
	global_load_lds_dwordx4 v[194:195], off
	s_mov_b32 m0, s57
	s_nop 0
	global_load_lds_dwordx4 v[234:235], off
	s_waitcnt vmcnt(8)
	s_waitcnt lgkmcnt(0)
	s_barrier
; #define PG8_STAGE(bufoff, gbase, voff) do { _Pragma("unroll") for (int _i = 0; _i < 2; ++_i) \
;         __builtin_amdgcn_global_load_lds((const unsigned*)((const char*)(gbase) + (voff)[_i]), (PG8_LAS unsigned*)(lds + (bufoff) + ldsw + _i * 8192), 16, 0, 0); } while (0)
; #define PG8_LDA(dst, b, h) do { _Pragma("unroll") for (int m = 0; m < 4; ++m) _Pragma("unroll") for (int k = 0; k < 2; ++k) dst[m][k] = *(const PG8_LAS bf16x8*)(lds + PG8_SA(b, h) + aoff + m * 2048 + k * 1024); } while (0)
; #define PG8_LDB(dst, b, h) do { _Pragma("unroll") for (int n = 0; n < 2; ++n) _Pragma("unroll") for (int k = 0; k < 2; ++k) dst[n][k] = *(const PG8_LAS bf16x8*)(lds + PG8_SB(b, h) + boff + n * 2048 + k * 1024); } while (0)
; #define PG8_MMA(ai, bj, At, Bt) do { __builtin_amdgcn_s_setprio(1); _Pragma("unroll") for (int m = 0; m < 4; ++m) _Pragma("unroll") for (int n = 0; n < 2; ++n) _Pragma("unroll") for (int k = 0; k < 2; ++k) \
;         acc[ai][bj][m][n] = __builtin_amdgcn_mfma_f32_16x16x32_bf16(Bt[n][k], At[m][k], acc[ai][bj][m][n], 0, 0, 0); __builtin_amdgcn_s_setprio(0); } while (0)
; #define PG8_WAIT_V(n) asm volatile("s_waitcnt vmcnt(" #n ")" ::: "memory")
; #define PG8_WAIT_L(n) asm volatile("s_waitcnt lgkmcnt(" #n ")" ::: "memory")
; #define PG8_BAR __builtin_amdgcn_s_barrier()
; #define PG8_SCHED __builtin_amdgcn_sched_barrier(0)
; template <class Epi, class Sched, bool ALIGN_EPI = false, bool SP2 = false>
; __device__ __forceinline__ void gemm_phase(PG8_LAS unsigned char* lds, const Gemm g, const Sched& S, const Epi& E) {
;     ...
;             PG8_WAIT_V(8); PG8_WAIT_L(0); PG8_BAR; PG8_MMA(1, 0, At, B0); PG8_MMA(1, 1, At, B1); PG8_BAR; PG8_SCHED;
;             PG8_LDB(B0, 1, 0); PG8_LDB(B1, 1, 1); PG8_SCHED; PG8_LDA(At, 1, 0); PG8_STAGE(PG8_SA(0, 1), a2 + hstepA, voffA);
;             PG8_WAIT_V(8); PG8_WAIT_L(0); PG8_BAR; PG8_MMA(0, 0, At, B0); PG8_MMA(0, 1, At, B1); PG8_BAR; PG8_SCHED;
	s_setprio 1
	s_waitcnt lgkmcnt(0)
	v_mfma_f32_16x16x32_bf16 v[62:65], v[142:145], v[202:205], v[62:65]
	v_mfma_f32_16x16x32_bf16 v[58:61], v[168:171], v[202:205], v[58:61]
	v_mfma_f32_16x16x32_bf16 v[46:49], v[142:145], v[210:213], v[46:49]
	v_mfma_f32_16x16x32_bf16 v[42:45], v[168:171], v[210:213], v[42:45]
	v_mfma_f32_16x16x32_bf16 v[30:33], v[142:145], v[218:221], v[30:33]
	v_mfma_f32_16x16x32_bf16 v[26:29], v[168:171], v[218:221], v[26:29]
	v_mfma_f32_16x16x32_bf16 v[14:17], v[142:145], v[226:229], v[14:17]
	v_mfma_f32_16x16x32_bf16 v[10:13], v[168:171], v[226:229], v[10:13]
	v_mfma_f32_16x16x32_bf16 v[62:65], v[150:153], v[206:209], v[62:65]
	v_mfma_f32_16x16x32_bf16 v[58:61], v[172:175], v[206:209], v[58:61]
	v_mfma_f32_16x16x32_bf16 v[46:49], v[150:153], v[214:217], v[46:49]
	v_mfma_f32_16x16x32_bf16 v[42:45], v[172:175], v[214:217], v[42:45]
	v_mfma_f32_16x16x32_bf16 v[30:33], v[150:153], v[222:225], v[30:33]
	v_mfma_f32_16x16x32_bf16 v[26:29], v[172:175], v[222:225], v[26:29]
	v_mfma_f32_16x16x32_bf16 v[14:17], v[150:153], v[236:239], v[14:17]
	v_mfma_f32_16x16x32_bf16 v[10:13], v[172:175], v[236:239], v[10:13]
	v_mfma_f32_16x16x32_bf16 v[54:57], v[176:179], v[202:205], v[54:57]
	v_mfma_f32_16x16x32_bf16 v[50:53], v[184:187], v[202:205], v[50:53]
	v_mfma_f32_16x16x32_bf16 v[38:41], v[176:179], v[210:213], v[38:41]
	v_mfma_f32_16x16x32_bf16 v[34:37], v[184:187], v[210:213], v[34:37]
	v_mfma_f32_16x16x32_bf16 v[22:25], v[176:179], v[218:221], v[22:25]
	v_mfma_f32_16x16x32_bf16 v[18:21], v[184:187], v[218:221], v[18:21]
	v_mfma_f32_16x16x32_bf16 v[6:9], v[176:179], v[226:229], v[6:9]
	v_mfma_f32_16x16x32_bf16 v[2:5], v[184:187], v[226:229], v[2:5]
	v_mfma_f32_16x16x32_bf16 v[54:57], v[180:183], v[206:209], v[54:57]
	v_mfma_f32_16x16x32_bf16 v[50:53], v[198:201], v[206:209], v[50:53]
	v_mfma_f32_16x16x32_bf16 v[38:41], v[180:183], v[214:217], v[38:41]
	v_mfma_f32_16x16x32_bf16 v[34:37], v[198:201], v[214:217], v[34:37]
	v_mfma_f32_16x16x32_bf16 v[22:25], v[180:183], v[222:225], v[22:25]
	v_mfma_f32_16x16x32_bf16 v[18:21], v[198:201], v[222:225], v[18:21]
	v_mfma_f32_16x16x32_bf16 v[6:9], v[180:183], v[236:239], v[6:9]
	v_mfma_f32_16x16x32_bf16 v[2:5], v[198:201], v[236:239], v[2:5]
	s_setprio 0
	s_barrier
	s_add_i32 s65, 0, 0x18000
	v_add_u32_e32 v167, s65, v157
	s_add_i32 s66, 0, 0x1c000
	ds_read_b128 v[142:145], v167
	ds_read_b128 v[150:153], v167 offset:1024
	ds_read_b128 v[168:171], v167 offset:2048
	ds_read_b128 v[172:175], v167 offset:3072
	v_add_u32_e32 v167, s66, v157
	ds_read_b128 v[176:179], v167
	ds_read_b128 v[180:183], v167 offset:1024
	ds_read_b128 v[184:187], v167 offset:2048
	ds_read_b128 v[198:201], v167 offset:3072
	s_add_u32 s50, s50, 0x40000
	s_addc_u32 s51, s51, 0
	s_mov_b32 m0, s58
	v_lshl_add_u64 v[246:247], s[50:51], 0, v[130:131]
	ds_read_b128 v[202:205], v166 offset:32768
	ds_read_b128 v[206:209], v166 offset:33792
	ds_read_b128 v[210:213], v166 offset:34816
	ds_read_b128 v[214:217], v166 offset:35840
	ds_read_b128 v[218:221], v166 offset:36864
	ds_read_b128 v[222:225], v166 offset:37888
	ds_read_b128 v[226:229], v166 offset:38912
	ds_read_b128 v[236:239], v166 offset:39936
	global_load_lds_dwordx4 v[246:247], off
	v_lshl_add_u64 v[246:247], s[50:51], 0, v[134:135]
	s_mov_b32 m0, s59
	s_nop 0
	global_load_lds_dwordx4 v[246:247], off
	s_waitcnt vmcnt(8)
	s_waitcnt lgkmcnt(0)
	s_barrier
	s_setprio 1
	s_waitcnt lgkmcnt(0)
	v_mfma_f32_16x16x32_bf16 v[126:129], v[142:145], v[202:205], v[126:129]
	v_mfma_f32_16x16x32_bf16 v[122:125], v[168:171], v[202:205], v[122:125]
	v_mfma_f32_16x16x32_bf16 v[110:113], v[142:145], v[210:213], v[110:113]
	v_mfma_f32_16x16x32_bf16 v[106:109], v[168:171], v[210:213], v[106:109]
	v_mfma_f32_16x16x32_bf16 v[94:97], v[142:145], v[218:221], v[94:97]
	v_mfma_f32_16x16x32_bf16 v[90:93], v[168:171], v[218:221], v[90:93]
	v_mfma_f32_16x16x32_bf16 v[78:81], v[142:145], v[226:229], v[78:81]
	v_mfma_f32_16x16x32_bf16 v[74:77], v[168:171], v[226:229], v[74:77]
	v_mfma_f32_16x16x32_bf16 v[126:129], v[150:153], v[206:209], v[126:129]
	v_mfma_f32_16x16x32_bf16 v[122:125], v[172:175], v[206:209], v[122:125]
	v_mfma_f32_16x16x32_bf16 v[110:113], v[150:153], v[214:217], v[110:113]
	v_mfma_f32_16x16x32_bf16 v[106:109], v[172:175], v[214:217], v[106:109]
	v_mfma_f32_16x16x32_bf16 v[94:97], v[150:153], v[222:225], v[94:97]
	v_mfma_f32_16x16x32_bf16 v[90:93], v[172:175], v[222:225], v[90:93]
	v_mfma_f32_16x16x32_bf16 v[78:81], v[150:153], v[236:239], v[78:81]
	v_mfma_f32_16x16x32_bf16 v[74:77], v[172:175], v[236:239], v[74:77]
	v_mfma_f32_16x16x32_bf16 v[118:121], v[176:179], v[202:205], v[118:121]
	v_mfma_f32_16x16x32_bf16 v[114:117], v[184:187], v[202:205], v[114:117]
	v_mfma_f32_16x16x32_bf16 v[102:105], v[176:179], v[210:213], v[102:105]
	v_mfma_f32_16x16x32_bf16 v[98:101], v[184:187], v[210:213], v[98:101]
	v_mfma_f32_16x16x32_bf16 v[86:89], v[176:179], v[218:221], v[86:89]
	v_mfma_f32_16x16x32_bf16 v[82:85], v[184:187], v[218:221], v[82:85]
	v_mfma_f32_16x16x32_bf16 v[70:73], v[176:179], v[226:229], v[70:73]
	v_mfma_f32_16x16x32_bf16 v[66:69], v[184:187], v[226:229], v[66:69]
	v_mfma_f32_16x16x32_bf16 v[118:121], v[180:183], v[206:209], v[118:121]
	v_mfma_f32_16x16x32_bf16 v[114:117], v[198:201], v[206:209], v[114:117]
	v_mfma_f32_16x16x32_bf16 v[102:105], v[180:183], v[214:217], v[102:105]
	v_mfma_f32_16x16x32_bf16 v[98:101], v[198:201], v[214:217], v[98:101]
	v_mfma_f32_16x16x32_bf16 v[86:89], v[180:183], v[222:225], v[86:89]
	v_mfma_f32_16x16x32_bf16 v[82:85], v[198:201], v[222:225], v[82:85]
	v_mfma_f32_16x16x32_bf16 v[70:73], v[180:183], v[236:239], v[70:73]
	v_mfma_f32_16x16x32_bf16 v[66:69], v[198:201], v[236:239], v[66:69]
	s_setprio 0
	s_barrier
; #define PG8_STAGE(bufoff, gbase, voff) do { _Pragma("unroll") for (int _i = 0; _i < 2; ++_i) \
;         __builtin_amdgcn_global_load_lds((const unsigned*)((const char*)(gbase) + (voff)[_i]), (PG8_LAS unsigned*)(lds + (bufoff) + ldsw + _i * 8192), 16, 0, 0); } while (0)
; #define PG8_LDA(dst, b, h) do { _Pragma("unroll") for (int m = 0; m < 4; ++m) _Pragma("unroll") for (int k = 0; k < 2; ++k) dst[m][k] = *(const PG8_LAS bf16x8*)(lds + PG8_SA(b, h) + aoff + m * 2048 + k * 1024); } while (0)
; #define PG8_MMA(ai, bj, At, Bt) do { __builtin_amdgcn_s_setprio(1); _Pragma("unroll") for (int m = 0; m < 4; ++m) _Pragma("unroll") for (int n = 0; n < 2; ++n) _Pragma("unroll") for (int k = 0; k < 2; ++k) \
;         acc[ai][bj][m][n] = __builtin_amdgcn_mfma_f32_16x16x32_bf16(Bt[n][k], At[m][k], acc[ai][bj][m][n], 0, 0, 0); __builtin_amdgcn_s_setprio(0); } while (0)
; #define PG8_WAIT_V(n) asm volatile("s_waitcnt vmcnt(" #n ")" ::: "memory")
; #define PG8_WAIT_L(n) asm volatile("s_waitcnt lgkmcnt(" #n ")" ::: "memory")
; #define PG8_BAR __builtin_amdgcn_s_barrier()
; #define PG8_SCHED __builtin_amdgcn_sched_barrier(0)
; template <class Epi, class Sched, bool ALIGN_EPI = false, bool SP2 = false>
; __device__ __forceinline__ void gemm_phase(PG8_LAS unsigned char* lds, const Gemm g, const Sched& S, const Epi& E) {
;     ...
;             PG8_LDA(At, 1, 1); PG8_STAGE(PG8_SB(1, 0), b3, voffB); PG8_STAGE(PG8_SB(1, 1), b3 + hstep, voffB); PG8_STAGE(PG8_SA(1, 0), a3, voffA);
;             PG8_WAIT_V(8); PG8_WAIT_L(0); PG8_BAR; PG8_MMA(1, 0, At, B0); PG8_MMA(1, 1, At, B1); PG8_BAR; PG8_SCHED;
;     ...
;         if constexpr (ALIGN_EPI) { if (wr == 0) PG8_BAR; }
	s_add_i32 s50, s65, s56
	v_lshl_add_u64 v[146:147], v[146:147], 0, s[88:89]
	s_mov_b32 m0, s50
	ds_read_b128 v[202:205], v166 offset:49152
	ds_read_b128 v[206:209], v166 offset:50176
	ds_read_b128 v[210:213], v166 offset:51200
	ds_read_b128 v[214:217], v166 offset:52224
	ds_read_b128 v[218:221], v166 offset:53248
	ds_read_b128 v[222:225], v166 offset:54272
	ds_read_b128 v[226:229], v166 offset:55296
	ds_read_b128 v[236:239], v166 offset:56320
	global_load_lds_dwordx4 v[146:147], off
	s_add_i32 m0, s50, 0x2000
	s_add_u32 s48, s48, 0x40080
	v_lshl_add_u64 v[146:147], v[190:191], 0, s[88:89]
	s_addc_u32 s49, s49, 0
	s_add_i32 s50, s66, s56
	global_load_lds_dwordx4 v[146:147], off
	v_lshl_add_u64 v[146:147], s[48:49], 0, v[132:133]
	s_mov_b32 m0, s50
	s_nop 0
	global_load_lds_dwordx4 v[146:147], off
	v_lshl_add_u64 v[146:147], s[48:49], 0, v[136:137]
	s_add_i32 m0, s50, 0x2000
	s_nop 0
	global_load_lds_dwordx4 v[146:147], off
	v_lshl_add_u64 v[146:147], v[194:195], 0, s[88:89]
	s_mov_b32 m0, s60
	s_nop 0
	global_load_lds_dwordx4 v[146:147], off
	v_lshl_add_u64 v[146:147], v[234:235], 0, s[88:89]
	s_mov_b32 m0, s61
	s_nop 0
	global_load_lds_dwordx4 v[146:147], off
	s_waitcnt vmcnt(8)
	s_waitcnt lgkmcnt(0)
	s_barrier
	s_setprio 1
	s_waitcnt lgkmcnt(0)
	v_mfma_f32_16x16x32_bf16 v[62:65], v[142:145], v[202:205], v[62:65]
	v_mfma_f32_16x16x32_bf16 v[58:61], v[168:171], v[202:205], v[58:61]
	v_mfma_f32_16x16x32_bf16 v[46:49], v[142:145], v[210:213], v[46:49]
	v_mfma_f32_16x16x32_bf16 v[42:45], v[168:171], v[210:213], v[42:45]
	v_mfma_f32_16x16x32_bf16 v[30:33], v[142:145], v[218:221], v[30:33]
	v_mfma_f32_16x16x32_bf16 v[26:29], v[168:171], v[218:221], v[26:29]
	v_mfma_f32_16x16x32_bf16 v[14:17], v[142:145], v[226:229], v[14:17]
	v_mfma_f32_16x16x32_bf16 v[10:13], v[168:171], v[226:229], v[10:13]
	v_mfma_f32_16x16x32_bf16 v[62:65], v[150:153], v[206:209], v[62:65]
	v_mfma_f32_16x16x32_bf16 v[58:61], v[172:175], v[206:209], v[58:61]
	v_mfma_f32_16x16x32_bf16 v[46:49], v[150:153], v[214:217], v[46:49]
	v_mfma_f32_16x16x32_bf16 v[42:45], v[172:175], v[214:217], v[42:45]
	v_mfma_f32_16x16x32_bf16 v[30:33], v[150:153], v[222:225], v[30:33]
	v_mfma_f32_16x16x32_bf16 v[26:29], v[172:175], v[222:225], v[26:29]
	v_mfma_f32_16x16x32_bf16 v[14:17], v[150:153], v[236:239], v[14:17]
	v_mfma_f32_16x16x32_bf16 v[10:13], v[172:175], v[236:239], v[10:13]
	v_mfma_f32_16x16x32_bf16 v[54:57], v[176:179], v[202:205], v[54:57]
	v_mfma_f32_16x16x32_bf16 v[50:53], v[184:187], v[202:205], v[50:53]
	v_mfma_f32_16x16x32_bf16 v[38:41], v[176:179], v[210:213], v[38:41]
	v_mfma_f32_16x16x32_bf16 v[34:37], v[184:187], v[210:213], v[34:37]
	v_mfma_f32_16x16x32_bf16 v[22:25], v[176:179], v[218:221], v[22:25]
	v_mfma_f32_16x16x32_bf16 v[18:21], v[184:187], v[218:221], v[18:21]
	v_mfma_f32_16x16x32_bf16 v[6:9], v[176:179], v[226:229], v[6:9]
	v_mfma_f32_16x16x32_bf16 v[2:5], v[184:187], v[226:229], v[2:5]
	v_mfma_f32_16x16x32_bf16 v[54:57], v[180:183], v[206:209], v[54:57]
	v_mfma_f32_16x16x32_bf16 v[50:53], v[198:201], v[206:209], v[50:53]
	v_mfma_f32_16x16x32_bf16 v[38:41], v[180:183], v[214:217], v[38:41]
	v_mfma_f32_16x16x32_bf16 v[34:37], v[198:201], v[214:217], v[34:37]
	v_mfma_f32_16x16x32_bf16 v[22:25], v[180:183], v[222:225], v[22:25]
	v_mfma_f32_16x16x32_bf16 v[18:21], v[198:201], v[222:225], v[18:21]
	v_mfma_f32_16x16x32_bf16 v[6:9], v[180:183], v[236:239], v[6:9]
	v_mfma_f32_16x16x32_bf16 v[2:5], v[198:201], v[236:239], v[2:5]
	s_setprio 0
	s_barrier
	s_add_i32 s53, s53, 2
	s_add_u32 s41, s41, 0x100
	s_addc_u32 s52, s52, 0
	s_add_u32 s44, s44, 0x100
	s_addc_u32 s45, s45, 0
	s_cmp_gt_u32 s53, 13
	s_cbranch_scc0 .LBB0_560
	s_and_b64 vcc, exec, s[4:5]
	s_cbranch_vccz .LBB0_563
	s_barrier

; #define PG8_STAGE(bufoff, gbase, voff) do { _Pragma("unroll") for (int _i = 0; _i < 2; ++_i) \
;         __builtin_amdgcn_global_load_lds((const unsigned*)((const char*)(gbase) + (voff)[_i]), (PG8_LAS unsigned*)(lds + (bufoff) + ldsw + _i * 8192), 16, 0, 0); } while (0)
; #define PG8_LDA(dst, b, h) do { _Pragma("unroll") for (int m = 0; m < 4; ++m) _Pragma("unroll") for (int k = 0; k < 2; ++k) dst[m][k] = *(const PG8_LAS bf16x8*)(lds + PG8_SA(b, h) + aoff + m * 2048 + k * 1024); } while (0)
; #define PG8_LDB(dst, b, h) do { _Pragma("unroll") for (int n = 0; n < 2; ++n) _Pragma("unroll") for (int k = 0; k < 2; ++k) dst[n][k] = *(const PG8_LAS bf16x8*)(lds + PG8_SB(b, h) + boff + n * 2048 + k * 1024); } while (0)
; #define PG8_MMA(ai, bj, At, Bt) do { __builtin_amdgcn_s_setprio(1); _Pragma("unroll") for (int m = 0; m < 4; ++m) _Pragma("unroll") for (int n = 0; n < 2; ++n) _Pragma("unroll") for (int k = 0; k < 2; ++k) \
;         acc[ai][bj][m][n] = __builtin_amdgcn_mfma_f32_16x16x32_bf16(Bt[n][k], At[m][k], acc[ai][bj][m][n], 0, 0, 0); __builtin_amdgcn_s_setprio(0); } while (0)
; #define PG8_WAIT_V(n) asm volatile("s_waitcnt vmcnt(" #n ")" ::: "memory")
; #define PG8_BAR __builtin_amdgcn_s_barrier()
; template <class Epi, class Sched, bool ALIGN_EPI = false, bool SP2 = false>
; __device__ __forceinline__ void gemm_phase(PG8_LAS unsigned char* lds, const Gemm g, const Sched& S, const Epi& E) {
;     ...
;         for (int t = 0; t < nt; t += 2) {
;             const bool last = (t == nt - 2);
;             const char* a1 = cA + (size_t)(t + 1) * kstep;
;             const char* a2 = last ? nA : cA + (size_t)(t + 2) * kstep; const char* b2 = last ? nB : cB + (size_t)(t + 2) * kstep;
;             const char* a3 = a2 + kstep; const char* b3 = b2 + kstep;
;             if (last && has_next) S.a_ready(nxt);
;             if constexpr (SP2) {
;             PG8_LDB(B0, 0, 0); PG8_LDB(B1, 0, 1); PG8_SCHED; PG8_LDA(At, 0, 0); PG8_STAGE(PG8_SA(1, 1), a1 + hstepA, voffA);
;             PG8_WAIT_V(8); PG8_WAIT_L(0); PG8_BAR; PG8_MMA(0, 0, At, B0); PG8_MMA(0, 1, At, B1); PG8_BAR; PG8_SCHED;
;             PG8_LDA(At, 0, 1); PG8_STAGE(PG8_SB(0, 0), b2, voffB); PG8_STAGE(PG8_SB(0, 1), b2 + hstep, voffB); PG8_STAGE(PG8_SA(0, 0), a2, voffA);
;             PG8_WAIT_V(8); PG8_WAIT_L(0); PG8_BAR; PG8_MMA(1, 0, At, B0); PG8_MMA(1, 1, At, B1); PG8_BAR; PG8_SCHED;
.LBB0_616:
	s_add_u32 s44, s42, 0xfffc0080
	s_addc_u32 s45, s43, -1
	s_add_i32 s65, 0, 0x10000
	s_cmp_eq_u32 s64, 12
	s_cselect_b32 s47, s13, s45
	s_cselect_b32 s46, s61, s44
	v_add_u32_e32 v142, s65, v144
	s_cselect_b32 s45, s7, s63
	s_cselect_b32 s44, s37, s62
	s_add_i32 s68, 0, 0x14000
	ds_read_b128 v[150:153], v142
	ds_read_b128 v[166:169], v142 offset:1024
	ds_read_b128 v[170:173], v142 offset:2048
	ds_read_b128 v[174:177], v142 offset:3072
	v_add_u32_e32 v142, s68, v144
	ds_read_b128 v[178:181], v142
	ds_read_b128 v[182:185], v142 offset:1024
	ds_read_b128 v[198:201], v142 offset:2048
	ds_read_b128 v[202:205], v142 offset:3072
	v_lshl_add_u64 v[142:143], s[42:43], 0, v[138:139]
	s_add_i32 m0, s51, 0xc000
	ds_read_b128 v[206:209], v146
	ds_read_b128 v[210:213], v146 offset:1024
	ds_read_b128 v[214:217], v146 offset:2048
	ds_read_b128 v[218:221], v146 offset:3072
	ds_read_b128 v[222:225], v146 offset:4096
	ds_read_b128 v[226:229], v146 offset:5120
	ds_read_b128 v[236:239], v146 offset:6144
	ds_read_b128 v[246:249], v146 offset:7168
	global_load_lds_dwordx4 v[142:143], off
	v_lshl_add_u64 v[142:143], s[42:43], 0, v[140:141]
	s_add_i32 m0, s51, 0xe000
	s_nop 0
	global_load_lds_dwordx4 v[142:143], off
	s_waitcnt vmcnt(8)
	s_waitcnt lgkmcnt(0)
	s_barrier
	s_setprio 1
	s_waitcnt lgkmcnt(0)
	v_mfma_f32_16x16x32_bf16 v[126:129], v[150:153], v[206:209], v[126:129]
	v_mfma_f32_16x16x32_bf16 v[122:125], v[170:173], v[206:209], v[122:125]
	v_mfma_f32_16x16x32_bf16 v[118:121], v[150:153], v[214:217], v[118:121]
	v_mfma_f32_16x16x32_bf16 v[110:113], v[170:173], v[214:217], v[110:113]
	v_mfma_f32_16x16x32_bf16 v[102:105], v[150:153], v[222:225], v[102:105]
	v_mfma_f32_16x16x32_bf16 v[94:97], v[170:173], v[222:225], v[94:97]
	v_mfma_f32_16x16x32_bf16 v[86:89], v[150:153], v[236:239], v[86:89]
	v_mfma_f32_16x16x32_bf16 v[78:81], v[170:173], v[236:239], v[78:81]
	v_mfma_f32_16x16x32_bf16 v[126:129], v[166:169], v[210:213], v[126:129]
	v_mfma_f32_16x16x32_bf16 v[122:125], v[174:177], v[210:213], v[122:125]
	v_mfma_f32_16x16x32_bf16 v[118:121], v[166:169], v[218:221], v[118:121]
	v_mfma_f32_16x16x32_bf16 v[110:113], v[174:177], v[218:221], v[110:113]
	v_mfma_f32_16x16x32_bf16 v[102:105], v[166:169], v[226:229], v[102:105]
	v_mfma_f32_16x16x32_bf16 v[94:97], v[174:177], v[226:229], v[94:97]
	v_mfma_f32_16x16x32_bf16 v[86:89], v[166:169], v[246:249], v[86:89]
	v_mfma_f32_16x16x32_bf16 v[78:81], v[174:177], v[246:249], v[78:81]
	v_mfma_f32_16x16x32_bf16 v[114:117], v[178:181], v[206:209], v[114:117]
	v_mfma_f32_16x16x32_bf16 v[106:109], v[198:201], v[206:209], v[106:109]
	v_mfma_f32_16x16x32_bf16 v[98:101], v[178:181], v[214:217], v[98:101]
	v_mfma_f32_16x16x32_bf16 v[90:93], v[198:201], v[214:217], v[90:93]
	v_mfma_f32_16x16x32_bf16 v[82:85], v[178:181], v[222:225], v[82:85]
	v_mfma_f32_16x16x32_bf16 v[74:77], v[198:201], v[222:225], v[74:77]
	v_mfma_f32_16x16x32_bf16 v[70:73], v[178:181], v[236:239], v[70:73]
	v_mfma_f32_16x16x32_bf16 v[66:69], v[198:201], v[236:239], v[66:69]
	v_mfma_f32_16x16x32_bf16 v[114:117], v[182:185], v[210:213], v[114:117]
	v_mfma_f32_16x16x32_bf16 v[106:109], v[202:205], v[210:213], v[106:109]
	v_mfma_f32_16x16x32_bf16 v[98:101], v[182:185], v[218:221], v[98:101]
	v_mfma_f32_16x16x32_bf16 v[90:93], v[202:205], v[218:221], v[90:93]
	v_mfma_f32_16x16x32_bf16 v[82:85], v[182:185], v[226:229], v[82:85]
	v_mfma_f32_16x16x32_bf16 v[74:77], v[202:205], v[226:229], v[74:77]
	v_mfma_f32_16x16x32_bf16 v[70:73], v[182:185], v[246:249], v[70:73]
	v_mfma_f32_16x16x32_bf16 v[66:69], v[202:205], v[246:249], v[66:69]
	s_setprio 0
	s_barrier
	s_add_i32 s65, s65, s50
	v_lshl_add_u64 v[142:143], s[44:45], 0, v[134:135]
	s_mov_b32 m0, s65
	ds_read_b128 v[206:209], v146 offset:16384
	ds_read_b128 v[210:213], v146 offset:17408
	ds_read_b128 v[214:217], v146 offset:18432
	ds_read_b128 v[218:221], v146 offset:19456
	ds_read_b128 v[222:225], v146 offset:20480
	ds_read_b128 v[226:229], v146 offset:21504
	ds_read_b128 v[236:239], v146 offset:22528
	ds_read_b128 v[246:249], v146 offset:23552
	global_load_lds_dwordx4 v[142:143], off
	s_add_i32 m0, s65, 0x2000
	s_add_u32 s66, s44, 0x40000
	v_lshl_add_u64 v[186:187], s[44:45], 0, v[130:131]
	s_addc_u32 s67, s45, 0
	s_add_i32 s65, s68, s50
	global_load_lds_dwordx4 v[186:187], off
	v_lshl_add_u64 v[190:191], s[66:67], 0, v[134:135]
	s_mov_b32 m0, s65
	v_lshl_add_u64 v[194:195], s[46:47], 0, v[132:133]
	global_load_lds_dwordx4 v[190:191], off
	v_lshl_add_u64 v[190:191], s[66:67], 0, v[130:131]
	s_add_i32 m0, s65, 0x2000
	s_nop 0
	global_load_lds_dwordx4 v[190:191], off
	v_lshl_add_u64 v[190:191], s[46:47], 0, v[136:137]
	s_mov_b32 m0, s51
	s_nop 0
	global_load_lds_dwordx4 v[190:191], off
	s_mov_b32 m0, s52
	s_nop 0
	global_load_lds_dwordx4 v[194:195], off
	s_waitcnt vmcnt(8)
	s_waitcnt lgkmcnt(0)
	s_barrier
; #define PG8_STAGE(bufoff, gbase, voff) do { _Pragma("unroll") for (int _i = 0; _i < 2; ++_i) \
;         __builtin_amdgcn_global_load_lds((const unsigned*)((const char*)(gbase) + (voff)[_i]), (PG8_LAS unsigned*)(lds + (bufoff) + ldsw + _i * 8192), 16, 0, 0); } while (0)
; #define PG8_LDA(dst, b, h) do { _Pragma("unroll") for (int m = 0; m < 4; ++m) _Pragma("unroll") for (int k = 0; k < 2; ++k) dst[m][k] = *(const PG8_LAS bf16x8*)(lds + PG8_SA(b, h) + aoff + m * 2048 + k * 1024); } while (0)
; #define PG8_LDB(dst, b, h) do { _Pragma("unroll") for (int n = 0; n < 2; ++n) _Pragma("unroll") for (int k = 0; k < 2; ++k) dst[n][k] = *(const PG8_LAS bf16x8*)(lds + PG8_SB(b, h) + boff + n * 2048 + k * 1024); } while (0)
; #define PG8_MMA(ai, bj, At, Bt) do { __builtin_amdgcn_s_setprio(1); _Pragma("unroll") for (int m = 0; m < 4; ++m) _Pragma("unroll") for (int n = 0; n < 2; ++n) _Pragma("unroll") for (int k = 0; k < 2; ++k) \
;         acc[ai][bj][m][n] = __builtin_amdgcn_mfma_f32_16x16x32_bf16(Bt[n][k], At[m][k], acc[ai][bj][m][n], 0, 0, 0); __builtin_amdgcn_s_setprio(0); } while (0)
; #define PG8_WAIT_V(n) asm volatile("s_waitcnt vmcnt(" #n ")" ::: "memory")
; #define PG8_WAIT_L(n) asm volatile("s_waitcnt lgkmcnt(" #n ")" ::: "memory")
; #define PG8_BAR __builtin_amdgcn_s_barrier()
; template <class Epi, class Sched, bool ALIGN_EPI = false, bool SP2 = false>
; __device__ __forceinline__ void gemm_phase(PG8_LAS unsigned char* lds, const Gemm g, const Sched& S, const Epi& E) {
;     ...
;             PG8_WAIT_V(8); PG8_WAIT_L(0); PG8_BAR; PG8_MMA(0, 0, At, B0); PG8_MMA(0, 1, At, B1); PG8_BAR; PG8_SCHED;
;             PG8_LDA(At, 0, 1); PG8_STAGE(PG8_SB(0, 0), b2, voffB); PG8_STAGE(PG8_SB(0, 1), b2 + hstep, voffB); PG8_STAGE(PG8_SA(0, 0), a2, voffA);
;             PG8_WAIT_V(8); PG8_WAIT_L(0); PG8_BAR; PG8_MMA(1, 0, At, B0); PG8_MMA(1, 1, At, B1); PG8_BAR; PG8_SCHED;
;             PG8_LDB(B0, 1, 0); PG8_LDB(B1, 1, 1); PG8_SCHED; PG8_LDA(At, 1, 0); PG8_STAGE(PG8_SA(0, 1), a2 + hstepA, voffA);
;             PG8_WAIT_V(8); PG8_WAIT_L(0); PG8_BAR; PG8_MMA(0, 0, At, B0); PG8_MMA(0, 1, At, B1); PG8_BAR; PG8_SCHED;
;             PG8_LDA(At, 1, 1); PG8_STAGE(PG8_SB(1, 0), b3, voffB); PG8_STAGE(PG8_SB(1, 1), b3 + hstep, voffB); PG8_STAGE(PG8_SA(1, 0), a3, voffA);
;             PG8_WAIT_V(8); PG8_WAIT_L(0); PG8_BAR; PG8_MMA(1, 0, At, B0); PG8_MMA(1, 1, At, B1); PG8_BAR; PG8_SCHED;
	s_setprio 1
	s_waitcnt lgkmcnt(0)
	v_mfma_f32_16x16x32_bf16 v[62:65], v[150:153], v[206:209], v[62:65]
	v_mfma_f32_16x16x32_bf16 v[58:61], v[170:173], v[206:209], v[58:61]
	v_mfma_f32_16x16x32_bf16 v[54:57], v[150:153], v[214:217], v[54:57]
	v_mfma_f32_16x16x32_bf16 v[46:49], v[170:173], v[214:217], v[46:49]
	v_mfma_f32_16x16x32_bf16 v[38:41], v[150:153], v[222:225], v[38:41]
	v_mfma_f32_16x16x32_bf16 v[30:33], v[170:173], v[222:225], v[30:33]
	v_mfma_f32_16x16x32_bf16 v[22:25], v[150:153], v[236:239], v[22:25]
	v_mfma_f32_16x16x32_bf16 v[14:17], v[170:173], v[236:239], v[14:17]
	v_mfma_f32_16x16x32_bf16 v[62:65], v[166:169], v[210:213], v[62:65]
	v_mfma_f32_16x16x32_bf16 v[58:61], v[174:177], v[210:213], v[58:61]
	v_mfma_f32_16x16x32_bf16 v[54:57], v[166:169], v[218:221], v[54:57]
	v_mfma_f32_16x16x32_bf16 v[46:49], v[174:177], v[218:221], v[46:49]
	v_mfma_f32_16x16x32_bf16 v[38:41], v[166:169], v[226:229], v[38:41]
	v_mfma_f32_16x16x32_bf16 v[30:33], v[174:177], v[226:229], v[30:33]
	v_mfma_f32_16x16x32_bf16 v[22:25], v[166:169], v[246:249], v[22:25]
	v_mfma_f32_16x16x32_bf16 v[14:17], v[174:177], v[246:249], v[14:17]
	v_mfma_f32_16x16x32_bf16 v[50:53], v[178:181], v[206:209], v[50:53]
	v_mfma_f32_16x16x32_bf16 v[42:45], v[198:201], v[206:209], v[42:45]
	v_mfma_f32_16x16x32_bf16 v[34:37], v[178:181], v[214:217], v[34:37]
	v_mfma_f32_16x16x32_bf16 v[26:29], v[198:201], v[214:217], v[26:29]
	v_mfma_f32_16x16x32_bf16 v[18:21], v[178:181], v[222:225], v[18:21]
	v_mfma_f32_16x16x32_bf16 v[10:13], v[198:201], v[222:225], v[10:13]
	v_mfma_f32_16x16x32_bf16 v[6:9], v[178:181], v[236:239], v[6:9]
	v_mfma_f32_16x16x32_bf16 v[2:5], v[198:201], v[236:239], v[2:5]
	v_mfma_f32_16x16x32_bf16 v[50:53], v[182:185], v[210:213], v[50:53]
	v_mfma_f32_16x16x32_bf16 v[42:45], v[202:205], v[210:213], v[42:45]
	v_mfma_f32_16x16x32_bf16 v[34:37], v[182:185], v[218:221], v[34:37]
	v_mfma_f32_16x16x32_bf16 v[26:29], v[202:205], v[218:221], v[26:29]
	v_mfma_f32_16x16x32_bf16 v[18:21], v[182:185], v[226:229], v[18:21]
	v_mfma_f32_16x16x32_bf16 v[10:13], v[202:205], v[226:229], v[10:13]
	v_mfma_f32_16x16x32_bf16 v[6:9], v[182:185], v[246:249], v[6:9]
	v_mfma_f32_16x16x32_bf16 v[2:5], v[202:205], v[246:249], v[2:5]
	s_setprio 0
	s_barrier
	s_add_i32 s65, 0, 0x18000
	v_add_u32_e32 v147, s65, v144
	s_add_i32 s66, 0, 0x1c000
	ds_read_b128 v[150:153], v147
	ds_read_b128 v[166:169], v147 offset:1024
	ds_read_b128 v[170:173], v147 offset:2048
	ds_read_b128 v[174:177], v147 offset:3072
	v_add_u32_e32 v147, s66, v144
	ds_read_b128 v[178:181], v147
	ds_read_b128 v[182:185], v147 offset:1024
	ds_read_b128 v[198:201], v147 offset:2048
	ds_read_b128 v[202:205], v147 offset:3072
	s_add_u32 s46, s46, 0x40000
	s_addc_u32 s47, s47, 0
	s_mov_b32 m0, s53
	v_lshl_add_u64 v[234:235], s[46:47], 0, v[136:137]
	ds_read_b128 v[206:209], v146 offset:32768
	ds_read_b128 v[210:213], v146 offset:33792
	ds_read_b128 v[214:217], v146 offset:34816
	ds_read_b128 v[218:221], v146 offset:35840
	ds_read_b128 v[222:225], v146 offset:36864
	ds_read_b128 v[226:229], v146 offset:37888
	ds_read_b128 v[236:239], v146 offset:38912
	ds_read_b128 v[246:249], v146 offset:39936
	global_load_lds_dwordx4 v[234:235], off
	v_lshl_add_u64 v[234:235], s[46:47], 0, v[132:133]
	s_mov_b32 m0, s54
	s_nop 0
	global_load_lds_dwordx4 v[234:235], off
	s_waitcnt vmcnt(8)
	s_waitcnt lgkmcnt(0)
	s_barrier
	s_setprio 1
	s_waitcnt lgkmcnt(0)
	v_mfma_f32_16x16x32_bf16 v[126:129], v[150:153], v[206:209], v[126:129]
	v_mfma_f32_16x16x32_bf16 v[122:125], v[170:173], v[206:209], v[122:125]
	v_mfma_f32_16x16x32_bf16 v[118:121], v[150:153], v[214:217], v[118:121]
	v_mfma_f32_16x16x32_bf16 v[110:113], v[170:173], v[214:217], v[110:113]
	v_mfma_f32_16x16x32_bf16 v[102:105], v[150:153], v[222:225], v[102:105]
	v_mfma_f32_16x16x32_bf16 v[94:97], v[170:173], v[222:225], v[94:97]
	v_mfma_f32_16x16x32_bf16 v[86:89], v[150:153], v[236:239], v[86:89]
	v_mfma_f32_16x16x32_bf16 v[78:81], v[170:173], v[236:239], v[78:81]
	v_mfma_f32_16x16x32_bf16 v[126:129], v[166:169], v[210:213], v[126:129]
	v_mfma_f32_16x16x32_bf16 v[122:125], v[174:177], v[210:213], v[122:125]
	v_mfma_f32_16x16x32_bf16 v[118:121], v[166:169], v[218:221], v[118:121]
	v_mfma_f32_16x16x32_bf16 v[110:113], v[174:177], v[218:221], v[110:113]
	v_mfma_f32_16x16x32_bf16 v[102:105], v[166:169], v[226:229], v[102:105]
	v_mfma_f32_16x16x32_bf16 v[94:97], v[174:177], v[226:229], v[94:97]
	v_mfma_f32_16x16x32_bf16 v[86:89], v[166:169], v[246:249], v[86:89]
	v_mfma_f32_16x16x32_bf16 v[78:81], v[174:177], v[246:249], v[78:81]
	v_mfma_f32_16x16x32_bf16 v[114:117], v[178:181], v[206:209], v[114:117]
	v_mfma_f32_16x16x32_bf16 v[106:109], v[198:201], v[206:209], v[106:109]
	v_mfma_f32_16x16x32_bf16 v[98:101], v[178:181], v[214:217], v[98:101]
	v_mfma_f32_16x16x32_bf16 v[90:93], v[198:201], v[214:217], v[90:93]
	v_mfma_f32_16x16x32_bf16 v[82:85], v[178:181], v[222:225], v[82:85]
	v_mfma_f32_16x16x32_bf16 v[74:77], v[198:201], v[222:225], v[74:77]
	v_mfma_f32_16x16x32_bf16 v[70:73], v[178:181], v[236:239], v[70:73]
	v_mfma_f32_16x16x32_bf16 v[66:69], v[198:201], v[236:239], v[66:69]
	v_mfma_f32_16x16x32_bf16 v[114:117], v[182:185], v[210:213], v[114:117]
	v_mfma_f32_16x16x32_bf16 v[106:109], v[202:205], v[210:213], v[106:109]
	v_mfma_f32_16x16x32_bf16 v[98:101], v[182:185], v[218:221], v[98:101]
	v_mfma_f32_16x16x32_bf16 v[90:93], v[202:205], v[218:221], v[90:93]
	v_mfma_f32_16x16x32_bf16 v[82:85], v[182:185], v[226:229], v[82:85]
	v_mfma_f32_16x16x32_bf16 v[74:77], v[202:205], v[226:229], v[74:77]
	v_mfma_f32_16x16x32_bf16 v[70:73], v[182:185], v[246:249], v[70:73]
	v_mfma_f32_16x16x32_bf16 v[66:69], v[202:205], v[246:249], v[66:69]
	s_setprio 0
	s_barrier
; #define PG8_STAGE(bufoff, gbase, voff) do { _Pragma("unroll") for (int _i = 0; _i < 2; ++_i) \
;         __builtin_amdgcn_global_load_lds((const unsigned*)((const char*)(gbase) + (voff)[_i]), (PG8_LAS unsigned*)(lds + (bufoff) + ldsw + _i * 8192), 16, 0, 0); } while (0)
; #define PG8_LDA(dst, b, h) do { _Pragma("unroll") for (int m = 0; m < 4; ++m) _Pragma("unroll") for (int k = 0; k < 2; ++k) dst[m][k] = *(const PG8_LAS bf16x8*)(lds + PG8_SA(b, h) + aoff + m * 2048 + k * 1024); } while (0)
; #define PG8_WAIT_V(n) asm volatile("s_waitcnt vmcnt(" #n ")" ::: "memory")
; template <class Epi, class Sched, bool ALIGN_EPI = false, bool SP2 = false>
; __device__ __forceinline__ void gemm_phase(PG8_LAS unsigned char* lds, const Gemm g, const Sched& S, const Epi& E) {
;     ...
;             PG8_LDA(At, 1, 1); PG8_STAGE(PG8_SB(1, 0), b3, voffB); PG8_STAGE(PG8_SB(1, 1), b3 + hstep, voffB); PG8_STAGE(PG8_SA(1, 0), a3, voffA);
;             PG8_WAIT_V(8); PG8_WAIT_L(0); PG8_BAR; PG8_MMA(1, 0, At, B0); PG8_MMA(1, 1, At, B1); PG8_BAR; PG8_SCHED;
;             } else {
;             PG8_LDB(B0, 0, 0); PG8_SCHED; PG8_LDA(At, 0, 0); PG8_STAGE(PG8_SA(1, 1), a1 + hstepA, voffA);
;             PG8_WAIT_L(8); PG8_BAR; PG8_WAIT_L(0); PG8_MMA(0, 0, At, B0); PG8_BAR; PG8_SCHED;
;             PG8_LDB(B1, 0, 1); PG8_STAGE(PG8_SB(0, 0), b2, voffB);
;             PG8_BAR; PG8_WAIT_L(0); PG8_MMA(0, 1, At, B1); PG8_BAR;
;             PG8_LDA(At, 0, 1); PG8_STAGE(PG8_SA(0, 0), a2, voffA);
;             PG8_BAR; PG8_WAIT_L(0); PG8_MMA(1, 0, At, B0); PG8_BAR; PG8_SCHED;
;             PG8_STAGE(PG8_SB(0, 1), b2 + hstep, voffB);
;             PG8_WAIT_V(6); PG8_BAR; PG8_MMA(1, 1, At, B1); PG8_BAR;
;             PG8_LDB(B0, 1, 0); PG8_SCHED; PG8_LDA(At, 1, 0); PG8_STAGE(PG8_SA(0, 1), a2 + hstepA, voffA);
;             PG8_WAIT_L(8); PG8_BAR; PG8_WAIT_L(0); PG8_MMA(0, 0, At, B0); PG8_BAR; PG8_SCHED;
;             PG8_LDB(B1, 1, 1); PG8_STAGE(PG8_SB(1, 0), b3, voffB);
;             PG8_BAR; PG8_WAIT_L(0); PG8_MMA(0, 1, At, B1); PG8_BAR;
;             PG8_LDA(At, 1, 1); PG8_STAGE(PG8_SA(1, 0), a3, voffA);
;             PG8_BAR; PG8_WAIT_L(0); PG8_MMA(1, 0, At, B0); PG8_BAR; PG8_SCHED;
;             PG8_STAGE(PG8_SB(1, 1), b3 + hstep, voffB);
;             PG8_WAIT_V(6); PG8_BAR; PG8_MMA(1, 1, At, B1); PG8_BAR;
;             }
;         }
;         if constexpr (ALIGN_EPI) { if (wr == 0) PG8_BAR; }
	s_add_i32 s46, s65, s50
	v_lshl_add_u64 v[142:143], v[142:143], 0, s[88:89]
	s_mov_b32 m0, s46
	ds_read_b128 v[206:209], v146 offset:49152
	ds_read_b128 v[210:213], v146 offset:50176
	ds_read_b128 v[214:217], v146 offset:51200
	ds_read_b128 v[218:221], v146 offset:52224
	ds_read_b128 v[222:225], v146 offset:53248
	ds_read_b128 v[226:229], v146 offset:54272
	ds_read_b128 v[236:239], v146 offset:55296
	ds_read_b128 v[246:249], v146 offset:56320
	global_load_lds_dwordx4 v[142:143], off
	s_add_i32 m0, s46, 0x2000
	s_add_u32 s44, s44, 0x40080
	v_lshl_add_u64 v[142:143], v[186:187], 0, s[88:89]
	s_addc_u32 s45, s45, 0
	s_add_i32 s46, s66, s50
	global_load_lds_dwordx4 v[142:143], off
	v_lshl_add_u64 v[142:143], s[44:45], 0, v[134:135]
	s_mov_b32 m0, s46
	s_nop 0
	global_load_lds_dwordx4 v[142:143], off
	v_lshl_add_u64 v[142:143], s[44:45], 0, v[130:131]
	s_add_i32 m0, s46, 0x2000
	s_nop 0
	global_load_lds_dwordx4 v[142:143], off
	v_lshl_add_u64 v[142:143], v[190:191], 0, s[88:89]
	s_mov_b32 m0, s56
	s_nop 0
	global_load_lds_dwordx4 v[142:143], off
	v_lshl_add_u64 v[142:143], v[194:195], 0, s[88:89]
	s_mov_b32 m0, s57
	s_nop 0
	global_load_lds_dwordx4 v[142:143], off
	s_waitcnt vmcnt(8)
	s_waitcnt lgkmcnt(0)
	s_barrier
	s_setprio 1
	s_waitcnt lgkmcnt(0)
	v_mfma_f32_16x16x32_bf16 v[62:65], v[150:153], v[206:209], v[62:65]
	v_mfma_f32_16x16x32_bf16 v[58:61], v[170:173], v[206:209], v[58:61]
	v_mfma_f32_16x16x32_bf16 v[54:57], v[150:153], v[214:217], v[54:57]
	v_mfma_f32_16x16x32_bf16 v[46:49], v[170:173], v[214:217], v[46:49]
	v_mfma_f32_16x16x32_bf16 v[38:41], v[150:153], v[222:225], v[38:41]
	v_mfma_f32_16x16x32_bf16 v[30:33], v[170:173], v[222:225], v[30:33]
	v_mfma_f32_16x16x32_bf16 v[22:25], v[150:153], v[236:239], v[22:25]
	v_mfma_f32_16x16x32_bf16 v[14:17], v[170:173], v[236:239], v[14:17]
	v_mfma_f32_16x16x32_bf16 v[62:65], v[166:169], v[210:213], v[62:65]
	v_mfma_f32_16x16x32_bf16 v[58:61], v[174:177], v[210:213], v[58:61]
	v_mfma_f32_16x16x32_bf16 v[54:57], v[166:169], v[218:221], v[54:57]
	v_mfma_f32_16x16x32_bf16 v[46:49], v[174:177], v[218:221], v[46:49]
	v_mfma_f32_16x16x32_bf16 v[38:41], v[166:169], v[226:229], v[38:41]
	v_mfma_f32_16x16x32_bf16 v[30:33], v[174:177], v[226:229], v[30:33]
	v_mfma_f32_16x16x32_bf16 v[22:25], v[166:169], v[246:249], v[22:25]
	v_mfma_f32_16x16x32_bf16 v[14:17], v[174:177], v[246:249], v[14:17]
	v_mfma_f32_16x16x32_bf16 v[50:53], v[178:181], v[206:209], v[50:53]
	v_mfma_f32_16x16x32_bf16 v[42:45], v[198:201], v[206:209], v[42:45]
	v_mfma_f32_16x16x32_bf16 v[34:37], v[178:181], v[214:217], v[34:37]
	v_mfma_f32_16x16x32_bf16 v[26:29], v[198:201], v[214:217], v[26:29]
	v_mfma_f32_16x16x32_bf16 v[18:21], v[178:181], v[222:225], v[18:21]
	v_mfma_f32_16x16x32_bf16 v[10:13], v[198:201], v[222:225], v[10:13]
	v_mfma_f32_16x16x32_bf16 v[6:9], v[178:181], v[236:239], v[6:9]
	v_mfma_f32_16x16x32_bf16 v[2:5], v[198:201], v[236:239], v[2:5]
	v_mfma_f32_16x16x32_bf16 v[50:53], v[182:185], v[210:213], v[50:53]
	v_mfma_f32_16x16x32_bf16 v[42:45], v[202:205], v[210:213], v[42:45]
	v_mfma_f32_16x16x32_bf16 v[34:37], v[182:185], v[218:221], v[34:37]
	v_mfma_f32_16x16x32_bf16 v[26:29], v[202:205], v[218:221], v[26:29]
	v_mfma_f32_16x16x32_bf16 v[18:21], v[182:185], v[226:229], v[18:21]
	v_mfma_f32_16x16x32_bf16 v[10:13], v[202:205], v[226:229], v[10:13]
	v_mfma_f32_16x16x32_bf16 v[6:9], v[182:185], v[246:249], v[6:9]
	v_mfma_f32_16x16x32_bf16 v[2:5], v[202:205], v[246:249], v[2:5]
	s_setprio 0
	s_barrier
	s_add_i32 s64, s64, 2
	s_add_u32 s42, s42, 0x100
	s_addc_u32 s43, s43, 0
	s_add_u32 s62, s62, 0x100
	s_addc_u32 s63, s63, 0
	s_cmp_gt_u32 s64, 13
	s_cbranch_scc0 .LBB0_616
	s_and_b64 vcc, exec, s[4:5]
	s_cbranch_vccz .LBB0_619
	s_barrier

; #define PG8_STAGE(bufoff, gbase, voff) do { _Pragma("unroll") for (int _i = 0; _i < 2; ++_i) \
;         __builtin_amdgcn_global_load_lds((const unsigned*)((const char*)(gbase) + (voff)[_i]), (PG8_LAS unsigned*)(lds + (bufoff) + ldsw + _i * 8192), 16, 0, 0); } while (0)
; #define PG8_LDA(dst, b, h) do { _Pragma("unroll") for (int m = 0; m < 4; ++m) _Pragma("unroll") for (int k = 0; k < 2; ++k) dst[m][k] = *(const PG8_LAS bf16x8*)(lds + PG8_SA(b, h) + aoff + m * 2048 + k * 1024); } while (0)
; #define PG8_LDB(dst, b, h) do { _Pragma("unroll") for (int n = 0; n < 2; ++n) _Pragma("unroll") for (int k = 0; k < 2; ++k) dst[n][k] = *(const PG8_LAS bf16x8*)(lds + PG8_SB(b, h) + boff + n * 2048 + k * 1024); } while (0)
; #define PG8_MMA(ai, bj, At, Bt) do { __builtin_amdgcn_s_setprio(1); _Pragma("unroll") for (int m = 0; m < 4; ++m) _Pragma("unroll") for (int n = 0; n < 2; ++n) _Pragma("unroll") for (int k = 0; k < 2; ++k) \
;         acc[ai][bj][m][n] = __builtin_amdgcn_mfma_f32_16x16x32_bf16(Bt[n][k], At[m][k], acc[ai][bj][m][n], 0, 0, 0); __builtin_amdgcn_s_setprio(0); } while (0)
; #define PG8_BAR __builtin_amdgcn_s_barrier()
; template <class Epi, class Sched, bool ALIGN_EPI = false, bool SP2 = false>
; __device__ __forceinline__ void gemm_phase(PG8_LAS unsigned char* lds, const Gemm g, const Sched& S, const Epi& E) {
;     ...
;         const bool has_next = S.next(ui + 1, nxt);
;         const char* nA = has_next ? (const char*)g.A + (size_t)nxt.pm * tstepA : cA; const char* nB = has_next ? (const char*)g.Bt + (size_t)nxt.pn * tstep : cB;
;         for (int t = 0; t < nt; t += 2) {
;             const bool last = (t == nt - 2);
;             const char* a1 = cA + (size_t)(t + 1) * kstep;
;             const char* a2 = last ? nA : cA + (size_t)(t + 2) * kstep; const char* b2 = last ? nB : cB + (size_t)(t + 2) * kstep;
;             const char* a3 = a2 + kstep; const char* b3 = b2 + kstep;
;             if (last && has_next) S.a_ready(nxt);
;             if constexpr (SP2) {
;             PG8_LDB(B0, 0, 0); PG8_LDB(B1, 0, 1); PG8_SCHED; PG8_LDA(At, 0, 0); PG8_STAGE(PG8_SA(1, 1), a1 + hstepA, voffA);
;             PG8_WAIT_V(8); PG8_WAIT_L(0); PG8_BAR; PG8_MMA(0, 0, At, B0); PG8_MMA(0, 1, At, B1); PG8_BAR; PG8_SCHED;
;             PG8_LDA(At, 0, 1); PG8_STAGE(PG8_SB(0, 0), b2, voffB); PG8_STAGE(PG8_SB(0, 1), b2 + hstep, voffB); PG8_STAGE(PG8_SA(0, 0), a2, voffA);
.LBB0_775:
	s_add_u32 s46, s44, 0xfffc0080
	s_addc_u32 s47, s45, -1
	s_add_i32 s65, 0, 0x10000
	s_cmp_eq_u32 s64, 12
	s_cselect_b32 s49, s9, s47
	s_cselect_b32 s48, s60, s46
	v_add_u32_e32 v142, s65, v144
	s_cselect_b32 s47, s7, s63
	s_cselect_b32 s46, s61, s62
	s_add_i32 s68, 0, 0x14000
	ds_read_b128 v[166:169], v142
	ds_read_b128 v[170:173], v142 offset:1024
	ds_read_b128 v[174:177], v142 offset:2048
	ds_read_b128 v[178:181], v142 offset:3072
	v_add_u32_e32 v142, s68, v144
	ds_read_b128 v[182:185], v142
	ds_read_b128 v[198:201], v142 offset:1024
	ds_read_b128 v[202:205], v142 offset:2048
	ds_read_b128 v[206:209], v142 offset:3072
	v_lshl_add_u64 v[142:143], s[44:45], 0, v[140:141]
	s_add_i32 m0, s52, 0xc000
	ds_read_b128 v[210:213], v146
	ds_read_b128 v[214:217], v146 offset:1024
	ds_read_b128 v[218:221], v146 offset:2048
	ds_read_b128 v[222:225], v146 offset:3072
	ds_read_b128 v[226:229], v146 offset:4096
	ds_read_b128 v[246:249], v146 offset:5120
	ds_read_b128 v[236:239], v146 offset:6144
	ds_read_b128 v[150:153], v146 offset:7168
	global_load_lds_dwordx4 v[142:143], off
	v_lshl_add_u64 v[142:143], s[44:45], 0, v[138:139]
	s_add_i32 m0, s52, 0xe000
	s_nop 0
	global_load_lds_dwordx4 v[142:143], off
	s_waitcnt vmcnt(8)
	s_waitcnt lgkmcnt(0)
	s_barrier
	s_setprio 1
	s_waitcnt lgkmcnt(0)
	v_mfma_f32_16x16x32_bf16 v[126:129], v[166:169], v[210:213], v[126:129]
	v_mfma_f32_16x16x32_bf16 v[118:121], v[174:177], v[210:213], v[118:121]
	v_mfma_f32_16x16x32_bf16 v[110:113], v[166:169], v[218:221], v[110:113]
	v_mfma_f32_16x16x32_bf16 v[102:105], v[174:177], v[218:221], v[102:105]
	v_mfma_f32_16x16x32_bf16 v[94:97], v[166:169], v[226:229], v[94:97]
	v_mfma_f32_16x16x32_bf16 v[86:89], v[174:177], v[226:229], v[86:89]
	v_mfma_f32_16x16x32_bf16 v[78:81], v[166:169], v[236:239], v[78:81]
	v_mfma_f32_16x16x32_bf16 v[70:73], v[174:177], v[236:239], v[70:73]
	v_mfma_f32_16x16x32_bf16 v[126:129], v[170:173], v[214:217], v[126:129]
	v_mfma_f32_16x16x32_bf16 v[118:121], v[178:181], v[214:217], v[118:121]
	v_mfma_f32_16x16x32_bf16 v[110:113], v[170:173], v[222:225], v[110:113]
	v_mfma_f32_16x16x32_bf16 v[102:105], v[178:181], v[222:225], v[102:105]
	v_mfma_f32_16x16x32_bf16 v[94:97], v[170:173], v[246:249], v[94:97]
	v_mfma_f32_16x16x32_bf16 v[86:89], v[178:181], v[246:249], v[86:89]
	v_mfma_f32_16x16x32_bf16 v[78:81], v[170:173], v[150:153], v[78:81]
	v_mfma_f32_16x16x32_bf16 v[70:73], v[178:181], v[150:153], v[70:73]
	v_mfma_f32_16x16x32_bf16 v[122:125], v[182:185], v[210:213], v[122:125]
	v_mfma_f32_16x16x32_bf16 v[114:117], v[202:205], v[210:213], v[114:117]
	v_mfma_f32_16x16x32_bf16 v[106:109], v[182:185], v[218:221], v[106:109]
	v_mfma_f32_16x16x32_bf16 v[98:101], v[202:205], v[218:221], v[98:101]
	v_mfma_f32_16x16x32_bf16 v[90:93], v[182:185], v[226:229], v[90:93]
	v_mfma_f32_16x16x32_bf16 v[82:85], v[202:205], v[226:229], v[82:85]
	v_mfma_f32_16x16x32_bf16 v[74:77], v[182:185], v[236:239], v[74:77]
	v_mfma_f32_16x16x32_bf16 v[66:69], v[202:205], v[236:239], v[66:69]
	v_mfma_f32_16x16x32_bf16 v[122:125], v[198:201], v[214:217], v[122:125]
	v_mfma_f32_16x16x32_bf16 v[114:117], v[206:209], v[214:217], v[114:117]
	v_mfma_f32_16x16x32_bf16 v[106:109], v[198:201], v[222:225], v[106:109]
	v_mfma_f32_16x16x32_bf16 v[98:101], v[206:209], v[222:225], v[98:101]
	v_mfma_f32_16x16x32_bf16 v[90:93], v[198:201], v[246:249], v[90:93]
	v_mfma_f32_16x16x32_bf16 v[82:85], v[206:209], v[246:249], v[82:85]
	v_mfma_f32_16x16x32_bf16 v[74:77], v[198:201], v[150:153], v[74:77]
	v_mfma_f32_16x16x32_bf16 v[66:69], v[206:209], v[150:153], v[66:69]
	s_setprio 0
	s_barrier
	s_add_i32 s65, s65, s50
	v_lshl_add_u64 v[142:143], s[46:47], 0, v[134:135]
	s_mov_b32 m0, s65
	ds_read_b128 v[150:153], v146 offset:16384
	ds_read_b128 v[210:213], v146 offset:17408
	ds_read_b128 v[214:217], v146 offset:18432
	ds_read_b128 v[218:221], v146 offset:19456
	ds_read_b128 v[222:225], v146 offset:20480
	ds_read_b128 v[226:229], v146 offset:21504
	ds_read_b128 v[236:239], v146 offset:22528
	ds_read_b128 v[246:249], v146 offset:23552
	global_load_lds_dwordx4 v[142:143], off
	s_add_i32 m0, s65, 0x2000
	s_add_u32 s66, s46, 0x40000
	v_lshl_add_u64 v[186:187], s[46:47], 0, v[130:131]
	s_addc_u32 s67, s47, 0
	s_add_i32 s65, s68, s50
	global_load_lds_dwordx4 v[186:187], off
	v_lshl_add_u64 v[190:191], s[66:67], 0, v[134:135]
	s_mov_b32 m0, s65
	v_lshl_add_u64 v[194:195], s[48:49], 0, v[132:133]
	global_load_lds_dwordx4 v[190:191], off
	v_lshl_add_u64 v[190:191], s[66:67], 0, v[130:131]
	s_add_i32 m0, s65, 0x2000
	s_nop 0
	global_load_lds_dwordx4 v[190:191], off
	v_lshl_add_u64 v[190:191], s[48:49], 0, v[136:137]
	s_mov_b32 m0, s52
	s_nop 0
	global_load_lds_dwordx4 v[190:191], off
	s_mov_b32 m0, s53
	s_nop 0
	global_load_lds_dwordx4 v[194:195], off
	s_waitcnt vmcnt(8)
	s_waitcnt lgkmcnt(0)
	s_barrier
; #define PG8_STAGE(bufoff, gbase, voff) do { _Pragma("unroll") for (int _i = 0; _i < 2; ++_i) \
;         __builtin_amdgcn_global_load_lds((const unsigned*)((const char*)(gbase) + (voff)[_i]), (PG8_LAS unsigned*)(lds + (bufoff) + ldsw + _i * 8192), 16, 0, 0); } while (0)
; #define PG8_LDA(dst, b, h) do { _Pragma("unroll") for (int m = 0; m < 4; ++m) _Pragma("unroll") for (int k = 0; k < 2; ++k) dst[m][k] = *(const PG8_LAS bf16x8*)(lds + PG8_SA(b, h) + aoff + m * 2048 + k * 1024); } while (0)
; #define PG8_LDB(dst, b, h) do { _Pragma("unroll") for (int n = 0; n < 2; ++n) _Pragma("unroll") for (int k = 0; k < 2; ++k) dst[n][k] = *(const PG8_LAS bf16x8*)(lds + PG8_SB(b, h) + boff + n * 2048 + k * 1024); } while (0)
; #define PG8_MMA(ai, bj, At, Bt) do { __builtin_amdgcn_s_setprio(1); _Pragma("unroll") for (int m = 0; m < 4; ++m) _Pragma("unroll") for (int n = 0; n < 2; ++n) _Pragma("unroll") for (int k = 0; k < 2; ++k) \
;         acc[ai][bj][m][n] = __builtin_amdgcn_mfma_f32_16x16x32_bf16(Bt[n][k], At[m][k], acc[ai][bj][m][n], 0, 0, 0); __builtin_amdgcn_s_setprio(0); } while (0)
; #define PG8_WAIT_V(n) asm volatile("s_waitcnt vmcnt(" #n ")" ::: "memory")
; #define PG8_WAIT_L(n) asm volatile("s_waitcnt lgkmcnt(" #n ")" ::: "memory")
; #define PG8_BAR __builtin_amdgcn_s_barrier()
; template <class Epi, class Sched, bool ALIGN_EPI = false, bool SP2 = false>
; __device__ __forceinline__ void gemm_phase(PG8_LAS unsigned char* lds, const Gemm g, const Sched& S, const Epi& E) {
;     ...
;             PG8_WAIT_V(8); PG8_WAIT_L(0); PG8_BAR; PG8_MMA(0, 0, At, B0); PG8_MMA(0, 1, At, B1); PG8_BAR; PG8_SCHED;
;             PG8_LDA(At, 0, 1); PG8_STAGE(PG8_SB(0, 0), b2, voffB); PG8_STAGE(PG8_SB(0, 1), b2 + hstep, voffB); PG8_STAGE(PG8_SA(0, 0), a2, voffA);
;             PG8_WAIT_V(8); PG8_WAIT_L(0); PG8_BAR; PG8_MMA(1, 0, At, B0); PG8_MMA(1, 1, At, B1); PG8_BAR; PG8_SCHED;
;             PG8_LDB(B0, 1, 0); PG8_LDB(B1, 1, 1); PG8_SCHED; PG8_LDA(At, 1, 0); PG8_STAGE(PG8_SA(0, 1), a2 + hstepA, voffA);
;             PG8_WAIT_V(8); PG8_WAIT_L(0); PG8_BAR; PG8_MMA(0, 0, At, B0); PG8_MMA(0, 1, At, B1); PG8_BAR; PG8_SCHED;
;             PG8_LDA(At, 1, 1); PG8_STAGE(PG8_SB(1, 0), b3, voffB); PG8_STAGE(PG8_SB(1, 1), b3 + hstep, voffB); PG8_STAGE(PG8_SA(1, 0), a3, voffA);
;             PG8_WAIT_V(8); PG8_WAIT_L(0); PG8_BAR; PG8_MMA(1, 0, At, B0); PG8_MMA(1, 1, At, B1); PG8_BAR; PG8_SCHED;
	s_setprio 1
	s_waitcnt lgkmcnt(0)
	v_mfma_f32_16x16x32_bf16 v[62:65], v[166:169], v[150:153], v[62:65]
	v_mfma_f32_16x16x32_bf16 v[54:57], v[174:177], v[150:153], v[54:57]
	v_mfma_f32_16x16x32_bf16 v[46:49], v[166:169], v[214:217], v[46:49]
	v_mfma_f32_16x16x32_bf16 v[38:41], v[174:177], v[214:217], v[38:41]
	v_mfma_f32_16x16x32_bf16 v[30:33], v[166:169], v[222:225], v[30:33]
	v_mfma_f32_16x16x32_bf16 v[22:25], v[174:177], v[222:225], v[22:25]
	v_mfma_f32_16x16x32_bf16 v[14:17], v[166:169], v[236:239], v[14:17]
	v_mfma_f32_16x16x32_bf16 v[6:9], v[174:177], v[236:239], v[6:9]
	v_mfma_f32_16x16x32_bf16 v[62:65], v[170:173], v[210:213], v[62:65]
	v_mfma_f32_16x16x32_bf16 v[54:57], v[178:181], v[210:213], v[54:57]
	v_mfma_f32_16x16x32_bf16 v[46:49], v[170:173], v[218:221], v[46:49]
	v_mfma_f32_16x16x32_bf16 v[38:41], v[178:181], v[218:221], v[38:41]
	v_mfma_f32_16x16x32_bf16 v[30:33], v[170:173], v[226:229], v[30:33]
	v_mfma_f32_16x16x32_bf16 v[22:25], v[178:181], v[226:229], v[22:25]
	v_mfma_f32_16x16x32_bf16 v[14:17], v[170:173], v[246:249], v[14:17]
	v_mfma_f32_16x16x32_bf16 v[6:9], v[178:181], v[246:249], v[6:9]
	v_mfma_f32_16x16x32_bf16 v[58:61], v[182:185], v[150:153], v[58:61]
	v_mfma_f32_16x16x32_bf16 v[50:53], v[202:205], v[150:153], v[50:53]
	v_mfma_f32_16x16x32_bf16 v[42:45], v[182:185], v[214:217], v[42:45]
	v_mfma_f32_16x16x32_bf16 v[34:37], v[202:205], v[214:217], v[34:37]
	v_mfma_f32_16x16x32_bf16 v[26:29], v[182:185], v[222:225], v[26:29]
	v_mfma_f32_16x16x32_bf16 v[18:21], v[202:205], v[222:225], v[18:21]
	v_mfma_f32_16x16x32_bf16 v[10:13], v[182:185], v[236:239], v[10:13]
	v_mfma_f32_16x16x32_bf16 v[2:5], v[202:205], v[236:239], v[2:5]
	v_mfma_f32_16x16x32_bf16 v[58:61], v[198:201], v[210:213], v[58:61]
	v_mfma_f32_16x16x32_bf16 v[50:53], v[206:209], v[210:213], v[50:53]
	v_mfma_f32_16x16x32_bf16 v[42:45], v[198:201], v[218:221], v[42:45]
	v_mfma_f32_16x16x32_bf16 v[34:37], v[206:209], v[218:221], v[34:37]
	v_mfma_f32_16x16x32_bf16 v[26:29], v[198:201], v[226:229], v[26:29]
	v_mfma_f32_16x16x32_bf16 v[18:21], v[206:209], v[226:229], v[18:21]
	v_mfma_f32_16x16x32_bf16 v[10:13], v[198:201], v[246:249], v[10:13]
	v_mfma_f32_16x16x32_bf16 v[2:5], v[206:209], v[246:249], v[2:5]
	s_setprio 0
	s_barrier
	s_add_i32 s65, 0, 0x18000
	v_add_u32_e32 v147, s65, v144
	s_add_i32 s66, 0, 0x1c000
	ds_read_b128 v[150:153], v147
	ds_read_b128 v[166:169], v147 offset:1024
	ds_read_b128 v[170:173], v147 offset:2048
	ds_read_b128 v[174:177], v147 offset:3072
	v_add_u32_e32 v147, s66, v144
	ds_read_b128 v[178:181], v147
	ds_read_b128 v[182:185], v147 offset:1024
	ds_read_b128 v[198:201], v147 offset:2048
	ds_read_b128 v[202:205], v147 offset:3072
	s_add_u32 s48, s48, 0x40000
	s_addc_u32 s49, s49, 0
	s_mov_b32 m0, s54
	v_lshl_add_u64 v[234:235], s[48:49], 0, v[136:137]
	ds_read_b128 v[206:209], v146 offset:32768
	ds_read_b128 v[210:213], v146 offset:33792
	ds_read_b128 v[214:217], v146 offset:34816
	ds_read_b128 v[218:221], v146 offset:35840
	ds_read_b128 v[222:225], v146 offset:36864
	ds_read_b128 v[226:229], v146 offset:37888
	ds_read_b128 v[236:239], v146 offset:38912
	ds_read_b128 v[246:249], v146 offset:39936
	global_load_lds_dwordx4 v[234:235], off
	v_lshl_add_u64 v[234:235], s[48:49], 0, v[132:133]
	s_mov_b32 m0, s55
	s_nop 0
	global_load_lds_dwordx4 v[234:235], off
	s_waitcnt vmcnt(8)
	s_waitcnt lgkmcnt(0)
	s_barrier
	s_setprio 1
	s_waitcnt lgkmcnt(0)
	v_mfma_f32_16x16x32_bf16 v[126:129], v[150:153], v[206:209], v[126:129]
	v_mfma_f32_16x16x32_bf16 v[118:121], v[170:173], v[206:209], v[118:121]
	v_mfma_f32_16x16x32_bf16 v[110:113], v[150:153], v[214:217], v[110:113]
	v_mfma_f32_16x16x32_bf16 v[102:105], v[170:173], v[214:217], v[102:105]
	v_mfma_f32_16x16x32_bf16 v[94:97], v[150:153], v[222:225], v[94:97]
	v_mfma_f32_16x16x32_bf16 v[86:89], v[170:173], v[222:225], v[86:89]
	v_mfma_f32_16x16x32_bf16 v[78:81], v[150:153], v[236:239], v[78:81]
	v_mfma_f32_16x16x32_bf16 v[70:73], v[170:173], v[236:239], v[70:73]
	v_mfma_f32_16x16x32_bf16 v[126:129], v[166:169], v[210:213], v[126:129]
	v_mfma_f32_16x16x32_bf16 v[118:121], v[174:177], v[210:213], v[118:121]
	v_mfma_f32_16x16x32_bf16 v[110:113], v[166:169], v[218:221], v[110:113]
	v_mfma_f32_16x16x32_bf16 v[102:105], v[174:177], v[218:221], v[102:105]
	v_mfma_f32_16x16x32_bf16 v[94:97], v[166:169], v[226:229], v[94:97]
	v_mfma_f32_16x16x32_bf16 v[86:89], v[174:177], v[226:229], v[86:89]
	v_mfma_f32_16x16x32_bf16 v[78:81], v[166:169], v[246:249], v[78:81]
	v_mfma_f32_16x16x32_bf16 v[70:73], v[174:177], v[246:249], v[70:73]
	v_mfma_f32_16x16x32_bf16 v[122:125], v[178:181], v[206:209], v[122:125]
	v_mfma_f32_16x16x32_bf16 v[114:117], v[198:201], v[206:209], v[114:117]
	v_mfma_f32_16x16x32_bf16 v[106:109], v[178:181], v[214:217], v[106:109]
	v_mfma_f32_16x16x32_bf16 v[98:101], v[198:201], v[214:217], v[98:101]
	v_mfma_f32_16x16x32_bf16 v[90:93], v[178:181], v[222:225], v[90:93]
	v_mfma_f32_16x16x32_bf16 v[82:85], v[198:201], v[222:225], v[82:85]
	v_mfma_f32_16x16x32_bf16 v[74:77], v[178:181], v[236:239], v[74:77]
	v_mfma_f32_16x16x32_bf16 v[66:69], v[198:201], v[236:239], v[66:69]
	v_mfma_f32_16x16x32_bf16 v[122:125], v[182:185], v[210:213], v[122:125]
	v_mfma_f32_16x16x32_bf16 v[114:117], v[202:205], v[210:213], v[114:117]
	v_mfma_f32_16x16x32_bf16 v[106:109], v[182:185], v[218:221], v[106:109]
	v_mfma_f32_16x16x32_bf16 v[98:101], v[202:205], v[218:221], v[98:101]
	v_mfma_f32_16x16x32_bf16 v[90:93], v[182:185], v[226:229], v[90:93]
	v_mfma_f32_16x16x32_bf16 v[82:85], v[202:205], v[226:229], v[82:85]
	v_mfma_f32_16x16x32_bf16 v[74:77], v[182:185], v[246:249], v[74:77]
	v_mfma_f32_16x16x32_bf16 v[66:69], v[202:205], v[246:249], v[66:69]
	s_setprio 0
	s_barrier
; #define PG8_STAGE(bufoff, gbase, voff) do { _Pragma("unroll") for (int _i = 0; _i < 2; ++_i) \
;         __builtin_amdgcn_global_load_lds((const unsigned*)((const char*)(gbase) + (voff)[_i]), (PG8_LAS unsigned*)(lds + (bufoff) + ldsw + _i * 8192), 16, 0, 0); } while (0)
; #define PG8_LDA(dst, b, h) do { _Pragma("unroll") for (int m = 0; m < 4; ++m) _Pragma("unroll") for (int k = 0; k < 2; ++k) dst[m][k] = *(const PG8_LAS bf16x8*)(lds + PG8_SA(b, h) + aoff + m * 2048 + k * 1024); } while (0)
; #define PG8_WAIT_V(n) asm volatile("s_waitcnt vmcnt(" #n ")" ::: "memory")
; template <class Epi, class Sched, bool ALIGN_EPI = false, bool SP2 = false>
; __device__ __forceinline__ void gemm_phase(PG8_LAS unsigned char* lds, const Gemm g, const Sched& S, const Epi& E) {
;     ...
;             PG8_LDA(At, 1, 1); PG8_STAGE(PG8_SB(1, 0), b3, voffB); PG8_STAGE(PG8_SB(1, 1), b3 + hstep, voffB); PG8_STAGE(PG8_SA(1, 0), a3, voffA);
;             PG8_WAIT_V(8); PG8_WAIT_L(0); PG8_BAR; PG8_MMA(1, 0, At, B0); PG8_MMA(1, 1, At, B1); PG8_BAR; PG8_SCHED;
;             } else {
;             PG8_LDB(B0, 0, 0); PG8_SCHED; PG8_LDA(At, 0, 0); PG8_STAGE(PG8_SA(1, 1), a1 + hstepA, voffA);
;             PG8_WAIT_L(8); PG8_BAR; PG8_WAIT_L(0); PG8_MMA(0, 0, At, B0); PG8_BAR; PG8_SCHED;
;             PG8_LDB(B1, 0, 1); PG8_STAGE(PG8_SB(0, 0), b2, voffB);
;             PG8_BAR; PG8_WAIT_L(0); PG8_MMA(0, 1, At, B1); PG8_BAR;
;             PG8_LDA(At, 0, 1); PG8_STAGE(PG8_SA(0, 0), a2, voffA);
;             PG8_BAR; PG8_WAIT_L(0); PG8_MMA(1, 0, At, B0); PG8_BAR; PG8_SCHED;
;             PG8_STAGE(PG8_SB(0, 1), b2 + hstep, voffB);
;             PG8_WAIT_V(6); PG8_BAR; PG8_MMA(1, 1, At, B1); PG8_BAR;
;             PG8_LDB(B0, 1, 0); PG8_SCHED; PG8_LDA(At, 1, 0); PG8_STAGE(PG8_SA(0, 1), a2 + hstepA, voffA);
;             PG8_WAIT_L(8); PG8_BAR; PG8_WAIT_L(0); PG8_MMA(0, 0, At, B0); PG8_BAR; PG8_SCHED;
;             PG8_LDB(B1, 1, 1); PG8_STAGE(PG8_SB(1, 0), b3, voffB);
;             PG8_BAR; PG8_WAIT_L(0); PG8_MMA(0, 1, At, B1); PG8_BAR;
;             PG8_LDA(At, 1, 1); PG8_STAGE(PG8_SA(1, 0), a3, voffA);
;             PG8_BAR; PG8_WAIT_L(0); PG8_MMA(1, 0, At, B0); PG8_BAR; PG8_SCHED;
;             PG8_STAGE(PG8_SB(1, 1), b3 + hstep, voffB);
;             PG8_WAIT_V(6); PG8_BAR; PG8_MMA(1, 1, At, B1); PG8_BAR;
;             }
;         }
;         if constexpr (ALIGN_EPI) { if (wr == 0) PG8_BAR; }
	s_add_i32 s48, s65, s50
	v_lshl_add_u64 v[142:143], v[142:143], 0, s[88:89]
	s_mov_b32 m0, s48
	ds_read_b128 v[206:209], v146 offset:49152
	ds_read_b128 v[210:213], v146 offset:50176
	ds_read_b128 v[214:217], v146 offset:51200
	ds_read_b128 v[218:221], v146 offset:52224
	ds_read_b128 v[222:225], v146 offset:53248
	ds_read_b128 v[226:229], v146 offset:54272
	ds_read_b128 v[236:239], v146 offset:55296
	ds_read_b128 v[246:249], v146 offset:56320
	global_load_lds_dwordx4 v[142:143], off
	s_add_i32 m0, s48, 0x2000
	s_add_u32 s46, s46, 0x40080
	v_lshl_add_u64 v[142:143], v[186:187], 0, s[88:89]
	s_addc_u32 s47, s47, 0
	s_add_i32 s48, s66, s50
	global_load_lds_dwordx4 v[142:143], off
	v_lshl_add_u64 v[142:143], s[46:47], 0, v[134:135]
	s_mov_b32 m0, s48
	s_nop 0
	global_load_lds_dwordx4 v[142:143], off
	v_lshl_add_u64 v[142:143], s[46:47], 0, v[130:131]
	s_add_i32 m0, s48, 0x2000
	s_nop 0
	global_load_lds_dwordx4 v[142:143], off
	v_lshl_add_u64 v[142:143], v[190:191], 0, s[88:89]
	s_mov_b32 m0, s57
	s_nop 0
	global_load_lds_dwordx4 v[142:143], off
	v_lshl_add_u64 v[142:143], v[194:195], 0, s[88:89]
	s_mov_b32 m0, s58
	s_nop 0
	global_load_lds_dwordx4 v[142:143], off
	s_waitcnt vmcnt(8)
	s_waitcnt lgkmcnt(0)
	s_barrier
	s_setprio 1
	s_waitcnt lgkmcnt(0)
	v_mfma_f32_16x16x32_bf16 v[62:65], v[150:153], v[206:209], v[62:65]
	v_mfma_f32_16x16x32_bf16 v[54:57], v[170:173], v[206:209], v[54:57]
	v_mfma_f32_16x16x32_bf16 v[46:49], v[150:153], v[214:217], v[46:49]
	v_mfma_f32_16x16x32_bf16 v[38:41], v[170:173], v[214:217], v[38:41]
	v_mfma_f32_16x16x32_bf16 v[30:33], v[150:153], v[222:225], v[30:33]
	v_mfma_f32_16x16x32_bf16 v[22:25], v[170:173], v[222:225], v[22:25]
	v_mfma_f32_16x16x32_bf16 v[14:17], v[150:153], v[236:239], v[14:17]
	v_mfma_f32_16x16x32_bf16 v[6:9], v[170:173], v[236:239], v[6:9]
	v_mfma_f32_16x16x32_bf16 v[62:65], v[166:169], v[210:213], v[62:65]
	v_mfma_f32_16x16x32_bf16 v[54:57], v[174:177], v[210:213], v[54:57]
	v_mfma_f32_16x16x32_bf16 v[46:49], v[166:169], v[218:221], v[46:49]
	v_mfma_f32_16x16x32_bf16 v[38:41], v[174:177], v[218:221], v[38:41]
	v_mfma_f32_16x16x32_bf16 v[30:33], v[166:169], v[226:229], v[30:33]
	v_mfma_f32_16x16x32_bf16 v[22:25], v[174:177], v[226:229], v[22:25]
	v_mfma_f32_16x16x32_bf16 v[14:17], v[166:169], v[246:249], v[14:17]
	v_mfma_f32_16x16x32_bf16 v[6:9], v[174:177], v[246:249], v[6:9]
	v_mfma_f32_16x16x32_bf16 v[58:61], v[178:181], v[206:209], v[58:61]
	v_mfma_f32_16x16x32_bf16 v[50:53], v[198:201], v[206:209], v[50:53]
	v_mfma_f32_16x16x32_bf16 v[42:45], v[178:181], v[214:217], v[42:45]
	v_mfma_f32_16x16x32_bf16 v[34:37], v[198:201], v[214:217], v[34:37]
	v_mfma_f32_16x16x32_bf16 v[26:29], v[178:181], v[222:225], v[26:29]
	v_mfma_f32_16x16x32_bf16 v[18:21], v[198:201], v[222:225], v[18:21]
	v_mfma_f32_16x16x32_bf16 v[10:13], v[178:181], v[236:239], v[10:13]
	v_mfma_f32_16x16x32_bf16 v[2:5], v[198:201], v[236:239], v[2:5]
	v_mfma_f32_16x16x32_bf16 v[58:61], v[182:185], v[210:213], v[58:61]
	v_mfma_f32_16x16x32_bf16 v[50:53], v[202:205], v[210:213], v[50:53]
	v_mfma_f32_16x16x32_bf16 v[42:45], v[182:185], v[218:221], v[42:45]
	v_mfma_f32_16x16x32_bf16 v[34:37], v[202:205], v[218:221], v[34:37]
	v_mfma_f32_16x16x32_bf16 v[26:29], v[182:185], v[226:229], v[26:29]
	v_mfma_f32_16x16x32_bf16 v[18:21], v[202:205], v[226:229], v[18:21]
	v_mfma_f32_16x16x32_bf16 v[10:13], v[182:185], v[246:249], v[10:13]
	v_mfma_f32_16x16x32_bf16 v[2:5], v[202:205], v[246:249], v[2:5]
	s_setprio 0
	s_barrier
	s_add_i32 s64, s64, 2
	s_add_u32 s62, s62, 0x100
	s_addc_u32 s63, s63, 0
	s_add_u32 s44, s44, 0x100
	s_addc_u32 s45, s45, 0
	s_cmp_gt_u32 s64, 13
	s_cbranch_scc0 .LBB0_775
	s_and_b64 vcc, exec, s[4:5]
	s_cbranch_vccz .LBB0_778
	s_barrier
